# EpiResid (7 bf16 instances): x_old loads prefetched 4 steps ahead into dead fragment regs, counted vmcnt so stores and atomics are never waited on
# baseline (speedup 1.0000x reference)
; #define PG8_STAGE(bufoff, gbase, voff) do { _Pragma("unroll") for (int _i = 0; _i < 2; ++_i) \
;         __builtin_amdgcn_global_load_lds((const unsigned*)((const char*)(gbase) + (voff)[_i]), (PG8_LAS unsigned*)(lds + (bufoff) + ldsw + _i * 8192), 16, 0, 0); } while (0)
; #define PG8_LDA(dst, b, h) do { _Pragma("unroll") for (int m = 0; m < 4; ++m) _Pragma("unroll") for (int k = 0; k < 2; ++k) dst[m][k] = *(const PG8_LAS bf16x8*)(lds + PG8_SA(b, h) + aoff + m * 2048 + k * 1024); } while (0)
; #define PG8_LDB(dst, b, h) do { _Pragma("unroll") for (int n = 0; n < 2; ++n) _Pragma("unroll") for (int k = 0; k < 2; ++k) dst[n][k] = *(const PG8_LAS bf16x8*)(lds + PG8_SB(b, h) + boff + n * 2048 + k * 1024); } while (0)
; #define PG8_MMA(ai, bj, At, Bt) do { __builtin_amdgcn_s_setprio(1); _Pragma("unroll") for (int m = 0; m < 4; ++m) _Pragma("unroll") for (int n = 0; n < 2; ++n) _Pragma("unroll") for (int k = 0; k < 2; ++k) \
;         acc[ai][bj][m][n] = __builtin_amdgcn_mfma_f32_16x16x32_bf16(Bt[n][k], At[m][k], acc[ai][bj][m][n], 0, 0, 0); __builtin_amdgcn_s_setprio(0); } while (0)
; #define PG8_WAIT_V(n) asm volatile("s_waitcnt vmcnt(" #n ")" ::: "memory")
; #define PG8_WAIT_L(n) asm volatile("s_waitcnt lgkmcnt(" #n ")" ::: "memory")
; #define PG8_BAR __builtin_amdgcn_s_barrier()
; #define PG8_SCHED __builtin_amdgcn_sched_barrier(0)
; template <class Epi, class Sched, bool ALIGN_EPI = false, bool SP2 = false>
; __device__ __forceinline__ void gemm_phase(PG8_LAS unsigned char* lds, const Gemm g, const Sched& S, const Epi& E) {
;     ...
;             if constexpr (SP2) {
;             PG8_LDB(B0, 0, 0); PG8_LDB(B1, 0, 1); PG8_SCHED; PG8_LDA(At, 0, 0); PG8_STAGE(PG8_SA(1, 1), a1 + hstep, voffA);
;             PG8_WAIT_V(8); PG8_WAIT_L(0); PG8_BAR; PG8_MMA(0, 0, At, B0); PG8_MMA(0, 1, At, B1); PG8_BAR; PG8_SCHED;
;             PG8_LDA(At, 0, 1); PG8_STAGE(PG8_SB(0, 0), b2, voffB); PG8_STAGE(PG8_SB(0, 1), b2 + hstep, voffB); PG8_STAGE(PG8_SA(0, 0), a2, voffA);
.LBB0_650:
	ds_read_b128 v[148:151], v155
	ds_read_b128 v[160:163], v155 offset:1024
	ds_read_b128 v[164:167], v155 offset:2048
	ds_read_b128 v[168:171], v155 offset:3072
	ds_read_b128 v[172:175], v156
	ds_read_b128 v[176:179], v156 offset:1024
	ds_read_b128 v[182:185], v156 offset:2048
	ds_read_b128 v[186:189], v156 offset:3072
	s_add_u32 s3, s60, 0xfffc0080
	s_addc_u32 s14, s61, -1
	s_cmp_eq_u32 s92, 12
	s_cselect_b32 s65, s51, s14
	s_cselect_b32 s64, s57, s3
	s_cselect_b32 s63, s49, s91
	s_cselect_b32 s62, s89, s90
	v_lshl_add_u64 v[202:203], s[60:61], 0, v[140:141]
	s_add_i32 m0, s43, 0xc000
	ds_read_b128 v[190:193], v157
	ds_read_b128 v[194:197], v157 offset:1024
	ds_read_b128 v[198:201], v157 offset:2048
	ds_read_b128 v[208:211], v157 offset:3072
	ds_read_b128 v[212:215], v157 offset:4096
	ds_read_b128 v[216:219], v157 offset:5120
	ds_read_b128 v[220:223], v157 offset:6144
	ds_read_b128 v[224:227], v157 offset:7168
	global_load_lds_dwordx4 v[202:203], off
	v_lshl_add_u64 v[202:203], s[60:61], 0, v[142:143]
	s_add_i32 m0, s43, 0xe000
	s_nop 0
	global_load_lds_dwordx4 v[202:203], off
	s_waitcnt vmcnt(8)
	s_waitcnt lgkmcnt(0)
	s_barrier
	s_setprio 1
	s_waitcnt lgkmcnt(0)
	v_mfma_f32_16x16x32_bf16 v[124:127], v[148:151], v[190:193], v[124:127]
	v_mfma_f32_16x16x32_bf16 v[120:123], v[164:167], v[190:193], v[120:123]
	v_mfma_f32_16x16x32_bf16 v[108:111], v[148:151], v[198:201], v[108:111]
	v_mfma_f32_16x16x32_bf16 v[104:107], v[164:167], v[198:201], v[104:107]
	v_mfma_f32_16x16x32_bf16 v[92:95], v[148:151], v[212:215], v[92:95]
	v_mfma_f32_16x16x32_bf16 v[88:91], v[164:167], v[212:215], v[88:91]
	v_mfma_f32_16x16x32_bf16 v[76:79], v[148:151], v[220:223], v[76:79]
	v_mfma_f32_16x16x32_bf16 v[72:75], v[164:167], v[220:223], v[72:75]
	v_mfma_f32_16x16x32_bf16 v[124:127], v[160:163], v[194:197], v[124:127]
	v_mfma_f32_16x16x32_bf16 v[120:123], v[168:171], v[194:197], v[120:123]
	v_mfma_f32_16x16x32_bf16 v[108:111], v[160:163], v[208:211], v[108:111]
	v_mfma_f32_16x16x32_bf16 v[104:107], v[168:171], v[208:211], v[104:107]
	v_mfma_f32_16x16x32_bf16 v[92:95], v[160:163], v[216:219], v[92:95]
	v_mfma_f32_16x16x32_bf16 v[88:91], v[168:171], v[216:219], v[88:91]
	v_mfma_f32_16x16x32_bf16 v[76:79], v[160:163], v[224:227], v[76:79]
	v_mfma_f32_16x16x32_bf16 v[72:75], v[168:171], v[224:227], v[72:75]
	s_setprio 0
	s_setprio 1
	v_mfma_f32_16x16x32_bf16 v[116:119], v[172:175], v[190:193], v[116:119]
	v_mfma_f32_16x16x32_bf16 v[112:115], v[182:185], v[190:193], v[112:115]
	v_mfma_f32_16x16x32_bf16 v[100:103], v[172:175], v[198:201], v[100:103]
	v_mfma_f32_16x16x32_bf16 v[96:99], v[182:185], v[198:201], v[96:99]
	v_mfma_f32_16x16x32_bf16 v[84:87], v[172:175], v[212:215], v[84:87]
	v_mfma_f32_16x16x32_bf16 v[80:83], v[182:185], v[212:215], v[80:83]
	v_mfma_f32_16x16x32_bf16 v[68:71], v[172:175], v[220:223], v[68:71]
	v_mfma_f32_16x16x32_bf16 v[64:67], v[182:185], v[220:223], v[64:67]
	v_mfma_f32_16x16x32_bf16 v[116:119], v[176:179], v[194:197], v[116:119]
	v_mfma_f32_16x16x32_bf16 v[112:115], v[186:189], v[194:197], v[112:115]
	v_mfma_f32_16x16x32_bf16 v[100:103], v[176:179], v[208:211], v[100:103]
	v_mfma_f32_16x16x32_bf16 v[96:99], v[186:189], v[208:211], v[96:99]
	v_mfma_f32_16x16x32_bf16 v[84:87], v[176:179], v[216:219], v[84:87]
	v_mfma_f32_16x16x32_bf16 v[80:83], v[186:189], v[216:219], v[80:83]
	v_mfma_f32_16x16x32_bf16 v[68:71], v[176:179], v[224:227], v[68:71]
	v_mfma_f32_16x16x32_bf16 v[64:67], v[186:189], v[224:227], v[64:67]
	s_setprio 0
	s_barrier
	s_add_i32 s3, s85, s34
	v_lshl_add_u64 v[202:203], s[62:63], 0, v[134:135]
	s_mov_b32 m0, s3
	ds_read_b128 v[190:193], v157 offset:16384
	ds_read_b128 v[194:197], v157 offset:17408
	ds_read_b128 v[198:201], v157 offset:18432
	ds_read_b128 v[208:211], v157 offset:19456
	ds_read_b128 v[212:215], v157 offset:20480
	ds_read_b128 v[216:219], v157 offset:21504
	ds_read_b128 v[220:223], v157 offset:22528
	ds_read_b128 v[224:227], v157 offset:23552
	global_load_lds_dwordx4 v[202:203], off
	s_add_i32 m0, s3, 0x2000
	s_add_u32 s14, s62, 0x40000
	v_lshl_add_u64 v[228:229], s[62:63], 0, v[138:139]
	s_addc_u32 s15, s63, 0
	s_add_i32 s3, s86, s34
	global_load_lds_dwordx4 v[228:229], off
	v_lshl_add_u64 v[230:231], s[14:15], 0, v[134:135]
	s_mov_b32 m0, s3
	v_lshl_add_u64 v[232:233], s[64:65], 0, v[136:137]
	global_load_lds_dwordx4 v[230:231], off
	v_lshl_add_u64 v[230:231], s[14:15], 0, v[138:139]
	s_add_i32 m0, s3, 0x2000
	s_nop 0
	global_load_lds_dwordx4 v[230:231], off
	v_lshl_add_u64 v[230:231], s[64:65], 0, v[132:133]
	s_mov_b32 m0, s43
	s_nop 0
	global_load_lds_dwordx4 v[230:231], off
	s_mov_b32 m0, s59
	s_nop 0
	global_load_lds_dwordx4 v[232:233], off
	s_waitcnt vmcnt(8)
	s_waitcnt lgkmcnt(0)
	s_barrier
; #define PG8_STAGE(bufoff, gbase, voff) do { _Pragma("unroll") for (int _i = 0; _i < 2; ++_i) \
;         __builtin_amdgcn_global_load_lds((const unsigned*)((const char*)(gbase) + (voff)[_i]), (PG8_LAS unsigned*)(lds + (bufoff) + ldsw + _i * 8192), 16, 0, 0); } while (0)
; #define PG8_LDA(dst, b, h) do { _Pragma("unroll") for (int m = 0; m < 4; ++m) _Pragma("unroll") for (int k = 0; k < 2; ++k) dst[m][k] = *(const PG8_LAS bf16x8*)(lds + PG8_SA(b, h) + aoff + m * 2048 + k * 1024); } while (0)
; #define PG8_LDB(dst, b, h) do { _Pragma("unroll") for (int n = 0; n < 2; ++n) _Pragma("unroll") for (int k = 0; k < 2; ++k) dst[n][k] = *(const PG8_LAS bf16x8*)(lds + PG8_SB(b, h) + boff + n * 2048 + k * 1024); } while (0)
; #define PG8_MMA(ai, bj, At, Bt) do { __builtin_amdgcn_s_setprio(1); _Pragma("unroll") for (int m = 0; m < 4; ++m) _Pragma("unroll") for (int n = 0; n < 2; ++n) _Pragma("unroll") for (int k = 0; k < 2; ++k) \
;         acc[ai][bj][m][n] = __builtin_amdgcn_mfma_f32_16x16x32_bf16(Bt[n][k], At[m][k], acc[ai][bj][m][n], 0, 0, 0); __builtin_amdgcn_s_setprio(0); } while (0)
; #define PG8_WAIT_V(n) asm volatile("s_waitcnt vmcnt(" #n ")" ::: "memory")
; #define PG8_WAIT_L(n) asm volatile("s_waitcnt lgkmcnt(" #n ")" ::: "memory")
; #define PG8_BAR __builtin_amdgcn_s_barrier()
; #define PG8_SCHED __builtin_amdgcn_sched_barrier(0)
; template <class Epi, class Sched, bool ALIGN_EPI = false, bool SP2 = false>
; __device__ __forceinline__ void gemm_phase(PG8_LAS unsigned char* lds, const Gemm g, const Sched& S, const Epi& E) {
;     ...
;             PG8_WAIT_V(8); PG8_WAIT_L(0); PG8_BAR; PG8_MMA(1, 0, At, B0); PG8_MMA(1, 1, At, B1); PG8_BAR; PG8_SCHED;
;             PG8_LDB(B0, 1, 0); PG8_LDB(B1, 1, 1); PG8_SCHED; PG8_LDA(At, 1, 0); PG8_STAGE(PG8_SA(0, 1), a2 + hstep, voffA);
;             PG8_WAIT_V(8); PG8_WAIT_L(0); PG8_BAR; PG8_MMA(0, 0, At, B0); PG8_MMA(0, 1, At, B1); PG8_BAR; PG8_SCHED;
	s_setprio 1
	s_waitcnt lgkmcnt(0)
	v_mfma_f32_16x16x32_bf16 v[60:63], v[148:151], v[190:193], v[60:63]
	v_mfma_f32_16x16x32_bf16 v[56:59], v[164:167], v[190:193], v[56:59]
	v_mfma_f32_16x16x32_bf16 v[44:47], v[148:151], v[198:201], v[44:47]
	v_mfma_f32_16x16x32_bf16 v[40:43], v[164:167], v[198:201], v[40:43]
	v_mfma_f32_16x16x32_bf16 v[28:31], v[148:151], v[212:215], v[28:31]
	v_mfma_f32_16x16x32_bf16 v[24:27], v[164:167], v[212:215], v[24:27]
	v_mfma_f32_16x16x32_bf16 v[12:15], v[148:151], v[220:223], v[12:15]
	v_mfma_f32_16x16x32_bf16 v[8:11], v[164:167], v[220:223], v[8:11]
	v_mfma_f32_16x16x32_bf16 v[60:63], v[160:163], v[194:197], v[60:63]
	v_mfma_f32_16x16x32_bf16 v[56:59], v[168:171], v[194:197], v[56:59]
	v_mfma_f32_16x16x32_bf16 v[44:47], v[160:163], v[208:211], v[44:47]
	v_mfma_f32_16x16x32_bf16 v[40:43], v[168:171], v[208:211], v[40:43]
	v_mfma_f32_16x16x32_bf16 v[28:31], v[160:163], v[216:219], v[28:31]
	v_mfma_f32_16x16x32_bf16 v[24:27], v[168:171], v[216:219], v[24:27]
	v_mfma_f32_16x16x32_bf16 v[12:15], v[160:163], v[224:227], v[12:15]
	v_mfma_f32_16x16x32_bf16 v[8:11], v[168:171], v[224:227], v[8:11]
	s_setprio 0
	s_setprio 1
	v_mfma_f32_16x16x32_bf16 v[52:55], v[172:175], v[190:193], v[52:55]
	v_mfma_f32_16x16x32_bf16 v[48:51], v[182:185], v[190:193], v[48:51]
	v_mfma_f32_16x16x32_bf16 v[36:39], v[172:175], v[198:201], v[36:39]
	v_mfma_f32_16x16x32_bf16 v[32:35], v[182:185], v[198:201], v[32:35]
	v_mfma_f32_16x16x32_bf16 v[20:23], v[172:175], v[212:215], v[20:23]
	v_mfma_f32_16x16x32_bf16 v[16:19], v[182:185], v[212:215], v[16:19]
	v_mfma_f32_16x16x32_bf16 v[4:7], v[172:175], v[220:223], v[4:7]
	v_mfma_f32_16x16x32_bf16 v[0:3], v[182:185], v[220:223], v[0:3]
	v_mfma_f32_16x16x32_bf16 v[52:55], v[176:179], v[194:197], v[52:55]
	v_mfma_f32_16x16x32_bf16 v[48:51], v[186:189], v[194:197], v[48:51]
	v_mfma_f32_16x16x32_bf16 v[36:39], v[176:179], v[208:211], v[36:39]
	v_mfma_f32_16x16x32_bf16 v[32:35], v[186:189], v[208:211], v[32:35]
	v_mfma_f32_16x16x32_bf16 v[20:23], v[176:179], v[216:219], v[20:23]
	v_mfma_f32_16x16x32_bf16 v[16:19], v[186:189], v[216:219], v[16:19]
	v_mfma_f32_16x16x32_bf16 v[4:7], v[176:179], v[224:227], v[4:7]
	v_mfma_f32_16x16x32_bf16 v[0:3], v[186:189], v[224:227], v[0:3]
	s_setprio 0
	s_barrier
	s_add_i32 s3, 0, 0x18000
	v_add_u32_e32 v159, s3, v131
	s_add_i32 s33, 0, 0x1c000
	ds_read_b128 v[148:151], v159
	ds_read_b128 v[160:163], v159 offset:1024
	ds_read_b128 v[164:167], v159 offset:2048
	ds_read_b128 v[168:171], v159 offset:3072
	v_add_u32_e32 v159, s33, v131
	ds_read_b128 v[172:175], v159
	ds_read_b128 v[176:179], v159 offset:1024
	ds_read_b128 v[182:185], v159 offset:2048
	ds_read_b128 v[186:189], v159 offset:3072
	s_add_u32 s14, s64, 0x40000
	s_addc_u32 s15, s65, 0
	s_mov_b32 m0, s66
	v_lshl_add_u64 v[234:235], s[14:15], 0, v[132:133]
	ds_read_b128 v[190:193], v157 offset:32768
	ds_read_b128 v[194:197], v157 offset:33792
	ds_read_b128 v[198:201], v157 offset:34816
	ds_read_b128 v[208:211], v157 offset:35840
	ds_read_b128 v[212:215], v157 offset:36864
	ds_read_b128 v[216:219], v157 offset:37888
	ds_read_b128 v[220:223], v157 offset:38912
	ds_read_b128 v[224:227], v157 offset:39936
	global_load_lds_dwordx4 v[234:235], off
	v_lshl_add_u64 v[234:235], s[14:15], 0, v[136:137]
	s_mov_b32 m0, s67
	s_nop 0
	global_load_lds_dwordx4 v[234:235], off
	s_waitcnt vmcnt(8)
	s_waitcnt lgkmcnt(0)
	s_barrier
	s_setprio 1
	s_waitcnt lgkmcnt(0)
	v_mfma_f32_16x16x32_bf16 v[124:127], v[148:151], v[190:193], v[124:127]
	v_mfma_f32_16x16x32_bf16 v[120:123], v[164:167], v[190:193], v[120:123]
	v_mfma_f32_16x16x32_bf16 v[108:111], v[148:151], v[198:201], v[108:111]
	v_mfma_f32_16x16x32_bf16 v[104:107], v[164:167], v[198:201], v[104:107]
	v_mfma_f32_16x16x32_bf16 v[92:95], v[148:151], v[212:215], v[92:95]
	v_mfma_f32_16x16x32_bf16 v[88:91], v[164:167], v[212:215], v[88:91]
	v_mfma_f32_16x16x32_bf16 v[76:79], v[148:151], v[220:223], v[76:79]
	v_mfma_f32_16x16x32_bf16 v[72:75], v[164:167], v[220:223], v[72:75]
	v_mfma_f32_16x16x32_bf16 v[124:127], v[160:163], v[194:197], v[124:127]
	v_mfma_f32_16x16x32_bf16 v[120:123], v[168:171], v[194:197], v[120:123]
	v_mfma_f32_16x16x32_bf16 v[108:111], v[160:163], v[208:211], v[108:111]
	v_mfma_f32_16x16x32_bf16 v[104:107], v[168:171], v[208:211], v[104:107]
	v_mfma_f32_16x16x32_bf16 v[92:95], v[160:163], v[216:219], v[92:95]
	v_mfma_f32_16x16x32_bf16 v[88:91], v[168:171], v[216:219], v[88:91]
	v_mfma_f32_16x16x32_bf16 v[76:79], v[160:163], v[224:227], v[76:79]
	v_mfma_f32_16x16x32_bf16 v[72:75], v[168:171], v[224:227], v[72:75]
	s_setprio 0
	s_setprio 1
	v_mfma_f32_16x16x32_bf16 v[116:119], v[172:175], v[190:193], v[116:119]
	v_mfma_f32_16x16x32_bf16 v[112:115], v[182:185], v[190:193], v[112:115]
	v_mfma_f32_16x16x32_bf16 v[100:103], v[172:175], v[198:201], v[100:103]
	v_mfma_f32_16x16x32_bf16 v[96:99], v[182:185], v[198:201], v[96:99]
	v_mfma_f32_16x16x32_bf16 v[84:87], v[172:175], v[212:215], v[84:87]
	v_mfma_f32_16x16x32_bf16 v[80:83], v[182:185], v[212:215], v[80:83]
	v_mfma_f32_16x16x32_bf16 v[68:71], v[172:175], v[220:223], v[68:71]
	v_mfma_f32_16x16x32_bf16 v[64:67], v[182:185], v[220:223], v[64:67]
	v_mfma_f32_16x16x32_bf16 v[116:119], v[176:179], v[194:197], v[116:119]
	v_mfma_f32_16x16x32_bf16 v[112:115], v[186:189], v[194:197], v[112:115]
	v_mfma_f32_16x16x32_bf16 v[100:103], v[176:179], v[208:211], v[100:103]
	v_mfma_f32_16x16x32_bf16 v[96:99], v[186:189], v[208:211], v[96:99]
	v_mfma_f32_16x16x32_bf16 v[84:87], v[176:179], v[216:219], v[84:87]
	v_mfma_f32_16x16x32_bf16 v[80:83], v[186:189], v[216:219], v[80:83]
	v_mfma_f32_16x16x32_bf16 v[68:71], v[176:179], v[224:227], v[68:71]
	v_mfma_f32_16x16x32_bf16 v[64:67], v[186:189], v[224:227], v[64:67]
	s_setprio 0
	s_barrier
; #define PG8_STAGE(bufoff, gbase, voff) do { _Pragma("unroll") for (int _i = 0; _i < 2; ++_i) \
;         __builtin_amdgcn_global_load_lds((const unsigned*)((const char*)(gbase) + (voff)[_i]), (PG8_LAS unsigned*)(lds + (bufoff) + ldsw + _i * 8192), 16, 0, 0); } while (0)
; #define PG8_LDA(dst, b, h) do { _Pragma("unroll") for (int m = 0; m < 4; ++m) _Pragma("unroll") for (int k = 0; k < 2; ++k) dst[m][k] = *(const PG8_LAS bf16x8*)(lds + PG8_SA(b, h) + aoff + m * 2048 + k * 1024); } while (0)
; #define PG8_MMA(ai, bj, At, Bt) do { __builtin_amdgcn_s_setprio(1); _Pragma("unroll") for (int m = 0; m < 4; ++m) _Pragma("unroll") for (int n = 0; n < 2; ++n) _Pragma("unroll") for (int k = 0; k < 2; ++k) \
;         acc[ai][bj][m][n] = __builtin_amdgcn_mfma_f32_16x16x32_bf16(Bt[n][k], At[m][k], acc[ai][bj][m][n], 0, 0, 0); __builtin_amdgcn_s_setprio(0); } while (0)
; #define PG8_WAIT_V(n) asm volatile("s_waitcnt vmcnt(" #n ")" ::: "memory")
; #define PG8_WAIT_L(n) asm volatile("s_waitcnt lgkmcnt(" #n ")" ::: "memory")
; #define PG8_BAR __builtin_amdgcn_s_barrier()
; #define PG8_SCHED __builtin_amdgcn_sched_barrier(0)
;     __device__ __forceinline__ void operator()(const f32x4 (&acc)[2][2][4][2], const Unit& u, int wr, int wc, int fr, int fq) const {
;     ...
;             for (int m = 0; m < 4; ++m) { const int row = row0 + ai * HALF + m * 16; const size_t off = (size_t)row * 1024 + col0; float s = 0.f;
; #pragma unroll
;                 for (int bj = 0; bj < 2; ++bj) { f32x4 a0, a1;
;                     if (xin32) { const float* p = xin32 + off + bj * HALF; a0 = *(const f32x4*)p; a1 = *(const f32x4*)(p + 4); }
;                     else { const u32x4 w = *(const u32x4*)(xb + off + bj * HALF);
; template <class Epi, class Sched, bool ALIGN_EPI = false, bool SP2 = false>
; __device__ __forceinline__ void gemm_phase(PG8_LAS unsigned char* lds, const Gemm g, const Sched& S, const Epi& E) {
;     ...
;             PG8_WAIT_V(8); PG8_WAIT_L(0); PG8_BAR; PG8_MMA(0, 0, At, B0); PG8_MMA(0, 1, At, B1); PG8_BAR; PG8_SCHED;
;             PG8_LDA(At, 1, 1); PG8_STAGE(PG8_SB(1, 0), b3, voffB); PG8_STAGE(PG8_SB(1, 1), b3 + hstep, voffB); PG8_STAGE(PG8_SA(1, 0), a3, voffA);
;             PG8_WAIT_V(8); PG8_WAIT_L(0); PG8_BAR; PG8_MMA(1, 0, At, B0); PG8_MMA(1, 1, At, B1); PG8_BAR; PG8_SCHED;
	s_add_i32 s3, s3, s34
	v_lshl_add_u64 v[202:203], v[202:203], 0, s[38:39]
	s_mov_b32 m0, s3
	ds_read_b128 v[190:193], v157 offset:49152
	ds_read_b128 v[194:197], v157 offset:50176
	ds_read_b128 v[198:201], v157 offset:51200
	ds_read_b128 v[208:211], v157 offset:52224
	ds_read_b128 v[212:215], v157 offset:53248
	ds_read_b128 v[216:219], v157 offset:54272
	ds_read_b128 v[220:223], v157 offset:55296
	ds_read_b128 v[224:227], v157 offset:56320
	global_load_lds_dwordx4 v[202:203], off
	s_add_i32 m0, s3, 0x2000
	s_add_u32 s14, s62, 0x40080
	v_lshl_add_u64 v[202:203], v[228:229], 0, s[38:39]
	s_addc_u32 s15, s63, 0
	s_add_i32 s3, s33, s34
	global_load_lds_dwordx4 v[202:203], off
	v_lshl_add_u64 v[202:203], s[14:15], 0, v[134:135]
	s_mov_b32 m0, s3
	s_nop 0
	global_load_lds_dwordx4 v[202:203], off
	v_lshl_add_u64 v[202:203], s[14:15], 0, v[138:139]
	s_add_i32 m0, s3, 0x2000
	s_nop 0
	global_load_lds_dwordx4 v[202:203], off
	v_lshl_add_u64 v[202:203], v[230:231], 0, s[38:39]
	s_mov_b32 m0, s75
	s_nop 0
	global_load_lds_dwordx4 v[202:203], off
	v_lshl_add_u64 v[202:203], v[232:233], 0, s[38:39]
	s_mov_b32 m0, s84
	s_nop 0
	global_load_lds_dwordx4 v[202:203], off
	s_waitcnt vmcnt(8)
	s_waitcnt lgkmcnt(0)
	s_barrier
	s_setprio 1
	s_waitcnt lgkmcnt(0)
	v_mfma_f32_16x16x32_bf16 v[60:63], v[148:151], v[190:193], v[60:63]
	v_mfma_f32_16x16x32_bf16 v[56:59], v[164:167], v[190:193], v[56:59]
	v_mfma_f32_16x16x32_bf16 v[44:47], v[148:151], v[198:201], v[44:47]
	v_mfma_f32_16x16x32_bf16 v[40:43], v[164:167], v[198:201], v[40:43]
	v_mfma_f32_16x16x32_bf16 v[28:31], v[148:151], v[212:215], v[28:31]
	v_mfma_f32_16x16x32_bf16 v[24:27], v[164:167], v[212:215], v[24:27]
	v_mfma_f32_16x16x32_bf16 v[12:15], v[148:151], v[220:223], v[12:15]
	v_mfma_f32_16x16x32_bf16 v[8:11], v[164:167], v[220:223], v[8:11]
	v_mfma_f32_16x16x32_bf16 v[60:63], v[160:163], v[194:197], v[60:63]
	v_mfma_f32_16x16x32_bf16 v[56:59], v[168:171], v[194:197], v[56:59]
	v_mfma_f32_16x16x32_bf16 v[44:47], v[160:163], v[208:211], v[44:47]
	v_mfma_f32_16x16x32_bf16 v[40:43], v[168:171], v[208:211], v[40:43]
	v_mfma_f32_16x16x32_bf16 v[28:31], v[160:163], v[216:219], v[28:31]
	v_mfma_f32_16x16x32_bf16 v[24:27], v[168:171], v[216:219], v[24:27]
	v_mfma_f32_16x16x32_bf16 v[12:15], v[160:163], v[224:227], v[12:15]
	v_mfma_f32_16x16x32_bf16 v[8:11], v[168:171], v[224:227], v[8:11]
	s_setprio 0
	s_setprio 1
	v_mfma_f32_16x16x32_bf16 v[52:55], v[172:175], v[190:193], v[52:55]
	v_mfma_f32_16x16x32_bf16 v[48:51], v[182:185], v[190:193], v[48:51]
	v_mfma_f32_16x16x32_bf16 v[36:39], v[172:175], v[198:201], v[36:39]
	v_mfma_f32_16x16x32_bf16 v[32:35], v[182:185], v[198:201], v[32:35]
	v_mfma_f32_16x16x32_bf16 v[20:23], v[172:175], v[212:215], v[20:23]
	v_mfma_f32_16x16x32_bf16 v[16:19], v[182:185], v[212:215], v[16:19]
	v_mfma_f32_16x16x32_bf16 v[4:7], v[172:175], v[220:223], v[4:7]
	v_mfma_f32_16x16x32_bf16 v[0:3], v[182:185], v[220:223], v[0:3]
	v_mfma_f32_16x16x32_bf16 v[52:55], v[176:179], v[194:197], v[52:55]
	v_mfma_f32_16x16x32_bf16 v[48:51], v[186:189], v[194:197], v[48:51]
	v_mfma_f32_16x16x32_bf16 v[36:39], v[176:179], v[208:211], v[36:39]
	v_mfma_f32_16x16x32_bf16 v[32:35], v[186:189], v[208:211], v[32:35]
	v_mfma_f32_16x16x32_bf16 v[20:23], v[176:179], v[216:219], v[20:23]
	v_mfma_f32_16x16x32_bf16 v[16:19], v[186:189], v[216:219], v[16:19]
	v_mfma_f32_16x16x32_bf16 v[4:7], v[176:179], v[224:227], v[4:7]
	v_mfma_f32_16x16x32_bf16 v[0:3], v[186:189], v[224:227], v[0:3]
	s_setprio 0
	s_barrier
	s_add_i32 s92, s92, 2
	s_add_u32 s60, s60, 0x100
	s_addc_u32 s61, s61, 0
	s_add_u32 s90, s90, 0x100
	s_addc_u32 s91, s91, 0
	s_cmp_gt_u32 s92, 13
	s_cbranch_scc0 .LBB0_650
	v_lshl_add_u32 v150, s58, 8, v129
	v_ashrrev_i32_e32 v151, 31, v150
	v_lshl_or_b32 v148, s56, 8, v154
	v_lshlrev_b64 v[160:161], 11, v[150:151]
	v_ashrrev_i32_e32 v149, 31, v148
	v_lshl_add_u64 v[160:161], s[22:23], 0, v[160:161]
	v_lshl_add_u64 v[170:171], v[148:149], 1, v[160:161]
	s_mov_b64 s[98:99], 0x8000
	s_mov_b64 s[100:101], 0x28000
	global_load_dwordx4 v[182:185], v[170:171], off
	global_load_dwordx4 v[186:189], v[170:171], off offset:256
	v_lshl_add_u64 v[198:199], v[170:171], 0, s[98:99]
	global_load_dwordx4 v[190:193], v[198:199], off
	global_load_dwordx4 v[194:197], v[198:199], off offset:256
	v_lshl_add_u64 v[198:199], v[198:199], 0, s[98:99]
	global_load_dwordx4 v[208:211], v[198:199], off
	global_load_dwordx4 v[212:215], v[198:199], off offset:256
	v_lshl_add_u64 v[198:199], v[198:199], 0, s[98:99]
	global_load_dwordx4 v[216:219], v[198:199], off
	global_load_dwordx4 v[220:223], v[198:199], off offset:256
	v_lshl_add_u64 v[198:199], v[198:199], 0, s[100:101]
	s_and_b64 vcc, exec, s[44:45]
	s_cbranch_vccz .LBB0_653
	s_barrier
; __device__ __forceinline__ void fx_add(float* p, size_t idx, float s) { atomicAdd((unsigned long long*)p + idx, (unsigned long long)(long long)(s * 4294967296.0f)); }
; __device__ __forceinline__ unsigned cvtpk(float lo, float hi) { f32x2v_ v = {lo, hi}; bf16x2v_ b = __builtin_convertvector(v, bf16x2v_); return __builtin_bit_cast(unsigned, b); }
;     __device__ __forceinline__ void operator()(const f32x4 (&acc)[2][2][4][2], const Unit& u, int wr, int wc, int fr, int fq) const {
;     ...
;             for (int m = 0; m < 4; ++m) { const int row = row0 + ai * HALF + m * 16; const size_t off = (size_t)row * 1024 + col0; float s = 0.f;
; #pragma unroll
;                 for (int bj = 0; bj < 2; ++bj) { f32x4 a0, a1;
;                     if (xin32) { const float* p = xin32 + off + bj * HALF; a0 = *(const f32x4*)p; a1 = *(const f32x4*)(p + 4); }
;                     else { const u32x4 w = *(const u32x4*)(xb + off + bj * HALF);
;                         a0 = (f32x4){__uint_as_float(w.x << 16), __uint_as_float(w.x & 0xffff0000u), __uint_as_float(w.y << 16), __uint_as_float(w.y & 0xffff0000u)};
;                         a1 = (f32x4){__uint_as_float(w.z << 16), __uint_as_float(w.z & 0xffff0000u), __uint_as_float(w.w << 16), __uint_as_float(w.w & 0xffff0000u)}; }
;                     const f32x4 v0 = a0 + acc[ai][bj][m][0] * alpha, v1 = a1 + acc[ai][bj][m][1] * alpha;
;                     u32x4 w; w.x = cvtpk(v0[0], v0[1]); w.y = cvtpk(v0[2], v0[3]); w.z = cvtpk(v1[0], v1[1]); w.w = cvtpk(v1[2], v1[3]);
;                     *(u32x4*)(xb + off + bj * HALF) = w;
;                     s += (v0[0] * v0[0] + v0[1] * v0[1]) + (v0[2] * v0[2] + v0[3] * v0[3]) + (v1[0] * v1[0] + v1[1] * v1[1]) + (v1[2] * v1[2] + v1[3] * v1[3]); }
;                 s += __shfl_xor(s, 16); s += __shfl_xor(s, 32);
;                 if (fq == 0) fx_add(ssout, row, s); }
.LBB0_653:
	s_nop 0
	s_nop 0
	v_and_b32_e32 v160, 64, v158
	v_xor_b32_e32 v159, 16, v158
	v_add_u32_e32 v160, 64, v160
	v_xor_b32_e32 v161, 32, v158
	v_cmp_lt_i32_e32 vcc, v159, v160
	s_waitcnt vmcnt(6)
	v_lshlrev_b32_e32 v172, 16, v182
	v_cndmask_b32_e32 v159, v158, v159, vcc
	v_cmp_lt_i32_e32 vcc, v161, v160
	v_and_b32_e32 v173, 0xffff0000, v182
	v_lshlrev_b32_e32 v162, 16, v183
	v_and_b32_e32 v163, 0xffff0000, v183
	v_lshlrev_b32_e32 v176, 16, v186
	v_and_b32_e32 v177, 0xffff0000, v186
	v_lshlrev_b32_e32 v166, 16, v187
	v_and_b32_e32 v167, 0xffff0000, v187
	v_cndmask_b32_e32 v161, v158, v161, vcc
	v_lshlrev_b32_e32 v174, 16, v184
	v_and_b32_e32 v175, 0xffff0000, v184
	v_lshlrev_b32_e32 v164, 16, v185
	v_and_b32_e32 v165, 0xffff0000, v185
	v_lshlrev_b32_e32 v178, 16, v188
	v_and_b32_e32 v179, 0xffff0000, v188
	v_lshlrev_b32_e32 v168, 16, v189
	v_and_b32_e32 v169, 0xffff0000, v189
	global_load_dwordx4 v[182:185], v[198:199], off
	global_load_dwordx4 v[186:189], v[198:199], off offset:256
	v_lshl_add_u64 v[198:199], v[198:199], 0, s[98:99]
	v_pk_add_f32 v[126:127], v[126:127], v[162:163]
	v_pk_add_f32 v[124:125], v[124:125], v[172:173]
	v_pk_add_f32 v[118:119], v[118:119], v[166:167]
	v_pk_add_f32 v[116:117], v[116:117], v[176:177]
	v_lshlrev_b32_e32 v160, 2, v159
	v_lshlrev_b32_e32 v159, 2, v161
	v_pk_add_f32 v[122:123], v[122:123], v[164:165]
	v_pk_add_f32 v[120:121], v[120:121], v[174:175]
	v_pk_add_f32 v[162:163], v[114:115], v[168:169]
	v_pk_add_f32 v[164:165], v[112:113], v[178:179]
	v_mul_f32_e32 v114, v125, v125
	v_mul_f32_e32 v115, v127, v127
	v_mul_f32_e32 v161, v117, v117
	v_mul_f32_e32 v166, v119, v119
	v_cvt_pk_bf16_f32 v112, v124, v125
	v_mul_f32_e32 v125, v121, v121
	v_mul_f32_e32 v167, v165, v165
	v_fmac_f32_e32 v114, v124, v124
	v_fmac_f32_e32 v115, v126, v126
	v_fmac_f32_e32 v161, v116, v116
	v_fmac_f32_e32 v166, v118, v118
	v_cvt_pk_bf16_f32 v113, v126, v127
	v_mul_f32_e32 v127, v123, v123
	v_mul_f32_e32 v168, v163, v163
	v_fmac_f32_e32 v125, v120, v120
	v_fmac_f32_e32 v167, v164, v164
	v_add_f32_e32 v114, v114, v115
	v_add_f32_e32 v115, v161, v166
	v_fmac_f32_e32 v127, v122, v122
	v_fmac_f32_e32 v168, v162, v162
	v_add_f32_e32 v114, v125, v114
	v_add_f32_e32 v115, v167, v115
	v_add_f32_e32 v114, v127, v114
	v_add_f32_e32 v115, v168, v115
	v_add_f32_e32 v124, v114, v115
	ds_bpermute_b32 v125, v160, v124
	v_cvt_pk_bf16_f32 v114, v120, v121
	v_cvt_pk_bf16_f32 v115, v122, v123
	global_store_dwordx4 v[170:171], v[112:115], off
	s_waitcnt lgkmcnt(0)
	s_nop 0
	v_add_f32_e32 v112, v124, v125
	ds_bpermute_b32 v113, v159, v112
	v_cvt_pk_bf16_f32 v114, v116, v117
	v_cvt_pk_bf16_f32 v115, v118, v119
	v_cvt_pk_bf16_f32 v116, v164, v165
	v_cvt_pk_bf16_f32 v117, v162, v163
	global_store_dwordx4 v[170:171], v[114:117], off offset:256
	s_and_saveexec_b64 s[56:57], s[6:7]
	s_cbranch_execz .LBB0_655
	s_waitcnt lgkmcnt(0)
	v_add_f32_e32 v112, v112, v113
	v_mul_f32_e32 v112, 0x4f800000, v112
	v_trunc_f32_e32 v112, v112
	v_mul_f32_e64 v113, |v112|, s87
	v_floor_f32_e32 v113, v113
	v_fma_f32 v114, v113, s88, |v112|
	v_cvt_u32_f32_e32 v114, v114
	v_cvt_u32_f32_e32 v113, v113
	v_ashrrev_i32_e32 v115, 31, v112
	v_xor_b32_e32 v112, v114, v115
	v_xor_b32_e32 v113, v113, v115
	v_sub_co_u32_e32 v112, vcc, v112, v115
	s_nop 1
	v_subb_co_u32_e32 v113, vcc, v113, v115, vcc
	v_lshl_add_u64 v[114:115], v[150:151], 3, s[10:11]
	global_atomic_add_x2 v[114:115], v[112:113], off
.LBB0_655:
	s_or_b64 exec, exec, s[56:57]
	v_or_b32_e32 v112, 16, v150
	s_waitcnt lgkmcnt(0)
	v_ashrrev_i32_e32 v113, 31, v112
	v_lshlrev_b64 v[114:115], 11, v[112:113]
	v_lshl_add_u64 v[114:115], s[22:23], 0, v[114:115]
	v_lshl_add_u64 v[122:123], v[148:149], 1, v[114:115]
	s_nop 0
	s_nop 0
	s_waitcnt vmcnt(10)
	v_lshlrev_b32_e32 v124, 16, v190
	v_and_b32_e32 v125, 0xffff0000, v190
	v_lshlrev_b32_e32 v114, 16, v191
	v_and_b32_e32 v115, 0xffff0000, v191
	s_waitcnt vmcnt(9)
	v_lshlrev_b32_e32 v162, 16, v194
	v_and_b32_e32 v163, 0xffff0000, v194
	v_lshlrev_b32_e32 v118, 16, v195
	v_and_b32_e32 v119, 0xffff0000, v195
	v_lshlrev_b32_e32 v126, 16, v192
	v_and_b32_e32 v127, 0xffff0000, v192
	v_lshlrev_b32_e32 v116, 16, v193
	v_and_b32_e32 v117, 0xffff0000, v193
	v_lshlrev_b32_e32 v164, 16, v196
	v_and_b32_e32 v165, 0xffff0000, v196
	v_lshlrev_b32_e32 v120, 16, v197
	v_and_b32_e32 v121, 0xffff0000, v197
	global_load_dwordx4 v[190:193], v[198:199], off
	global_load_dwordx4 v[194:197], v[198:199], off offset:256
	v_lshl_add_u64 v[198:199], v[198:199], 0, s[98:99]
	v_pk_add_f32 v[110:111], v[110:111], v[114:115]
	v_pk_add_f32 v[108:109], v[108:109], v[124:125]
	v_pk_add_f32 v[102:103], v[102:103], v[118:119]
	v_pk_add_f32 v[100:101], v[100:101], v[162:163]
	v_pk_add_f32 v[106:107], v[106:107], v[116:117]
	v_pk_add_f32 v[104:105], v[104:105], v[126:127]
	v_pk_add_f32 v[114:115], v[98:99], v[120:121]
	v_pk_add_f32 v[116:117], v[96:97], v[164:165]
	v_mul_f32_e32 v98, v109, v109
	v_mul_f32_e32 v99, v111, v111
	v_mul_f32_e32 v118, v101, v101
	v_mul_f32_e32 v119, v103, v103
	v_cvt_pk_bf16_f32 v96, v108, v109
	v_mul_f32_e32 v109, v105, v105
	v_mul_f32_e32 v120, v117, v117
	v_fmac_f32_e32 v98, v108, v108
	v_fmac_f32_e32 v99, v110, v110
	v_fmac_f32_e32 v118, v100, v100
	v_fmac_f32_e32 v119, v102, v102
	v_cvt_pk_bf16_f32 v97, v110, v111
	v_mul_f32_e32 v111, v107, v107
	v_mul_f32_e32 v121, v115, v115
	v_fmac_f32_e32 v109, v104, v104
	v_fmac_f32_e32 v120, v116, v116
	v_add_f32_e32 v98, v98, v99
	v_add_f32_e32 v99, v118, v119
	v_fmac_f32_e32 v111, v106, v106
	v_fmac_f32_e32 v121, v114, v114
	v_add_f32_e32 v98, v109, v98
	v_add_f32_e32 v99, v120, v99
	v_add_f32_e32 v98, v111, v98
	v_add_f32_e32 v99, v121, v99
	v_add_f32_e32 v108, v98, v99
	ds_bpermute_b32 v109, v160, v108
	v_cvt_pk_bf16_f32 v98, v104, v105
	v_cvt_pk_bf16_f32 v99, v106, v107
	global_store_dwordx4 v[122:123], v[96:99], off
	s_waitcnt lgkmcnt(0)
	s_nop 0
	v_add_f32_e32 v96, v108, v109
	ds_bpermute_b32 v97, v159, v96
	v_cvt_pk_bf16_f32 v98, v100, v101
	v_cvt_pk_bf16_f32 v99, v102, v103
	v_cvt_pk_bf16_f32 v100, v116, v117
	v_cvt_pk_bf16_f32 v101, v114, v115
	global_store_dwordx4 v[122:123], v[98:101], off offset:256
	s_and_saveexec_b64 s[56:57], s[6:7]
	s_cbranch_execz .LBB0_657
	s_waitcnt lgkmcnt(0)
	v_add_f32_e32 v96, v96, v97
	v_mul_f32_e32 v96, 0x4f800000, v96
	v_trunc_f32_e32 v96, v96
	v_mul_f32_e64 v97, |v96|, s87
	v_floor_f32_e32 v97, v97
	v_fma_f32 v98, v97, s88, |v96|
	v_cvt_u32_f32_e32 v98, v98
	v_cvt_u32_f32_e32 v97, v97
	v_ashrrev_i32_e32 v99, 31, v96
	v_xor_b32_e32 v96, v98, v99
	v_xor_b32_e32 v97, v97, v99
	v_sub_co_u32_e32 v96, vcc, v96, v99
	s_nop 1
	v_subb_co_u32_e32 v97, vcc, v97, v99, vcc
	v_lshl_add_u64 v[98:99], v[112:113], 3, s[10:11]
	global_atomic_add_x2 v[98:99], v[96:97], off
; __device__ __forceinline__ void fx_add(float* p, size_t idx, float s) { atomicAdd((unsigned long long*)p + idx, (unsigned long long)(long long)(s * 4294967296.0f)); }
; __device__ __forceinline__ unsigned cvtpk(float lo, float hi) { f32x2v_ v = {lo, hi}; bf16x2v_ b = __builtin_convertvector(v, bf16x2v_); return __builtin_bit_cast(unsigned, b); }
;     __device__ __forceinline__ void operator()(const f32x4 (&acc)[2][2][4][2], const Unit& u, int wr, int wc, int fr, int fq) const {
;     ...
;             for (int m = 0; m < 4; ++m) { const int row = row0 + ai * HALF + m * 16; const size_t off = (size_t)row * 1024 + col0; float s = 0.f;
; #pragma unroll
;                 for (int bj = 0; bj < 2; ++bj) { f32x4 a0, a1;
;                     if (xin32) { const float* p = xin32 + off + bj * HALF; a0 = *(const f32x4*)p; a1 = *(const f32x4*)(p + 4); }
;                     else { const u32x4 w = *(const u32x4*)(xb + off + bj * HALF);
;                         a0 = (f32x4){__uint_as_float(w.x << 16), __uint_as_float(w.x & 0xffff0000u), __uint_as_float(w.y << 16), __uint_as_float(w.y & 0xffff0000u)};
;                         a1 = (f32x4){__uint_as_float(w.z << 16), __uint_as_float(w.z & 0xffff0000u), __uint_as_float(w.w << 16), __uint_as_float(w.w & 0xffff0000u)}; }
;                     const f32x4 v0 = a0 + acc[ai][bj][m][0] * alpha, v1 = a1 + acc[ai][bj][m][1] * alpha;
;                     u32x4 w; w.x = cvtpk(v0[0], v0[1]); w.y = cvtpk(v0[2], v0[3]); w.z = cvtpk(v1[0], v1[1]); w.w = cvtpk(v1[2], v1[3]);
;                     *(u32x4*)(xb + off + bj * HALF) = w;
;                     s += (v0[0] * v0[0] + v0[1] * v0[1]) + (v0[2] * v0[2] + v0[3] * v0[3]) + (v1[0] * v1[0] + v1[1] * v1[1]) + (v1[2] * v1[2] + v1[3] * v1[3]); }
;                 s += __shfl_xor(s, 16); s += __shfl_xor(s, 32);
;                 if (fq == 0) fx_add(ssout, row, s); }
.LBB0_657:
	s_or_b64 exec, exec, s[56:57]
	v_or_b32_e32 v96, 32, v150
	s_waitcnt lgkmcnt(0)
	v_ashrrev_i32_e32 v97, 31, v96
	v_lshlrev_b64 v[98:99], 11, v[96:97]
	v_lshl_add_u64 v[98:99], s[22:23], 0, v[98:99]
	v_lshl_add_u64 v[106:107], v[148:149], 1, v[98:99]
	s_nop 0
	s_nop 0
	s_waitcnt vmcnt(13)
	v_lshlrev_b32_e32 v108, 16, v208
	v_and_b32_e32 v109, 0xffff0000, v208
	v_lshlrev_b32_e32 v98, 16, v209
	v_and_b32_e32 v99, 0xffff0000, v209
	s_waitcnt vmcnt(12)
	v_lshlrev_b32_e32 v112, 16, v212
	v_and_b32_e32 v113, 0xffff0000, v212
	v_lshlrev_b32_e32 v102, 16, v213
	v_and_b32_e32 v103, 0xffff0000, v213
	v_lshlrev_b32_e32 v110, 16, v210
	v_and_b32_e32 v111, 0xffff0000, v210
	v_lshlrev_b32_e32 v100, 16, v211
	v_and_b32_e32 v101, 0xffff0000, v211
	v_lshlrev_b32_e32 v114, 16, v214
	v_and_b32_e32 v115, 0xffff0000, v214
	v_lshlrev_b32_e32 v104, 16, v215
	v_and_b32_e32 v105, 0xffff0000, v215
	global_load_dwordx4 v[208:211], v[198:199], off
	global_load_dwordx4 v[212:215], v[198:199], off offset:256
	v_lshl_add_u64 v[198:199], v[198:199], 0, s[98:99]
	v_pk_add_f32 v[94:95], v[94:95], v[98:99]
	v_pk_add_f32 v[92:93], v[92:93], v[108:109]
	v_pk_add_f32 v[86:87], v[86:87], v[102:103]
	v_pk_add_f32 v[84:85], v[84:85], v[112:113]
	v_pk_add_f32 v[90:91], v[90:91], v[100:101]
	v_pk_add_f32 v[88:89], v[88:89], v[110:111]
	v_pk_add_f32 v[98:99], v[82:83], v[104:105]
	v_pk_add_f32 v[100:101], v[80:81], v[114:115]
	v_mul_f32_e32 v82, v93, v93
	v_mul_f32_e32 v83, v95, v95
	v_mul_f32_e32 v102, v85, v85
	v_mul_f32_e32 v103, v87, v87
	v_cvt_pk_bf16_f32 v80, v92, v93
	v_mul_f32_e32 v93, v89, v89
	v_mul_f32_e32 v104, v101, v101
	v_fmac_f32_e32 v82, v92, v92
	v_fmac_f32_e32 v83, v94, v94
	v_fmac_f32_e32 v102, v84, v84
	v_fmac_f32_e32 v103, v86, v86
	v_cvt_pk_bf16_f32 v81, v94, v95
	v_mul_f32_e32 v95, v91, v91
	v_mul_f32_e32 v105, v99, v99
	v_fmac_f32_e32 v93, v88, v88
	v_fmac_f32_e32 v104, v100, v100
	v_add_f32_e32 v82, v82, v83
	v_add_f32_e32 v83, v102, v103
	v_fmac_f32_e32 v95, v90, v90
	v_fmac_f32_e32 v105, v98, v98
	v_add_f32_e32 v82, v93, v82
	v_add_f32_e32 v83, v104, v83
	v_add_f32_e32 v82, v95, v82
	v_add_f32_e32 v83, v105, v83
	v_add_f32_e32 v92, v82, v83
	ds_bpermute_b32 v93, v160, v92
	v_cvt_pk_bf16_f32 v82, v88, v89
	v_cvt_pk_bf16_f32 v83, v90, v91
	global_store_dwordx4 v[106:107], v[80:83], off
	s_waitcnt lgkmcnt(0)
	s_nop 0
	v_add_f32_e32 v80, v92, v93
	ds_bpermute_b32 v81, v159, v80
	v_cvt_pk_bf16_f32 v82, v84, v85
	v_cvt_pk_bf16_f32 v83, v86, v87
	v_cvt_pk_bf16_f32 v84, v100, v101
	v_cvt_pk_bf16_f32 v85, v98, v99
	global_store_dwordx4 v[106:107], v[82:85], off offset:256
	s_and_saveexec_b64 s[56:57], s[6:7]
	s_cbranch_execz .LBB0_659
	s_waitcnt lgkmcnt(0)
	v_add_f32_e32 v80, v80, v81
	v_mul_f32_e32 v80, 0x4f800000, v80
	v_trunc_f32_e32 v80, v80
	v_mul_f32_e64 v81, |v80|, s87
	v_floor_f32_e32 v81, v81
	v_fma_f32 v82, v81, s88, |v80|
	v_cvt_u32_f32_e32 v82, v82
	v_cvt_u32_f32_e32 v81, v81
	v_ashrrev_i32_e32 v83, 31, v80
	v_xor_b32_e32 v80, v82, v83
	v_xor_b32_e32 v81, v81, v83
	v_sub_co_u32_e32 v80, vcc, v80, v83
	s_nop 1
	v_subb_co_u32_e32 v81, vcc, v81, v83, vcc
	v_lshl_add_u64 v[82:83], v[96:97], 3, s[10:11]
	global_atomic_add_x2 v[82:83], v[80:81], off
.LBB0_659:
	s_or_b64 exec, exec, s[56:57]
	v_or_b32_e32 v80, 48, v150
	s_waitcnt lgkmcnt(0)
	v_ashrrev_i32_e32 v81, 31, v80
	v_lshlrev_b64 v[82:83], 11, v[80:81]
	v_lshl_add_u64 v[82:83], s[22:23], 0, v[82:83]
	v_lshl_add_u64 v[90:91], v[148:149], 1, v[82:83]
	s_nop 0
	s_nop 0
	s_waitcnt vmcnt(16)
	v_lshlrev_b32_e32 v92, 16, v216
	v_and_b32_e32 v93, 0xffff0000, v216
	v_lshlrev_b32_e32 v82, 16, v217
	v_and_b32_e32 v83, 0xffff0000, v217
	s_waitcnt vmcnt(15)
	v_lshlrev_b32_e32 v96, 16, v220
	v_and_b32_e32 v97, 0xffff0000, v220
	v_lshlrev_b32_e32 v86, 16, v221
	v_and_b32_e32 v87, 0xffff0000, v221
	v_lshlrev_b32_e32 v94, 16, v218
	v_and_b32_e32 v95, 0xffff0000, v218
	v_lshlrev_b32_e32 v84, 16, v219
	v_and_b32_e32 v85, 0xffff0000, v219
	v_lshlrev_b32_e32 v98, 16, v222
	v_and_b32_e32 v99, 0xffff0000, v222
	v_lshlrev_b32_e32 v88, 16, v223
	v_and_b32_e32 v89, 0xffff0000, v223
	global_load_dwordx4 v[216:219], v[198:199], off
	global_load_dwordx4 v[220:223], v[198:199], off offset:256
	v_pk_add_f32 v[78:79], v[78:79], v[82:83]
	v_pk_add_f32 v[76:77], v[76:77], v[92:93]
	v_pk_add_f32 v[70:71], v[70:71], v[86:87]
	v_pk_add_f32 v[68:69], v[68:69], v[96:97]
	v_pk_add_f32 v[74:75], v[74:75], v[84:85]
	v_pk_add_f32 v[72:73], v[72:73], v[94:95]
	v_pk_add_f32 v[82:83], v[66:67], v[88:89]
	v_pk_add_f32 v[84:85], v[64:65], v[98:99]
	v_mul_f32_e32 v66, v77, v77
	v_mul_f32_e32 v67, v79, v79
	v_mul_f32_e32 v86, v69, v69
	v_mul_f32_e32 v87, v71, v71
	v_cvt_pk_bf16_f32 v64, v76, v77
	v_mul_f32_e32 v77, v73, v73
	v_mul_f32_e32 v88, v85, v85
	v_fmac_f32_e32 v66, v76, v76
	v_fmac_f32_e32 v67, v78, v78
	v_fmac_f32_e32 v86, v68, v68
	v_fmac_f32_e32 v87, v70, v70
	v_cvt_pk_bf16_f32 v65, v78, v79
	v_mul_f32_e32 v79, v75, v75
	v_mul_f32_e32 v89, v83, v83
	v_fmac_f32_e32 v77, v72, v72
	v_fmac_f32_e32 v88, v84, v84
	v_add_f32_e32 v66, v66, v67
	v_add_f32_e32 v67, v86, v87
	v_fmac_f32_e32 v79, v74, v74
	v_fmac_f32_e32 v89, v82, v82
	v_add_f32_e32 v66, v77, v66
	v_add_f32_e32 v67, v88, v67
	v_add_f32_e32 v66, v79, v66
	v_add_f32_e32 v67, v89, v67
	v_add_f32_e32 v76, v66, v67
	ds_bpermute_b32 v77, v160, v76
	v_cvt_pk_bf16_f32 v66, v72, v73
	v_cvt_pk_bf16_f32 v67, v74, v75
	global_store_dwordx4 v[90:91], v[64:67], off
	s_waitcnt lgkmcnt(0)
	s_nop 0
	v_add_f32_e32 v64, v76, v77
	ds_bpermute_b32 v65, v159, v64
	v_cvt_pk_bf16_f32 v66, v68, v69
	v_cvt_pk_bf16_f32 v67, v70, v71
	v_cvt_pk_bf16_f32 v68, v84, v85
	v_cvt_pk_bf16_f32 v69, v82, v83
	global_store_dwordx4 v[90:91], v[66:69], off offset:256
	s_and_saveexec_b64 s[56:57], s[6:7]
	s_cbranch_execz .LBB0_661
	s_waitcnt lgkmcnt(0)
	v_add_f32_e32 v64, v64, v65
	v_mul_f32_e32 v64, 0x4f800000, v64
	v_trunc_f32_e32 v64, v64
	v_mul_f32_e64 v65, |v64|, s87
	v_floor_f32_e32 v65, v65
	v_fma_f32 v66, v65, s88, |v64|
	v_cvt_u32_f32_e32 v66, v66
	v_cvt_u32_f32_e32 v65, v65
	v_ashrrev_i32_e32 v67, 31, v64
	v_xor_b32_e32 v64, v66, v67
	v_xor_b32_e32 v65, v65, v67
	v_sub_co_u32_e32 v64, vcc, v64, v67
	s_nop 1
	v_subb_co_u32_e32 v65, vcc, v65, v67, vcc
	v_lshl_add_u64 v[66:67], v[80:81], 3, s[10:11]
	global_atomic_add_x2 v[66:67], v[64:65], off
; __device__ __forceinline__ void fx_add(float* p, size_t idx, float s) { atomicAdd((unsigned long long*)p + idx, (unsigned long long)(long long)(s * 4294967296.0f)); }
; __device__ __forceinline__ unsigned cvtpk(float lo, float hi) { f32x2v_ v = {lo, hi}; bf16x2v_ b = __builtin_convertvector(v, bf16x2v_); return __builtin_bit_cast(unsigned, b); }
;     __device__ __forceinline__ void operator()(const f32x4 (&acc)[2][2][4][2], const Unit& u, int wr, int wc, int fr, int fq) const {
;     ...
;             for (int m = 0; m < 4; ++m) { const int row = row0 + ai * HALF + m * 16; const size_t off = (size_t)row * 1024 + col0; float s = 0.f;
; #pragma unroll
;                 for (int bj = 0; bj < 2; ++bj) { f32x4 a0, a1;
;                     if (xin32) { const float* p = xin32 + off + bj * HALF; a0 = *(const f32x4*)p; a1 = *(const f32x4*)(p + 4); }
;                     else { const u32x4 w = *(const u32x4*)(xb + off + bj * HALF);
;                         a0 = (f32x4){__uint_as_float(w.x << 16), __uint_as_float(w.x & 0xffff0000u), __uint_as_float(w.y << 16), __uint_as_float(w.y & 0xffff0000u)};
;                         a1 = (f32x4){__uint_as_float(w.z << 16), __uint_as_float(w.z & 0xffff0000u), __uint_as_float(w.w << 16), __uint_as_float(w.w & 0xffff0000u)}; }
;                     const f32x4 v0 = a0 + acc[ai][bj][m][0] * alpha, v1 = a1 + acc[ai][bj][m][1] * alpha;
;                     u32x4 w; w.x = cvtpk(v0[0], v0[1]); w.y = cvtpk(v0[2], v0[3]); w.z = cvtpk(v1[0], v1[1]); w.w = cvtpk(v1[2], v1[3]);
;                     *(u32x4*)(xb + off + bj * HALF) = w;
;                     s += (v0[0] * v0[0] + v0[1] * v0[1]) + (v0[2] * v0[2] + v0[3] * v0[3]) + (v1[0] * v1[0] + v1[1] * v1[1]) + (v1[2] * v1[2] + v1[3] * v1[3]); }
;                 s += __shfl_xor(s, 16); s += __shfl_xor(s, 32);
;                 if (fq == 0) fx_add(ssout, row, s); }
.LBB0_661:
	s_or_b64 exec, exec, s[56:57]
	v_add_u32_e32 v64, 0x80, v150
	s_waitcnt lgkmcnt(0)
	v_ashrrev_i32_e32 v65, 31, v64
	v_lshlrev_b64 v[66:67], 11, v[64:65]
	v_lshl_add_u64 v[66:67], s[22:23], 0, v[66:67]
	v_lshl_add_u64 v[74:75], v[148:149], 1, v[66:67]
	s_nop 0
	s_nop 0
	s_waitcnt vmcnt(19)
	v_lshlrev_b32_e32 v76, 16, v182
	v_and_b32_e32 v77, 0xffff0000, v182
	v_lshlrev_b32_e32 v66, 16, v183
	v_and_b32_e32 v67, 0xffff0000, v183
	s_waitcnt vmcnt(18)
	v_lshlrev_b32_e32 v80, 16, v186
	v_and_b32_e32 v81, 0xffff0000, v186
	v_lshlrev_b32_e32 v70, 16, v187
	v_and_b32_e32 v71, 0xffff0000, v187
	v_lshlrev_b32_e32 v78, 16, v184
	v_and_b32_e32 v79, 0xffff0000, v184
	v_lshlrev_b32_e32 v68, 16, v185
	v_and_b32_e32 v69, 0xffff0000, v185
	v_lshlrev_b32_e32 v82, 16, v188
	v_and_b32_e32 v83, 0xffff0000, v188
	v_lshlrev_b32_e32 v72, 16, v189
	v_and_b32_e32 v73, 0xffff0000, v189
	v_pk_add_f32 v[62:63], v[62:63], v[66:67]
	v_pk_add_f32 v[60:61], v[60:61], v[76:77]
	v_pk_add_f32 v[54:55], v[54:55], v[70:71]
	v_pk_add_f32 v[52:53], v[52:53], v[80:81]
	v_pk_add_f32 v[58:59], v[58:59], v[68:69]
	v_pk_add_f32 v[56:57], v[56:57], v[78:79]
	v_pk_add_f32 v[66:67], v[50:51], v[72:73]
	v_pk_add_f32 v[68:69], v[48:49], v[82:83]
	v_mul_f32_e32 v50, v61, v61
	v_mul_f32_e32 v51, v63, v63
	v_mul_f32_e32 v70, v53, v53
	v_mul_f32_e32 v71, v55, v55
	v_cvt_pk_bf16_f32 v48, v60, v61
	v_mul_f32_e32 v61, v57, v57
	v_mul_f32_e32 v72, v69, v69
	v_fmac_f32_e32 v50, v60, v60
	v_fmac_f32_e32 v51, v62, v62
	v_fmac_f32_e32 v70, v52, v52
	v_fmac_f32_e32 v71, v54, v54
	v_cvt_pk_bf16_f32 v49, v62, v63
	v_mul_f32_e32 v63, v59, v59
	v_mul_f32_e32 v73, v67, v67
	v_fmac_f32_e32 v61, v56, v56
	v_fmac_f32_e32 v72, v68, v68
	v_add_f32_e32 v50, v50, v51
	v_add_f32_e32 v51, v70, v71
	v_fmac_f32_e32 v63, v58, v58
	v_fmac_f32_e32 v73, v66, v66
	v_add_f32_e32 v50, v61, v50
	v_add_f32_e32 v51, v72, v51
	v_add_f32_e32 v50, v63, v50
	v_add_f32_e32 v51, v73, v51
	v_add_f32_e32 v60, v50, v51
	ds_bpermute_b32 v61, v160, v60
	v_cvt_pk_bf16_f32 v50, v56, v57
	v_cvt_pk_bf16_f32 v51, v58, v59
	global_store_dwordx4 v[74:75], v[48:51], off
	s_waitcnt lgkmcnt(0)
	s_nop 0
	v_add_f32_e32 v48, v60, v61
	ds_bpermute_b32 v49, v159, v48
	v_cvt_pk_bf16_f32 v50, v52, v53
	v_cvt_pk_bf16_f32 v51, v54, v55
	v_cvt_pk_bf16_f32 v52, v68, v69
	v_cvt_pk_bf16_f32 v53, v66, v67
	global_store_dwordx4 v[74:75], v[50:53], off offset:256
	s_and_saveexec_b64 s[56:57], s[6:7]
	s_cbranch_execz .LBB0_663
	s_waitcnt lgkmcnt(0)
	v_add_f32_e32 v48, v48, v49
	v_mul_f32_e32 v48, 0x4f800000, v48
	v_trunc_f32_e32 v48, v48
	v_mul_f32_e64 v49, |v48|, s87
	v_floor_f32_e32 v49, v49
	v_fma_f32 v50, v49, s88, |v48|
	v_cvt_u32_f32_e32 v50, v50
	v_cvt_u32_f32_e32 v49, v49
	v_ashrrev_i32_e32 v51, 31, v48
	v_xor_b32_e32 v48, v50, v51
	v_xor_b32_e32 v49, v49, v51
	v_sub_co_u32_e32 v48, vcc, v48, v51
	s_nop 1
	v_subb_co_u32_e32 v49, vcc, v49, v51, vcc
	v_lshl_add_u64 v[50:51], v[64:65], 3, s[10:11]
	global_atomic_add_x2 v[50:51], v[48:49], off
.LBB0_663:
	s_or_b64 exec, exec, s[56:57]
	v_add_u32_e32 v48, 0x90, v150
	s_waitcnt lgkmcnt(0)
	v_ashrrev_i32_e32 v49, 31, v48
	v_lshlrev_b64 v[50:51], 11, v[48:49]
	v_lshl_add_u64 v[50:51], s[22:23], 0, v[50:51]
	v_lshl_add_u64 v[58:59], v[148:149], 1, v[50:51]
	s_nop 0
	s_nop 0
	s_waitcnt vmcnt(17)
	v_lshlrev_b32_e32 v60, 16, v190
	v_and_b32_e32 v61, 0xffff0000, v190
	v_lshlrev_b32_e32 v50, 16, v191
	v_and_b32_e32 v51, 0xffff0000, v191
	s_waitcnt vmcnt(16)
	v_lshlrev_b32_e32 v64, 16, v194
	v_and_b32_e32 v65, 0xffff0000, v194
	v_lshlrev_b32_e32 v54, 16, v195
	v_and_b32_e32 v55, 0xffff0000, v195
	v_lshlrev_b32_e32 v62, 16, v192
	v_and_b32_e32 v63, 0xffff0000, v192
	v_lshlrev_b32_e32 v52, 16, v193
	v_and_b32_e32 v53, 0xffff0000, v193
	v_lshlrev_b32_e32 v66, 16, v196
	v_and_b32_e32 v67, 0xffff0000, v196
	v_lshlrev_b32_e32 v56, 16, v197
	v_and_b32_e32 v57, 0xffff0000, v197
	v_pk_add_f32 v[46:47], v[46:47], v[50:51]
	v_pk_add_f32 v[44:45], v[44:45], v[60:61]
	v_pk_add_f32 v[38:39], v[38:39], v[54:55]
	v_pk_add_f32 v[36:37], v[36:37], v[64:65]
	v_pk_add_f32 v[42:43], v[42:43], v[52:53]
	v_pk_add_f32 v[40:41], v[40:41], v[62:63]
	v_pk_add_f32 v[50:51], v[34:35], v[56:57]
	v_pk_add_f32 v[52:53], v[32:33], v[66:67]
	v_mul_f32_e32 v34, v45, v45
	v_mul_f32_e32 v35, v47, v47
	v_mul_f32_e32 v54, v37, v37
	v_mul_f32_e32 v55, v39, v39
	v_cvt_pk_bf16_f32 v32, v44, v45
	v_mul_f32_e32 v45, v41, v41
	v_mul_f32_e32 v56, v53, v53
	v_fmac_f32_e32 v34, v44, v44
	v_fmac_f32_e32 v35, v46, v46
	v_fmac_f32_e32 v54, v36, v36
	v_fmac_f32_e32 v55, v38, v38
	v_cvt_pk_bf16_f32 v33, v46, v47
	v_mul_f32_e32 v47, v43, v43
	v_mul_f32_e32 v57, v51, v51
	v_fmac_f32_e32 v45, v40, v40
	v_fmac_f32_e32 v56, v52, v52
	v_add_f32_e32 v34, v34, v35
	v_add_f32_e32 v35, v54, v55
	v_fmac_f32_e32 v47, v42, v42
	v_fmac_f32_e32 v57, v50, v50
	v_add_f32_e32 v34, v45, v34
	v_add_f32_e32 v35, v56, v35
	v_add_f32_e32 v34, v47, v34
	v_add_f32_e32 v35, v57, v35
	v_add_f32_e32 v44, v34, v35
	ds_bpermute_b32 v45, v160, v44
	v_cvt_pk_bf16_f32 v34, v40, v41
	v_cvt_pk_bf16_f32 v35, v42, v43
	global_store_dwordx4 v[58:59], v[32:35], off
	s_waitcnt lgkmcnt(0)
	s_nop 0
	v_add_f32_e32 v32, v44, v45
	ds_bpermute_b32 v33, v159, v32
	v_cvt_pk_bf16_f32 v34, v36, v37
	v_cvt_pk_bf16_f32 v35, v38, v39
	v_cvt_pk_bf16_f32 v36, v52, v53
	v_cvt_pk_bf16_f32 v37, v50, v51
	global_store_dwordx4 v[58:59], v[34:37], off offset:256
	s_and_saveexec_b64 s[56:57], s[6:7]
	s_cbranch_execz .LBB0_665
	s_waitcnt lgkmcnt(0)
	v_add_f32_e32 v32, v32, v33
	v_mul_f32_e32 v32, 0x4f800000, v32
	v_trunc_f32_e32 v32, v32
	v_mul_f32_e64 v33, |v32|, s87
	v_floor_f32_e32 v33, v33
	v_fma_f32 v34, v33, s88, |v32|
	v_cvt_u32_f32_e32 v34, v34
	v_cvt_u32_f32_e32 v33, v33
	v_ashrrev_i32_e32 v35, 31, v32
	v_xor_b32_e32 v32, v34, v35
	v_xor_b32_e32 v33, v33, v35
	v_sub_co_u32_e32 v32, vcc, v32, v35
	s_nop 1
	v_subb_co_u32_e32 v33, vcc, v33, v35, vcc
	v_lshl_add_u64 v[34:35], v[48:49], 3, s[10:11]
	global_atomic_add_x2 v[34:35], v[32:33], off
; __device__ __forceinline__ void fx_add(float* p, size_t idx, float s) { atomicAdd((unsigned long long*)p + idx, (unsigned long long)(long long)(s * 4294967296.0f)); }
; __device__ __forceinline__ unsigned cvtpk(float lo, float hi) { f32x2v_ v = {lo, hi}; bf16x2v_ b = __builtin_convertvector(v, bf16x2v_); return __builtin_bit_cast(unsigned, b); }
;     __device__ __forceinline__ void operator()(const f32x4 (&acc)[2][2][4][2], const Unit& u, int wr, int wc, int fr, int fq) const {
;     ...
;             for (int m = 0; m < 4; ++m) { const int row = row0 + ai * HALF + m * 16; const size_t off = (size_t)row * 1024 + col0; float s = 0.f;
; #pragma unroll
;                 for (int bj = 0; bj < 2; ++bj) { f32x4 a0, a1;
;                     if (xin32) { const float* p = xin32 + off + bj * HALF; a0 = *(const f32x4*)p; a1 = *(const f32x4*)(p + 4); }
;                     else { const u32x4 w = *(const u32x4*)(xb + off + bj * HALF);
;                         a0 = (f32x4){__uint_as_float(w.x << 16), __uint_as_float(w.x & 0xffff0000u), __uint_as_float(w.y << 16), __uint_as_float(w.y & 0xffff0000u)};
;                         a1 = (f32x4){__uint_as_float(w.z << 16), __uint_as_float(w.z & 0xffff0000u), __uint_as_float(w.w << 16), __uint_as_float(w.w & 0xffff0000u)}; }
;                     const f32x4 v0 = a0 + acc[ai][bj][m][0] * alpha, v1 = a1 + acc[ai][bj][m][1] * alpha;
;                     u32x4 w; w.x = cvtpk(v0[0], v0[1]); w.y = cvtpk(v0[2], v0[3]); w.z = cvtpk(v1[0], v1[1]); w.w = cvtpk(v1[2], v1[3]);
;                     *(u32x4*)(xb + off + bj * HALF) = w;
;                     s += (v0[0] * v0[0] + v0[1] * v0[1]) + (v0[2] * v0[2] + v0[3] * v0[3]) + (v1[0] * v1[0] + v1[1] * v1[1]) + (v1[2] * v1[2] + v1[3] * v1[3]); }
;                 s += __shfl_xor(s, 16); s += __shfl_xor(s, 32);
;                 if (fq == 0) fx_add(ssout, row, s); }
.LBB0_665:
	s_or_b64 exec, exec, s[56:57]
	v_add_u32_e32 v32, 0xa0, v150
	s_waitcnt lgkmcnt(0)
	v_ashrrev_i32_e32 v33, 31, v32
	v_lshlrev_b64 v[34:35], 11, v[32:33]
	v_lshl_add_u64 v[34:35], s[22:23], 0, v[34:35]
	v_lshl_add_u64 v[42:43], v[148:149], 1, v[34:35]
	s_nop 0
	s_nop 0
	s_waitcnt vmcnt(15)
	v_lshlrev_b32_e32 v44, 16, v208
	v_and_b32_e32 v45, 0xffff0000, v208
	v_lshlrev_b32_e32 v34, 16, v209
	v_and_b32_e32 v35, 0xffff0000, v209
	s_waitcnt vmcnt(14)
	v_lshlrev_b32_e32 v48, 16, v212
	v_and_b32_e32 v49, 0xffff0000, v212
	v_lshlrev_b32_e32 v38, 16, v213
	v_and_b32_e32 v39, 0xffff0000, v213
	v_lshlrev_b32_e32 v46, 16, v210
	v_and_b32_e32 v47, 0xffff0000, v210
	v_lshlrev_b32_e32 v36, 16, v211
	v_and_b32_e32 v37, 0xffff0000, v211
	v_lshlrev_b32_e32 v50, 16, v214
	v_and_b32_e32 v51, 0xffff0000, v214
	v_lshlrev_b32_e32 v40, 16, v215
	v_and_b32_e32 v41, 0xffff0000, v215
	v_pk_add_f32 v[30:31], v[30:31], v[34:35]
	v_pk_add_f32 v[28:29], v[28:29], v[44:45]
	v_pk_add_f32 v[22:23], v[22:23], v[38:39]
	v_pk_add_f32 v[20:21], v[20:21], v[48:49]
	v_pk_add_f32 v[26:27], v[26:27], v[36:37]
	v_pk_add_f32 v[24:25], v[24:25], v[46:47]
	v_pk_add_f32 v[34:35], v[18:19], v[40:41]
	v_pk_add_f32 v[36:37], v[16:17], v[50:51]
	v_mul_f32_e32 v18, v29, v29
	v_mul_f32_e32 v19, v31, v31
	v_mul_f32_e32 v38, v21, v21
	v_mul_f32_e32 v39, v23, v23
	v_cvt_pk_bf16_f32 v16, v28, v29
	v_mul_f32_e32 v29, v25, v25
	v_mul_f32_e32 v40, v37, v37
	v_fmac_f32_e32 v18, v28, v28
	v_fmac_f32_e32 v19, v30, v30
	v_fmac_f32_e32 v38, v20, v20
	v_fmac_f32_e32 v39, v22, v22
	v_cvt_pk_bf16_f32 v17, v30, v31
	v_mul_f32_e32 v31, v27, v27
	v_mul_f32_e32 v41, v35, v35
	v_fmac_f32_e32 v29, v24, v24
	v_fmac_f32_e32 v40, v36, v36
	v_add_f32_e32 v18, v18, v19
	v_add_f32_e32 v19, v38, v39
	v_fmac_f32_e32 v31, v26, v26
	v_fmac_f32_e32 v41, v34, v34
	v_add_f32_e32 v18, v29, v18
	v_add_f32_e32 v19, v40, v19
	v_add_f32_e32 v18, v31, v18
	v_add_f32_e32 v19, v41, v19
	v_add_f32_e32 v28, v18, v19
	ds_bpermute_b32 v29, v160, v28
	v_cvt_pk_bf16_f32 v18, v24, v25
	v_cvt_pk_bf16_f32 v19, v26, v27
	global_store_dwordx4 v[42:43], v[16:19], off
	s_waitcnt lgkmcnt(0)
	s_nop 0
	v_add_f32_e32 v16, v28, v29
	ds_bpermute_b32 v17, v159, v16
	v_cvt_pk_bf16_f32 v18, v20, v21
	v_cvt_pk_bf16_f32 v19, v22, v23
	v_cvt_pk_bf16_f32 v20, v36, v37
	v_cvt_pk_bf16_f32 v21, v34, v35
	global_store_dwordx4 v[42:43], v[18:21], off offset:256
	s_and_saveexec_b64 s[56:57], s[6:7]
	s_cbranch_execz .LBB0_667
	s_waitcnt lgkmcnt(0)
	v_add_f32_e32 v16, v16, v17
	v_mul_f32_e32 v16, 0x4f800000, v16
	v_trunc_f32_e32 v16, v16
	v_mul_f32_e64 v17, |v16|, s87
	v_floor_f32_e32 v17, v17
	v_fma_f32 v18, v17, s88, |v16|
	v_cvt_u32_f32_e32 v18, v18
	v_cvt_u32_f32_e32 v17, v17
	v_ashrrev_i32_e32 v19, 31, v16
	v_xor_b32_e32 v16, v18, v19
	v_xor_b32_e32 v17, v17, v19
	v_sub_co_u32_e32 v16, vcc, v16, v19
	s_nop 1
	v_subb_co_u32_e32 v17, vcc, v17, v19, vcc
	v_lshl_add_u64 v[18:19], v[32:33], 3, s[10:11]
	global_atomic_add_x2 v[18:19], v[16:17], off
.LBB0_667:
	s_or_b64 exec, exec, s[56:57]
	v_add_u32_e32 v16, 0xb0, v150
	s_waitcnt lgkmcnt(0)
	v_ashrrev_i32_e32 v17, 31, v16
	v_lshlrev_b64 v[18:19], 11, v[16:17]
	v_lshl_add_u64 v[18:19], s[22:23], 0, v[18:19]
	v_lshl_add_u64 v[26:27], v[148:149], 1, v[18:19]
	s_nop 0
	s_nop 0
	s_waitcnt vmcnt(13)
	v_lshlrev_b32_e32 v28, 16, v216
	v_and_b32_e32 v29, 0xffff0000, v216
	v_lshlrev_b32_e32 v18, 16, v217
	v_and_b32_e32 v19, 0xffff0000, v217
	s_waitcnt vmcnt(12)
	v_lshlrev_b32_e32 v32, 16, v220
	v_and_b32_e32 v33, 0xffff0000, v220
	v_lshlrev_b32_e32 v22, 16, v221
	v_and_b32_e32 v23, 0xffff0000, v221
	v_lshlrev_b32_e32 v30, 16, v218
	v_and_b32_e32 v31, 0xffff0000, v218
	v_lshlrev_b32_e32 v20, 16, v219
	v_and_b32_e32 v21, 0xffff0000, v219
	v_lshlrev_b32_e32 v34, 16, v222
	v_and_b32_e32 v35, 0xffff0000, v222
	v_lshlrev_b32_e32 v24, 16, v223
	v_and_b32_e32 v25, 0xffff0000, v223
	v_pk_add_f32 v[14:15], v[14:15], v[18:19]
	v_pk_add_f32 v[12:13], v[12:13], v[28:29]
	v_pk_add_f32 v[6:7], v[6:7], v[22:23]
	v_pk_add_f32 v[4:5], v[4:5], v[32:33]
	v_pk_add_f32 v[10:11], v[10:11], v[20:21]
	v_pk_add_f32 v[8:9], v[8:9], v[30:31]
	v_pk_add_f32 v[18:19], v[2:3], v[24:25]
	v_pk_add_f32 v[20:21], v[0:1], v[34:35]
	v_mul_f32_e32 v2, v13, v13
	v_mul_f32_e32 v3, v15, v15
	v_mul_f32_e32 v22, v5, v5
	v_mul_f32_e32 v23, v7, v7
	v_cvt_pk_bf16_f32 v0, v12, v13
	v_mul_f32_e32 v13, v9, v9
	v_mul_f32_e32 v24, v21, v21
	v_fmac_f32_e32 v2, v12, v12
	v_fmac_f32_e32 v3, v14, v14
	v_fmac_f32_e32 v22, v4, v4
	v_fmac_f32_e32 v23, v6, v6
	v_cvt_pk_bf16_f32 v1, v14, v15
	v_mul_f32_e32 v15, v11, v11
	v_mul_f32_e32 v25, v19, v19
	v_fmac_f32_e32 v13, v8, v8
	v_fmac_f32_e32 v24, v20, v20
	v_add_f32_e32 v2, v2, v3
	v_add_f32_e32 v3, v22, v23
	v_fmac_f32_e32 v15, v10, v10
	v_fmac_f32_e32 v25, v18, v18
	v_add_f32_e32 v2, v13, v2
	v_add_f32_e32 v3, v24, v3
	v_add_f32_e32 v2, v15, v2
	v_add_f32_e32 v3, v25, v3
	v_add_f32_e32 v12, v2, v3
	ds_bpermute_b32 v13, v160, v12
	v_cvt_pk_bf16_f32 v2, v8, v9
	v_cvt_pk_bf16_f32 v3, v10, v11
	global_store_dwordx4 v[26:27], v[0:3], off
	s_waitcnt lgkmcnt(0)
	s_nop 0
	v_add_f32_e32 v0, v12, v13
	ds_bpermute_b32 v1, v159, v0
	v_cvt_pk_bf16_f32 v2, v4, v5
	v_cvt_pk_bf16_f32 v3, v6, v7
	v_cvt_pk_bf16_f32 v4, v20, v21
	v_cvt_pk_bf16_f32 v5, v18, v19
	global_store_dwordx4 v[26:27], v[2:5], off offset:256
	s_and_saveexec_b64 s[56:57], s[6:7]
	s_cbranch_execz .LBB0_669
	s_waitcnt lgkmcnt(0)
	v_add_f32_e32 v0, v0, v1
	v_mul_f32_e32 v0, 0x4f800000, v0
	v_trunc_f32_e32 v0, v0
	v_mul_f32_e64 v1, |v0|, s87
	v_floor_f32_e32 v1, v1
	v_fma_f32 v2, v1, s88, |v0|
	v_cvt_u32_f32_e32 v2, v2
	v_cvt_u32_f32_e32 v1, v1
	v_ashrrev_i32_e32 v3, 31, v0
	v_xor_b32_e32 v0, v2, v3
	v_xor_b32_e32 v1, v1, v3
	v_sub_co_u32_e32 v0, vcc, v0, v3
	s_nop 1
	v_subb_co_u32_e32 v1, vcc, v1, v3, vcc
	v_lshl_add_u64 v[2:3], v[16:17], 3, s[10:11]
	global_atomic_add_x2 v[2:3], v[0:1], off

; #define PG8_STAGE(bufoff, gbase, voff) do { _Pragma("unroll") for (int _i = 0; _i < 2; ++_i) \
;         __builtin_amdgcn_global_load_lds((const unsigned*)((const char*)(gbase) + (voff)[_i]), (PG8_LAS unsigned*)(lds + (bufoff) + ldsw + _i * 8192), 16, 0, 0); } while (0)
; #define PG8_LDA(dst, b, h) do { _Pragma("unroll") for (int m = 0; m < 4; ++m) _Pragma("unroll") for (int k = 0; k < 2; ++k) dst[m][k] = *(const PG8_LAS bf16x8*)(lds + PG8_SA(b, h) + aoff + m * 2048 + k * 1024); } while (0)
; #define PG8_LDB(dst, b, h) do { _Pragma("unroll") for (int n = 0; n < 2; ++n) _Pragma("unroll") for (int k = 0; k < 2; ++k) dst[n][k] = *(const PG8_LAS bf16x8*)(lds + PG8_SB(b, h) + boff + n * 2048 + k * 1024); } while (0)
; #define PG8_MMA(ai, bj, At, Bt) do { __builtin_amdgcn_s_setprio(1); _Pragma("unroll") for (int m = 0; m < 4; ++m) _Pragma("unroll") for (int n = 0; n < 2; ++n) _Pragma("unroll") for (int k = 0; k < 2; ++k) \
;         acc[ai][bj][m][n] = __builtin_amdgcn_mfma_f32_16x16x32_bf16(Bt[n][k], At[m][k], acc[ai][bj][m][n], 0, 0, 0); __builtin_amdgcn_s_setprio(0); } while (0)
; #define PG8_WAIT_V(n) asm volatile("s_waitcnt vmcnt(" #n ")" ::: "memory")
; #define PG8_WAIT_L(n) asm volatile("s_waitcnt lgkmcnt(" #n ")" ::: "memory")
; #define PG8_BAR __builtin_amdgcn_s_barrier()
; #define PG8_SCHED __builtin_amdgcn_sched_barrier(0)
; template <class Epi, class Sched, bool ALIGN_EPI = false, bool SP2 = false>
; __device__ __forceinline__ void gemm_phase(PG8_LAS unsigned char* lds, const Gemm g, const Sched& S, const Epi& E) {
;     ...
;             if constexpr (SP2) {
;             PG8_LDB(B0, 0, 0); PG8_LDB(B1, 0, 1); PG8_SCHED; PG8_LDA(At, 0, 0); PG8_STAGE(PG8_SA(1, 1), a1 + hstep, voffA);
;             PG8_WAIT_V(8); PG8_WAIT_L(0); PG8_BAR; PG8_MMA(0, 0, At, B0); PG8_MMA(0, 1, At, B1); PG8_BAR; PG8_SCHED;
;             PG8_LDA(At, 0, 1); PG8_STAGE(PG8_SB(0, 0), b2, voffB); PG8_STAGE(PG8_SB(0, 1), b2 + hstep, voffB); PG8_STAGE(PG8_SA(0, 0), a2, voffA);
.LBB0_873:
	ds_read_b128 v[144:147], v151
	ds_read_b128 v[156:159], v151 offset:1024
	ds_read_b128 v[160:163], v151 offset:2048
	ds_read_b128 v[164:167], v151 offset:3072
	ds_read_b128 v[168:171], v152
	ds_read_b128 v[172:175], v152 offset:1024
	ds_read_b128 v[176:179], v152 offset:2048
	ds_read_b128 v[182:185], v152 offset:3072
	s_add_u32 s3, s58, 0xfffe0080
	s_addc_u32 s33, s59, -1
	s_cmp_eq_u32 s87, 4
	s_cselect_b32 s63, s49, s33
	s_cselect_b32 s62, s55, s3
	s_cselect_b32 s61, s45, s86
	s_cselect_b32 s60, s84, s85
	v_lshl_add_u64 v[202:203], s[58:59], 0, v[136:137]
	s_add_i32 m0, s15, 0xc000
	ds_read_b128 v[186:189], v153
	ds_read_b128 v[190:193], v153 offset:1024
	ds_read_b128 v[194:197], v153 offset:2048
	ds_read_b128 v[198:201], v153 offset:3072
	ds_read_b128 v[208:211], v153 offset:4096
	ds_read_b128 v[212:215], v153 offset:5120
	ds_read_b128 v[216:219], v153 offset:6144
	ds_read_b128 v[220:223], v153 offset:7168
	global_load_lds_dwordx4 v[202:203], off
	v_lshl_add_u64 v[202:203], s[58:59], 0, v[138:139]
	s_add_i32 m0, s15, 0xe000
	s_nop 0
	global_load_lds_dwordx4 v[202:203], off
	s_waitcnt vmcnt(8)
	s_waitcnt lgkmcnt(0)
	s_barrier
	s_setprio 1
	s_waitcnt lgkmcnt(0)
	v_mfma_f32_16x16x32_bf16 v[124:127], v[144:147], v[186:189], v[124:127]
	v_mfma_f32_16x16x32_bf16 v[120:123], v[160:163], v[186:189], v[120:123]
	v_mfma_f32_16x16x32_bf16 v[108:111], v[144:147], v[194:197], v[108:111]
	v_mfma_f32_16x16x32_bf16 v[104:107], v[160:163], v[194:197], v[104:107]
	v_mfma_f32_16x16x32_bf16 v[92:95], v[144:147], v[208:211], v[92:95]
	v_mfma_f32_16x16x32_bf16 v[88:91], v[160:163], v[208:211], v[88:91]
	v_mfma_f32_16x16x32_bf16 v[76:79], v[144:147], v[216:219], v[76:79]
	v_mfma_f32_16x16x32_bf16 v[72:75], v[160:163], v[216:219], v[72:75]
	v_mfma_f32_16x16x32_bf16 v[124:127], v[156:159], v[190:193], v[124:127]
	v_mfma_f32_16x16x32_bf16 v[120:123], v[164:167], v[190:193], v[120:123]
	v_mfma_f32_16x16x32_bf16 v[108:111], v[156:159], v[198:201], v[108:111]
	v_mfma_f32_16x16x32_bf16 v[104:107], v[164:167], v[198:201], v[104:107]
	v_mfma_f32_16x16x32_bf16 v[92:95], v[156:159], v[212:215], v[92:95]
	v_mfma_f32_16x16x32_bf16 v[88:91], v[164:167], v[212:215], v[88:91]
	v_mfma_f32_16x16x32_bf16 v[76:79], v[156:159], v[220:223], v[76:79]
	v_mfma_f32_16x16x32_bf16 v[72:75], v[164:167], v[220:223], v[72:75]
	s_setprio 0
	s_setprio 1
	v_mfma_f32_16x16x32_bf16 v[116:119], v[168:171], v[186:189], v[116:119]
	v_mfma_f32_16x16x32_bf16 v[112:115], v[176:179], v[186:189], v[112:115]
	v_mfma_f32_16x16x32_bf16 v[100:103], v[168:171], v[194:197], v[100:103]
	v_mfma_f32_16x16x32_bf16 v[96:99], v[176:179], v[194:197], v[96:99]
	v_mfma_f32_16x16x32_bf16 v[84:87], v[168:171], v[208:211], v[84:87]
	v_mfma_f32_16x16x32_bf16 v[80:83], v[176:179], v[208:211], v[80:83]
	v_mfma_f32_16x16x32_bf16 v[68:71], v[168:171], v[216:219], v[68:71]
	v_mfma_f32_16x16x32_bf16 v[64:67], v[176:179], v[216:219], v[64:67]
	v_mfma_f32_16x16x32_bf16 v[116:119], v[172:175], v[190:193], v[116:119]
	v_mfma_f32_16x16x32_bf16 v[112:115], v[182:185], v[190:193], v[112:115]
	v_mfma_f32_16x16x32_bf16 v[100:103], v[172:175], v[198:201], v[100:103]
	v_mfma_f32_16x16x32_bf16 v[96:99], v[182:185], v[198:201], v[96:99]
	v_mfma_f32_16x16x32_bf16 v[84:87], v[172:175], v[212:215], v[84:87]
	v_mfma_f32_16x16x32_bf16 v[80:83], v[182:185], v[212:215], v[80:83]
	v_mfma_f32_16x16x32_bf16 v[68:71], v[172:175], v[220:223], v[68:71]
	v_mfma_f32_16x16x32_bf16 v[64:67], v[182:185], v[220:223], v[64:67]
	s_setprio 0
	s_barrier
	s_add_i32 s3, s74, s14
	v_lshl_add_u64 v[202:203], s[60:61], 0, v[130:131]
	s_mov_b32 m0, s3
	ds_read_b128 v[186:189], v153 offset:16384
	ds_read_b128 v[190:193], v153 offset:17408
	ds_read_b128 v[194:197], v153 offset:18432
	ds_read_b128 v[198:201], v153 offset:19456
	ds_read_b128 v[208:211], v153 offset:20480
	ds_read_b128 v[212:215], v153 offset:21504
	ds_read_b128 v[216:219], v153 offset:22528
	ds_read_b128 v[220:223], v153 offset:23552
	global_load_lds_dwordx4 v[202:203], off
	s_add_i32 m0, s3, 0x2000
	s_add_u32 s78, s60, 0x20000
	v_lshl_add_u64 v[224:225], s[60:61], 0, v[134:135]
	s_addc_u32 s79, s61, 0
	s_add_i32 s3, s75, s14
	global_load_lds_dwordx4 v[224:225], off
	v_lshl_add_u64 v[226:227], s[78:79], 0, v[130:131]
	s_mov_b32 m0, s3
	v_lshl_add_u64 v[228:229], s[62:63], 0, v[132:133]
	global_load_lds_dwordx4 v[226:227], off
	v_lshl_add_u64 v[226:227], s[78:79], 0, v[134:135]
	s_add_i32 m0, s3, 0x2000
	s_nop 0
	global_load_lds_dwordx4 v[226:227], off
	v_lshl_add_u64 v[226:227], s[62:63], 0, v[128:129]
	s_mov_b32 m0, s15
	s_nop 0
	global_load_lds_dwordx4 v[226:227], off
	s_mov_b32 m0, s34
	s_nop 0
	global_load_lds_dwordx4 v[228:229], off
	s_waitcnt vmcnt(8)
	s_waitcnt lgkmcnt(0)
	s_barrier
; #define PG8_STAGE(bufoff, gbase, voff) do { _Pragma("unroll") for (int _i = 0; _i < 2; ++_i) \
;         __builtin_amdgcn_global_load_lds((const unsigned*)((const char*)(gbase) + (voff)[_i]), (PG8_LAS unsigned*)(lds + (bufoff) + ldsw + _i * 8192), 16, 0, 0); } while (0)
; #define PG8_LDA(dst, b, h) do { _Pragma("unroll") for (int m = 0; m < 4; ++m) _Pragma("unroll") for (int k = 0; k < 2; ++k) dst[m][k] = *(const PG8_LAS bf16x8*)(lds + PG8_SA(b, h) + aoff + m * 2048 + k * 1024); } while (0)
; #define PG8_LDB(dst, b, h) do { _Pragma("unroll") for (int n = 0; n < 2; ++n) _Pragma("unroll") for (int k = 0; k < 2; ++k) dst[n][k] = *(const PG8_LAS bf16x8*)(lds + PG8_SB(b, h) + boff + n * 2048 + k * 1024); } while (0)
; #define PG8_MMA(ai, bj, At, Bt) do { __builtin_amdgcn_s_setprio(1); _Pragma("unroll") for (int m = 0; m < 4; ++m) _Pragma("unroll") for (int n = 0; n < 2; ++n) _Pragma("unroll") for (int k = 0; k < 2; ++k) \
;         acc[ai][bj][m][n] = __builtin_amdgcn_mfma_f32_16x16x32_bf16(Bt[n][k], At[m][k], acc[ai][bj][m][n], 0, 0, 0); __builtin_amdgcn_s_setprio(0); } while (0)
; #define PG8_WAIT_V(n) asm volatile("s_waitcnt vmcnt(" #n ")" ::: "memory")
; #define PG8_WAIT_L(n) asm volatile("s_waitcnt lgkmcnt(" #n ")" ::: "memory")
; #define PG8_BAR __builtin_amdgcn_s_barrier()
; #define PG8_SCHED __builtin_amdgcn_sched_barrier(0)
; template <class Epi, class Sched, bool ALIGN_EPI = false, bool SP2 = false>
; __device__ __forceinline__ void gemm_phase(PG8_LAS unsigned char* lds, const Gemm g, const Sched& S, const Epi& E) {
;     ...
;             PG8_WAIT_V(8); PG8_WAIT_L(0); PG8_BAR; PG8_MMA(1, 0, At, B0); PG8_MMA(1, 1, At, B1); PG8_BAR; PG8_SCHED;
;             PG8_LDB(B0, 1, 0); PG8_LDB(B1, 1, 1); PG8_SCHED; PG8_LDA(At, 1, 0); PG8_STAGE(PG8_SA(0, 1), a2 + hstep, voffA);
;             PG8_WAIT_V(8); PG8_WAIT_L(0); PG8_BAR; PG8_MMA(0, 0, At, B0); PG8_MMA(0, 1, At, B1); PG8_BAR; PG8_SCHED;
	s_setprio 1
	s_waitcnt lgkmcnt(0)
	v_mfma_f32_16x16x32_bf16 v[60:63], v[144:147], v[186:189], v[60:63]
	v_mfma_f32_16x16x32_bf16 v[56:59], v[160:163], v[186:189], v[56:59]
	v_mfma_f32_16x16x32_bf16 v[44:47], v[144:147], v[194:197], v[44:47]
	v_mfma_f32_16x16x32_bf16 v[40:43], v[160:163], v[194:197], v[40:43]
	v_mfma_f32_16x16x32_bf16 v[28:31], v[144:147], v[208:211], v[28:31]
	v_mfma_f32_16x16x32_bf16 v[24:27], v[160:163], v[208:211], v[24:27]
	v_mfma_f32_16x16x32_bf16 v[12:15], v[144:147], v[216:219], v[12:15]
	v_mfma_f32_16x16x32_bf16 v[8:11], v[160:163], v[216:219], v[8:11]
	v_mfma_f32_16x16x32_bf16 v[60:63], v[156:159], v[190:193], v[60:63]
	v_mfma_f32_16x16x32_bf16 v[56:59], v[164:167], v[190:193], v[56:59]
	v_mfma_f32_16x16x32_bf16 v[44:47], v[156:159], v[198:201], v[44:47]
	v_mfma_f32_16x16x32_bf16 v[40:43], v[164:167], v[198:201], v[40:43]
	v_mfma_f32_16x16x32_bf16 v[28:31], v[156:159], v[212:215], v[28:31]
	v_mfma_f32_16x16x32_bf16 v[24:27], v[164:167], v[212:215], v[24:27]
	v_mfma_f32_16x16x32_bf16 v[12:15], v[156:159], v[220:223], v[12:15]
	v_mfma_f32_16x16x32_bf16 v[8:11], v[164:167], v[220:223], v[8:11]
	s_setprio 0
	s_setprio 1
	v_mfma_f32_16x16x32_bf16 v[52:55], v[168:171], v[186:189], v[52:55]
	v_mfma_f32_16x16x32_bf16 v[48:51], v[176:179], v[186:189], v[48:51]
	v_mfma_f32_16x16x32_bf16 v[36:39], v[168:171], v[194:197], v[36:39]
	v_mfma_f32_16x16x32_bf16 v[32:35], v[176:179], v[194:197], v[32:35]
	v_mfma_f32_16x16x32_bf16 v[20:23], v[168:171], v[208:211], v[20:23]
	v_mfma_f32_16x16x32_bf16 v[16:19], v[176:179], v[208:211], v[16:19]
	v_mfma_f32_16x16x32_bf16 v[4:7], v[168:171], v[216:219], v[4:7]
	v_mfma_f32_16x16x32_bf16 v[0:3], v[176:179], v[216:219], v[0:3]
	v_mfma_f32_16x16x32_bf16 v[52:55], v[172:175], v[190:193], v[52:55]
	v_mfma_f32_16x16x32_bf16 v[48:51], v[182:185], v[190:193], v[48:51]
	v_mfma_f32_16x16x32_bf16 v[36:39], v[172:175], v[198:201], v[36:39]
	v_mfma_f32_16x16x32_bf16 v[32:35], v[182:185], v[198:201], v[32:35]
	v_mfma_f32_16x16x32_bf16 v[20:23], v[172:175], v[212:215], v[20:23]
	v_mfma_f32_16x16x32_bf16 v[16:19], v[182:185], v[212:215], v[16:19]
	v_mfma_f32_16x16x32_bf16 v[4:7], v[172:175], v[220:223], v[4:7]
	v_mfma_f32_16x16x32_bf16 v[0:3], v[182:185], v[220:223], v[0:3]
	s_setprio 0
	s_barrier
	s_add_i32 s3, 0, 0x18000
	v_add_u32_e32 v155, s3, v149
	s_add_i32 s33, 0, 0x1c000
	ds_read_b128 v[144:147], v155
	ds_read_b128 v[156:159], v155 offset:1024
	ds_read_b128 v[160:163], v155 offset:2048
	ds_read_b128 v[164:167], v155 offset:3072
	v_add_u32_e32 v155, s33, v149
	ds_read_b128 v[168:171], v155
	ds_read_b128 v[172:175], v155 offset:1024
	ds_read_b128 v[176:179], v155 offset:2048
	ds_read_b128 v[182:185], v155 offset:3072
	s_add_u32 s62, s62, 0x20000
	s_addc_u32 s63, s63, 0
	s_mov_b32 m0, s57
	v_lshl_add_u64 v[230:231], s[62:63], 0, v[128:129]
	ds_read_b128 v[186:189], v153 offset:32768
	ds_read_b128 v[190:193], v153 offset:33792
	ds_read_b128 v[194:197], v153 offset:34816
	ds_read_b128 v[198:201], v153 offset:35840
	ds_read_b128 v[208:211], v153 offset:36864
	ds_read_b128 v[212:215], v153 offset:37888
	ds_read_b128 v[216:219], v153 offset:38912
	ds_read_b128 v[220:223], v153 offset:39936
	global_load_lds_dwordx4 v[230:231], off
	v_lshl_add_u64 v[230:231], s[62:63], 0, v[132:133]
	s_mov_b32 m0, s64
	s_nop 0
	global_load_lds_dwordx4 v[230:231], off
	s_waitcnt vmcnt(8)
	s_waitcnt lgkmcnt(0)
	s_barrier
	s_setprio 1
	s_waitcnt lgkmcnt(0)
	v_mfma_f32_16x16x32_bf16 v[124:127], v[144:147], v[186:189], v[124:127]
	v_mfma_f32_16x16x32_bf16 v[120:123], v[160:163], v[186:189], v[120:123]
	v_mfma_f32_16x16x32_bf16 v[108:111], v[144:147], v[194:197], v[108:111]
	v_mfma_f32_16x16x32_bf16 v[104:107], v[160:163], v[194:197], v[104:107]
	v_mfma_f32_16x16x32_bf16 v[92:95], v[144:147], v[208:211], v[92:95]
	v_mfma_f32_16x16x32_bf16 v[88:91], v[160:163], v[208:211], v[88:91]
	v_mfma_f32_16x16x32_bf16 v[76:79], v[144:147], v[216:219], v[76:79]
	v_mfma_f32_16x16x32_bf16 v[72:75], v[160:163], v[216:219], v[72:75]
	v_mfma_f32_16x16x32_bf16 v[124:127], v[156:159], v[190:193], v[124:127]
	v_mfma_f32_16x16x32_bf16 v[120:123], v[164:167], v[190:193], v[120:123]
	v_mfma_f32_16x16x32_bf16 v[108:111], v[156:159], v[198:201], v[108:111]
	v_mfma_f32_16x16x32_bf16 v[104:107], v[164:167], v[198:201], v[104:107]
	v_mfma_f32_16x16x32_bf16 v[92:95], v[156:159], v[212:215], v[92:95]
	v_mfma_f32_16x16x32_bf16 v[88:91], v[164:167], v[212:215], v[88:91]
	v_mfma_f32_16x16x32_bf16 v[76:79], v[156:159], v[220:223], v[76:79]
	v_mfma_f32_16x16x32_bf16 v[72:75], v[164:167], v[220:223], v[72:75]
	s_setprio 0
	s_setprio 1
	v_mfma_f32_16x16x32_bf16 v[116:119], v[168:171], v[186:189], v[116:119]
	v_mfma_f32_16x16x32_bf16 v[112:115], v[176:179], v[186:189], v[112:115]
	v_mfma_f32_16x16x32_bf16 v[100:103], v[168:171], v[194:197], v[100:103]
	v_mfma_f32_16x16x32_bf16 v[96:99], v[176:179], v[194:197], v[96:99]
	v_mfma_f32_16x16x32_bf16 v[84:87], v[168:171], v[208:211], v[84:87]
	v_mfma_f32_16x16x32_bf16 v[80:83], v[176:179], v[208:211], v[80:83]
	v_mfma_f32_16x16x32_bf16 v[68:71], v[168:171], v[216:219], v[68:71]
	v_mfma_f32_16x16x32_bf16 v[64:67], v[176:179], v[216:219], v[64:67]
	v_mfma_f32_16x16x32_bf16 v[116:119], v[172:175], v[190:193], v[116:119]
	v_mfma_f32_16x16x32_bf16 v[112:115], v[182:185], v[190:193], v[112:115]
	v_mfma_f32_16x16x32_bf16 v[100:103], v[172:175], v[198:201], v[100:103]
	v_mfma_f32_16x16x32_bf16 v[96:99], v[182:185], v[198:201], v[96:99]
	v_mfma_f32_16x16x32_bf16 v[84:87], v[172:175], v[212:215], v[84:87]
	v_mfma_f32_16x16x32_bf16 v[80:83], v[182:185], v[212:215], v[80:83]
	v_mfma_f32_16x16x32_bf16 v[68:71], v[172:175], v[220:223], v[68:71]
	v_mfma_f32_16x16x32_bf16 v[64:67], v[182:185], v[220:223], v[64:67]
	s_setprio 0
	s_barrier
; #define PG8_STAGE(bufoff, gbase, voff) do { _Pragma("unroll") for (int _i = 0; _i < 2; ++_i) \
;         __builtin_amdgcn_global_load_lds((const unsigned*)((const char*)(gbase) + (voff)[_i]), (PG8_LAS unsigned*)(lds + (bufoff) + ldsw + _i * 8192), 16, 0, 0); } while (0)
; #define PG8_LDA(dst, b, h) do { _Pragma("unroll") for (int m = 0; m < 4; ++m) _Pragma("unroll") for (int k = 0; k < 2; ++k) dst[m][k] = *(const PG8_LAS bf16x8*)(lds + PG8_SA(b, h) + aoff + m * 2048 + k * 1024); } while (0)
; #define PG8_MMA(ai, bj, At, Bt) do { __builtin_amdgcn_s_setprio(1); _Pragma("unroll") for (int m = 0; m < 4; ++m) _Pragma("unroll") for (int n = 0; n < 2; ++n) _Pragma("unroll") for (int k = 0; k < 2; ++k) \
;         acc[ai][bj][m][n] = __builtin_amdgcn_mfma_f32_16x16x32_bf16(Bt[n][k], At[m][k], acc[ai][bj][m][n], 0, 0, 0); __builtin_amdgcn_s_setprio(0); } while (0)
; #define PG8_WAIT_V(n) asm volatile("s_waitcnt vmcnt(" #n ")" ::: "memory")
; #define PG8_WAIT_L(n) asm volatile("s_waitcnt lgkmcnt(" #n ")" ::: "memory")
; #define PG8_BAR __builtin_amdgcn_s_barrier()
; #define PG8_SCHED __builtin_amdgcn_sched_barrier(0)
;     __device__ __forceinline__ void operator()(const f32x4 (&acc)[2][2][4][2], const Unit& u, int wr, int wc, int fr, int fq) const {
;     ...
;             for (int m = 0; m < 4; ++m) { const int row = row0 + ai * HALF + m * 16; const size_t off = (size_t)row * 1024 + col0; float s = 0.f;
; #pragma unroll
;                 for (int bj = 0; bj < 2; ++bj) { f32x4 a0, a1;
;                     if (xin32) { const float* p = xin32 + off + bj * HALF; a0 = *(const f32x4*)p; a1 = *(const f32x4*)(p + 4); }
;                     else { const u32x4 w = *(const u32x4*)(xb + off + bj * HALF);
; template <class Epi, class Sched, bool ALIGN_EPI = false, bool SP2 = false>
; __device__ __forceinline__ void gemm_phase(PG8_LAS unsigned char* lds, const Gemm g, const Sched& S, const Epi& E) {
;     ...
;             PG8_WAIT_V(8); PG8_WAIT_L(0); PG8_BAR; PG8_MMA(0, 0, At, B0); PG8_MMA(0, 1, At, B1); PG8_BAR; PG8_SCHED;
;             PG8_LDA(At, 1, 1); PG8_STAGE(PG8_SB(1, 0), b3, voffB); PG8_STAGE(PG8_SB(1, 1), b3 + hstep, voffB); PG8_STAGE(PG8_SA(1, 0), a3, voffA);
;             PG8_WAIT_V(8); PG8_WAIT_L(0); PG8_BAR; PG8_MMA(1, 0, At, B0); PG8_MMA(1, 1, At, B1); PG8_BAR; PG8_SCHED;
	s_add_i32 s3, s3, s14
	v_lshl_add_u64 v[202:203], v[202:203], 0, s[38:39]
	s_mov_b32 m0, s3
	ds_read_b128 v[186:189], v153 offset:49152
	ds_read_b128 v[190:193], v153 offset:50176
	ds_read_b128 v[194:197], v153 offset:51200
	ds_read_b128 v[198:201], v153 offset:52224
	ds_read_b128 v[208:211], v153 offset:53248
	ds_read_b128 v[212:215], v153 offset:54272
	ds_read_b128 v[216:219], v153 offset:55296
	ds_read_b128 v[220:223], v153 offset:56320
	global_load_lds_dwordx4 v[202:203], off
	s_add_i32 m0, s3, 0x2000
	s_add_u32 s60, s60, 0x20080
	v_lshl_add_u64 v[202:203], v[224:225], 0, s[38:39]
	s_addc_u32 s61, s61, 0
	s_add_i32 s3, s33, s14
	global_load_lds_dwordx4 v[202:203], off
	v_lshl_add_u64 v[202:203], s[60:61], 0, v[130:131]
	s_mov_b32 m0, s3
	s_nop 0
	global_load_lds_dwordx4 v[202:203], off
	v_lshl_add_u64 v[202:203], s[60:61], 0, v[134:135]
	s_add_i32 m0, s3, 0x2000
	s_nop 0
	global_load_lds_dwordx4 v[202:203], off
	v_lshl_add_u64 v[202:203], v[226:227], 0, s[38:39]
	s_mov_b32 m0, s66
	s_nop 0
	global_load_lds_dwordx4 v[202:203], off
	v_lshl_add_u64 v[202:203], v[228:229], 0, s[38:39]
	s_mov_b32 m0, s67
	s_nop 0
	global_load_lds_dwordx4 v[202:203], off
	s_waitcnt vmcnt(8)
	s_waitcnt lgkmcnt(0)
	s_barrier
	s_setprio 1
	s_waitcnt lgkmcnt(0)
	v_mfma_f32_16x16x32_bf16 v[60:63], v[144:147], v[186:189], v[60:63]
	v_mfma_f32_16x16x32_bf16 v[56:59], v[160:163], v[186:189], v[56:59]
	v_mfma_f32_16x16x32_bf16 v[44:47], v[144:147], v[194:197], v[44:47]
	v_mfma_f32_16x16x32_bf16 v[40:43], v[160:163], v[194:197], v[40:43]
	v_mfma_f32_16x16x32_bf16 v[28:31], v[144:147], v[208:211], v[28:31]
	v_mfma_f32_16x16x32_bf16 v[24:27], v[160:163], v[208:211], v[24:27]
	v_mfma_f32_16x16x32_bf16 v[12:15], v[144:147], v[216:219], v[12:15]
	v_mfma_f32_16x16x32_bf16 v[8:11], v[160:163], v[216:219], v[8:11]
	v_mfma_f32_16x16x32_bf16 v[60:63], v[156:159], v[190:193], v[60:63]
	v_mfma_f32_16x16x32_bf16 v[56:59], v[164:167], v[190:193], v[56:59]
	v_mfma_f32_16x16x32_bf16 v[44:47], v[156:159], v[198:201], v[44:47]
	v_mfma_f32_16x16x32_bf16 v[40:43], v[164:167], v[198:201], v[40:43]
	v_mfma_f32_16x16x32_bf16 v[28:31], v[156:159], v[212:215], v[28:31]
	v_mfma_f32_16x16x32_bf16 v[24:27], v[164:167], v[212:215], v[24:27]
	v_mfma_f32_16x16x32_bf16 v[12:15], v[156:159], v[220:223], v[12:15]
	v_mfma_f32_16x16x32_bf16 v[8:11], v[164:167], v[220:223], v[8:11]
	s_setprio 0
	s_setprio 1
	v_mfma_f32_16x16x32_bf16 v[52:55], v[168:171], v[186:189], v[52:55]
	v_mfma_f32_16x16x32_bf16 v[48:51], v[176:179], v[186:189], v[48:51]
	v_mfma_f32_16x16x32_bf16 v[36:39], v[168:171], v[194:197], v[36:39]
	v_mfma_f32_16x16x32_bf16 v[32:35], v[176:179], v[194:197], v[32:35]
	v_mfma_f32_16x16x32_bf16 v[20:23], v[168:171], v[208:211], v[20:23]
	v_mfma_f32_16x16x32_bf16 v[16:19], v[176:179], v[208:211], v[16:19]
	v_mfma_f32_16x16x32_bf16 v[4:7], v[168:171], v[216:219], v[4:7]
	v_mfma_f32_16x16x32_bf16 v[0:3], v[176:179], v[216:219], v[0:3]
	v_mfma_f32_16x16x32_bf16 v[52:55], v[172:175], v[190:193], v[52:55]
	v_mfma_f32_16x16x32_bf16 v[48:51], v[182:185], v[190:193], v[48:51]
	v_mfma_f32_16x16x32_bf16 v[36:39], v[172:175], v[198:201], v[36:39]
	v_mfma_f32_16x16x32_bf16 v[32:35], v[182:185], v[198:201], v[32:35]
	v_mfma_f32_16x16x32_bf16 v[20:23], v[172:175], v[212:215], v[20:23]
	v_mfma_f32_16x16x32_bf16 v[16:19], v[182:185], v[212:215], v[16:19]
	v_mfma_f32_16x16x32_bf16 v[4:7], v[172:175], v[220:223], v[4:7]
	v_mfma_f32_16x16x32_bf16 v[0:3], v[182:185], v[220:223], v[0:3]
	s_setprio 0
	s_barrier
	s_add_i32 s87, s87, 2
	s_add_u32 s58, s58, 0x100
	s_addc_u32 s59, s59, 0
	s_add_u32 s85, s85, 0x100
	s_addc_u32 s86, s86, 0
	s_cmp_gt_u32 s87, 5
	s_cbranch_scc0 .LBB0_873
	v_lshl_add_u32 v146, s56, 8, v148
	v_ashrrev_i32_e32 v147, 31, v146
	v_lshl_or_b32 v144, s54, 8, v150
	v_lshlrev_b64 v[156:157], 11, v[146:147]
	v_ashrrev_i32_e32 v145, 31, v144
	v_lshl_add_u64 v[156:157], s[22:23], 0, v[156:157]
	v_lshl_add_u64 v[166:167], v[144:145], 1, v[156:157]
	s_mov_b64 s[98:99], 0x8000
	s_mov_b64 s[100:101], 0x28000
	global_load_dwordx4 v[182:185], v[166:167], off
	global_load_dwordx4 v[186:189], v[166:167], off offset:256
	v_lshl_add_u64 v[198:199], v[166:167], 0, s[98:99]
	global_load_dwordx4 v[190:193], v[198:199], off
	global_load_dwordx4 v[194:197], v[198:199], off offset:256
	v_lshl_add_u64 v[198:199], v[198:199], 0, s[98:99]
	global_load_dwordx4 v[208:211], v[198:199], off
	global_load_dwordx4 v[212:215], v[198:199], off offset:256
	v_lshl_add_u64 v[198:199], v[198:199], 0, s[98:99]
	global_load_dwordx4 v[216:219], v[198:199], off
	global_load_dwordx4 v[220:223], v[198:199], off offset:256
	v_lshl_add_u64 v[198:199], v[198:199], 0, s[100:101]
	s_and_b64 vcc, exec, s[42:43]
	s_cbranch_vccz .LBB0_876
	s_barrier
; __device__ __forceinline__ void fx_add(float* p, size_t idx, float s) { atomicAdd((unsigned long long*)p + idx, (unsigned long long)(long long)(s * 4294967296.0f)); }
; __device__ __forceinline__ unsigned cvtpk(float lo, float hi) { f32x2v_ v = {lo, hi}; bf16x2v_ b = __builtin_convertvector(v, bf16x2v_); return __builtin_bit_cast(unsigned, b); }
;     __device__ __forceinline__ void operator()(const f32x4 (&acc)[2][2][4][2], const Unit& u, int wr, int wc, int fr, int fq) const {
;     ...
;             for (int m = 0; m < 4; ++m) { const int row = row0 + ai * HALF + m * 16; const size_t off = (size_t)row * 1024 + col0; float s = 0.f;
; #pragma unroll
;                 for (int bj = 0; bj < 2; ++bj) { f32x4 a0, a1;
;                     if (xin32) { const float* p = xin32 + off + bj * HALF; a0 = *(const f32x4*)p; a1 = *(const f32x4*)(p + 4); }
;                     else { const u32x4 w = *(const u32x4*)(xb + off + bj * HALF);
;                         a0 = (f32x4){__uint_as_float(w.x << 16), __uint_as_float(w.x & 0xffff0000u), __uint_as_float(w.y << 16), __uint_as_float(w.y & 0xffff0000u)};
;                         a1 = (f32x4){__uint_as_float(w.z << 16), __uint_as_float(w.z & 0xffff0000u), __uint_as_float(w.w << 16), __uint_as_float(w.w & 0xffff0000u)}; }
;                     const f32x4 v0 = a0 + acc[ai][bj][m][0] * alpha, v1 = a1 + acc[ai][bj][m][1] * alpha;
;                     u32x4 w; w.x = cvtpk(v0[0], v0[1]); w.y = cvtpk(v0[2], v0[3]); w.z = cvtpk(v1[0], v1[1]); w.w = cvtpk(v1[2], v1[3]);
;                     *(u32x4*)(xb + off + bj * HALF) = w;
;                     s += (v0[0] * v0[0] + v0[1] * v0[1]) + (v0[2] * v0[2] + v0[3] * v0[3]) + (v1[0] * v1[0] + v1[1] * v1[1]) + (v1[2] * v1[2] + v1[3] * v1[3]); }
;                 s += __shfl_xor(s, 16); s += __shfl_xor(s, 32);
;                 if (fq == 0) fx_add(ssout, row, s); }
.LBB0_876:
	s_nop 0
	s_nop 0
	v_and_b32_e32 v156, 64, v154
	v_xor_b32_e32 v155, 16, v154
	v_add_u32_e32 v156, 64, v156
	v_xor_b32_e32 v157, 32, v154
	v_cmp_lt_i32_e32 vcc, v155, v156
	s_waitcnt vmcnt(6)
	v_lshlrev_b32_e32 v168, 16, v182
	v_cndmask_b32_e32 v155, v154, v155, vcc
	v_cmp_lt_i32_e32 vcc, v157, v156
	v_and_b32_e32 v169, 0xffff0000, v182
	v_lshlrev_b32_e32 v158, 16, v183
	v_and_b32_e32 v159, 0xffff0000, v183
	v_lshlrev_b32_e32 v172, 16, v186
	v_and_b32_e32 v173, 0xffff0000, v186
	v_lshlrev_b32_e32 v162, 16, v187
	v_and_b32_e32 v163, 0xffff0000, v187
	v_cndmask_b32_e32 v157, v154, v157, vcc
	v_lshlrev_b32_e32 v170, 16, v184
	v_and_b32_e32 v171, 0xffff0000, v184
	v_lshlrev_b32_e32 v160, 16, v185
	v_and_b32_e32 v161, 0xffff0000, v185
	v_lshlrev_b32_e32 v174, 16, v188
	v_and_b32_e32 v175, 0xffff0000, v188
	v_lshlrev_b32_e32 v164, 16, v189
	v_and_b32_e32 v165, 0xffff0000, v189
	global_load_dwordx4 v[182:185], v[198:199], off
	global_load_dwordx4 v[186:189], v[198:199], off offset:256
	v_lshl_add_u64 v[198:199], v[198:199], 0, s[98:99]
	v_pk_add_f32 v[126:127], v[126:127], v[158:159]
	v_pk_add_f32 v[124:125], v[124:125], v[168:169]
	v_pk_add_f32 v[118:119], v[118:119], v[162:163]
	v_pk_add_f32 v[116:117], v[116:117], v[172:173]
	v_lshlrev_b32_e32 v156, 2, v155
	v_lshlrev_b32_e32 v155, 2, v157
	v_pk_add_f32 v[122:123], v[122:123], v[160:161]
	v_pk_add_f32 v[120:121], v[120:121], v[170:171]
	v_pk_add_f32 v[158:159], v[114:115], v[164:165]
	v_pk_add_f32 v[160:161], v[112:113], v[174:175]
	v_mul_f32_e32 v114, v125, v125
	v_mul_f32_e32 v115, v127, v127
	v_mul_f32_e32 v157, v117, v117
	v_mul_f32_e32 v162, v119, v119
	v_cvt_pk_bf16_f32 v112, v124, v125
	v_mul_f32_e32 v125, v121, v121
	v_mul_f32_e32 v163, v161, v161
	v_fmac_f32_e32 v114, v124, v124
	v_fmac_f32_e32 v115, v126, v126
	v_fmac_f32_e32 v157, v116, v116
	v_fmac_f32_e32 v162, v118, v118
	v_cvt_pk_bf16_f32 v113, v126, v127
	v_mul_f32_e32 v127, v123, v123
	v_mul_f32_e32 v164, v159, v159
	v_fmac_f32_e32 v125, v120, v120
	v_fmac_f32_e32 v163, v160, v160
	v_add_f32_e32 v114, v114, v115
	v_add_f32_e32 v115, v157, v162
	v_fmac_f32_e32 v127, v122, v122
	v_fmac_f32_e32 v164, v158, v158
	v_add_f32_e32 v114, v125, v114
	v_add_f32_e32 v115, v163, v115
	v_add_f32_e32 v114, v127, v114
	v_add_f32_e32 v115, v164, v115
	v_add_f32_e32 v124, v114, v115
	ds_bpermute_b32 v125, v156, v124
	v_cvt_pk_bf16_f32 v114, v120, v121
	v_cvt_pk_bf16_f32 v115, v122, v123
	global_store_dwordx4 v[166:167], v[112:115], off
	s_waitcnt lgkmcnt(0)
	s_nop 0
	v_add_f32_e32 v112, v124, v125
	ds_bpermute_b32 v113, v155, v112
	v_cvt_pk_bf16_f32 v114, v116, v117
	v_cvt_pk_bf16_f32 v115, v118, v119
	v_cvt_pk_bf16_f32 v116, v160, v161
	v_cvt_pk_bf16_f32 v117, v158, v159
	global_store_dwordx4 v[166:167], v[114:117], off offset:256
	s_and_saveexec_b64 s[54:55], s[8:9]
	s_cbranch_execz .LBB0_878
	s_waitcnt lgkmcnt(0)
	v_add_f32_e32 v112, v112, v113
	v_mul_f32_e32 v112, 0x4f800000, v112
	v_trunc_f32_e32 v112, v112
	v_mul_f32_e64 v113, |v112|, s82
	v_floor_f32_e32 v113, v113
	v_fma_f32 v114, v113, s83, |v112|
	v_cvt_u32_f32_e32 v114, v114
	v_cvt_u32_f32_e32 v113, v113
	v_ashrrev_i32_e32 v115, 31, v112
	v_xor_b32_e32 v112, v114, v115
	v_xor_b32_e32 v113, v113, v115
	v_sub_co_u32_e32 v112, vcc, v112, v115
	s_nop 1
	v_subb_co_u32_e32 v113, vcc, v113, v115, vcc
	v_lshl_add_u64 v[114:115], v[146:147], 3, s[0:1]
	global_atomic_add_x2 v[114:115], v[112:113], off
.LBB0_878:
	s_or_b64 exec, exec, s[54:55]
	v_or_b32_e32 v112, 16, v146
	s_waitcnt lgkmcnt(0)
	v_ashrrev_i32_e32 v113, 31, v112
	v_lshlrev_b64 v[114:115], 11, v[112:113]
	v_lshl_add_u64 v[114:115], s[22:23], 0, v[114:115]
	v_lshl_add_u64 v[122:123], v[144:145], 1, v[114:115]
	s_nop 0
	s_nop 0
	s_waitcnt vmcnt(10)
	v_lshlrev_b32_e32 v124, 16, v190
	v_and_b32_e32 v125, 0xffff0000, v190
	v_lshlrev_b32_e32 v114, 16, v191
	v_and_b32_e32 v115, 0xffff0000, v191
	s_waitcnt vmcnt(9)
	v_lshlrev_b32_e32 v158, 16, v194
	v_and_b32_e32 v159, 0xffff0000, v194
	v_lshlrev_b32_e32 v118, 16, v195
	v_and_b32_e32 v119, 0xffff0000, v195
	v_lshlrev_b32_e32 v126, 16, v192
	v_and_b32_e32 v127, 0xffff0000, v192
	v_lshlrev_b32_e32 v116, 16, v193
	v_and_b32_e32 v117, 0xffff0000, v193
	v_lshlrev_b32_e32 v160, 16, v196
	v_and_b32_e32 v161, 0xffff0000, v196
	v_lshlrev_b32_e32 v120, 16, v197
	v_and_b32_e32 v121, 0xffff0000, v197
	global_load_dwordx4 v[190:193], v[198:199], off
	global_load_dwordx4 v[194:197], v[198:199], off offset:256
	v_lshl_add_u64 v[198:199], v[198:199], 0, s[98:99]
	v_pk_add_f32 v[110:111], v[110:111], v[114:115]
	v_pk_add_f32 v[108:109], v[108:109], v[124:125]
	v_pk_add_f32 v[102:103], v[102:103], v[118:119]
	v_pk_add_f32 v[100:101], v[100:101], v[158:159]
	v_pk_add_f32 v[106:107], v[106:107], v[116:117]
	v_pk_add_f32 v[104:105], v[104:105], v[126:127]
	v_pk_add_f32 v[114:115], v[98:99], v[120:121]
	v_pk_add_f32 v[116:117], v[96:97], v[160:161]
	v_mul_f32_e32 v98, v109, v109
	v_mul_f32_e32 v99, v111, v111
	v_mul_f32_e32 v118, v101, v101
	v_mul_f32_e32 v119, v103, v103
	v_cvt_pk_bf16_f32 v96, v108, v109
	v_mul_f32_e32 v109, v105, v105
	v_mul_f32_e32 v120, v117, v117
	v_fmac_f32_e32 v98, v108, v108
	v_fmac_f32_e32 v99, v110, v110
	v_fmac_f32_e32 v118, v100, v100
	v_fmac_f32_e32 v119, v102, v102
	v_cvt_pk_bf16_f32 v97, v110, v111
	v_mul_f32_e32 v111, v107, v107
	v_mul_f32_e32 v121, v115, v115
	v_fmac_f32_e32 v109, v104, v104
	v_fmac_f32_e32 v120, v116, v116
	v_add_f32_e32 v98, v98, v99
	v_add_f32_e32 v99, v118, v119
	v_fmac_f32_e32 v111, v106, v106
	v_fmac_f32_e32 v121, v114, v114
	v_add_f32_e32 v98, v109, v98
	v_add_f32_e32 v99, v120, v99
	v_add_f32_e32 v98, v111, v98
	v_add_f32_e32 v99, v121, v99
	v_add_f32_e32 v108, v98, v99
	ds_bpermute_b32 v109, v156, v108
	v_cvt_pk_bf16_f32 v98, v104, v105
	v_cvt_pk_bf16_f32 v99, v106, v107
	global_store_dwordx4 v[122:123], v[96:99], off
	s_waitcnt lgkmcnt(0)
	s_nop 0
	v_add_f32_e32 v96, v108, v109
	ds_bpermute_b32 v97, v155, v96
	v_cvt_pk_bf16_f32 v98, v100, v101
	v_cvt_pk_bf16_f32 v99, v102, v103
	v_cvt_pk_bf16_f32 v100, v116, v117
	v_cvt_pk_bf16_f32 v101, v114, v115
	global_store_dwordx4 v[122:123], v[98:101], off offset:256
	s_and_saveexec_b64 s[54:55], s[8:9]
	s_cbranch_execz .LBB0_880
	s_waitcnt lgkmcnt(0)
	v_add_f32_e32 v96, v96, v97
	v_mul_f32_e32 v96, 0x4f800000, v96
	v_trunc_f32_e32 v96, v96
	v_mul_f32_e64 v97, |v96|, s82
	v_floor_f32_e32 v97, v97
	v_fma_f32 v98, v97, s83, |v96|
	v_cvt_u32_f32_e32 v98, v98
	v_cvt_u32_f32_e32 v97, v97
	v_ashrrev_i32_e32 v99, 31, v96
	v_xor_b32_e32 v96, v98, v99
	v_xor_b32_e32 v97, v97, v99
	v_sub_co_u32_e32 v96, vcc, v96, v99
	s_nop 1
	v_subb_co_u32_e32 v97, vcc, v97, v99, vcc
	v_lshl_add_u64 v[98:99], v[112:113], 3, s[0:1]
	global_atomic_add_x2 v[98:99], v[96:97], off
; __device__ __forceinline__ void fx_add(float* p, size_t idx, float s) { atomicAdd((unsigned long long*)p + idx, (unsigned long long)(long long)(s * 4294967296.0f)); }
; __device__ __forceinline__ unsigned cvtpk(float lo, float hi) { f32x2v_ v = {lo, hi}; bf16x2v_ b = __builtin_convertvector(v, bf16x2v_); return __builtin_bit_cast(unsigned, b); }
;     __device__ __forceinline__ void operator()(const f32x4 (&acc)[2][2][4][2], const Unit& u, int wr, int wc, int fr, int fq) const {
;     ...
;             for (int m = 0; m < 4; ++m) { const int row = row0 + ai * HALF + m * 16; const size_t off = (size_t)row * 1024 + col0; float s = 0.f;
; #pragma unroll
;                 for (int bj = 0; bj < 2; ++bj) { f32x4 a0, a1;
;                     if (xin32) { const float* p = xin32 + off + bj * HALF; a0 = *(const f32x4*)p; a1 = *(const f32x4*)(p + 4); }
;                     else { const u32x4 w = *(const u32x4*)(xb + off + bj * HALF);
;                         a0 = (f32x4){__uint_as_float(w.x << 16), __uint_as_float(w.x & 0xffff0000u), __uint_as_float(w.y << 16), __uint_as_float(w.y & 0xffff0000u)};
;                         a1 = (f32x4){__uint_as_float(w.z << 16), __uint_as_float(w.z & 0xffff0000u), __uint_as_float(w.w << 16), __uint_as_float(w.w & 0xffff0000u)}; }
;                     const f32x4 v0 = a0 + acc[ai][bj][m][0] * alpha, v1 = a1 + acc[ai][bj][m][1] * alpha;
;                     u32x4 w; w.x = cvtpk(v0[0], v0[1]); w.y = cvtpk(v0[2], v0[3]); w.z = cvtpk(v1[0], v1[1]); w.w = cvtpk(v1[2], v1[3]);
;                     *(u32x4*)(xb + off + bj * HALF) = w;
;                     s += (v0[0] * v0[0] + v0[1] * v0[1]) + (v0[2] * v0[2] + v0[3] * v0[3]) + (v1[0] * v1[0] + v1[1] * v1[1]) + (v1[2] * v1[2] + v1[3] * v1[3]); }
;                 s += __shfl_xor(s, 16); s += __shfl_xor(s, 32);
;                 if (fq == 0) fx_add(ssout, row, s); }
.LBB0_880:
	s_or_b64 exec, exec, s[54:55]
	v_or_b32_e32 v96, 32, v146
	s_waitcnt lgkmcnt(0)
	v_ashrrev_i32_e32 v97, 31, v96
	v_lshlrev_b64 v[98:99], 11, v[96:97]
	v_lshl_add_u64 v[98:99], s[22:23], 0, v[98:99]
	v_lshl_add_u64 v[106:107], v[144:145], 1, v[98:99]
	s_nop 0
	s_nop 0
	s_waitcnt vmcnt(13)
	v_lshlrev_b32_e32 v108, 16, v208
	v_and_b32_e32 v109, 0xffff0000, v208
	v_lshlrev_b32_e32 v98, 16, v209
	v_and_b32_e32 v99, 0xffff0000, v209
	s_waitcnt vmcnt(12)
	v_lshlrev_b32_e32 v112, 16, v212
	v_and_b32_e32 v113, 0xffff0000, v212
	v_lshlrev_b32_e32 v102, 16, v213
	v_and_b32_e32 v103, 0xffff0000, v213
	v_lshlrev_b32_e32 v110, 16, v210
	v_and_b32_e32 v111, 0xffff0000, v210
	v_lshlrev_b32_e32 v100, 16, v211
	v_and_b32_e32 v101, 0xffff0000, v211
	v_lshlrev_b32_e32 v114, 16, v214
	v_and_b32_e32 v115, 0xffff0000, v214
	v_lshlrev_b32_e32 v104, 16, v215
	v_and_b32_e32 v105, 0xffff0000, v215
	global_load_dwordx4 v[208:211], v[198:199], off
	global_load_dwordx4 v[212:215], v[198:199], off offset:256
	v_lshl_add_u64 v[198:199], v[198:199], 0, s[98:99]
	v_pk_add_f32 v[94:95], v[94:95], v[98:99]
	v_pk_add_f32 v[92:93], v[92:93], v[108:109]
	v_pk_add_f32 v[86:87], v[86:87], v[102:103]
	v_pk_add_f32 v[84:85], v[84:85], v[112:113]
	v_pk_add_f32 v[90:91], v[90:91], v[100:101]
	v_pk_add_f32 v[88:89], v[88:89], v[110:111]
	v_pk_add_f32 v[98:99], v[82:83], v[104:105]
	v_pk_add_f32 v[100:101], v[80:81], v[114:115]
	v_mul_f32_e32 v82, v93, v93
	v_mul_f32_e32 v83, v95, v95
	v_mul_f32_e32 v102, v85, v85
	v_mul_f32_e32 v103, v87, v87
	v_cvt_pk_bf16_f32 v80, v92, v93
	v_mul_f32_e32 v93, v89, v89
	v_mul_f32_e32 v104, v101, v101
	v_fmac_f32_e32 v82, v92, v92
	v_fmac_f32_e32 v83, v94, v94
	v_fmac_f32_e32 v102, v84, v84
	v_fmac_f32_e32 v103, v86, v86
	v_cvt_pk_bf16_f32 v81, v94, v95
	v_mul_f32_e32 v95, v91, v91
	v_mul_f32_e32 v105, v99, v99
	v_fmac_f32_e32 v93, v88, v88
	v_fmac_f32_e32 v104, v100, v100
	v_add_f32_e32 v82, v82, v83
	v_add_f32_e32 v83, v102, v103
	v_fmac_f32_e32 v95, v90, v90
	v_fmac_f32_e32 v105, v98, v98
	v_add_f32_e32 v82, v93, v82
	v_add_f32_e32 v83, v104, v83
	v_add_f32_e32 v82, v95, v82
	v_add_f32_e32 v83, v105, v83
	v_add_f32_e32 v92, v82, v83
	ds_bpermute_b32 v93, v156, v92
	v_cvt_pk_bf16_f32 v82, v88, v89
	v_cvt_pk_bf16_f32 v83, v90, v91
	global_store_dwordx4 v[106:107], v[80:83], off
	s_waitcnt lgkmcnt(0)
	s_nop 0
	v_add_f32_e32 v80, v92, v93
	ds_bpermute_b32 v81, v155, v80
	v_cvt_pk_bf16_f32 v82, v84, v85
	v_cvt_pk_bf16_f32 v83, v86, v87
	v_cvt_pk_bf16_f32 v84, v100, v101
	v_cvt_pk_bf16_f32 v85, v98, v99
	global_store_dwordx4 v[106:107], v[82:85], off offset:256
	s_and_saveexec_b64 s[54:55], s[8:9]
	s_cbranch_execz .LBB0_882
	s_waitcnt lgkmcnt(0)
	v_add_f32_e32 v80, v80, v81
	v_mul_f32_e32 v80, 0x4f800000, v80
	v_trunc_f32_e32 v80, v80
	v_mul_f32_e64 v81, |v80|, s82
	v_floor_f32_e32 v81, v81
	v_fma_f32 v82, v81, s83, |v80|
	v_cvt_u32_f32_e32 v82, v82
	v_cvt_u32_f32_e32 v81, v81
	v_ashrrev_i32_e32 v83, 31, v80
	v_xor_b32_e32 v80, v82, v83
	v_xor_b32_e32 v81, v81, v83
	v_sub_co_u32_e32 v80, vcc, v80, v83
	s_nop 1
	v_subb_co_u32_e32 v81, vcc, v81, v83, vcc
	v_lshl_add_u64 v[82:83], v[96:97], 3, s[0:1]
	global_atomic_add_x2 v[82:83], v[80:81], off
.LBB0_882:
	s_or_b64 exec, exec, s[54:55]
	v_or_b32_e32 v80, 48, v146
	s_waitcnt lgkmcnt(0)
	v_ashrrev_i32_e32 v81, 31, v80
	v_lshlrev_b64 v[82:83], 11, v[80:81]
	v_lshl_add_u64 v[82:83], s[22:23], 0, v[82:83]
	v_lshl_add_u64 v[90:91], v[144:145], 1, v[82:83]
	s_nop 0
	s_nop 0
	s_waitcnt vmcnt(16)
	v_lshlrev_b32_e32 v92, 16, v216
	v_and_b32_e32 v93, 0xffff0000, v216
	v_lshlrev_b32_e32 v82, 16, v217
	v_and_b32_e32 v83, 0xffff0000, v217
	s_waitcnt vmcnt(15)
	v_lshlrev_b32_e32 v96, 16, v220
	v_and_b32_e32 v97, 0xffff0000, v220
	v_lshlrev_b32_e32 v86, 16, v221
	v_and_b32_e32 v87, 0xffff0000, v221
	v_lshlrev_b32_e32 v94, 16, v218
	v_and_b32_e32 v95, 0xffff0000, v218
	v_lshlrev_b32_e32 v84, 16, v219
	v_and_b32_e32 v85, 0xffff0000, v219
	v_lshlrev_b32_e32 v98, 16, v222
	v_and_b32_e32 v99, 0xffff0000, v222
	v_lshlrev_b32_e32 v88, 16, v223
	v_and_b32_e32 v89, 0xffff0000, v223
	global_load_dwordx4 v[216:219], v[198:199], off
	global_load_dwordx4 v[220:223], v[198:199], off offset:256
	v_pk_add_f32 v[78:79], v[78:79], v[82:83]
	v_pk_add_f32 v[76:77], v[76:77], v[92:93]
	v_pk_add_f32 v[70:71], v[70:71], v[86:87]
	v_pk_add_f32 v[68:69], v[68:69], v[96:97]
	v_pk_add_f32 v[74:75], v[74:75], v[84:85]
	v_pk_add_f32 v[72:73], v[72:73], v[94:95]
	v_pk_add_f32 v[82:83], v[66:67], v[88:89]
	v_pk_add_f32 v[84:85], v[64:65], v[98:99]
	v_mul_f32_e32 v66, v77, v77
	v_mul_f32_e32 v67, v79, v79
	v_mul_f32_e32 v86, v69, v69
	v_mul_f32_e32 v87, v71, v71
	v_cvt_pk_bf16_f32 v64, v76, v77
	v_mul_f32_e32 v77, v73, v73
	v_mul_f32_e32 v88, v85, v85
	v_fmac_f32_e32 v66, v76, v76
	v_fmac_f32_e32 v67, v78, v78
	v_fmac_f32_e32 v86, v68, v68
	v_fmac_f32_e32 v87, v70, v70
	v_cvt_pk_bf16_f32 v65, v78, v79
	v_mul_f32_e32 v79, v75, v75
	v_mul_f32_e32 v89, v83, v83
	v_fmac_f32_e32 v77, v72, v72
	v_fmac_f32_e32 v88, v84, v84
	v_add_f32_e32 v66, v66, v67
	v_add_f32_e32 v67, v86, v87
	v_fmac_f32_e32 v79, v74, v74
	v_fmac_f32_e32 v89, v82, v82
	v_add_f32_e32 v66, v77, v66
	v_add_f32_e32 v67, v88, v67
	v_add_f32_e32 v66, v79, v66
	v_add_f32_e32 v67, v89, v67
	v_add_f32_e32 v76, v66, v67
	ds_bpermute_b32 v77, v156, v76
	v_cvt_pk_bf16_f32 v66, v72, v73
	v_cvt_pk_bf16_f32 v67, v74, v75
	global_store_dwordx4 v[90:91], v[64:67], off
	s_waitcnt lgkmcnt(0)
	s_nop 0
	v_add_f32_e32 v64, v76, v77
	ds_bpermute_b32 v65, v155, v64
	v_cvt_pk_bf16_f32 v66, v68, v69
	v_cvt_pk_bf16_f32 v67, v70, v71
	v_cvt_pk_bf16_f32 v68, v84, v85
	v_cvt_pk_bf16_f32 v69, v82, v83
	global_store_dwordx4 v[90:91], v[66:69], off offset:256
	s_and_saveexec_b64 s[54:55], s[8:9]
	s_cbranch_execz .LBB0_884
	s_waitcnt lgkmcnt(0)
	v_add_f32_e32 v64, v64, v65
	v_mul_f32_e32 v64, 0x4f800000, v64
	v_trunc_f32_e32 v64, v64
	v_mul_f32_e64 v65, |v64|, s82
	v_floor_f32_e32 v65, v65
	v_fma_f32 v66, v65, s83, |v64|
	v_cvt_u32_f32_e32 v66, v66
	v_cvt_u32_f32_e32 v65, v65
	v_ashrrev_i32_e32 v67, 31, v64
	v_xor_b32_e32 v64, v66, v67
	v_xor_b32_e32 v65, v65, v67
	v_sub_co_u32_e32 v64, vcc, v64, v67
	s_nop 1
	v_subb_co_u32_e32 v65, vcc, v65, v67, vcc
	v_lshl_add_u64 v[66:67], v[80:81], 3, s[0:1]
	global_atomic_add_x2 v[66:67], v[64:65], off
; __device__ __forceinline__ void fx_add(float* p, size_t idx, float s) { atomicAdd((unsigned long long*)p + idx, (unsigned long long)(long long)(s * 4294967296.0f)); }
; __device__ __forceinline__ unsigned cvtpk(float lo, float hi) { f32x2v_ v = {lo, hi}; bf16x2v_ b = __builtin_convertvector(v, bf16x2v_); return __builtin_bit_cast(unsigned, b); }
;     __device__ __forceinline__ void operator()(const f32x4 (&acc)[2][2][4][2], const Unit& u, int wr, int wc, int fr, int fq) const {
;     ...
;             for (int m = 0; m < 4; ++m) { const int row = row0 + ai * HALF + m * 16; const size_t off = (size_t)row * 1024 + col0; float s = 0.f;
; #pragma unroll
;                 for (int bj = 0; bj < 2; ++bj) { f32x4 a0, a1;
;                     if (xin32) { const float* p = xin32 + off + bj * HALF; a0 = *(const f32x4*)p; a1 = *(const f32x4*)(p + 4); }
;                     else { const u32x4 w = *(const u32x4*)(xb + off + bj * HALF);
;                         a0 = (f32x4){__uint_as_float(w.x << 16), __uint_as_float(w.x & 0xffff0000u), __uint_as_float(w.y << 16), __uint_as_float(w.y & 0xffff0000u)};
;                         a1 = (f32x4){__uint_as_float(w.z << 16), __uint_as_float(w.z & 0xffff0000u), __uint_as_float(w.w << 16), __uint_as_float(w.w & 0xffff0000u)}; }
;                     const f32x4 v0 = a0 + acc[ai][bj][m][0] * alpha, v1 = a1 + acc[ai][bj][m][1] * alpha;
;                     u32x4 w; w.x = cvtpk(v0[0], v0[1]); w.y = cvtpk(v0[2], v0[3]); w.z = cvtpk(v1[0], v1[1]); w.w = cvtpk(v1[2], v1[3]);
;                     *(u32x4*)(xb + off + bj * HALF) = w;
;                     s += (v0[0] * v0[0] + v0[1] * v0[1]) + (v0[2] * v0[2] + v0[3] * v0[3]) + (v1[0] * v1[0] + v1[1] * v1[1]) + (v1[2] * v1[2] + v1[3] * v1[3]); }
;                 s += __shfl_xor(s, 16); s += __shfl_xor(s, 32);
;                 if (fq == 0) fx_add(ssout, row, s); }
.LBB0_884:
	s_or_b64 exec, exec, s[54:55]
	v_add_u32_e32 v64, 0x80, v146
	s_waitcnt lgkmcnt(0)
	v_ashrrev_i32_e32 v65, 31, v64
	v_lshlrev_b64 v[66:67], 11, v[64:65]
	v_lshl_add_u64 v[66:67], s[22:23], 0, v[66:67]
	v_lshl_add_u64 v[74:75], v[144:145], 1, v[66:67]
	s_nop 0
	s_nop 0
	s_waitcnt vmcnt(19)
	v_lshlrev_b32_e32 v76, 16, v182
	v_and_b32_e32 v77, 0xffff0000, v182
	v_lshlrev_b32_e32 v66, 16, v183
	v_and_b32_e32 v67, 0xffff0000, v183
	s_waitcnt vmcnt(18)
	v_lshlrev_b32_e32 v80, 16, v186
	v_and_b32_e32 v81, 0xffff0000, v186
	v_lshlrev_b32_e32 v70, 16, v187
	v_and_b32_e32 v71, 0xffff0000, v187
	v_lshlrev_b32_e32 v78, 16, v184
	v_and_b32_e32 v79, 0xffff0000, v184
	v_lshlrev_b32_e32 v68, 16, v185
	v_and_b32_e32 v69, 0xffff0000, v185
	v_lshlrev_b32_e32 v82, 16, v188
	v_and_b32_e32 v83, 0xffff0000, v188
	v_lshlrev_b32_e32 v72, 16, v189
	v_and_b32_e32 v73, 0xffff0000, v189
	v_pk_add_f32 v[62:63], v[62:63], v[66:67]
	v_pk_add_f32 v[60:61], v[60:61], v[76:77]
	v_pk_add_f32 v[54:55], v[54:55], v[70:71]
	v_pk_add_f32 v[52:53], v[52:53], v[80:81]
	v_pk_add_f32 v[58:59], v[58:59], v[68:69]
	v_pk_add_f32 v[56:57], v[56:57], v[78:79]
	v_pk_add_f32 v[66:67], v[50:51], v[72:73]
	v_pk_add_f32 v[68:69], v[48:49], v[82:83]
	v_mul_f32_e32 v50, v61, v61
	v_mul_f32_e32 v51, v63, v63
	v_mul_f32_e32 v70, v53, v53
	v_mul_f32_e32 v71, v55, v55
	v_cvt_pk_bf16_f32 v48, v60, v61
	v_mul_f32_e32 v61, v57, v57
	v_mul_f32_e32 v72, v69, v69
	v_fmac_f32_e32 v50, v60, v60
	v_fmac_f32_e32 v51, v62, v62
	v_fmac_f32_e32 v70, v52, v52
	v_fmac_f32_e32 v71, v54, v54
	v_cvt_pk_bf16_f32 v49, v62, v63
	v_mul_f32_e32 v63, v59, v59
	v_mul_f32_e32 v73, v67, v67
	v_fmac_f32_e32 v61, v56, v56
	v_fmac_f32_e32 v72, v68, v68
	v_add_f32_e32 v50, v50, v51
	v_add_f32_e32 v51, v70, v71
	v_fmac_f32_e32 v63, v58, v58
	v_fmac_f32_e32 v73, v66, v66
	v_add_f32_e32 v50, v61, v50
	v_add_f32_e32 v51, v72, v51
	v_add_f32_e32 v50, v63, v50
	v_add_f32_e32 v51, v73, v51
	v_add_f32_e32 v60, v50, v51
	ds_bpermute_b32 v61, v156, v60
	v_cvt_pk_bf16_f32 v50, v56, v57
	v_cvt_pk_bf16_f32 v51, v58, v59
	global_store_dwordx4 v[74:75], v[48:51], off
	s_waitcnt lgkmcnt(0)
	s_nop 0
	v_add_f32_e32 v48, v60, v61
	ds_bpermute_b32 v49, v155, v48
	v_cvt_pk_bf16_f32 v50, v52, v53
	v_cvt_pk_bf16_f32 v51, v54, v55
	v_cvt_pk_bf16_f32 v52, v68, v69
	v_cvt_pk_bf16_f32 v53, v66, v67
	global_store_dwordx4 v[74:75], v[50:53], off offset:256
	s_and_saveexec_b64 s[54:55], s[8:9]
	s_cbranch_execz .LBB0_886
	s_waitcnt lgkmcnt(0)
	v_add_f32_e32 v48, v48, v49
	v_mul_f32_e32 v48, 0x4f800000, v48
	v_trunc_f32_e32 v48, v48
	v_mul_f32_e64 v49, |v48|, s82
	v_floor_f32_e32 v49, v49
	v_fma_f32 v50, v49, s83, |v48|
	v_cvt_u32_f32_e32 v50, v50
	v_cvt_u32_f32_e32 v49, v49
	v_ashrrev_i32_e32 v51, 31, v48
	v_xor_b32_e32 v48, v50, v51
	v_xor_b32_e32 v49, v49, v51
	v_sub_co_u32_e32 v48, vcc, v48, v51
	s_nop 1
	v_subb_co_u32_e32 v49, vcc, v49, v51, vcc
	v_lshl_add_u64 v[50:51], v[64:65], 3, s[0:1]
	global_atomic_add_x2 v[50:51], v[48:49], off
.LBB0_886:
	s_or_b64 exec, exec, s[54:55]
	v_add_u32_e32 v48, 0x90, v146
	s_waitcnt lgkmcnt(0)
	v_ashrrev_i32_e32 v49, 31, v48
	v_lshlrev_b64 v[50:51], 11, v[48:49]
	v_lshl_add_u64 v[50:51], s[22:23], 0, v[50:51]
	v_lshl_add_u64 v[58:59], v[144:145], 1, v[50:51]
	s_nop 0
	s_nop 0
	s_waitcnt vmcnt(17)
	v_lshlrev_b32_e32 v60, 16, v190
	v_and_b32_e32 v61, 0xffff0000, v190
	v_lshlrev_b32_e32 v50, 16, v191
	v_and_b32_e32 v51, 0xffff0000, v191
	s_waitcnt vmcnt(16)
	v_lshlrev_b32_e32 v64, 16, v194
	v_and_b32_e32 v65, 0xffff0000, v194
	v_lshlrev_b32_e32 v54, 16, v195
	v_and_b32_e32 v55, 0xffff0000, v195
	v_lshlrev_b32_e32 v62, 16, v192
	v_and_b32_e32 v63, 0xffff0000, v192
	v_lshlrev_b32_e32 v52, 16, v193
	v_and_b32_e32 v53, 0xffff0000, v193
	v_lshlrev_b32_e32 v66, 16, v196
	v_and_b32_e32 v67, 0xffff0000, v196
	v_lshlrev_b32_e32 v56, 16, v197
	v_and_b32_e32 v57, 0xffff0000, v197
	v_pk_add_f32 v[46:47], v[46:47], v[50:51]
	v_pk_add_f32 v[44:45], v[44:45], v[60:61]
	v_pk_add_f32 v[38:39], v[38:39], v[54:55]
	v_pk_add_f32 v[36:37], v[36:37], v[64:65]
	v_pk_add_f32 v[42:43], v[42:43], v[52:53]
	v_pk_add_f32 v[40:41], v[40:41], v[62:63]
	v_pk_add_f32 v[50:51], v[34:35], v[56:57]
	v_pk_add_f32 v[52:53], v[32:33], v[66:67]
	v_mul_f32_e32 v34, v45, v45
	v_mul_f32_e32 v35, v47, v47
	v_mul_f32_e32 v54, v37, v37
	v_mul_f32_e32 v55, v39, v39
	v_cvt_pk_bf16_f32 v32, v44, v45
	v_mul_f32_e32 v45, v41, v41
	v_mul_f32_e32 v56, v53, v53
	v_fmac_f32_e32 v34, v44, v44
	v_fmac_f32_e32 v35, v46, v46
	v_fmac_f32_e32 v54, v36, v36
	v_fmac_f32_e32 v55, v38, v38
	v_cvt_pk_bf16_f32 v33, v46, v47
	v_mul_f32_e32 v47, v43, v43
	v_mul_f32_e32 v57, v51, v51
	v_fmac_f32_e32 v45, v40, v40
	v_fmac_f32_e32 v56, v52, v52
	v_add_f32_e32 v34, v34, v35
	v_add_f32_e32 v35, v54, v55
	v_fmac_f32_e32 v47, v42, v42
	v_fmac_f32_e32 v57, v50, v50
	v_add_f32_e32 v34, v45, v34
	v_add_f32_e32 v35, v56, v35
	v_add_f32_e32 v34, v47, v34
	v_add_f32_e32 v35, v57, v35
	v_add_f32_e32 v44, v34, v35
	ds_bpermute_b32 v45, v156, v44
	v_cvt_pk_bf16_f32 v34, v40, v41
	v_cvt_pk_bf16_f32 v35, v42, v43
	global_store_dwordx4 v[58:59], v[32:35], off
	s_waitcnt lgkmcnt(0)
	s_nop 0
	v_add_f32_e32 v32, v44, v45
	ds_bpermute_b32 v33, v155, v32
	v_cvt_pk_bf16_f32 v34, v36, v37
	v_cvt_pk_bf16_f32 v35, v38, v39
	v_cvt_pk_bf16_f32 v36, v52, v53
	v_cvt_pk_bf16_f32 v37, v50, v51
	global_store_dwordx4 v[58:59], v[34:37], off offset:256
	s_and_saveexec_b64 s[54:55], s[8:9]
	s_cbranch_execz .LBB0_888
	s_waitcnt lgkmcnt(0)
	v_add_f32_e32 v32, v32, v33
	v_mul_f32_e32 v32, 0x4f800000, v32
	v_trunc_f32_e32 v32, v32
	v_mul_f32_e64 v33, |v32|, s82
	v_floor_f32_e32 v33, v33
	v_fma_f32 v34, v33, s83, |v32|
	v_cvt_u32_f32_e32 v34, v34
	v_cvt_u32_f32_e32 v33, v33
	v_ashrrev_i32_e32 v35, 31, v32
	v_xor_b32_e32 v32, v34, v35
	v_xor_b32_e32 v33, v33, v35
	v_sub_co_u32_e32 v32, vcc, v32, v35
	s_nop 1
	v_subb_co_u32_e32 v33, vcc, v33, v35, vcc
	v_lshl_add_u64 v[34:35], v[48:49], 3, s[0:1]
	global_atomic_add_x2 v[34:35], v[32:33], off
; __device__ __forceinline__ void fx_add(float* p, size_t idx, float s) { atomicAdd((unsigned long long*)p + idx, (unsigned long long)(long long)(s * 4294967296.0f)); }
; __device__ __forceinline__ unsigned cvtpk(float lo, float hi) { f32x2v_ v = {lo, hi}; bf16x2v_ b = __builtin_convertvector(v, bf16x2v_); return __builtin_bit_cast(unsigned, b); }
;     __device__ __forceinline__ void operator()(const f32x4 (&acc)[2][2][4][2], const Unit& u, int wr, int wc, int fr, int fq) const {
;     ...
;             for (int m = 0; m < 4; ++m) { const int row = row0 + ai * HALF + m * 16; const size_t off = (size_t)row * 1024 + col0; float s = 0.f;
; #pragma unroll
;                 for (int bj = 0; bj < 2; ++bj) { f32x4 a0, a1;
;                     if (xin32) { const float* p = xin32 + off + bj * HALF; a0 = *(const f32x4*)p; a1 = *(const f32x4*)(p + 4); }
;                     else { const u32x4 w = *(const u32x4*)(xb + off + bj * HALF);
;                         a0 = (f32x4){__uint_as_float(w.x << 16), __uint_as_float(w.x & 0xffff0000u), __uint_as_float(w.y << 16), __uint_as_float(w.y & 0xffff0000u)};
;                         a1 = (f32x4){__uint_as_float(w.z << 16), __uint_as_float(w.z & 0xffff0000u), __uint_as_float(w.w << 16), __uint_as_float(w.w & 0xffff0000u)}; }
;                     const f32x4 v0 = a0 + acc[ai][bj][m][0] * alpha, v1 = a1 + acc[ai][bj][m][1] * alpha;
;                     u32x4 w; w.x = cvtpk(v0[0], v0[1]); w.y = cvtpk(v0[2], v0[3]); w.z = cvtpk(v1[0], v1[1]); w.w = cvtpk(v1[2], v1[3]);
;                     *(u32x4*)(xb + off + bj * HALF) = w;
;                     s += (v0[0] * v0[0] + v0[1] * v0[1]) + (v0[2] * v0[2] + v0[3] * v0[3]) + (v1[0] * v1[0] + v1[1] * v1[1]) + (v1[2] * v1[2] + v1[3] * v1[3]); }
;                 s += __shfl_xor(s, 16); s += __shfl_xor(s, 32);
;                 if (fq == 0) fx_add(ssout, row, s); }
.LBB0_888:
	s_or_b64 exec, exec, s[54:55]
	v_add_u32_e32 v32, 0xa0, v146
	s_waitcnt lgkmcnt(0)
	v_ashrrev_i32_e32 v33, 31, v32
	v_lshlrev_b64 v[34:35], 11, v[32:33]
	v_lshl_add_u64 v[34:35], s[22:23], 0, v[34:35]
	v_lshl_add_u64 v[42:43], v[144:145], 1, v[34:35]
	s_nop 0
	s_nop 0
	s_waitcnt vmcnt(15)
	v_lshlrev_b32_e32 v44, 16, v208
	v_and_b32_e32 v45, 0xffff0000, v208
	v_lshlrev_b32_e32 v34, 16, v209
	v_and_b32_e32 v35, 0xffff0000, v209
	s_waitcnt vmcnt(14)
	v_lshlrev_b32_e32 v48, 16, v212
	v_and_b32_e32 v49, 0xffff0000, v212
	v_lshlrev_b32_e32 v38, 16, v213
	v_and_b32_e32 v39, 0xffff0000, v213
	v_lshlrev_b32_e32 v46, 16, v210
	v_and_b32_e32 v47, 0xffff0000, v210
	v_lshlrev_b32_e32 v36, 16, v211
	v_and_b32_e32 v37, 0xffff0000, v211
	v_lshlrev_b32_e32 v50, 16, v214
	v_and_b32_e32 v51, 0xffff0000, v214
	v_lshlrev_b32_e32 v40, 16, v215
	v_and_b32_e32 v41, 0xffff0000, v215
	v_pk_add_f32 v[30:31], v[30:31], v[34:35]
	v_pk_add_f32 v[28:29], v[28:29], v[44:45]
	v_pk_add_f32 v[22:23], v[22:23], v[38:39]
	v_pk_add_f32 v[20:21], v[20:21], v[48:49]
	v_pk_add_f32 v[26:27], v[26:27], v[36:37]
	v_pk_add_f32 v[24:25], v[24:25], v[46:47]
	v_pk_add_f32 v[34:35], v[18:19], v[40:41]
	v_pk_add_f32 v[36:37], v[16:17], v[50:51]
	v_mul_f32_e32 v18, v29, v29
	v_mul_f32_e32 v19, v31, v31
	v_mul_f32_e32 v38, v21, v21
	v_mul_f32_e32 v39, v23, v23
	v_cvt_pk_bf16_f32 v16, v28, v29
	v_mul_f32_e32 v29, v25, v25
	v_mul_f32_e32 v40, v37, v37
	v_fmac_f32_e32 v18, v28, v28
	v_fmac_f32_e32 v19, v30, v30
	v_fmac_f32_e32 v38, v20, v20
	v_fmac_f32_e32 v39, v22, v22
	v_cvt_pk_bf16_f32 v17, v30, v31
	v_mul_f32_e32 v31, v27, v27
	v_mul_f32_e32 v41, v35, v35
	v_fmac_f32_e32 v29, v24, v24
	v_fmac_f32_e32 v40, v36, v36
	v_add_f32_e32 v18, v18, v19
	v_add_f32_e32 v19, v38, v39
	v_fmac_f32_e32 v31, v26, v26
	v_fmac_f32_e32 v41, v34, v34
	v_add_f32_e32 v18, v29, v18
	v_add_f32_e32 v19, v40, v19
	v_add_f32_e32 v18, v31, v18
	v_add_f32_e32 v19, v41, v19
	v_add_f32_e32 v28, v18, v19
	ds_bpermute_b32 v29, v156, v28
	v_cvt_pk_bf16_f32 v18, v24, v25
	v_cvt_pk_bf16_f32 v19, v26, v27
	global_store_dwordx4 v[42:43], v[16:19], off
	s_waitcnt lgkmcnt(0)
	s_nop 0
	v_add_f32_e32 v16, v28, v29
	ds_bpermute_b32 v17, v155, v16
	v_cvt_pk_bf16_f32 v18, v20, v21
	v_cvt_pk_bf16_f32 v19, v22, v23
	v_cvt_pk_bf16_f32 v20, v36, v37
	v_cvt_pk_bf16_f32 v21, v34, v35
	global_store_dwordx4 v[42:43], v[18:21], off offset:256
	s_and_saveexec_b64 s[54:55], s[8:9]
	s_cbranch_execz .LBB0_890
	s_waitcnt lgkmcnt(0)
	v_add_f32_e32 v16, v16, v17
	v_mul_f32_e32 v16, 0x4f800000, v16
	v_trunc_f32_e32 v16, v16
	v_mul_f32_e64 v17, |v16|, s82
	v_floor_f32_e32 v17, v17
	v_fma_f32 v18, v17, s83, |v16|
	v_cvt_u32_f32_e32 v18, v18
	v_cvt_u32_f32_e32 v17, v17
	v_ashrrev_i32_e32 v19, 31, v16
	v_xor_b32_e32 v16, v18, v19
	v_xor_b32_e32 v17, v17, v19
	v_sub_co_u32_e32 v16, vcc, v16, v19
	s_nop 1
	v_subb_co_u32_e32 v17, vcc, v17, v19, vcc
	v_lshl_add_u64 v[18:19], v[32:33], 3, s[0:1]
	global_atomic_add_x2 v[18:19], v[16:17], off
.LBB0_890:
	s_or_b64 exec, exec, s[54:55]
	v_add_u32_e32 v16, 0xb0, v146
	s_waitcnt lgkmcnt(0)
	v_ashrrev_i32_e32 v17, 31, v16
	v_lshlrev_b64 v[18:19], 11, v[16:17]
	v_lshl_add_u64 v[18:19], s[22:23], 0, v[18:19]
	v_lshl_add_u64 v[26:27], v[144:145], 1, v[18:19]
	s_nop 0
	s_nop 0
	s_waitcnt vmcnt(13)
	v_lshlrev_b32_e32 v28, 16, v216
	v_and_b32_e32 v29, 0xffff0000, v216
	v_lshlrev_b32_e32 v18, 16, v217
	v_and_b32_e32 v19, 0xffff0000, v217
	s_waitcnt vmcnt(12)
	v_lshlrev_b32_e32 v32, 16, v220
	v_and_b32_e32 v33, 0xffff0000, v220
	v_lshlrev_b32_e32 v22, 16, v221
	v_and_b32_e32 v23, 0xffff0000, v221
	v_lshlrev_b32_e32 v30, 16, v218
	v_and_b32_e32 v31, 0xffff0000, v218
	v_lshlrev_b32_e32 v20, 16, v219
	v_and_b32_e32 v21, 0xffff0000, v219
	v_lshlrev_b32_e32 v34, 16, v222
	v_and_b32_e32 v35, 0xffff0000, v222
	v_lshlrev_b32_e32 v24, 16, v223
	v_and_b32_e32 v25, 0xffff0000, v223
	v_pk_add_f32 v[14:15], v[14:15], v[18:19]
	v_pk_add_f32 v[12:13], v[12:13], v[28:29]
	v_pk_add_f32 v[6:7], v[6:7], v[22:23]
	v_pk_add_f32 v[4:5], v[4:5], v[32:33]
	v_pk_add_f32 v[10:11], v[10:11], v[20:21]
	v_pk_add_f32 v[8:9], v[8:9], v[30:31]
	v_pk_add_f32 v[18:19], v[2:3], v[24:25]
	v_pk_add_f32 v[20:21], v[0:1], v[34:35]
	v_mul_f32_e32 v2, v13, v13
	v_mul_f32_e32 v3, v15, v15
	v_mul_f32_e32 v22, v5, v5
	v_mul_f32_e32 v23, v7, v7
	v_cvt_pk_bf16_f32 v0, v12, v13
	v_mul_f32_e32 v13, v9, v9
	v_mul_f32_e32 v24, v21, v21
	v_fmac_f32_e32 v2, v12, v12
	v_fmac_f32_e32 v3, v14, v14
	v_fmac_f32_e32 v22, v4, v4
	v_fmac_f32_e32 v23, v6, v6
	v_cvt_pk_bf16_f32 v1, v14, v15
	v_mul_f32_e32 v15, v11, v11
	v_mul_f32_e32 v25, v19, v19
	v_fmac_f32_e32 v13, v8, v8
	v_fmac_f32_e32 v24, v20, v20
	v_add_f32_e32 v2, v2, v3
	v_add_f32_e32 v3, v22, v23
	v_fmac_f32_e32 v15, v10, v10
	v_fmac_f32_e32 v25, v18, v18
	v_add_f32_e32 v2, v13, v2
	v_add_f32_e32 v3, v24, v3
	v_add_f32_e32 v2, v15, v2
	v_add_f32_e32 v3, v25, v3
	v_add_f32_e32 v12, v2, v3
	ds_bpermute_b32 v13, v156, v12
	v_cvt_pk_bf16_f32 v2, v8, v9
	v_cvt_pk_bf16_f32 v3, v10, v11
	global_store_dwordx4 v[26:27], v[0:3], off
	s_waitcnt lgkmcnt(0)
	s_nop 0
	v_add_f32_e32 v0, v12, v13
	ds_bpermute_b32 v1, v155, v0
	v_cvt_pk_bf16_f32 v2, v4, v5
	v_cvt_pk_bf16_f32 v3, v6, v7
	v_cvt_pk_bf16_f32 v4, v20, v21
	v_cvt_pk_bf16_f32 v5, v18, v19
	global_store_dwordx4 v[26:27], v[2:5], off offset:256
	s_and_saveexec_b64 s[54:55], s[8:9]
	s_cbranch_execz .LBB0_892
	s_waitcnt lgkmcnt(0)
	v_add_f32_e32 v0, v0, v1
	v_mul_f32_e32 v0, 0x4f800000, v0
	v_trunc_f32_e32 v0, v0
	v_mul_f32_e64 v1, |v0|, s82
	v_floor_f32_e32 v1, v1
	v_fma_f32 v2, v1, s83, |v0|
	v_cvt_u32_f32_e32 v2, v2
	v_cvt_u32_f32_e32 v1, v1
	v_ashrrev_i32_e32 v3, 31, v0
	v_xor_b32_e32 v0, v2, v3
	v_xor_b32_e32 v1, v1, v3
	v_sub_co_u32_e32 v0, vcc, v0, v3
	s_nop 1
	v_subb_co_u32_e32 v1, vcc, v1, v3, vcc
	v_lshl_add_u64 v[2:3], v[16:17], 3, s[0:1]
	global_atomic_add_x2 v[2:3], v[0:1], off

; #define PG8_STAGE(bufoff, gbase, voff) do { _Pragma("unroll") for (int _i = 0; _i < 2; ++_i) \
;         __builtin_amdgcn_global_load_lds((const unsigned*)((const char*)(gbase) + (voff)[_i]), (PG8_LAS unsigned*)(lds + (bufoff) + ldsw + _i * 8192), 16, 0, 0); } while (0)
; #define PG8_LDA(dst, b, h) do { _Pragma("unroll") for (int m = 0; m < 4; ++m) _Pragma("unroll") for (int k = 0; k < 2; ++k) dst[m][k] = *(const PG8_LAS bf16x8*)(lds + PG8_SA(b, h) + aoff + m * 2048 + k * 1024); } while (0)
; #define PG8_LDB(dst, b, h) do { _Pragma("unroll") for (int n = 0; n < 2; ++n) _Pragma("unroll") for (int k = 0; k < 2; ++k) dst[n][k] = *(const PG8_LAS bf16x8*)(lds + PG8_SB(b, h) + boff + n * 2048 + k * 1024); } while (0)
; #define PG8_MMA(ai, bj, At, Bt) do { __builtin_amdgcn_s_setprio(1); _Pragma("unroll") for (int m = 0; m < 4; ++m) _Pragma("unroll") for (int n = 0; n < 2; ++n) _Pragma("unroll") for (int k = 0; k < 2; ++k) \
;         acc[ai][bj][m][n] = __builtin_amdgcn_mfma_f32_16x16x32_bf16(Bt[n][k], At[m][k], acc[ai][bj][m][n], 0, 0, 0); __builtin_amdgcn_s_setprio(0); } while (0)
; #define PG8_WAIT_V(n) asm volatile("s_waitcnt vmcnt(" #n ")" ::: "memory")
; #define PG8_WAIT_L(n) asm volatile("s_waitcnt lgkmcnt(" #n ")" ::: "memory")
; #define PG8_BAR __builtin_amdgcn_s_barrier()
; #define PG8_SCHED __builtin_amdgcn_sched_barrier(0)
; template <class Epi, class Sched, bool ALIGN_EPI = false, bool SP2 = false>
; __device__ __forceinline__ void gemm_phase(PG8_LAS unsigned char* lds, const Gemm g, const Sched& S, const Epi& E) {
;     ...
;             if constexpr (SP2) {
;             PG8_LDB(B0, 0, 0); PG8_LDB(B1, 0, 1); PG8_SCHED; PG8_LDA(At, 0, 0); PG8_STAGE(PG8_SA(1, 1), a1 + hstep, voffA);
;             PG8_WAIT_V(8); PG8_WAIT_L(0); PG8_BAR; PG8_MMA(0, 0, At, B0); PG8_MMA(0, 1, At, B1); PG8_BAR; PG8_SCHED;
;             PG8_LDA(At, 0, 1); PG8_STAGE(PG8_SB(0, 0), b2, voffB); PG8_STAGE(PG8_SB(0, 1), b2 + hstep, voffB); PG8_STAGE(PG8_SA(0, 0), a2, voffA);
.LBB0_1035:
	ds_read_b128 v[144:147], v151
	ds_read_b128 v[156:159], v151 offset:1024
	ds_read_b128 v[160:163], v151 offset:2048
	ds_read_b128 v[164:167], v151 offset:3072
	ds_read_b128 v[168:171], v152
	ds_read_b128 v[172:175], v152 offset:1024
	ds_read_b128 v[176:179], v152 offset:2048
	ds_read_b128 v[182:185], v152 offset:3072
	s_add_u32 s52, s50, 0x100
	s_addc_u32 s53, s51, 0
	s_cmp_eq_u32 s77, 40
	s_cselect_b32 s57, s1, s53
	s_cselect_b32 s56, s0, s52
	s_cselect_b32 s55, s49, s76
	s_cselect_b32 s54, s48, s75
	v_lshl_add_u64 v[202:203], s[50:51], 0, v[136:137]
	s_add_i32 m0, s14, 0xc000
	ds_read_b128 v[186:189], v153
	ds_read_b128 v[190:193], v153 offset:1024
	ds_read_b128 v[194:197], v153 offset:2048
	ds_read_b128 v[198:201], v153 offset:3072
	ds_read_b128 v[208:211], v153 offset:4096
	ds_read_b128 v[212:215], v153 offset:5120
	ds_read_b128 v[216:219], v153 offset:6144
	ds_read_b128 v[220:223], v153 offset:7168
	global_load_lds_dwordx4 v[202:203], off
	v_lshl_add_u64 v[202:203], s[50:51], 0, v[138:139]
	s_add_i32 m0, s14, 0xe000
	s_nop 0
	global_load_lds_dwordx4 v[202:203], off
	s_waitcnt vmcnt(8)
	s_waitcnt lgkmcnt(0)
	s_barrier
	s_setprio 1
	s_waitcnt lgkmcnt(0)
	v_mfma_f32_16x16x32_bf16 v[124:127], v[144:147], v[186:189], v[124:127]
	v_mfma_f32_16x16x32_bf16 v[120:123], v[160:163], v[186:189], v[120:123]
	v_mfma_f32_16x16x32_bf16 v[108:111], v[144:147], v[194:197], v[108:111]
	v_mfma_f32_16x16x32_bf16 v[104:107], v[160:163], v[194:197], v[104:107]
	v_mfma_f32_16x16x32_bf16 v[92:95], v[144:147], v[208:211], v[92:95]
	v_mfma_f32_16x16x32_bf16 v[88:91], v[160:163], v[208:211], v[88:91]
	v_mfma_f32_16x16x32_bf16 v[76:79], v[144:147], v[216:219], v[76:79]
	v_mfma_f32_16x16x32_bf16 v[72:75], v[160:163], v[216:219], v[72:75]
	v_mfma_f32_16x16x32_bf16 v[124:127], v[156:159], v[190:193], v[124:127]
	v_mfma_f32_16x16x32_bf16 v[120:123], v[164:167], v[190:193], v[120:123]
	v_mfma_f32_16x16x32_bf16 v[108:111], v[156:159], v[198:201], v[108:111]
	v_mfma_f32_16x16x32_bf16 v[104:107], v[164:167], v[198:201], v[104:107]
	v_mfma_f32_16x16x32_bf16 v[92:95], v[156:159], v[212:215], v[92:95]
	v_mfma_f32_16x16x32_bf16 v[88:91], v[164:167], v[212:215], v[88:91]
	v_mfma_f32_16x16x32_bf16 v[76:79], v[156:159], v[220:223], v[76:79]
	v_mfma_f32_16x16x32_bf16 v[72:75], v[164:167], v[220:223], v[72:75]
	s_setprio 0
	s_setprio 1
	v_mfma_f32_16x16x32_bf16 v[116:119], v[168:171], v[186:189], v[116:119]
	v_mfma_f32_16x16x32_bf16 v[112:115], v[176:179], v[186:189], v[112:115]
	v_mfma_f32_16x16x32_bf16 v[100:103], v[168:171], v[194:197], v[100:103]
	v_mfma_f32_16x16x32_bf16 v[96:99], v[176:179], v[194:197], v[96:99]
	v_mfma_f32_16x16x32_bf16 v[84:87], v[168:171], v[208:211], v[84:87]
	v_mfma_f32_16x16x32_bf16 v[80:83], v[176:179], v[208:211], v[80:83]
	v_mfma_f32_16x16x32_bf16 v[68:71], v[168:171], v[216:219], v[68:71]
	v_mfma_f32_16x16x32_bf16 v[64:67], v[176:179], v[216:219], v[64:67]
	v_mfma_f32_16x16x32_bf16 v[116:119], v[172:175], v[190:193], v[116:119]
	v_mfma_f32_16x16x32_bf16 v[112:115], v[182:185], v[190:193], v[112:115]
	v_mfma_f32_16x16x32_bf16 v[100:103], v[172:175], v[198:201], v[100:103]
	v_mfma_f32_16x16x32_bf16 v[96:99], v[182:185], v[198:201], v[96:99]
	v_mfma_f32_16x16x32_bf16 v[84:87], v[172:175], v[212:215], v[84:87]
	v_mfma_f32_16x16x32_bf16 v[80:83], v[182:185], v[212:215], v[80:83]
	v_mfma_f32_16x16x32_bf16 v[68:71], v[172:175], v[220:223], v[68:71]
	v_mfma_f32_16x16x32_bf16 v[64:67], v[182:185], v[220:223], v[64:67]
	s_setprio 0
	s_barrier
	s_add_i32 s50, s61, s3
	v_lshl_add_u64 v[202:203], s[54:55], 0, v[130:131]
	s_mov_b32 m0, s50
	ds_read_b128 v[186:189], v153 offset:16384
	ds_read_b128 v[190:193], v153 offset:17408
	ds_read_b128 v[194:197], v153 offset:18432
	ds_read_b128 v[198:201], v153 offset:19456
	ds_read_b128 v[208:211], v153 offset:20480
	ds_read_b128 v[212:215], v153 offset:21504
	ds_read_b128 v[216:219], v153 offset:22528
	ds_read_b128 v[220:223], v153 offset:23552
	global_load_lds_dwordx4 v[202:203], off
	s_add_i32 m0, s50, 0x2000
	s_add_u32 s50, s54, 0xb0000
	v_lshl_add_u64 v[224:225], s[54:55], 0, v[134:135]
	s_addc_u32 s51, s55, 0
	s_add_i32 s78, s62, s3
	global_load_lds_dwordx4 v[224:225], off
	v_lshl_add_u64 v[226:227], s[50:51], 0, v[130:131]
	s_mov_b32 m0, s78
	v_lshl_add_u64 v[228:229], s[56:57], 0, v[132:133]
	global_load_lds_dwordx4 v[226:227], off
	v_lshl_add_u64 v[226:227], s[50:51], 0, v[134:135]
	s_add_i32 m0, s78, 0x2000
	s_nop 0
	global_load_lds_dwordx4 v[226:227], off
	v_lshl_add_u64 v[226:227], s[56:57], 0, v[128:129]
	s_mov_b32 m0, s14
	s_nop 0
	global_load_lds_dwordx4 v[226:227], off
	s_mov_b32 m0, s15
	s_nop 0
	global_load_lds_dwordx4 v[228:229], off
	s_waitcnt vmcnt(8)
	s_waitcnt lgkmcnt(0)
	s_barrier
; #define PG8_STAGE(bufoff, gbase, voff) do { _Pragma("unroll") for (int _i = 0; _i < 2; ++_i) \
;         __builtin_amdgcn_global_load_lds((const unsigned*)((const char*)(gbase) + (voff)[_i]), (PG8_LAS unsigned*)(lds + (bufoff) + ldsw + _i * 8192), 16, 0, 0); } while (0)
; #define PG8_LDA(dst, b, h) do { _Pragma("unroll") for (int m = 0; m < 4; ++m) _Pragma("unroll") for (int k = 0; k < 2; ++k) dst[m][k] = *(const PG8_LAS bf16x8*)(lds + PG8_SA(b, h) + aoff + m * 2048 + k * 1024); } while (0)
; #define PG8_LDB(dst, b, h) do { _Pragma("unroll") for (int n = 0; n < 2; ++n) _Pragma("unroll") for (int k = 0; k < 2; ++k) dst[n][k] = *(const PG8_LAS bf16x8*)(lds + PG8_SB(b, h) + boff + n * 2048 + k * 1024); } while (0)
; #define PG8_MMA(ai, bj, At, Bt) do { __builtin_amdgcn_s_setprio(1); _Pragma("unroll") for (int m = 0; m < 4; ++m) _Pragma("unroll") for (int n = 0; n < 2; ++n) _Pragma("unroll") for (int k = 0; k < 2; ++k) \
;         acc[ai][bj][m][n] = __builtin_amdgcn_mfma_f32_16x16x32_bf16(Bt[n][k], At[m][k], acc[ai][bj][m][n], 0, 0, 0); __builtin_amdgcn_s_setprio(0); } while (0)
; #define PG8_WAIT_V(n) asm volatile("s_waitcnt vmcnt(" #n ")" ::: "memory")
; #define PG8_WAIT_L(n) asm volatile("s_waitcnt lgkmcnt(" #n ")" ::: "memory")
; #define PG8_BAR __builtin_amdgcn_s_barrier()
; #define PG8_SCHED __builtin_amdgcn_sched_barrier(0)
; template <class Epi, class Sched, bool ALIGN_EPI = false, bool SP2 = false>
; __device__ __forceinline__ void gemm_phase(PG8_LAS unsigned char* lds, const Gemm g, const Sched& S, const Epi& E) {
;     ...
;             PG8_WAIT_V(8); PG8_WAIT_L(0); PG8_BAR; PG8_MMA(1, 0, At, B0); PG8_MMA(1, 1, At, B1); PG8_BAR; PG8_SCHED;
;             PG8_LDB(B0, 1, 0); PG8_LDB(B1, 1, 1); PG8_SCHED; PG8_LDA(At, 1, 0); PG8_STAGE(PG8_SA(0, 1), a2 + hstep, voffA);
;             PG8_WAIT_V(8); PG8_WAIT_L(0); PG8_BAR; PG8_MMA(0, 0, At, B0); PG8_MMA(0, 1, At, B1); PG8_BAR; PG8_SCHED;
	s_setprio 1
	s_waitcnt lgkmcnt(0)
	v_mfma_f32_16x16x32_bf16 v[60:63], v[144:147], v[186:189], v[60:63]
	v_mfma_f32_16x16x32_bf16 v[56:59], v[160:163], v[186:189], v[56:59]
	v_mfma_f32_16x16x32_bf16 v[44:47], v[144:147], v[194:197], v[44:47]
	v_mfma_f32_16x16x32_bf16 v[40:43], v[160:163], v[194:197], v[40:43]
	v_mfma_f32_16x16x32_bf16 v[28:31], v[144:147], v[208:211], v[28:31]
	v_mfma_f32_16x16x32_bf16 v[24:27], v[160:163], v[208:211], v[24:27]
	v_mfma_f32_16x16x32_bf16 v[12:15], v[144:147], v[216:219], v[12:15]
	v_mfma_f32_16x16x32_bf16 v[8:11], v[160:163], v[216:219], v[8:11]
	v_mfma_f32_16x16x32_bf16 v[60:63], v[156:159], v[190:193], v[60:63]
	v_mfma_f32_16x16x32_bf16 v[56:59], v[164:167], v[190:193], v[56:59]
	v_mfma_f32_16x16x32_bf16 v[44:47], v[156:159], v[198:201], v[44:47]
	v_mfma_f32_16x16x32_bf16 v[40:43], v[164:167], v[198:201], v[40:43]
	v_mfma_f32_16x16x32_bf16 v[28:31], v[156:159], v[212:215], v[28:31]
	v_mfma_f32_16x16x32_bf16 v[24:27], v[164:167], v[212:215], v[24:27]
	v_mfma_f32_16x16x32_bf16 v[12:15], v[156:159], v[220:223], v[12:15]
	v_mfma_f32_16x16x32_bf16 v[8:11], v[164:167], v[220:223], v[8:11]
	s_setprio 0
	s_setprio 1
	v_mfma_f32_16x16x32_bf16 v[52:55], v[168:171], v[186:189], v[52:55]
	v_mfma_f32_16x16x32_bf16 v[48:51], v[176:179], v[186:189], v[48:51]
	v_mfma_f32_16x16x32_bf16 v[36:39], v[168:171], v[194:197], v[36:39]
	v_mfma_f32_16x16x32_bf16 v[32:35], v[176:179], v[194:197], v[32:35]
	v_mfma_f32_16x16x32_bf16 v[20:23], v[168:171], v[208:211], v[20:23]
	v_mfma_f32_16x16x32_bf16 v[16:19], v[176:179], v[208:211], v[16:19]
	v_mfma_f32_16x16x32_bf16 v[4:7], v[168:171], v[216:219], v[4:7]
	v_mfma_f32_16x16x32_bf16 v[0:3], v[176:179], v[216:219], v[0:3]
	v_mfma_f32_16x16x32_bf16 v[52:55], v[172:175], v[190:193], v[52:55]
	v_mfma_f32_16x16x32_bf16 v[48:51], v[182:185], v[190:193], v[48:51]
	v_mfma_f32_16x16x32_bf16 v[36:39], v[172:175], v[198:201], v[36:39]
	v_mfma_f32_16x16x32_bf16 v[32:35], v[182:185], v[198:201], v[32:35]
	v_mfma_f32_16x16x32_bf16 v[20:23], v[172:175], v[212:215], v[20:23]
	v_mfma_f32_16x16x32_bf16 v[16:19], v[182:185], v[212:215], v[16:19]
	v_mfma_f32_16x16x32_bf16 v[4:7], v[172:175], v[220:223], v[4:7]
	v_mfma_f32_16x16x32_bf16 v[0:3], v[182:185], v[220:223], v[0:3]
	s_setprio 0
	s_barrier
	s_add_i32 s78, 0, 0x18000
	v_add_u32_e32 v155, s78, v149
	s_add_i32 s79, 0, 0x1c000
	ds_read_b128 v[144:147], v155
	ds_read_b128 v[156:159], v155 offset:1024
	ds_read_b128 v[160:163], v155 offset:2048
	ds_read_b128 v[164:167], v155 offset:3072
	v_add_u32_e32 v155, s79, v149
	ds_read_b128 v[168:171], v155
	ds_read_b128 v[172:175], v155 offset:1024
	ds_read_b128 v[176:179], v155 offset:2048
	ds_read_b128 v[182:185], v155 offset:3072
	s_add_u32 s50, s56, 0xb0000
	s_addc_u32 s51, s57, 0
	s_mov_b32 m0, s33
	v_lshl_add_u64 v[230:231], s[50:51], 0, v[128:129]
	ds_read_b128 v[186:189], v153 offset:32768
	ds_read_b128 v[190:193], v153 offset:33792
	ds_read_b128 v[194:197], v153 offset:34816
	ds_read_b128 v[198:201], v153 offset:35840
	ds_read_b128 v[208:211], v153 offset:36864
	ds_read_b128 v[212:215], v153 offset:37888
	ds_read_b128 v[216:219], v153 offset:38912
	ds_read_b128 v[220:223], v153 offset:39936
	global_load_lds_dwordx4 v[230:231], off
	v_lshl_add_u64 v[230:231], s[50:51], 0, v[132:133]
	s_mov_b32 m0, s34
	s_nop 0
	global_load_lds_dwordx4 v[230:231], off
	s_waitcnt vmcnt(8)
	s_waitcnt lgkmcnt(0)
	s_barrier
	s_setprio 1
	s_waitcnt lgkmcnt(0)
	v_mfma_f32_16x16x32_bf16 v[124:127], v[144:147], v[186:189], v[124:127]
	v_mfma_f32_16x16x32_bf16 v[120:123], v[160:163], v[186:189], v[120:123]
	v_mfma_f32_16x16x32_bf16 v[108:111], v[144:147], v[194:197], v[108:111]
	v_mfma_f32_16x16x32_bf16 v[104:107], v[160:163], v[194:197], v[104:107]
	v_mfma_f32_16x16x32_bf16 v[92:95], v[144:147], v[208:211], v[92:95]
	v_mfma_f32_16x16x32_bf16 v[88:91], v[160:163], v[208:211], v[88:91]
	v_mfma_f32_16x16x32_bf16 v[76:79], v[144:147], v[216:219], v[76:79]
	v_mfma_f32_16x16x32_bf16 v[72:75], v[160:163], v[216:219], v[72:75]
	v_mfma_f32_16x16x32_bf16 v[124:127], v[156:159], v[190:193], v[124:127]
	v_mfma_f32_16x16x32_bf16 v[120:123], v[164:167], v[190:193], v[120:123]
	v_mfma_f32_16x16x32_bf16 v[108:111], v[156:159], v[198:201], v[108:111]
	v_mfma_f32_16x16x32_bf16 v[104:107], v[164:167], v[198:201], v[104:107]
	v_mfma_f32_16x16x32_bf16 v[92:95], v[156:159], v[212:215], v[92:95]
	v_mfma_f32_16x16x32_bf16 v[88:91], v[164:167], v[212:215], v[88:91]
	v_mfma_f32_16x16x32_bf16 v[76:79], v[156:159], v[220:223], v[76:79]
	v_mfma_f32_16x16x32_bf16 v[72:75], v[164:167], v[220:223], v[72:75]
	s_setprio 0
	s_setprio 1
	v_mfma_f32_16x16x32_bf16 v[116:119], v[168:171], v[186:189], v[116:119]
	v_mfma_f32_16x16x32_bf16 v[112:115], v[176:179], v[186:189], v[112:115]
	v_mfma_f32_16x16x32_bf16 v[100:103], v[168:171], v[194:197], v[100:103]
	v_mfma_f32_16x16x32_bf16 v[96:99], v[176:179], v[194:197], v[96:99]
	v_mfma_f32_16x16x32_bf16 v[84:87], v[168:171], v[208:211], v[84:87]
	v_mfma_f32_16x16x32_bf16 v[80:83], v[176:179], v[208:211], v[80:83]
	v_mfma_f32_16x16x32_bf16 v[68:71], v[168:171], v[216:219], v[68:71]
	v_mfma_f32_16x16x32_bf16 v[64:67], v[176:179], v[216:219], v[64:67]
	v_mfma_f32_16x16x32_bf16 v[116:119], v[172:175], v[190:193], v[116:119]
	v_mfma_f32_16x16x32_bf16 v[112:115], v[182:185], v[190:193], v[112:115]
	v_mfma_f32_16x16x32_bf16 v[100:103], v[172:175], v[198:201], v[100:103]
	v_mfma_f32_16x16x32_bf16 v[96:99], v[182:185], v[198:201], v[96:99]
	v_mfma_f32_16x16x32_bf16 v[84:87], v[172:175], v[212:215], v[84:87]
	v_mfma_f32_16x16x32_bf16 v[80:83], v[182:185], v[212:215], v[80:83]
	v_mfma_f32_16x16x32_bf16 v[68:71], v[172:175], v[220:223], v[68:71]
	v_mfma_f32_16x16x32_bf16 v[64:67], v[182:185], v[220:223], v[64:67]
	s_setprio 0
	s_barrier
; #define PG8_STAGE(bufoff, gbase, voff) do { _Pragma("unroll") for (int _i = 0; _i < 2; ++_i) \
;         __builtin_amdgcn_global_load_lds((const unsigned*)((const char*)(gbase) + (voff)[_i]), (PG8_LAS unsigned*)(lds + (bufoff) + ldsw + _i * 8192), 16, 0, 0); } while (0)
; #define PG8_LDA(dst, b, h) do { _Pragma("unroll") for (int m = 0; m < 4; ++m) _Pragma("unroll") for (int k = 0; k < 2; ++k) dst[m][k] = *(const PG8_LAS bf16x8*)(lds + PG8_SA(b, h) + aoff + m * 2048 + k * 1024); } while (0)
; #define PG8_MMA(ai, bj, At, Bt) do { __builtin_amdgcn_s_setprio(1); _Pragma("unroll") for (int m = 0; m < 4; ++m) _Pragma("unroll") for (int n = 0; n < 2; ++n) _Pragma("unroll") for (int k = 0; k < 2; ++k) \
;         acc[ai][bj][m][n] = __builtin_amdgcn_mfma_f32_16x16x32_bf16(Bt[n][k], At[m][k], acc[ai][bj][m][n], 0, 0, 0); __builtin_amdgcn_s_setprio(0); } while (0)
; #define PG8_WAIT_V(n) asm volatile("s_waitcnt vmcnt(" #n ")" ::: "memory")
; #define PG8_WAIT_L(n) asm volatile("s_waitcnt lgkmcnt(" #n ")" ::: "memory")
; #define PG8_BAR __builtin_amdgcn_s_barrier()
; #define PG8_SCHED __builtin_amdgcn_sched_barrier(0)
;     __device__ __forceinline__ void operator()(const f32x4 (&acc)[2][2][4][2], const Unit& u, int wr, int wc, int fr, int fq) const {
;     ...
;             for (int m = 0; m < 4; ++m) { const int row = row0 + ai * HALF + m * 16; const size_t off = (size_t)row * 1024 + col0; float s = 0.f;
; #pragma unroll
;                 for (int bj = 0; bj < 2; ++bj) { f32x4 a0, a1;
;                     if (xin32) { const float* p = xin32 + off + bj * HALF; a0 = *(const f32x4*)p; a1 = *(const f32x4*)(p + 4); }
;                     else { const u32x4 w = *(const u32x4*)(xb + off + bj * HALF);
; template <class Epi, class Sched, bool ALIGN_EPI = false, bool SP2 = false>
; __device__ __forceinline__ void gemm_phase(PG8_LAS unsigned char* lds, const Gemm g, const Sched& S, const Epi& E) {
;     ...
;             PG8_WAIT_V(8); PG8_WAIT_L(0); PG8_BAR; PG8_MMA(0, 0, At, B0); PG8_MMA(0, 1, At, B1); PG8_BAR; PG8_SCHED;
;             PG8_LDA(At, 1, 1); PG8_STAGE(PG8_SB(1, 0), b3, voffB); PG8_STAGE(PG8_SB(1, 1), b3 + hstep, voffB); PG8_STAGE(PG8_SA(1, 0), a3, voffA);
;             PG8_WAIT_V(8); PG8_WAIT_L(0); PG8_BAR; PG8_MMA(1, 0, At, B0); PG8_MMA(1, 1, At, B1); PG8_BAR; PG8_SCHED;
	s_add_i32 s50, s78, s3
	v_lshl_add_u64 v[202:203], v[202:203], 0, s[42:43]
	s_mov_b32 m0, s50
	ds_read_b128 v[186:189], v153 offset:49152
	ds_read_b128 v[190:193], v153 offset:50176
	ds_read_b128 v[194:197], v153 offset:51200
	ds_read_b128 v[198:201], v153 offset:52224
	ds_read_b128 v[208:211], v153 offset:53248
	ds_read_b128 v[212:215], v153 offset:54272
	ds_read_b128 v[216:219], v153 offset:55296
	ds_read_b128 v[220:223], v153 offset:56320
	global_load_lds_dwordx4 v[202:203], off
	s_add_i32 m0, s50, 0x2000
	s_add_u32 s50, s54, 0xb0080
	v_lshl_add_u64 v[202:203], v[224:225], 0, s[42:43]
	s_addc_u32 s51, s55, 0
	s_add_i32 s54, s79, s3
	global_load_lds_dwordx4 v[202:203], off
	v_lshl_add_u64 v[202:203], s[50:51], 0, v[130:131]
	s_mov_b32 m0, s54
	s_nop 0
	global_load_lds_dwordx4 v[202:203], off
	v_lshl_add_u64 v[202:203], s[50:51], 0, v[134:135]
	s_add_i32 m0, s54, 0x2000
	s_nop 0
	global_load_lds_dwordx4 v[202:203], off
	v_lshl_add_u64 v[202:203], v[226:227], 0, s[42:43]
	s_mov_b32 m0, s59
	s_nop 0
	global_load_lds_dwordx4 v[202:203], off
	v_lshl_add_u64 v[202:203], v[228:229], 0, s[42:43]
	s_mov_b32 m0, s60
	s_nop 0
	global_load_lds_dwordx4 v[202:203], off
	s_waitcnt vmcnt(8)
	s_waitcnt lgkmcnt(0)
	s_barrier
	s_setprio 1
	s_waitcnt lgkmcnt(0)
	v_mfma_f32_16x16x32_bf16 v[60:63], v[144:147], v[186:189], v[60:63]
	v_mfma_f32_16x16x32_bf16 v[56:59], v[160:163], v[186:189], v[56:59]
	v_mfma_f32_16x16x32_bf16 v[44:47], v[144:147], v[194:197], v[44:47]
	v_mfma_f32_16x16x32_bf16 v[40:43], v[160:163], v[194:197], v[40:43]
	v_mfma_f32_16x16x32_bf16 v[28:31], v[144:147], v[208:211], v[28:31]
	v_mfma_f32_16x16x32_bf16 v[24:27], v[160:163], v[208:211], v[24:27]
	v_mfma_f32_16x16x32_bf16 v[12:15], v[144:147], v[216:219], v[12:15]
	v_mfma_f32_16x16x32_bf16 v[8:11], v[160:163], v[216:219], v[8:11]
	v_mfma_f32_16x16x32_bf16 v[60:63], v[156:159], v[190:193], v[60:63]
	v_mfma_f32_16x16x32_bf16 v[56:59], v[164:167], v[190:193], v[56:59]
	v_mfma_f32_16x16x32_bf16 v[44:47], v[156:159], v[198:201], v[44:47]
	v_mfma_f32_16x16x32_bf16 v[40:43], v[164:167], v[198:201], v[40:43]
	v_mfma_f32_16x16x32_bf16 v[28:31], v[156:159], v[212:215], v[28:31]
	v_mfma_f32_16x16x32_bf16 v[24:27], v[164:167], v[212:215], v[24:27]
	v_mfma_f32_16x16x32_bf16 v[12:15], v[156:159], v[220:223], v[12:15]
	v_mfma_f32_16x16x32_bf16 v[8:11], v[164:167], v[220:223], v[8:11]
	s_setprio 0
	s_setprio 1
	v_mfma_f32_16x16x32_bf16 v[52:55], v[168:171], v[186:189], v[52:55]
	v_mfma_f32_16x16x32_bf16 v[48:51], v[176:179], v[186:189], v[48:51]
	v_mfma_f32_16x16x32_bf16 v[36:39], v[168:171], v[194:197], v[36:39]
	v_mfma_f32_16x16x32_bf16 v[32:35], v[176:179], v[194:197], v[32:35]
	v_mfma_f32_16x16x32_bf16 v[20:23], v[168:171], v[208:211], v[20:23]
	v_mfma_f32_16x16x32_bf16 v[16:19], v[176:179], v[208:211], v[16:19]
	v_mfma_f32_16x16x32_bf16 v[4:7], v[168:171], v[216:219], v[4:7]
	v_mfma_f32_16x16x32_bf16 v[0:3], v[176:179], v[216:219], v[0:3]
	v_mfma_f32_16x16x32_bf16 v[52:55], v[172:175], v[190:193], v[52:55]
	v_mfma_f32_16x16x32_bf16 v[48:51], v[182:185], v[190:193], v[48:51]
	v_mfma_f32_16x16x32_bf16 v[36:39], v[172:175], v[198:201], v[36:39]
	v_mfma_f32_16x16x32_bf16 v[32:35], v[182:185], v[198:201], v[32:35]
	v_mfma_f32_16x16x32_bf16 v[20:23], v[172:175], v[212:215], v[20:23]
	v_mfma_f32_16x16x32_bf16 v[16:19], v[182:185], v[212:215], v[16:19]
	v_mfma_f32_16x16x32_bf16 v[4:7], v[172:175], v[220:223], v[4:7]
	v_mfma_f32_16x16x32_bf16 v[0:3], v[182:185], v[220:223], v[0:3]
	s_setprio 0
	s_barrier
	s_add_i32 s77, s77, 2
	s_add_u32 s75, s75, 0x100
	s_addc_u32 s76, s76, 0
	s_cmp_gt_u32 s77, 41
	s_mov_b64 s[50:51], s[52:53]
	s_cbranch_scc0 .LBB0_1035
	v_lshl_add_u32 v146, s74, 8, v148
	v_ashrrev_i32_e32 v147, 31, v146
	v_lshl_or_b32 v144, s67, 8, v150
	v_lshlrev_b64 v[156:157], 11, v[146:147]
	v_ashrrev_i32_e32 v145, 31, v144
	v_lshl_add_u64 v[156:157], s[22:23], 0, v[156:157]
	v_lshl_add_u64 v[166:167], v[144:145], 1, v[156:157]
	s_mov_b64 s[98:99], 0x8000
	s_mov_b64 s[100:101], 0x28000
	global_load_dwordx4 v[182:185], v[166:167], off
	global_load_dwordx4 v[186:189], v[166:167], off offset:256
	v_lshl_add_u64 v[198:199], v[166:167], 0, s[98:99]
	global_load_dwordx4 v[190:193], v[198:199], off
	global_load_dwordx4 v[194:197], v[198:199], off offset:256
	v_lshl_add_u64 v[198:199], v[198:199], 0, s[98:99]
	global_load_dwordx4 v[208:211], v[198:199], off
	global_load_dwordx4 v[212:215], v[198:199], off offset:256
	v_lshl_add_u64 v[198:199], v[198:199], 0, s[98:99]
	global_load_dwordx4 v[216:219], v[198:199], off
	global_load_dwordx4 v[220:223], v[198:199], off offset:256
	v_lshl_add_u64 v[198:199], v[198:199], 0, s[100:101]
	s_and_b64 vcc, exec, s[44:45]
	s_cbranch_vccz .LBB0_1038
	s_barrier
; __device__ __forceinline__ void fx_add(float* p, size_t idx, float s) { atomicAdd((unsigned long long*)p + idx, (unsigned long long)(long long)(s * 4294967296.0f)); }
; __device__ __forceinline__ unsigned cvtpk(float lo, float hi) { f32x2v_ v = {lo, hi}; bf16x2v_ b = __builtin_convertvector(v, bf16x2v_); return __builtin_bit_cast(unsigned, b); }
;     __device__ __forceinline__ void operator()(const f32x4 (&acc)[2][2][4][2], const Unit& u, int wr, int wc, int fr, int fq) const {
;     ...
;             for (int m = 0; m < 4; ++m) { const int row = row0 + ai * HALF + m * 16; const size_t off = (size_t)row * 1024 + col0; float s = 0.f;
; #pragma unroll
;                 for (int bj = 0; bj < 2; ++bj) { f32x4 a0, a1;
;                     if (xin32) { const float* p = xin32 + off + bj * HALF; a0 = *(const f32x4*)p; a1 = *(const f32x4*)(p + 4); }
;                     else { const u32x4 w = *(const u32x4*)(xb + off + bj * HALF);
;                         a0 = (f32x4){__uint_as_float(w.x << 16), __uint_as_float(w.x & 0xffff0000u), __uint_as_float(w.y << 16), __uint_as_float(w.y & 0xffff0000u)};
;                         a1 = (f32x4){__uint_as_float(w.z << 16), __uint_as_float(w.z & 0xffff0000u), __uint_as_float(w.w << 16), __uint_as_float(w.w & 0xffff0000u)}; }
;                     const f32x4 v0 = a0 + acc[ai][bj][m][0] * alpha, v1 = a1 + acc[ai][bj][m][1] * alpha;
;                     u32x4 w; w.x = cvtpk(v0[0], v0[1]); w.y = cvtpk(v0[2], v0[3]); w.z = cvtpk(v1[0], v1[1]); w.w = cvtpk(v1[2], v1[3]);
;                     *(u32x4*)(xb + off + bj * HALF) = w;
;                     s += (v0[0] * v0[0] + v0[1] * v0[1]) + (v0[2] * v0[2] + v0[3] * v0[3]) + (v1[0] * v1[0] + v1[1] * v1[1]) + (v1[2] * v1[2] + v1[3] * v1[3]); }
;                 s += __shfl_xor(s, 16); s += __shfl_xor(s, 32);
;                 if (fq == 0) fx_add(ssout, row, s); }
.LBB0_1038:
	s_nop 0
	s_nop 0
	v_and_b32_e32 v156, 64, v154
	v_xor_b32_e32 v155, 16, v154
	v_add_u32_e32 v156, 64, v156
	v_xor_b32_e32 v157, 32, v154
	v_cmp_lt_i32_e32 vcc, v155, v156
	s_waitcnt vmcnt(6)
	v_lshlrev_b32_e32 v168, 16, v182
	v_cndmask_b32_e32 v155, v154, v155, vcc
	v_cmp_lt_i32_e32 vcc, v157, v156
	v_and_b32_e32 v169, 0xffff0000, v182
	v_lshlrev_b32_e32 v158, 16, v183
	v_and_b32_e32 v159, 0xffff0000, v183
	v_lshlrev_b32_e32 v172, 16, v186
	v_and_b32_e32 v173, 0xffff0000, v186
	v_lshlrev_b32_e32 v162, 16, v187
	v_and_b32_e32 v163, 0xffff0000, v187
	v_cndmask_b32_e32 v157, v154, v157, vcc
	v_lshlrev_b32_e32 v170, 16, v184
	v_and_b32_e32 v171, 0xffff0000, v184
	v_lshlrev_b32_e32 v160, 16, v185
	v_and_b32_e32 v161, 0xffff0000, v185
	v_lshlrev_b32_e32 v174, 16, v188
	v_and_b32_e32 v175, 0xffff0000, v188
	v_lshlrev_b32_e32 v164, 16, v189
	v_and_b32_e32 v165, 0xffff0000, v189
	global_load_dwordx4 v[182:185], v[198:199], off
	global_load_dwordx4 v[186:189], v[198:199], off offset:256
	v_lshl_add_u64 v[198:199], v[198:199], 0, s[98:99]
	v_pk_fma_f32 v[126:127], v[126:127], 0.5, v[158:159] op_sel_hi:[1,0,1]
	v_pk_fma_f32 v[124:125], v[124:125], 0.5, v[168:169] op_sel_hi:[1,0,1]
	v_pk_fma_f32 v[118:119], v[118:119], 0.5, v[162:163] op_sel_hi:[1,0,1]
	v_pk_fma_f32 v[116:117], v[116:117], 0.5, v[172:173] op_sel_hi:[1,0,1]
	v_lshlrev_b32_e32 v156, 2, v155
	v_lshlrev_b32_e32 v155, 2, v157
	v_pk_fma_f32 v[122:123], v[122:123], 0.5, v[160:161] op_sel_hi:[1,0,1]
	v_pk_fma_f32 v[120:121], v[120:121], 0.5, v[170:171] op_sel_hi:[1,0,1]
	v_pk_fma_f32 v[158:159], v[114:115], 0.5, v[164:165] op_sel_hi:[1,0,1]
	v_pk_fma_f32 v[160:161], v[112:113], 0.5, v[174:175] op_sel_hi:[1,0,1]
	v_mul_f32_e32 v114, v125, v125
	v_mul_f32_e32 v115, v127, v127
	v_mul_f32_e32 v157, v117, v117
	v_mul_f32_e32 v162, v119, v119
	v_cvt_pk_bf16_f32 v112, v124, v125
	v_mul_f32_e32 v125, v121, v121
	v_mul_f32_e32 v163, v161, v161
	v_fmac_f32_e32 v114, v124, v124
	v_fmac_f32_e32 v115, v126, v126
	v_fmac_f32_e32 v157, v116, v116
	v_fmac_f32_e32 v162, v118, v118
	v_cvt_pk_bf16_f32 v113, v126, v127
	v_mul_f32_e32 v127, v123, v123
	v_mul_f32_e32 v164, v159, v159
	v_fmac_f32_e32 v125, v120, v120
	v_fmac_f32_e32 v163, v160, v160
	v_add_f32_e32 v114, v114, v115
	v_add_f32_e32 v115, v157, v162
	v_fmac_f32_e32 v127, v122, v122
	v_fmac_f32_e32 v164, v158, v158
	v_add_f32_e32 v114, v125, v114
	v_add_f32_e32 v115, v163, v115
	v_add_f32_e32 v114, v127, v114
	v_add_f32_e32 v115, v164, v115
	v_add_f32_e32 v124, v114, v115
	ds_bpermute_b32 v125, v156, v124
	v_cvt_pk_bf16_f32 v114, v120, v121
	v_cvt_pk_bf16_f32 v115, v122, v123
	global_store_dwordx4 v[166:167], v[112:115], off
	s_waitcnt lgkmcnt(0)
	s_nop 0
	v_add_f32_e32 v112, v124, v125
	ds_bpermute_b32 v113, v155, v112
	v_cvt_pk_bf16_f32 v114, v116, v117
	v_cvt_pk_bf16_f32 v115, v118, v119
	v_cvt_pk_bf16_f32 v116, v160, v161
	v_cvt_pk_bf16_f32 v117, v158, v159
	global_store_dwordx4 v[166:167], v[114:117], off offset:256
	s_and_saveexec_b64 s[50:51], s[10:11]
	s_cbranch_execz .LBB0_1040
	s_waitcnt lgkmcnt(0)
	v_add_f32_e32 v112, v112, v113
	v_mul_f32_e32 v112, 0x4f800000, v112
	v_trunc_f32_e32 v112, v112
	v_mul_f32_e64 v113, |v112|, s63
	v_floor_f32_e32 v113, v113
	v_fma_f32 v114, v113, s64, |v112|
	v_cvt_u32_f32_e32 v114, v114
	v_cvt_u32_f32_e32 v113, v113
	v_ashrrev_i32_e32 v115, 31, v112
	v_xor_b32_e32 v112, v114, v115
	v_xor_b32_e32 v113, v113, v115
	v_sub_co_u32_e32 v112, vcc, v112, v115
	s_nop 1
	v_subb_co_u32_e32 v113, vcc, v113, v115, vcc
	v_lshl_add_u64 v[114:115], v[146:147], 3, s[36:37]
	global_atomic_add_x2 v[114:115], v[112:113], off
.LBB0_1040:
	s_or_b64 exec, exec, s[50:51]
	v_or_b32_e32 v112, 16, v146
	s_waitcnt lgkmcnt(0)
	v_ashrrev_i32_e32 v113, 31, v112
	v_lshlrev_b64 v[114:115], 11, v[112:113]
	v_lshl_add_u64 v[114:115], s[22:23], 0, v[114:115]
	v_lshl_add_u64 v[122:123], v[144:145], 1, v[114:115]
	s_nop 0
	s_nop 0
	s_waitcnt vmcnt(10)
	v_lshlrev_b32_e32 v124, 16, v190
	v_and_b32_e32 v125, 0xffff0000, v190
	v_lshlrev_b32_e32 v114, 16, v191
	v_and_b32_e32 v115, 0xffff0000, v191
	s_waitcnt vmcnt(9)
	v_lshlrev_b32_e32 v158, 16, v194
	v_and_b32_e32 v159, 0xffff0000, v194
	v_lshlrev_b32_e32 v118, 16, v195
	v_and_b32_e32 v119, 0xffff0000, v195
	v_lshlrev_b32_e32 v126, 16, v192
	v_and_b32_e32 v127, 0xffff0000, v192
	v_lshlrev_b32_e32 v116, 16, v193
	v_and_b32_e32 v117, 0xffff0000, v193
	v_lshlrev_b32_e32 v160, 16, v196
	v_and_b32_e32 v161, 0xffff0000, v196
	v_lshlrev_b32_e32 v120, 16, v197
	v_and_b32_e32 v121, 0xffff0000, v197
	global_load_dwordx4 v[190:193], v[198:199], off
	global_load_dwordx4 v[194:197], v[198:199], off offset:256
	v_lshl_add_u64 v[198:199], v[198:199], 0, s[98:99]
	v_pk_fma_f32 v[110:111], v[110:111], 0.5, v[114:115] op_sel_hi:[1,0,1]
	v_pk_fma_f32 v[108:109], v[108:109], 0.5, v[124:125] op_sel_hi:[1,0,1]
	v_pk_fma_f32 v[102:103], v[102:103], 0.5, v[118:119] op_sel_hi:[1,0,1]
	v_pk_fma_f32 v[100:101], v[100:101], 0.5, v[158:159] op_sel_hi:[1,0,1]
	v_pk_fma_f32 v[106:107], v[106:107], 0.5, v[116:117] op_sel_hi:[1,0,1]
	v_pk_fma_f32 v[104:105], v[104:105], 0.5, v[126:127] op_sel_hi:[1,0,1]
	v_pk_fma_f32 v[114:115], v[98:99], 0.5, v[120:121] op_sel_hi:[1,0,1]
	v_pk_fma_f32 v[116:117], v[96:97], 0.5, v[160:161] op_sel_hi:[1,0,1]
	v_mul_f32_e32 v98, v109, v109
	v_mul_f32_e32 v99, v111, v111
	v_mul_f32_e32 v118, v101, v101
	v_mul_f32_e32 v119, v103, v103
	v_cvt_pk_bf16_f32 v96, v108, v109
	v_mul_f32_e32 v109, v105, v105
	v_mul_f32_e32 v120, v117, v117
	v_fmac_f32_e32 v98, v108, v108
	v_fmac_f32_e32 v99, v110, v110
	v_fmac_f32_e32 v118, v100, v100
	v_fmac_f32_e32 v119, v102, v102
	v_cvt_pk_bf16_f32 v97, v110, v111
	v_mul_f32_e32 v111, v107, v107
	v_mul_f32_e32 v121, v115, v115
	v_fmac_f32_e32 v109, v104, v104
	v_fmac_f32_e32 v120, v116, v116
	v_add_f32_e32 v98, v98, v99
	v_add_f32_e32 v99, v118, v119
	v_fmac_f32_e32 v111, v106, v106
	v_fmac_f32_e32 v121, v114, v114
	v_add_f32_e32 v98, v109, v98
	v_add_f32_e32 v99, v120, v99
	v_add_f32_e32 v98, v111, v98
	v_add_f32_e32 v99, v121, v99
	v_add_f32_e32 v108, v98, v99
	ds_bpermute_b32 v109, v156, v108
	v_cvt_pk_bf16_f32 v98, v104, v105
	v_cvt_pk_bf16_f32 v99, v106, v107
	global_store_dwordx4 v[122:123], v[96:99], off
	s_waitcnt lgkmcnt(0)
	s_nop 0
	v_add_f32_e32 v96, v108, v109
	ds_bpermute_b32 v97, v155, v96
	v_cvt_pk_bf16_f32 v98, v100, v101
	v_cvt_pk_bf16_f32 v99, v102, v103
	v_cvt_pk_bf16_f32 v100, v116, v117
	v_cvt_pk_bf16_f32 v101, v114, v115
	global_store_dwordx4 v[122:123], v[98:101], off offset:256
	s_and_saveexec_b64 s[50:51], s[10:11]
	s_cbranch_execz .LBB0_1042
; __device__ __forceinline__ void fx_add(float* p, size_t idx, float s) { atomicAdd((unsigned long long*)p + idx, (unsigned long long)(long long)(s * 4294967296.0f)); }
; __device__ __forceinline__ unsigned cvtpk(float lo, float hi) { f32x2v_ v = {lo, hi}; bf16x2v_ b = __builtin_convertvector(v, bf16x2v_); return __builtin_bit_cast(unsigned, b); }
;     __device__ __forceinline__ void operator()(const f32x4 (&acc)[2][2][4][2], const Unit& u, int wr, int wc, int fr, int fq) const {
;     ...
;             for (int m = 0; m < 4; ++m) { const int row = row0 + ai * HALF + m * 16; const size_t off = (size_t)row * 1024 + col0; float s = 0.f;
; #pragma unroll
;                 for (int bj = 0; bj < 2; ++bj) { f32x4 a0, a1;
;                     if (xin32) { const float* p = xin32 + off + bj * HALF; a0 = *(const f32x4*)p; a1 = *(const f32x4*)(p + 4); }
;                     else { const u32x4 w = *(const u32x4*)(xb + off + bj * HALF);
;                         a0 = (f32x4){__uint_as_float(w.x << 16), __uint_as_float(w.x & 0xffff0000u), __uint_as_float(w.y << 16), __uint_as_float(w.y & 0xffff0000u)};
;                         a1 = (f32x4){__uint_as_float(w.z << 16), __uint_as_float(w.z & 0xffff0000u), __uint_as_float(w.w << 16), __uint_as_float(w.w & 0xffff0000u)}; }
;                     const f32x4 v0 = a0 + acc[ai][bj][m][0] * alpha, v1 = a1 + acc[ai][bj][m][1] * alpha;
;                     u32x4 w; w.x = cvtpk(v0[0], v0[1]); w.y = cvtpk(v0[2], v0[3]); w.z = cvtpk(v1[0], v1[1]); w.w = cvtpk(v1[2], v1[3]);
;                     *(u32x4*)(xb + off + bj * HALF) = w;
;                     s += (v0[0] * v0[0] + v0[1] * v0[1]) + (v0[2] * v0[2] + v0[3] * v0[3]) + (v1[0] * v1[0] + v1[1] * v1[1]) + (v1[2] * v1[2] + v1[3] * v1[3]); }
;                 s += __shfl_xor(s, 16); s += __shfl_xor(s, 32);
;                 if (fq == 0) fx_add(ssout, row, s); }
	s_waitcnt lgkmcnt(0)
	v_add_f32_e32 v96, v96, v97
	v_mul_f32_e32 v96, 0x4f800000, v96
	v_trunc_f32_e32 v96, v96
	v_mul_f32_e64 v97, |v96|, s63
	v_floor_f32_e32 v97, v97
	v_fma_f32 v98, v97, s64, |v96|
	v_cvt_u32_f32_e32 v98, v98
	v_cvt_u32_f32_e32 v97, v97
	v_ashrrev_i32_e32 v99, 31, v96
	v_xor_b32_e32 v96, v98, v99
	v_xor_b32_e32 v97, v97, v99
	v_sub_co_u32_e32 v96, vcc, v96, v99
	s_nop 1
	v_subb_co_u32_e32 v97, vcc, v97, v99, vcc
	v_lshl_add_u64 v[98:99], v[112:113], 3, s[36:37]
	global_atomic_add_x2 v[98:99], v[96:97], off
.LBB0_1042:
	s_or_b64 exec, exec, s[50:51]
	v_or_b32_e32 v96, 32, v146
	s_waitcnt lgkmcnt(0)
	v_ashrrev_i32_e32 v97, 31, v96
	v_lshlrev_b64 v[98:99], 11, v[96:97]
	v_lshl_add_u64 v[98:99], s[22:23], 0, v[98:99]
	v_lshl_add_u64 v[106:107], v[144:145], 1, v[98:99]
	s_nop 0
	s_nop 0
	s_waitcnt vmcnt(13)
	v_lshlrev_b32_e32 v108, 16, v208
	v_and_b32_e32 v109, 0xffff0000, v208
	v_lshlrev_b32_e32 v98, 16, v209
	v_and_b32_e32 v99, 0xffff0000, v209
	s_waitcnt vmcnt(12)
	v_lshlrev_b32_e32 v112, 16, v212
	v_and_b32_e32 v113, 0xffff0000, v212
	v_lshlrev_b32_e32 v102, 16, v213
	v_and_b32_e32 v103, 0xffff0000, v213
	v_lshlrev_b32_e32 v110, 16, v210
	v_and_b32_e32 v111, 0xffff0000, v210
	v_lshlrev_b32_e32 v100, 16, v211
	v_and_b32_e32 v101, 0xffff0000, v211
	v_lshlrev_b32_e32 v114, 16, v214
	v_and_b32_e32 v115, 0xffff0000, v214
	v_lshlrev_b32_e32 v104, 16, v215
	v_and_b32_e32 v105, 0xffff0000, v215
	global_load_dwordx4 v[208:211], v[198:199], off
	global_load_dwordx4 v[212:215], v[198:199], off offset:256
	v_lshl_add_u64 v[198:199], v[198:199], 0, s[98:99]
	v_pk_fma_f32 v[94:95], v[94:95], 0.5, v[98:99] op_sel_hi:[1,0,1]
	v_pk_fma_f32 v[92:93], v[92:93], 0.5, v[108:109] op_sel_hi:[1,0,1]
	v_pk_fma_f32 v[86:87], v[86:87], 0.5, v[102:103] op_sel_hi:[1,0,1]
	v_pk_fma_f32 v[84:85], v[84:85], 0.5, v[112:113] op_sel_hi:[1,0,1]
	v_pk_fma_f32 v[90:91], v[90:91], 0.5, v[100:101] op_sel_hi:[1,0,1]
	v_pk_fma_f32 v[88:89], v[88:89], 0.5, v[110:111] op_sel_hi:[1,0,1]
	v_pk_fma_f32 v[98:99], v[82:83], 0.5, v[104:105] op_sel_hi:[1,0,1]
	v_pk_fma_f32 v[100:101], v[80:81], 0.5, v[114:115] op_sel_hi:[1,0,1]
	v_mul_f32_e32 v82, v93, v93
	v_mul_f32_e32 v83, v95, v95
	v_mul_f32_e32 v102, v85, v85
	v_mul_f32_e32 v103, v87, v87
	v_cvt_pk_bf16_f32 v80, v92, v93
	v_mul_f32_e32 v93, v89, v89
	v_mul_f32_e32 v104, v101, v101
	v_fmac_f32_e32 v82, v92, v92
	v_fmac_f32_e32 v83, v94, v94
	v_fmac_f32_e32 v102, v84, v84
	v_fmac_f32_e32 v103, v86, v86
	v_cvt_pk_bf16_f32 v81, v94, v95
	v_mul_f32_e32 v95, v91, v91
	v_mul_f32_e32 v105, v99, v99
	v_fmac_f32_e32 v93, v88, v88
	v_fmac_f32_e32 v104, v100, v100
	v_add_f32_e32 v82, v82, v83
	v_add_f32_e32 v83, v102, v103
	v_fmac_f32_e32 v95, v90, v90
	v_fmac_f32_e32 v105, v98, v98
	v_add_f32_e32 v82, v93, v82
	v_add_f32_e32 v83, v104, v83
	v_add_f32_e32 v82, v95, v82
	v_add_f32_e32 v83, v105, v83
	v_add_f32_e32 v92, v82, v83
	ds_bpermute_b32 v93, v156, v92
	v_cvt_pk_bf16_f32 v82, v88, v89
	v_cvt_pk_bf16_f32 v83, v90, v91
	global_store_dwordx4 v[106:107], v[80:83], off
	s_waitcnt lgkmcnt(0)
	s_nop 0
	v_add_f32_e32 v80, v92, v93
	ds_bpermute_b32 v81, v155, v80
	v_cvt_pk_bf16_f32 v82, v84, v85
	v_cvt_pk_bf16_f32 v83, v86, v87
	v_cvt_pk_bf16_f32 v84, v100, v101
	v_cvt_pk_bf16_f32 v85, v98, v99
	global_store_dwordx4 v[106:107], v[82:85], off offset:256
	s_and_saveexec_b64 s[50:51], s[10:11]
	s_cbranch_execz .LBB0_1044
	s_waitcnt lgkmcnt(0)
	v_add_f32_e32 v80, v80, v81
	v_mul_f32_e32 v80, 0x4f800000, v80
	v_trunc_f32_e32 v80, v80
	v_mul_f32_e64 v81, |v80|, s63
	v_floor_f32_e32 v81, v81
	v_fma_f32 v82, v81, s64, |v80|
	v_cvt_u32_f32_e32 v82, v82
	v_cvt_u32_f32_e32 v81, v81
	v_ashrrev_i32_e32 v83, 31, v80
	v_xor_b32_e32 v80, v82, v83
	v_xor_b32_e32 v81, v81, v83
	v_sub_co_u32_e32 v80, vcc, v80, v83
	s_nop 1
	v_subb_co_u32_e32 v81, vcc, v81, v83, vcc
	v_lshl_add_u64 v[82:83], v[96:97], 3, s[36:37]
	global_atomic_add_x2 v[82:83], v[80:81], off
.LBB0_1044:
	s_or_b64 exec, exec, s[50:51]
	v_or_b32_e32 v80, 48, v146
	s_waitcnt lgkmcnt(0)
	v_ashrrev_i32_e32 v81, 31, v80
	v_lshlrev_b64 v[82:83], 11, v[80:81]
	v_lshl_add_u64 v[82:83], s[22:23], 0, v[82:83]
	v_lshl_add_u64 v[90:91], v[144:145], 1, v[82:83]
	s_nop 0
	s_nop 0
	s_waitcnt vmcnt(16)
	v_lshlrev_b32_e32 v92, 16, v216
	v_and_b32_e32 v93, 0xffff0000, v216
	v_lshlrev_b32_e32 v82, 16, v217
	v_and_b32_e32 v83, 0xffff0000, v217
	s_waitcnt vmcnt(15)
	v_lshlrev_b32_e32 v96, 16, v220
	v_and_b32_e32 v97, 0xffff0000, v220
	v_lshlrev_b32_e32 v86, 16, v221
	v_and_b32_e32 v87, 0xffff0000, v221
	v_lshlrev_b32_e32 v94, 16, v218
	v_and_b32_e32 v95, 0xffff0000, v218
	v_lshlrev_b32_e32 v84, 16, v219
	v_and_b32_e32 v85, 0xffff0000, v219
	v_lshlrev_b32_e32 v98, 16, v222
	v_and_b32_e32 v99, 0xffff0000, v222
	v_lshlrev_b32_e32 v88, 16, v223
	v_and_b32_e32 v89, 0xffff0000, v223
	global_load_dwordx4 v[216:219], v[198:199], off
	global_load_dwordx4 v[220:223], v[198:199], off offset:256
	v_pk_fma_f32 v[78:79], v[78:79], 0.5, v[82:83] op_sel_hi:[1,0,1]
	v_pk_fma_f32 v[76:77], v[76:77], 0.5, v[92:93] op_sel_hi:[1,0,1]
	v_pk_fma_f32 v[70:71], v[70:71], 0.5, v[86:87] op_sel_hi:[1,0,1]
	v_pk_fma_f32 v[68:69], v[68:69], 0.5, v[96:97] op_sel_hi:[1,0,1]
	v_pk_fma_f32 v[74:75], v[74:75], 0.5, v[84:85] op_sel_hi:[1,0,1]
	v_pk_fma_f32 v[72:73], v[72:73], 0.5, v[94:95] op_sel_hi:[1,0,1]
	v_pk_fma_f32 v[82:83], v[66:67], 0.5, v[88:89] op_sel_hi:[1,0,1]
	v_pk_fma_f32 v[84:85], v[64:65], 0.5, v[98:99] op_sel_hi:[1,0,1]
	v_mul_f32_e32 v66, v77, v77
	v_mul_f32_e32 v67, v79, v79
	v_mul_f32_e32 v86, v69, v69
	v_mul_f32_e32 v87, v71, v71
	v_cvt_pk_bf16_f32 v64, v76, v77
	v_mul_f32_e32 v77, v73, v73
	v_mul_f32_e32 v88, v85, v85
	v_fmac_f32_e32 v66, v76, v76
	v_fmac_f32_e32 v67, v78, v78
	v_fmac_f32_e32 v86, v68, v68
	v_fmac_f32_e32 v87, v70, v70
	v_cvt_pk_bf16_f32 v65, v78, v79
	v_mul_f32_e32 v79, v75, v75
	v_mul_f32_e32 v89, v83, v83
	v_fmac_f32_e32 v77, v72, v72
	v_fmac_f32_e32 v88, v84, v84
	v_add_f32_e32 v66, v66, v67
	v_add_f32_e32 v67, v86, v87
	v_fmac_f32_e32 v79, v74, v74
	v_fmac_f32_e32 v89, v82, v82
	v_add_f32_e32 v66, v77, v66
	v_add_f32_e32 v67, v88, v67
	v_add_f32_e32 v66, v79, v66
	v_add_f32_e32 v67, v89, v67
	v_add_f32_e32 v76, v66, v67
	ds_bpermute_b32 v77, v156, v76
	v_cvt_pk_bf16_f32 v66, v72, v73
	v_cvt_pk_bf16_f32 v67, v74, v75
	global_store_dwordx4 v[90:91], v[64:67], off
	s_waitcnt lgkmcnt(0)
	s_nop 0
	v_add_f32_e32 v64, v76, v77
	ds_bpermute_b32 v65, v155, v64
	v_cvt_pk_bf16_f32 v66, v68, v69
	v_cvt_pk_bf16_f32 v67, v70, v71
	v_cvt_pk_bf16_f32 v68, v84, v85
	v_cvt_pk_bf16_f32 v69, v82, v83
	global_store_dwordx4 v[90:91], v[66:69], off offset:256
	s_and_saveexec_b64 s[50:51], s[10:11]
	s_cbranch_execz .LBB0_1046
; __device__ __forceinline__ void fx_add(float* p, size_t idx, float s) { atomicAdd((unsigned long long*)p + idx, (unsigned long long)(long long)(s * 4294967296.0f)); }
; __device__ __forceinline__ unsigned cvtpk(float lo, float hi) { f32x2v_ v = {lo, hi}; bf16x2v_ b = __builtin_convertvector(v, bf16x2v_); return __builtin_bit_cast(unsigned, b); }
;     __device__ __forceinline__ void operator()(const f32x4 (&acc)[2][2][4][2], const Unit& u, int wr, int wc, int fr, int fq) const {
;     ...
;             for (int m = 0; m < 4; ++m) { const int row = row0 + ai * HALF + m * 16; const size_t off = (size_t)row * 1024 + col0; float s = 0.f;
; #pragma unroll
;                 for (int bj = 0; bj < 2; ++bj) { f32x4 a0, a1;
;                     if (xin32) { const float* p = xin32 + off + bj * HALF; a0 = *(const f32x4*)p; a1 = *(const f32x4*)(p + 4); }
;                     else { const u32x4 w = *(const u32x4*)(xb + off + bj * HALF);
;                         a0 = (f32x4){__uint_as_float(w.x << 16), __uint_as_float(w.x & 0xffff0000u), __uint_as_float(w.y << 16), __uint_as_float(w.y & 0xffff0000u)};
;                         a1 = (f32x4){__uint_as_float(w.z << 16), __uint_as_float(w.z & 0xffff0000u), __uint_as_float(w.w << 16), __uint_as_float(w.w & 0xffff0000u)}; }
;                     const f32x4 v0 = a0 + acc[ai][bj][m][0] * alpha, v1 = a1 + acc[ai][bj][m][1] * alpha;
;                     u32x4 w; w.x = cvtpk(v0[0], v0[1]); w.y = cvtpk(v0[2], v0[3]); w.z = cvtpk(v1[0], v1[1]); w.w = cvtpk(v1[2], v1[3]);
;                     *(u32x4*)(xb + off + bj * HALF) = w;
;                     s += (v0[0] * v0[0] + v0[1] * v0[1]) + (v0[2] * v0[2] + v0[3] * v0[3]) + (v1[0] * v1[0] + v1[1] * v1[1]) + (v1[2] * v1[2] + v1[3] * v1[3]); }
;                 s += __shfl_xor(s, 16); s += __shfl_xor(s, 32);
;                 if (fq == 0) fx_add(ssout, row, s); }
	s_waitcnt lgkmcnt(0)
	v_add_f32_e32 v64, v64, v65
	v_mul_f32_e32 v64, 0x4f800000, v64
	v_trunc_f32_e32 v64, v64
	v_mul_f32_e64 v65, |v64|, s63
	v_floor_f32_e32 v65, v65
	v_fma_f32 v66, v65, s64, |v64|
	v_cvt_u32_f32_e32 v66, v66
	v_cvt_u32_f32_e32 v65, v65
	v_ashrrev_i32_e32 v67, 31, v64
	v_xor_b32_e32 v64, v66, v67
	v_xor_b32_e32 v65, v65, v67
	v_sub_co_u32_e32 v64, vcc, v64, v67
	s_nop 1
	v_subb_co_u32_e32 v65, vcc, v65, v67, vcc
	v_lshl_add_u64 v[66:67], v[80:81], 3, s[36:37]
	global_atomic_add_x2 v[66:67], v[64:65], off
.LBB0_1046:
	s_or_b64 exec, exec, s[50:51]
	v_add_u32_e32 v64, 0x80, v146
	s_waitcnt lgkmcnt(0)
	v_ashrrev_i32_e32 v65, 31, v64
	v_lshlrev_b64 v[66:67], 11, v[64:65]
	v_lshl_add_u64 v[66:67], s[22:23], 0, v[66:67]
	v_lshl_add_u64 v[74:75], v[144:145], 1, v[66:67]
	s_nop 0
	s_nop 0
	s_waitcnt vmcnt(19)
	v_lshlrev_b32_e32 v76, 16, v182
	v_and_b32_e32 v77, 0xffff0000, v182
	v_lshlrev_b32_e32 v66, 16, v183
	v_and_b32_e32 v67, 0xffff0000, v183
	s_waitcnt vmcnt(18)
	v_lshlrev_b32_e32 v80, 16, v186
	v_and_b32_e32 v81, 0xffff0000, v186
	v_lshlrev_b32_e32 v70, 16, v187
	v_and_b32_e32 v71, 0xffff0000, v187
	v_lshlrev_b32_e32 v78, 16, v184
	v_and_b32_e32 v79, 0xffff0000, v184
	v_lshlrev_b32_e32 v68, 16, v185
	v_and_b32_e32 v69, 0xffff0000, v185
	v_lshlrev_b32_e32 v82, 16, v188
	v_and_b32_e32 v83, 0xffff0000, v188
	v_lshlrev_b32_e32 v72, 16, v189
	v_and_b32_e32 v73, 0xffff0000, v189
	v_pk_fma_f32 v[62:63], v[62:63], 0.5, v[66:67] op_sel_hi:[1,0,1]
	v_pk_fma_f32 v[60:61], v[60:61], 0.5, v[76:77] op_sel_hi:[1,0,1]
	v_pk_fma_f32 v[54:55], v[54:55], 0.5, v[70:71] op_sel_hi:[1,0,1]
	v_pk_fma_f32 v[52:53], v[52:53], 0.5, v[80:81] op_sel_hi:[1,0,1]
	v_pk_fma_f32 v[58:59], v[58:59], 0.5, v[68:69] op_sel_hi:[1,0,1]
	v_pk_fma_f32 v[56:57], v[56:57], 0.5, v[78:79] op_sel_hi:[1,0,1]
	v_pk_fma_f32 v[66:67], v[50:51], 0.5, v[72:73] op_sel_hi:[1,0,1]
	v_pk_fma_f32 v[68:69], v[48:49], 0.5, v[82:83] op_sel_hi:[1,0,1]
	v_mul_f32_e32 v50, v61, v61
	v_mul_f32_e32 v51, v63, v63
	v_mul_f32_e32 v70, v53, v53
	v_mul_f32_e32 v71, v55, v55
	v_cvt_pk_bf16_f32 v48, v60, v61
	v_mul_f32_e32 v61, v57, v57
	v_mul_f32_e32 v72, v69, v69
	v_fmac_f32_e32 v50, v60, v60
	v_fmac_f32_e32 v51, v62, v62
	v_fmac_f32_e32 v70, v52, v52
	v_fmac_f32_e32 v71, v54, v54
	v_cvt_pk_bf16_f32 v49, v62, v63
	v_mul_f32_e32 v63, v59, v59
	v_mul_f32_e32 v73, v67, v67
	v_fmac_f32_e32 v61, v56, v56
	v_fmac_f32_e32 v72, v68, v68
	v_add_f32_e32 v50, v50, v51
	v_add_f32_e32 v51, v70, v71
	v_fmac_f32_e32 v63, v58, v58
	v_fmac_f32_e32 v73, v66, v66
	v_add_f32_e32 v50, v61, v50
	v_add_f32_e32 v51, v72, v51
	v_add_f32_e32 v50, v63, v50
	v_add_f32_e32 v51, v73, v51
	v_add_f32_e32 v60, v50, v51
	ds_bpermute_b32 v61, v156, v60
	v_cvt_pk_bf16_f32 v50, v56, v57
	v_cvt_pk_bf16_f32 v51, v58, v59
	global_store_dwordx4 v[74:75], v[48:51], off
	s_waitcnt lgkmcnt(0)
	s_nop 0
	v_add_f32_e32 v48, v60, v61
	ds_bpermute_b32 v49, v155, v48
	v_cvt_pk_bf16_f32 v50, v52, v53
	v_cvt_pk_bf16_f32 v51, v54, v55
	v_cvt_pk_bf16_f32 v52, v68, v69
	v_cvt_pk_bf16_f32 v53, v66, v67
	global_store_dwordx4 v[74:75], v[50:53], off offset:256
	s_and_saveexec_b64 s[50:51], s[10:11]
	s_cbranch_execz .LBB0_1048
	s_waitcnt lgkmcnt(0)
	v_add_f32_e32 v48, v48, v49
	v_mul_f32_e32 v48, 0x4f800000, v48
	v_trunc_f32_e32 v48, v48
	v_mul_f32_e64 v49, |v48|, s63
	v_floor_f32_e32 v49, v49
	v_fma_f32 v50, v49, s64, |v48|
	v_cvt_u32_f32_e32 v50, v50
	v_cvt_u32_f32_e32 v49, v49
	v_ashrrev_i32_e32 v51, 31, v48
	v_xor_b32_e32 v48, v50, v51
	v_xor_b32_e32 v49, v49, v51
	v_sub_co_u32_e32 v48, vcc, v48, v51
	s_nop 1
	v_subb_co_u32_e32 v49, vcc, v49, v51, vcc
	v_lshl_add_u64 v[50:51], v[64:65], 3, s[36:37]
	global_atomic_add_x2 v[50:51], v[48:49], off
.LBB0_1048:
	s_or_b64 exec, exec, s[50:51]
	v_add_u32_e32 v48, 0x90, v146
	s_waitcnt lgkmcnt(0)
	v_ashrrev_i32_e32 v49, 31, v48
	v_lshlrev_b64 v[50:51], 11, v[48:49]
	v_lshl_add_u64 v[50:51], s[22:23], 0, v[50:51]
	v_lshl_add_u64 v[58:59], v[144:145], 1, v[50:51]
	s_nop 0
	s_nop 0
	s_waitcnt vmcnt(17)
	v_lshlrev_b32_e32 v60, 16, v190
	v_and_b32_e32 v61, 0xffff0000, v190
	v_lshlrev_b32_e32 v50, 16, v191
	v_and_b32_e32 v51, 0xffff0000, v191
	s_waitcnt vmcnt(16)
	v_lshlrev_b32_e32 v64, 16, v194
	v_and_b32_e32 v65, 0xffff0000, v194
	v_lshlrev_b32_e32 v54, 16, v195
	v_and_b32_e32 v55, 0xffff0000, v195
	v_lshlrev_b32_e32 v62, 16, v192
	v_and_b32_e32 v63, 0xffff0000, v192
	v_lshlrev_b32_e32 v52, 16, v193
	v_and_b32_e32 v53, 0xffff0000, v193
	v_lshlrev_b32_e32 v66, 16, v196
	v_and_b32_e32 v67, 0xffff0000, v196
	v_lshlrev_b32_e32 v56, 16, v197
	v_and_b32_e32 v57, 0xffff0000, v197
	v_pk_fma_f32 v[46:47], v[46:47], 0.5, v[50:51] op_sel_hi:[1,0,1]
	v_pk_fma_f32 v[44:45], v[44:45], 0.5, v[60:61] op_sel_hi:[1,0,1]
	v_pk_fma_f32 v[38:39], v[38:39], 0.5, v[54:55] op_sel_hi:[1,0,1]
	v_pk_fma_f32 v[36:37], v[36:37], 0.5, v[64:65] op_sel_hi:[1,0,1]
	v_pk_fma_f32 v[42:43], v[42:43], 0.5, v[52:53] op_sel_hi:[1,0,1]
	v_pk_fma_f32 v[40:41], v[40:41], 0.5, v[62:63] op_sel_hi:[1,0,1]
	v_pk_fma_f32 v[50:51], v[34:35], 0.5, v[56:57] op_sel_hi:[1,0,1]
	v_pk_fma_f32 v[52:53], v[32:33], 0.5, v[66:67] op_sel_hi:[1,0,1]
	v_mul_f32_e32 v34, v45, v45
	v_mul_f32_e32 v35, v47, v47
	v_mul_f32_e32 v54, v37, v37
	v_mul_f32_e32 v55, v39, v39
	v_cvt_pk_bf16_f32 v32, v44, v45
	v_mul_f32_e32 v45, v41, v41
	v_mul_f32_e32 v56, v53, v53
	v_fmac_f32_e32 v34, v44, v44
	v_fmac_f32_e32 v35, v46, v46
	v_fmac_f32_e32 v54, v36, v36
	v_fmac_f32_e32 v55, v38, v38
	v_cvt_pk_bf16_f32 v33, v46, v47
	v_mul_f32_e32 v47, v43, v43
	v_mul_f32_e32 v57, v51, v51
	v_fmac_f32_e32 v45, v40, v40
	v_fmac_f32_e32 v56, v52, v52
	v_add_f32_e32 v34, v34, v35
	v_add_f32_e32 v35, v54, v55
	v_fmac_f32_e32 v47, v42, v42
	v_fmac_f32_e32 v57, v50, v50
	v_add_f32_e32 v34, v45, v34
	v_add_f32_e32 v35, v56, v35
	v_add_f32_e32 v34, v47, v34
	v_add_f32_e32 v35, v57, v35
	v_add_f32_e32 v44, v34, v35
	ds_bpermute_b32 v45, v156, v44
	v_cvt_pk_bf16_f32 v34, v40, v41
	v_cvt_pk_bf16_f32 v35, v42, v43
	global_store_dwordx4 v[58:59], v[32:35], off
	s_waitcnt lgkmcnt(0)
	s_nop 0
	v_add_f32_e32 v32, v44, v45
	ds_bpermute_b32 v33, v155, v32
	v_cvt_pk_bf16_f32 v34, v36, v37
	v_cvt_pk_bf16_f32 v35, v38, v39
	v_cvt_pk_bf16_f32 v36, v52, v53
	v_cvt_pk_bf16_f32 v37, v50, v51
	global_store_dwordx4 v[58:59], v[34:37], off offset:256
	s_and_saveexec_b64 s[50:51], s[10:11]
	s_cbranch_execz .LBB0_1050
	s_waitcnt lgkmcnt(0)
	v_add_f32_e32 v32, v32, v33
	v_mul_f32_e32 v32, 0x4f800000, v32
	v_trunc_f32_e32 v32, v32
	v_mul_f32_e64 v33, |v32|, s63
	v_floor_f32_e32 v33, v33
	v_fma_f32 v34, v33, s64, |v32|
	v_cvt_u32_f32_e32 v34, v34
	v_cvt_u32_f32_e32 v33, v33
	v_ashrrev_i32_e32 v35, 31, v32
	v_xor_b32_e32 v32, v34, v35
	v_xor_b32_e32 v33, v33, v35
	v_sub_co_u32_e32 v32, vcc, v32, v35
	s_nop 1
	v_subb_co_u32_e32 v33, vcc, v33, v35, vcc
	v_lshl_add_u64 v[34:35], v[48:49], 3, s[36:37]
	global_atomic_add_x2 v[34:35], v[32:33], off
; __device__ __forceinline__ void fx_add(float* p, size_t idx, float s) { atomicAdd((unsigned long long*)p + idx, (unsigned long long)(long long)(s * 4294967296.0f)); }
; __device__ __forceinline__ unsigned cvtpk(float lo, float hi) { f32x2v_ v = {lo, hi}; bf16x2v_ b = __builtin_convertvector(v, bf16x2v_); return __builtin_bit_cast(unsigned, b); }
;     __device__ __forceinline__ void operator()(const f32x4 (&acc)[2][2][4][2], const Unit& u, int wr, int wc, int fr, int fq) const {
;     ...
;             for (int m = 0; m < 4; ++m) { const int row = row0 + ai * HALF + m * 16; const size_t off = (size_t)row * 1024 + col0; float s = 0.f;
; #pragma unroll
;                 for (int bj = 0; bj < 2; ++bj) { f32x4 a0, a1;
;                     if (xin32) { const float* p = xin32 + off + bj * HALF; a0 = *(const f32x4*)p; a1 = *(const f32x4*)(p + 4); }
;                     else { const u32x4 w = *(const u32x4*)(xb + off + bj * HALF);
;                         a0 = (f32x4){__uint_as_float(w.x << 16), __uint_as_float(w.x & 0xffff0000u), __uint_as_float(w.y << 16), __uint_as_float(w.y & 0xffff0000u)};
;                         a1 = (f32x4){__uint_as_float(w.z << 16), __uint_as_float(w.z & 0xffff0000u), __uint_as_float(w.w << 16), __uint_as_float(w.w & 0xffff0000u)}; }
;                     const f32x4 v0 = a0 + acc[ai][bj][m][0] * alpha, v1 = a1 + acc[ai][bj][m][1] * alpha;
;                     u32x4 w; w.x = cvtpk(v0[0], v0[1]); w.y = cvtpk(v0[2], v0[3]); w.z = cvtpk(v1[0], v1[1]); w.w = cvtpk(v1[2], v1[3]);
;                     *(u32x4*)(xb + off + bj * HALF) = w;
;                     s += (v0[0] * v0[0] + v0[1] * v0[1]) + (v0[2] * v0[2] + v0[3] * v0[3]) + (v1[0] * v1[0] + v1[1] * v1[1]) + (v1[2] * v1[2] + v1[3] * v1[3]); }
;                 s += __shfl_xor(s, 16); s += __shfl_xor(s, 32);
;                 if (fq == 0) fx_add(ssout, row, s); }
.LBB0_1050:
	s_or_b64 exec, exec, s[50:51]
	v_add_u32_e32 v32, 0xa0, v146
	s_waitcnt lgkmcnt(0)
	v_ashrrev_i32_e32 v33, 31, v32
	v_lshlrev_b64 v[34:35], 11, v[32:33]
	v_lshl_add_u64 v[34:35], s[22:23], 0, v[34:35]
	v_lshl_add_u64 v[42:43], v[144:145], 1, v[34:35]
	s_nop 0
	s_nop 0
	s_waitcnt vmcnt(15)
	v_lshlrev_b32_e32 v44, 16, v208
	v_and_b32_e32 v45, 0xffff0000, v208
	v_lshlrev_b32_e32 v34, 16, v209
	v_and_b32_e32 v35, 0xffff0000, v209
	s_waitcnt vmcnt(14)
	v_lshlrev_b32_e32 v48, 16, v212
	v_and_b32_e32 v49, 0xffff0000, v212
	v_lshlrev_b32_e32 v38, 16, v213
	v_and_b32_e32 v39, 0xffff0000, v213
	v_lshlrev_b32_e32 v46, 16, v210
	v_and_b32_e32 v47, 0xffff0000, v210
	v_lshlrev_b32_e32 v36, 16, v211
	v_and_b32_e32 v37, 0xffff0000, v211
	v_lshlrev_b32_e32 v50, 16, v214
	v_and_b32_e32 v51, 0xffff0000, v214
	v_lshlrev_b32_e32 v40, 16, v215
	v_and_b32_e32 v41, 0xffff0000, v215
	v_pk_fma_f32 v[30:31], v[30:31], 0.5, v[34:35] op_sel_hi:[1,0,1]
	v_pk_fma_f32 v[28:29], v[28:29], 0.5, v[44:45] op_sel_hi:[1,0,1]
	v_pk_fma_f32 v[22:23], v[22:23], 0.5, v[38:39] op_sel_hi:[1,0,1]
	v_pk_fma_f32 v[20:21], v[20:21], 0.5, v[48:49] op_sel_hi:[1,0,1]
	v_pk_fma_f32 v[26:27], v[26:27], 0.5, v[36:37] op_sel_hi:[1,0,1]
	v_pk_fma_f32 v[24:25], v[24:25], 0.5, v[46:47] op_sel_hi:[1,0,1]
	v_pk_fma_f32 v[34:35], v[18:19], 0.5, v[40:41] op_sel_hi:[1,0,1]
	v_pk_fma_f32 v[36:37], v[16:17], 0.5, v[50:51] op_sel_hi:[1,0,1]
	v_mul_f32_e32 v18, v29, v29
	v_mul_f32_e32 v19, v31, v31
	v_mul_f32_e32 v38, v21, v21
	v_mul_f32_e32 v39, v23, v23
	v_cvt_pk_bf16_f32 v16, v28, v29
	v_mul_f32_e32 v29, v25, v25
	v_mul_f32_e32 v40, v37, v37
	v_fmac_f32_e32 v18, v28, v28
	v_fmac_f32_e32 v19, v30, v30
	v_fmac_f32_e32 v38, v20, v20
	v_fmac_f32_e32 v39, v22, v22
	v_cvt_pk_bf16_f32 v17, v30, v31
	v_mul_f32_e32 v31, v27, v27
	v_mul_f32_e32 v41, v35, v35
	v_fmac_f32_e32 v29, v24, v24
	v_fmac_f32_e32 v40, v36, v36
	v_add_f32_e32 v18, v18, v19
	v_add_f32_e32 v19, v38, v39
	v_fmac_f32_e32 v31, v26, v26
	v_fmac_f32_e32 v41, v34, v34
	v_add_f32_e32 v18, v29, v18
	v_add_f32_e32 v19, v40, v19
	v_add_f32_e32 v18, v31, v18
	v_add_f32_e32 v19, v41, v19
	v_add_f32_e32 v28, v18, v19
	ds_bpermute_b32 v29, v156, v28
	v_cvt_pk_bf16_f32 v18, v24, v25
	v_cvt_pk_bf16_f32 v19, v26, v27
	global_store_dwordx4 v[42:43], v[16:19], off
	s_waitcnt lgkmcnt(0)
	s_nop 0
	v_add_f32_e32 v16, v28, v29
	ds_bpermute_b32 v17, v155, v16
	v_cvt_pk_bf16_f32 v18, v20, v21
	v_cvt_pk_bf16_f32 v19, v22, v23
	v_cvt_pk_bf16_f32 v20, v36, v37
	v_cvt_pk_bf16_f32 v21, v34, v35
	global_store_dwordx4 v[42:43], v[18:21], off offset:256
	s_and_saveexec_b64 s[50:51], s[10:11]
	s_cbranch_execz .LBB0_1052
	s_waitcnt lgkmcnt(0)
	v_add_f32_e32 v16, v16, v17
	v_mul_f32_e32 v16, 0x4f800000, v16
	v_trunc_f32_e32 v16, v16
	v_mul_f32_e64 v17, |v16|, s63
	v_floor_f32_e32 v17, v17
	v_fma_f32 v18, v17, s64, |v16|
	v_cvt_u32_f32_e32 v18, v18
	v_cvt_u32_f32_e32 v17, v17
	v_ashrrev_i32_e32 v19, 31, v16
	v_xor_b32_e32 v16, v18, v19
	v_xor_b32_e32 v17, v17, v19
	v_sub_co_u32_e32 v16, vcc, v16, v19
	s_nop 1
	v_subb_co_u32_e32 v17, vcc, v17, v19, vcc
	v_lshl_add_u64 v[18:19], v[32:33], 3, s[36:37]
	global_atomic_add_x2 v[18:19], v[16:17], off
.LBB0_1052:
	s_or_b64 exec, exec, s[50:51]
	v_add_u32_e32 v16, 0xb0, v146
	s_waitcnt lgkmcnt(0)
	v_ashrrev_i32_e32 v17, 31, v16
	v_lshlrev_b64 v[18:19], 11, v[16:17]
	v_lshl_add_u64 v[18:19], s[22:23], 0, v[18:19]
	v_lshl_add_u64 v[26:27], v[144:145], 1, v[18:19]
	s_nop 0
	s_nop 0
	s_waitcnt vmcnt(13)
	v_lshlrev_b32_e32 v28, 16, v216
	v_and_b32_e32 v29, 0xffff0000, v216
	v_lshlrev_b32_e32 v18, 16, v217
	v_and_b32_e32 v19, 0xffff0000, v217
	s_waitcnt vmcnt(12)
	v_lshlrev_b32_e32 v32, 16, v220
	v_and_b32_e32 v33, 0xffff0000, v220
	v_lshlrev_b32_e32 v22, 16, v221
	v_and_b32_e32 v23, 0xffff0000, v221
	v_lshlrev_b32_e32 v30, 16, v218
	v_and_b32_e32 v31, 0xffff0000, v218
	v_lshlrev_b32_e32 v20, 16, v219
	v_and_b32_e32 v21, 0xffff0000, v219
	v_lshlrev_b32_e32 v34, 16, v222
	v_and_b32_e32 v35, 0xffff0000, v222
	v_lshlrev_b32_e32 v24, 16, v223
	v_and_b32_e32 v25, 0xffff0000, v223
	v_pk_fma_f32 v[14:15], v[14:15], 0.5, v[18:19] op_sel_hi:[1,0,1]
	v_pk_fma_f32 v[12:13], v[12:13], 0.5, v[28:29] op_sel_hi:[1,0,1]
	v_pk_fma_f32 v[6:7], v[6:7], 0.5, v[22:23] op_sel_hi:[1,0,1]
	v_pk_fma_f32 v[4:5], v[4:5], 0.5, v[32:33] op_sel_hi:[1,0,1]
	v_pk_fma_f32 v[10:11], v[10:11], 0.5, v[20:21] op_sel_hi:[1,0,1]
	v_pk_fma_f32 v[8:9], v[8:9], 0.5, v[30:31] op_sel_hi:[1,0,1]
	v_pk_fma_f32 v[18:19], v[2:3], 0.5, v[24:25] op_sel_hi:[1,0,1]
	v_pk_fma_f32 v[20:21], v[0:1], 0.5, v[34:35] op_sel_hi:[1,0,1]
	v_mul_f32_e32 v2, v13, v13
	v_mul_f32_e32 v3, v15, v15
	v_mul_f32_e32 v22, v5, v5
	v_mul_f32_e32 v23, v7, v7
	v_cvt_pk_bf16_f32 v0, v12, v13
	v_mul_f32_e32 v13, v9, v9
	v_mul_f32_e32 v24, v21, v21
	v_fmac_f32_e32 v2, v12, v12
	v_fmac_f32_e32 v3, v14, v14
	v_fmac_f32_e32 v22, v4, v4
	v_fmac_f32_e32 v23, v6, v6
	v_cvt_pk_bf16_f32 v1, v14, v15
	v_mul_f32_e32 v15, v11, v11
	v_mul_f32_e32 v25, v19, v19
	v_fmac_f32_e32 v13, v8, v8
	v_fmac_f32_e32 v24, v20, v20
	v_add_f32_e32 v2, v2, v3
	v_add_f32_e32 v3, v22, v23
	v_fmac_f32_e32 v15, v10, v10
	v_fmac_f32_e32 v25, v18, v18
	v_add_f32_e32 v2, v13, v2
	v_add_f32_e32 v3, v24, v3
	v_add_f32_e32 v2, v15, v2
	v_add_f32_e32 v3, v25, v3
	v_add_f32_e32 v12, v2, v3
	ds_bpermute_b32 v13, v156, v12
	v_cvt_pk_bf16_f32 v2, v8, v9
	v_cvt_pk_bf16_f32 v3, v10, v11
	global_store_dwordx4 v[26:27], v[0:3], off
	s_waitcnt lgkmcnt(0)
	s_nop 0
	v_add_f32_e32 v0, v12, v13
	ds_bpermute_b32 v1, v155, v0
	v_cvt_pk_bf16_f32 v2, v4, v5
	v_cvt_pk_bf16_f32 v3, v6, v7
	v_cvt_pk_bf16_f32 v4, v20, v21
	v_cvt_pk_bf16_f32 v5, v18, v19
	global_store_dwordx4 v[26:27], v[2:5], off offset:256
	s_and_saveexec_b64 s[50:51], s[10:11]
	s_cbranch_execz .LBB0_1054
	s_waitcnt lgkmcnt(0)
	v_add_f32_e32 v0, v0, v1
	v_mul_f32_e32 v0, 0x4f800000, v0
	v_trunc_f32_e32 v0, v0
	v_mul_f32_e64 v1, |v0|, s63
	v_floor_f32_e32 v1, v1
	v_fma_f32 v2, v1, s64, |v0|
	v_cvt_u32_f32_e32 v2, v2
	v_cvt_u32_f32_e32 v1, v1
	v_ashrrev_i32_e32 v3, 31, v0
	v_xor_b32_e32 v0, v2, v3
	v_xor_b32_e32 v1, v1, v3
	v_sub_co_u32_e32 v0, vcc, v0, v3
	s_nop 1
	v_subb_co_u32_e32 v1, vcc, v1, v3, vcc
	v_lshl_add_u64 v[2:3], v[16:17], 3, s[36:37]
	global_atomic_add_x2 v[2:3], v[0:1], off

; #define PG8_STAGE(bufoff, gbase, voff) do { _Pragma("unroll") for (int _i = 0; _i < 2; ++_i) \
;         __builtin_amdgcn_global_load_lds((const unsigned*)((const char*)(gbase) + (voff)[_i]), (PG8_LAS unsigned*)(lds + (bufoff) + ldsw + _i * 8192), 16, 0, 0); } while (0)
; #define PG8_LDA(dst, b, h) do { _Pragma("unroll") for (int m = 0; m < 4; ++m) _Pragma("unroll") for (int k = 0; k < 2; ++k) dst[m][k] = *(const PG8_LAS bf16x8*)(lds + PG8_SA(b, h) + aoff + m * 2048 + k * 1024); } while (0)
; #define PG8_LDB(dst, b, h) do { _Pragma("unroll") for (int n = 0; n < 2; ++n) _Pragma("unroll") for (int k = 0; k < 2; ++k) dst[n][k] = *(const PG8_LAS bf16x8*)(lds + PG8_SB(b, h) + boff + n * 2048 + k * 1024); } while (0)
; #define PG8_MMA(ai, bj, At, Bt) do { __builtin_amdgcn_s_setprio(1); _Pragma("unroll") for (int m = 0; m < 4; ++m) _Pragma("unroll") for (int n = 0; n < 2; ++n) _Pragma("unroll") for (int k = 0; k < 2; ++k) \
;         acc[ai][bj][m][n] = __builtin_amdgcn_mfma_f32_16x16x32_bf16(Bt[n][k], At[m][k], acc[ai][bj][m][n], 0, 0, 0); __builtin_amdgcn_s_setprio(0); } while (0)
; #define PG8_WAIT_V(n) asm volatile("s_waitcnt vmcnt(" #n ")" ::: "memory")
; #define PG8_WAIT_L(n) asm volatile("s_waitcnt lgkmcnt(" #n ")" ::: "memory")
; #define PG8_BAR __builtin_amdgcn_s_barrier()
; #define PG8_SCHED __builtin_amdgcn_sched_barrier(0)
; template <class Epi, class Sched, bool ALIGN_EPI = false, bool SP2 = false>
; __device__ __forceinline__ void gemm_phase(PG8_LAS unsigned char* lds, const Gemm g, const Sched& S, const Epi& E) {
;     ...
;             PG8_LDB(B0, 0, 0); PG8_LDB(B1, 0, 1); PG8_SCHED; PG8_LDA(At, 0, 0); PG8_STAGE(PG8_SA(1, 1), a1 + hstep, voffA);
;             PG8_WAIT_V(8); PG8_WAIT_L(0); PG8_BAR; PG8_MMA(0, 0, At, B0); PG8_MMA(0, 1, At, B1); PG8_BAR; PG8_SCHED;
;             PG8_LDA(At, 0, 1); PG8_STAGE(PG8_SB(0, 0), b2, voffB); PG8_STAGE(PG8_SB(0, 1), b2 + hstep, voffB); PG8_STAGE(PG8_SA(0, 0), a2, voffA);
;             PG8_WAIT_V(8); PG8_WAIT_L(0); PG8_BAR; PG8_MMA(1, 0, At, B0); PG8_MMA(1, 1, At, B1); PG8_BAR; PG8_SCHED;
.LBB0_1197:
	ds_read_b128 v[144:147], v151
	ds_read_b128 v[156:159], v151 offset:1024
	ds_read_b128 v[160:163], v151 offset:2048
	ds_read_b128 v[164:167], v151 offset:3072
	ds_read_b128 v[168:171], v152
	ds_read_b128 v[172:175], v152 offset:1024
	ds_read_b128 v[176:179], v152 offset:2048
	ds_read_b128 v[182:185], v152 offset:3072
	s_add_u32 s52, s50, 0x100
	s_addc_u32 s53, s51, 0
	s_cmp_eq_u32 s84, 40
	s_cselect_b32 s57, s1, s53
	s_cselect_b32 s56, s0, s52
	s_cselect_b32 s55, s49, s83
	s_cselect_b32 s54, s48, s82
	v_lshl_add_u64 v[224:225], s[50:51], 0, v[136:137]
	s_add_i32 m0, s34, 0xc000
	ds_read_b128 v[186:189], v153
	ds_read_b128 v[190:193], v153 offset:1024
	ds_read_b128 v[194:197], v153 offset:2048
	ds_read_b128 v[198:201], v153 offset:3072
	ds_read_b128 v[208:211], v153 offset:4096
	ds_read_b128 v[212:215], v153 offset:5120
	ds_read_b128 v[216:219], v153 offset:6144
	ds_read_b128 v[220:223], v153 offset:7168
	global_load_lds_dwordx4 v[224:225], off
	v_lshl_add_u64 v[224:225], s[50:51], 0, v[138:139]
	s_add_i32 m0, s34, 0xe000
	s_nop 0
	global_load_lds_dwordx4 v[224:225], off
	s_waitcnt vmcnt(8)
	s_waitcnt lgkmcnt(0)
	s_barrier
	s_setprio 1
	s_waitcnt lgkmcnt(0)
	v_mfma_f32_16x16x32_bf16 v[124:127], v[144:147], v[186:189], v[124:127]
	v_mfma_f32_16x16x32_bf16 v[120:123], v[160:163], v[186:189], v[120:123]
	v_mfma_f32_16x16x32_bf16 v[108:111], v[144:147], v[194:197], v[108:111]
	v_mfma_f32_16x16x32_bf16 v[104:107], v[160:163], v[194:197], v[104:107]
	v_mfma_f32_16x16x32_bf16 v[92:95], v[144:147], v[208:211], v[92:95]
	v_mfma_f32_16x16x32_bf16 v[88:91], v[160:163], v[208:211], v[88:91]
	v_mfma_f32_16x16x32_bf16 v[76:79], v[144:147], v[216:219], v[76:79]
	v_mfma_f32_16x16x32_bf16 v[72:75], v[160:163], v[216:219], v[72:75]
	v_mfma_f32_16x16x32_bf16 v[124:127], v[156:159], v[190:193], v[124:127]
	v_mfma_f32_16x16x32_bf16 v[120:123], v[164:167], v[190:193], v[120:123]
	v_mfma_f32_16x16x32_bf16 v[108:111], v[156:159], v[198:201], v[108:111]
	v_mfma_f32_16x16x32_bf16 v[104:107], v[164:167], v[198:201], v[104:107]
	v_mfma_f32_16x16x32_bf16 v[92:95], v[156:159], v[212:215], v[92:95]
	v_mfma_f32_16x16x32_bf16 v[88:91], v[164:167], v[212:215], v[88:91]
	v_mfma_f32_16x16x32_bf16 v[76:79], v[156:159], v[220:223], v[76:79]
	v_mfma_f32_16x16x32_bf16 v[72:75], v[164:167], v[220:223], v[72:75]
	s_setprio 0
	s_setprio 1
	v_mfma_f32_16x16x32_bf16 v[116:119], v[168:171], v[186:189], v[116:119]
	v_mfma_f32_16x16x32_bf16 v[112:115], v[176:179], v[186:189], v[112:115]
	v_mfma_f32_16x16x32_bf16 v[100:103], v[168:171], v[194:197], v[100:103]
	v_mfma_f32_16x16x32_bf16 v[96:99], v[176:179], v[194:197], v[96:99]
	v_mfma_f32_16x16x32_bf16 v[84:87], v[168:171], v[208:211], v[84:87]
	v_mfma_f32_16x16x32_bf16 v[80:83], v[176:179], v[208:211], v[80:83]
	v_mfma_f32_16x16x32_bf16 v[68:71], v[168:171], v[216:219], v[68:71]
	v_mfma_f32_16x16x32_bf16 v[64:67], v[176:179], v[216:219], v[64:67]
	v_mfma_f32_16x16x32_bf16 v[116:119], v[172:175], v[190:193], v[116:119]
	v_mfma_f32_16x16x32_bf16 v[112:115], v[182:185], v[190:193], v[112:115]
	v_mfma_f32_16x16x32_bf16 v[100:103], v[172:175], v[198:201], v[100:103]
	v_mfma_f32_16x16x32_bf16 v[96:99], v[182:185], v[198:201], v[96:99]
	v_mfma_f32_16x16x32_bf16 v[84:87], v[172:175], v[212:215], v[84:87]
	v_mfma_f32_16x16x32_bf16 v[80:83], v[182:185], v[212:215], v[80:83]
	v_mfma_f32_16x16x32_bf16 v[68:71], v[172:175], v[220:223], v[68:71]
	v_mfma_f32_16x16x32_bf16 v[64:67], v[182:185], v[220:223], v[64:67]
	s_setprio 0
	s_barrier
	s_add_i32 s50, s64, s33
	v_lshl_add_u64 v[224:225], s[54:55], 0, v[130:131]
	s_mov_b32 m0, s50
	ds_read_b128 v[186:189], v153 offset:16384
	ds_read_b128 v[190:193], v153 offset:17408
	ds_read_b128 v[194:197], v153 offset:18432
	ds_read_b128 v[198:201], v153 offset:19456
	ds_read_b128 v[208:211], v153 offset:20480
	ds_read_b128 v[212:215], v153 offset:21504
	ds_read_b128 v[216:219], v153 offset:22528
	ds_read_b128 v[220:223], v153 offset:23552
	global_load_lds_dwordx4 v[224:225], off
	s_add_i32 m0, s50, 0x2000
	s_add_u32 s50, s54, 0xb0000
	v_lshl_add_u64 v[226:227], s[54:55], 0, v[134:135]
	s_addc_u32 s51, s55, 0
	s_add_i32 s78, s65, s33
	global_load_lds_dwordx4 v[226:227], off
	v_lshl_add_u64 v[228:229], s[50:51], 0, v[130:131]
	s_mov_b32 m0, s78
	v_lshl_add_u64 v[230:231], s[56:57], 0, v[132:133]
	global_load_lds_dwordx4 v[228:229], off
	v_lshl_add_u64 v[228:229], s[50:51], 0, v[134:135]
	s_add_i32 m0, s78, 0x2000
	s_nop 0
	global_load_lds_dwordx4 v[228:229], off
	v_lshl_add_u64 v[228:229], s[56:57], 0, v[128:129]
	s_mov_b32 m0, s34
	s_nop 0
	global_load_lds_dwordx4 v[228:229], off
	s_mov_b32 m0, s58
	s_nop 0
	global_load_lds_dwordx4 v[230:231], off
	s_waitcnt vmcnt(8)
	s_waitcnt lgkmcnt(0)
	s_barrier
; #define PG8_STAGE(bufoff, gbase, voff) do { _Pragma("unroll") for (int _i = 0; _i < 2; ++_i) \
;         __builtin_amdgcn_global_load_lds((const unsigned*)((const char*)(gbase) + (voff)[_i]), (PG8_LAS unsigned*)(lds + (bufoff) + ldsw + _i * 8192), 16, 0, 0); } while (0)
; #define PG8_LDA(dst, b, h) do { _Pragma("unroll") for (int m = 0; m < 4; ++m) _Pragma("unroll") for (int k = 0; k < 2; ++k) dst[m][k] = *(const PG8_LAS bf16x8*)(lds + PG8_SA(b, h) + aoff + m * 2048 + k * 1024); } while (0)
; #define PG8_LDB(dst, b, h) do { _Pragma("unroll") for (int n = 0; n < 2; ++n) _Pragma("unroll") for (int k = 0; k < 2; ++k) dst[n][k] = *(const PG8_LAS bf16x8*)(lds + PG8_SB(b, h) + boff + n * 2048 + k * 1024); } while (0)
; #define PG8_MMA(ai, bj, At, Bt) do { __builtin_amdgcn_s_setprio(1); _Pragma("unroll") for (int m = 0; m < 4; ++m) _Pragma("unroll") for (int n = 0; n < 2; ++n) _Pragma("unroll") for (int k = 0; k < 2; ++k) \
;         acc[ai][bj][m][n] = __builtin_amdgcn_mfma_f32_16x16x32_bf16(Bt[n][k], At[m][k], acc[ai][bj][m][n], 0, 0, 0); __builtin_amdgcn_s_setprio(0); } while (0)
; #define PG8_WAIT_V(n) asm volatile("s_waitcnt vmcnt(" #n ")" ::: "memory")
; #define PG8_WAIT_L(n) asm volatile("s_waitcnt lgkmcnt(" #n ")" ::: "memory")
; #define PG8_BAR __builtin_amdgcn_s_barrier()
; #define PG8_SCHED __builtin_amdgcn_sched_barrier(0)
; template <class Epi, class Sched, bool ALIGN_EPI = false, bool SP2 = false>
; __device__ __forceinline__ void gemm_phase(PG8_LAS unsigned char* lds, const Gemm g, const Sched& S, const Epi& E) {
;     ...
;             PG8_LDA(At, 0, 1); PG8_STAGE(PG8_SB(0, 0), b2, voffB); PG8_STAGE(PG8_SB(0, 1), b2 + hstep, voffB); PG8_STAGE(PG8_SA(0, 0), a2, voffA);
;             PG8_WAIT_V(8); PG8_WAIT_L(0); PG8_BAR; PG8_MMA(1, 0, At, B0); PG8_MMA(1, 1, At, B1); PG8_BAR; PG8_SCHED;
;             PG8_LDB(B0, 1, 0); PG8_LDB(B1, 1, 1); PG8_SCHED; PG8_LDA(At, 1, 0); PG8_STAGE(PG8_SA(0, 1), a2 + hstep, voffA);
;             PG8_WAIT_V(8); PG8_WAIT_L(0); PG8_BAR; PG8_MMA(0, 0, At, B0); PG8_MMA(0, 1, At, B1); PG8_BAR; PG8_SCHED;
	s_setprio 1
	s_waitcnt lgkmcnt(0)
	v_mfma_f32_16x16x32_bf16 v[60:63], v[144:147], v[186:189], v[60:63]
	v_mfma_f32_16x16x32_bf16 v[56:59], v[160:163], v[186:189], v[56:59]
	v_mfma_f32_16x16x32_bf16 v[44:47], v[144:147], v[194:197], v[44:47]
	v_mfma_f32_16x16x32_bf16 v[40:43], v[160:163], v[194:197], v[40:43]
	v_mfma_f32_16x16x32_bf16 v[28:31], v[144:147], v[208:211], v[28:31]
	v_mfma_f32_16x16x32_bf16 v[24:27], v[160:163], v[208:211], v[24:27]
	v_mfma_f32_16x16x32_bf16 v[12:15], v[144:147], v[216:219], v[12:15]
	v_mfma_f32_16x16x32_bf16 v[8:11], v[160:163], v[216:219], v[8:11]
	v_mfma_f32_16x16x32_bf16 v[60:63], v[156:159], v[190:193], v[60:63]
	v_mfma_f32_16x16x32_bf16 v[56:59], v[164:167], v[190:193], v[56:59]
	v_mfma_f32_16x16x32_bf16 v[44:47], v[156:159], v[198:201], v[44:47]
	v_mfma_f32_16x16x32_bf16 v[40:43], v[164:167], v[198:201], v[40:43]
	v_mfma_f32_16x16x32_bf16 v[28:31], v[156:159], v[212:215], v[28:31]
	v_mfma_f32_16x16x32_bf16 v[24:27], v[164:167], v[212:215], v[24:27]
	v_mfma_f32_16x16x32_bf16 v[12:15], v[156:159], v[220:223], v[12:15]
	v_mfma_f32_16x16x32_bf16 v[8:11], v[164:167], v[220:223], v[8:11]
	s_setprio 0
	s_setprio 1
	v_mfma_f32_16x16x32_bf16 v[52:55], v[168:171], v[186:189], v[52:55]
	v_mfma_f32_16x16x32_bf16 v[48:51], v[176:179], v[186:189], v[48:51]
	v_mfma_f32_16x16x32_bf16 v[36:39], v[168:171], v[194:197], v[36:39]
	v_mfma_f32_16x16x32_bf16 v[32:35], v[176:179], v[194:197], v[32:35]
	v_mfma_f32_16x16x32_bf16 v[20:23], v[168:171], v[208:211], v[20:23]
	v_mfma_f32_16x16x32_bf16 v[16:19], v[176:179], v[208:211], v[16:19]
	v_mfma_f32_16x16x32_bf16 v[4:7], v[168:171], v[216:219], v[4:7]
	v_mfma_f32_16x16x32_bf16 v[0:3], v[176:179], v[216:219], v[0:3]
	v_mfma_f32_16x16x32_bf16 v[52:55], v[172:175], v[190:193], v[52:55]
	v_mfma_f32_16x16x32_bf16 v[48:51], v[182:185], v[190:193], v[48:51]
	v_mfma_f32_16x16x32_bf16 v[36:39], v[172:175], v[198:201], v[36:39]
	v_mfma_f32_16x16x32_bf16 v[32:35], v[182:185], v[198:201], v[32:35]
	v_mfma_f32_16x16x32_bf16 v[20:23], v[172:175], v[212:215], v[20:23]
	v_mfma_f32_16x16x32_bf16 v[16:19], v[182:185], v[212:215], v[16:19]
	v_mfma_f32_16x16x32_bf16 v[4:7], v[172:175], v[220:223], v[4:7]
	v_mfma_f32_16x16x32_bf16 v[0:3], v[182:185], v[220:223], v[0:3]
	s_setprio 0
	s_barrier
	s_add_i32 s78, 0, 0x18000
	v_add_u32_e32 v155, s78, v149
	s_add_i32 s79, 0, 0x1c000
	ds_read_b128 v[144:147], v155
	ds_read_b128 v[156:159], v155 offset:1024
	ds_read_b128 v[160:163], v155 offset:2048
	ds_read_b128 v[164:167], v155 offset:3072
	v_add_u32_e32 v155, s79, v149
	ds_read_b128 v[168:171], v155
	ds_read_b128 v[172:175], v155 offset:1024
	ds_read_b128 v[176:179], v155 offset:2048
	ds_read_b128 v[182:185], v155 offset:3072
	s_add_u32 s50, s56, 0xb0000
	s_addc_u32 s51, s57, 0
	s_mov_b32 m0, s59
	v_lshl_add_u64 v[232:233], s[50:51], 0, v[128:129]
	ds_read_b128 v[186:189], v153 offset:32768
	ds_read_b128 v[190:193], v153 offset:33792
	ds_read_b128 v[194:197], v153 offset:34816
	ds_read_b128 v[198:201], v153 offset:35840
	ds_read_b128 v[208:211], v153 offset:36864
	ds_read_b128 v[212:215], v153 offset:37888
	ds_read_b128 v[216:219], v153 offset:38912
	ds_read_b128 v[220:223], v153 offset:39936
	global_load_lds_dwordx4 v[232:233], off
	v_lshl_add_u64 v[232:233], s[50:51], 0, v[132:133]
	s_mov_b32 m0, s60
	s_nop 0
	global_load_lds_dwordx4 v[232:233], off
	s_waitcnt vmcnt(8)
	s_waitcnt lgkmcnt(0)
	s_barrier
	s_setprio 1
	s_waitcnt lgkmcnt(0)
	v_mfma_f32_16x16x32_bf16 v[124:127], v[144:147], v[186:189], v[124:127]
	v_mfma_f32_16x16x32_bf16 v[120:123], v[160:163], v[186:189], v[120:123]
	v_mfma_f32_16x16x32_bf16 v[108:111], v[144:147], v[194:197], v[108:111]
	v_mfma_f32_16x16x32_bf16 v[104:107], v[160:163], v[194:197], v[104:107]
	v_mfma_f32_16x16x32_bf16 v[92:95], v[144:147], v[208:211], v[92:95]
	v_mfma_f32_16x16x32_bf16 v[88:91], v[160:163], v[208:211], v[88:91]
	v_mfma_f32_16x16x32_bf16 v[76:79], v[144:147], v[216:219], v[76:79]
	v_mfma_f32_16x16x32_bf16 v[72:75], v[160:163], v[216:219], v[72:75]
	v_mfma_f32_16x16x32_bf16 v[124:127], v[156:159], v[190:193], v[124:127]
	v_mfma_f32_16x16x32_bf16 v[120:123], v[164:167], v[190:193], v[120:123]
	v_mfma_f32_16x16x32_bf16 v[108:111], v[156:159], v[198:201], v[108:111]
	v_mfma_f32_16x16x32_bf16 v[104:107], v[164:167], v[198:201], v[104:107]
	v_mfma_f32_16x16x32_bf16 v[92:95], v[156:159], v[212:215], v[92:95]
	v_mfma_f32_16x16x32_bf16 v[88:91], v[164:167], v[212:215], v[88:91]
	v_mfma_f32_16x16x32_bf16 v[76:79], v[156:159], v[220:223], v[76:79]
	v_mfma_f32_16x16x32_bf16 v[72:75], v[164:167], v[220:223], v[72:75]
	s_setprio 0
	s_setprio 1
	v_mfma_f32_16x16x32_bf16 v[116:119], v[168:171], v[186:189], v[116:119]
	v_mfma_f32_16x16x32_bf16 v[112:115], v[176:179], v[186:189], v[112:115]
	v_mfma_f32_16x16x32_bf16 v[100:103], v[168:171], v[194:197], v[100:103]
	v_mfma_f32_16x16x32_bf16 v[96:99], v[176:179], v[194:197], v[96:99]
	v_mfma_f32_16x16x32_bf16 v[84:87], v[168:171], v[208:211], v[84:87]
	v_mfma_f32_16x16x32_bf16 v[80:83], v[176:179], v[208:211], v[80:83]
	v_mfma_f32_16x16x32_bf16 v[68:71], v[168:171], v[216:219], v[68:71]
	v_mfma_f32_16x16x32_bf16 v[64:67], v[176:179], v[216:219], v[64:67]
	v_mfma_f32_16x16x32_bf16 v[116:119], v[172:175], v[190:193], v[116:119]
	v_mfma_f32_16x16x32_bf16 v[112:115], v[182:185], v[190:193], v[112:115]
	v_mfma_f32_16x16x32_bf16 v[100:103], v[172:175], v[198:201], v[100:103]
	v_mfma_f32_16x16x32_bf16 v[96:99], v[182:185], v[198:201], v[96:99]
	v_mfma_f32_16x16x32_bf16 v[84:87], v[172:175], v[212:215], v[84:87]
	v_mfma_f32_16x16x32_bf16 v[80:83], v[182:185], v[212:215], v[80:83]
	v_mfma_f32_16x16x32_bf16 v[68:71], v[172:175], v[220:223], v[68:71]
	v_mfma_f32_16x16x32_bf16 v[64:67], v[182:185], v[220:223], v[64:67]
	s_setprio 0
	s_barrier
; #define PG8_STAGE(bufoff, gbase, voff) do { _Pragma("unroll") for (int _i = 0; _i < 2; ++_i) \
;         __builtin_amdgcn_global_load_lds((const unsigned*)((const char*)(gbase) + (voff)[_i]), (PG8_LAS unsigned*)(lds + (bufoff) + ldsw + _i * 8192), 16, 0, 0); } while (0)
; #define PG8_LDA(dst, b, h) do { _Pragma("unroll") for (int m = 0; m < 4; ++m) _Pragma("unroll") for (int k = 0; k < 2; ++k) dst[m][k] = *(const PG8_LAS bf16x8*)(lds + PG8_SA(b, h) + aoff + m * 2048 + k * 1024); } while (0)
; #define PG8_MMA(ai, bj, At, Bt) do { __builtin_amdgcn_s_setprio(1); _Pragma("unroll") for (int m = 0; m < 4; ++m) _Pragma("unroll") for (int n = 0; n < 2; ++n) _Pragma("unroll") for (int k = 0; k < 2; ++k) \
;         acc[ai][bj][m][n] = __builtin_amdgcn_mfma_f32_16x16x32_bf16(Bt[n][k], At[m][k], acc[ai][bj][m][n], 0, 0, 0); __builtin_amdgcn_s_setprio(0); } while (0)
; #define PG8_WAIT_V(n) asm volatile("s_waitcnt vmcnt(" #n ")" ::: "memory")
; #define PG8_WAIT_L(n) asm volatile("s_waitcnt lgkmcnt(" #n ")" ::: "memory")
; #define PG8_BAR __builtin_amdgcn_s_barrier()
; #define PG8_SCHED __builtin_amdgcn_sched_barrier(0)
;     __device__ __forceinline__ void operator()(const f32x4 (&acc)[2][2][4][2], const Unit& u, int wr, int wc, int fr, int fq) const {
;     ...
;             for (int m = 0; m < 4; ++m) { const int row = row0 + ai * HALF + m * 16; const size_t off = (size_t)row * 1024 + col0; float s = 0.f;
; #pragma unroll
;                 for (int bj = 0; bj < 2; ++bj) { f32x4 a0, a1;
;                     if (xin32) { const float* p = xin32 + off + bj * HALF; a0 = *(const f32x4*)p; a1 = *(const f32x4*)(p + 4); }
;                     else { const u32x4 w = *(const u32x4*)(xb + off + bj * HALF);
; template <class Epi, class Sched, bool ALIGN_EPI = false, bool SP2 = false>
; __device__ __forceinline__ void gemm_phase(PG8_LAS unsigned char* lds, const Gemm g, const Sched& S, const Epi& E) {
;     ...
;             PG8_LDA(At, 1, 1); PG8_STAGE(PG8_SB(1, 0), b3, voffB); PG8_STAGE(PG8_SB(1, 1), b3 + hstep, voffB); PG8_STAGE(PG8_SA(1, 0), a3, voffA);
;             PG8_WAIT_V(8); PG8_WAIT_L(0); PG8_BAR; PG8_MMA(1, 0, At, B0); PG8_MMA(1, 1, At, B1); PG8_BAR; PG8_SCHED;
	s_add_i32 s50, s78, s33
	v_lshl_add_u64 v[224:225], v[224:225], 0, s[42:43]
	s_mov_b32 m0, s50
	ds_read_b128 v[186:189], v153 offset:49152
	ds_read_b128 v[190:193], v153 offset:50176
	ds_read_b128 v[194:197], v153 offset:51200
	ds_read_b128 v[198:201], v153 offset:52224
	ds_read_b128 v[208:211], v153 offset:53248
	ds_read_b128 v[212:215], v153 offset:54272
	ds_read_b128 v[216:219], v153 offset:55296
	ds_read_b128 v[220:223], v153 offset:56320
	global_load_lds_dwordx4 v[224:225], off
	s_add_i32 m0, s50, 0x2000
	s_add_u32 s50, s54, 0xb0080
	v_lshl_add_u64 v[224:225], v[226:227], 0, s[42:43]
	s_addc_u32 s51, s55, 0
	s_add_i32 s54, s79, s33
	global_load_lds_dwordx4 v[224:225], off
	v_lshl_add_u64 v[224:225], s[50:51], 0, v[130:131]
	s_mov_b32 m0, s54
	s_nop 0
	global_load_lds_dwordx4 v[224:225], off
	v_lshl_add_u64 v[224:225], s[50:51], 0, v[134:135]
	s_add_i32 m0, s54, 0x2000
	s_nop 0
	global_load_lds_dwordx4 v[224:225], off
	v_lshl_add_u64 v[224:225], v[228:229], 0, s[42:43]
	s_mov_b32 m0, s62
	s_nop 0
	global_load_lds_dwordx4 v[224:225], off
	v_lshl_add_u64 v[224:225], v[230:231], 0, s[42:43]
	s_mov_b32 m0, s63
	s_nop 0
	global_load_lds_dwordx4 v[224:225], off
	s_waitcnt vmcnt(8)
	s_waitcnt lgkmcnt(0)
	s_barrier
	s_setprio 1
	s_waitcnt lgkmcnt(0)
	v_mfma_f32_16x16x32_bf16 v[60:63], v[144:147], v[186:189], v[60:63]
	v_mfma_f32_16x16x32_bf16 v[56:59], v[160:163], v[186:189], v[56:59]
	v_mfma_f32_16x16x32_bf16 v[44:47], v[144:147], v[194:197], v[44:47]
	v_mfma_f32_16x16x32_bf16 v[40:43], v[160:163], v[194:197], v[40:43]
	v_mfma_f32_16x16x32_bf16 v[28:31], v[144:147], v[208:211], v[28:31]
	v_mfma_f32_16x16x32_bf16 v[24:27], v[160:163], v[208:211], v[24:27]
	v_mfma_f32_16x16x32_bf16 v[12:15], v[144:147], v[216:219], v[12:15]
	v_mfma_f32_16x16x32_bf16 v[8:11], v[160:163], v[216:219], v[8:11]
	v_mfma_f32_16x16x32_bf16 v[60:63], v[156:159], v[190:193], v[60:63]
	v_mfma_f32_16x16x32_bf16 v[56:59], v[164:167], v[190:193], v[56:59]
	v_mfma_f32_16x16x32_bf16 v[44:47], v[156:159], v[198:201], v[44:47]
	v_mfma_f32_16x16x32_bf16 v[40:43], v[164:167], v[198:201], v[40:43]
	v_mfma_f32_16x16x32_bf16 v[28:31], v[156:159], v[212:215], v[28:31]
	v_mfma_f32_16x16x32_bf16 v[24:27], v[164:167], v[212:215], v[24:27]
	v_mfma_f32_16x16x32_bf16 v[12:15], v[156:159], v[220:223], v[12:15]
	v_mfma_f32_16x16x32_bf16 v[8:11], v[164:167], v[220:223], v[8:11]
	s_setprio 0
	s_setprio 1
	v_mfma_f32_16x16x32_bf16 v[52:55], v[168:171], v[186:189], v[52:55]
	v_mfma_f32_16x16x32_bf16 v[48:51], v[176:179], v[186:189], v[48:51]
	v_mfma_f32_16x16x32_bf16 v[36:39], v[168:171], v[194:197], v[36:39]
	v_mfma_f32_16x16x32_bf16 v[32:35], v[176:179], v[194:197], v[32:35]
	v_mfma_f32_16x16x32_bf16 v[20:23], v[168:171], v[208:211], v[20:23]
	v_mfma_f32_16x16x32_bf16 v[16:19], v[176:179], v[208:211], v[16:19]
	v_mfma_f32_16x16x32_bf16 v[4:7], v[168:171], v[216:219], v[4:7]
	v_mfma_f32_16x16x32_bf16 v[0:3], v[176:179], v[216:219], v[0:3]
	v_mfma_f32_16x16x32_bf16 v[52:55], v[172:175], v[190:193], v[52:55]
	v_mfma_f32_16x16x32_bf16 v[48:51], v[182:185], v[190:193], v[48:51]
	v_mfma_f32_16x16x32_bf16 v[36:39], v[172:175], v[198:201], v[36:39]
	v_mfma_f32_16x16x32_bf16 v[32:35], v[182:185], v[198:201], v[32:35]
	v_mfma_f32_16x16x32_bf16 v[20:23], v[172:175], v[212:215], v[20:23]
	v_mfma_f32_16x16x32_bf16 v[16:19], v[182:185], v[212:215], v[16:19]
	v_mfma_f32_16x16x32_bf16 v[4:7], v[172:175], v[220:223], v[4:7]
	v_mfma_f32_16x16x32_bf16 v[0:3], v[182:185], v[220:223], v[0:3]
	s_setprio 0
	s_barrier
	s_add_i32 s84, s84, 2
	s_add_u32 s82, s82, 0x100
	s_addc_u32 s83, s83, 0
	s_cmp_gt_u32 s84, 41
	s_mov_b64 s[50:51], s[52:53]
	s_cbranch_scc0 .LBB0_1197
	v_lshl_add_u32 v146, s77, 8, v148
	v_ashrrev_i32_e32 v147, 31, v146
	v_lshl_or_b32 v144, s76, 8, v150
	v_lshlrev_b64 v[156:157], 11, v[146:147]
	v_ashrrev_i32_e32 v145, 31, v144
	v_lshl_add_u64 v[156:157], s[22:23], 0, v[156:157]
	v_lshl_add_u64 v[166:167], v[144:145], 1, v[156:157]
	s_mov_b64 s[98:99], 0x8000
	s_mov_b64 s[100:101], 0x28000
	global_load_dwordx4 v[182:185], v[166:167], off
	global_load_dwordx4 v[186:189], v[166:167], off offset:256
	v_lshl_add_u64 v[198:199], v[166:167], 0, s[98:99]
	global_load_dwordx4 v[190:193], v[198:199], off
	global_load_dwordx4 v[194:197], v[198:199], off offset:256
	v_lshl_add_u64 v[198:199], v[198:199], 0, s[98:99]
	global_load_dwordx4 v[208:211], v[198:199], off
	global_load_dwordx4 v[212:215], v[198:199], off offset:256
	v_lshl_add_u64 v[198:199], v[198:199], 0, s[98:99]
	global_load_dwordx4 v[216:219], v[198:199], off
	global_load_dwordx4 v[220:223], v[198:199], off offset:256
	v_lshl_add_u64 v[198:199], v[198:199], 0, s[100:101]
	s_and_b64 vcc, exec, s[44:45]
	s_cbranch_vccz .LBB0_1200
	s_barrier
; __device__ __forceinline__ void fx_add(float* p, size_t idx, float s) { atomicAdd((unsigned long long*)p + idx, (unsigned long long)(long long)(s * 4294967296.0f)); }
; __device__ __forceinline__ unsigned cvtpk(float lo, float hi) { f32x2v_ v = {lo, hi}; bf16x2v_ b = __builtin_convertvector(v, bf16x2v_); return __builtin_bit_cast(unsigned, b); }
;     __device__ __forceinline__ void operator()(const f32x4 (&acc)[2][2][4][2], const Unit& u, int wr, int wc, int fr, int fq) const {
;     ...
;             for (int m = 0; m < 4; ++m) { const int row = row0 + ai * HALF + m * 16; const size_t off = (size_t)row * 1024 + col0; float s = 0.f;
; #pragma unroll
;                 for (int bj = 0; bj < 2; ++bj) { f32x4 a0, a1;
;                     if (xin32) { const float* p = xin32 + off + bj * HALF; a0 = *(const f32x4*)p; a1 = *(const f32x4*)(p + 4); }
;                     else { const u32x4 w = *(const u32x4*)(xb + off + bj * HALF);
;                         a0 = (f32x4){__uint_as_float(w.x << 16), __uint_as_float(w.x & 0xffff0000u), __uint_as_float(w.y << 16), __uint_as_float(w.y & 0xffff0000u)};
;                         a1 = (f32x4){__uint_as_float(w.z << 16), __uint_as_float(w.z & 0xffff0000u), __uint_as_float(w.w << 16), __uint_as_float(w.w & 0xffff0000u)}; }
;                     const f32x4 v0 = a0 + acc[ai][bj][m][0] * alpha, v1 = a1 + acc[ai][bj][m][1] * alpha;
;                     u32x4 w; w.x = cvtpk(v0[0], v0[1]); w.y = cvtpk(v0[2], v0[3]); w.z = cvtpk(v1[0], v1[1]); w.w = cvtpk(v1[2], v1[3]);
;                     *(u32x4*)(xb + off + bj * HALF) = w;
;                     s += (v0[0] * v0[0] + v0[1] * v0[1]) + (v0[2] * v0[2] + v0[3] * v0[3]) + (v1[0] * v1[0] + v1[1] * v1[1]) + (v1[2] * v1[2] + v1[3] * v1[3]); }
;                 s += __shfl_xor(s, 16); s += __shfl_xor(s, 32);
;                 if (fq == 0) fx_add(ssout, row, s); }
.LBB0_1200:
	s_nop 0
	s_nop 0
	v_and_b32_e32 v156, 64, v154
	v_xor_b32_e32 v155, 16, v154
	v_add_u32_e32 v156, 64, v156
	v_xor_b32_e32 v157, 32, v154
	v_cmp_lt_i32_e32 vcc, v155, v156
	s_waitcnt vmcnt(6)
	v_lshlrev_b32_e32 v168, 16, v182
	v_cndmask_b32_e32 v155, v154, v155, vcc
	v_cmp_lt_i32_e32 vcc, v157, v156
	v_and_b32_e32 v169, 0xffff0000, v182
	v_lshlrev_b32_e32 v158, 16, v183
	v_and_b32_e32 v159, 0xffff0000, v183
	v_lshlrev_b32_e32 v172, 16, v186
	v_and_b32_e32 v173, 0xffff0000, v186
	v_lshlrev_b32_e32 v162, 16, v187
	v_and_b32_e32 v163, 0xffff0000, v187
	v_cndmask_b32_e32 v157, v154, v157, vcc
	v_lshlrev_b32_e32 v170, 16, v184
	v_and_b32_e32 v171, 0xffff0000, v184
	v_lshlrev_b32_e32 v160, 16, v185
	v_and_b32_e32 v161, 0xffff0000, v185
	v_lshlrev_b32_e32 v174, 16, v188
	v_and_b32_e32 v175, 0xffff0000, v188
	v_lshlrev_b32_e32 v164, 16, v189
	v_and_b32_e32 v165, 0xffff0000, v189
	global_load_dwordx4 v[182:185], v[198:199], off
	global_load_dwordx4 v[186:189], v[198:199], off offset:256
	v_lshl_add_u64 v[198:199], v[198:199], 0, s[98:99]
	v_pk_fma_f32 v[126:127], v[126:127], 0.5, v[158:159] op_sel_hi:[1,0,1]
	v_pk_fma_f32 v[124:125], v[124:125], 0.5, v[168:169] op_sel_hi:[1,0,1]
	v_pk_fma_f32 v[118:119], v[118:119], 0.5, v[162:163] op_sel_hi:[1,0,1]
	v_pk_fma_f32 v[116:117], v[116:117], 0.5, v[172:173] op_sel_hi:[1,0,1]
	v_lshlrev_b32_e32 v156, 2, v155
	v_lshlrev_b32_e32 v155, 2, v157
	v_pk_fma_f32 v[122:123], v[122:123], 0.5, v[160:161] op_sel_hi:[1,0,1]
	v_pk_fma_f32 v[120:121], v[120:121], 0.5, v[170:171] op_sel_hi:[1,0,1]
	v_pk_fma_f32 v[158:159], v[114:115], 0.5, v[164:165] op_sel_hi:[1,0,1]
	v_pk_fma_f32 v[160:161], v[112:113], 0.5, v[174:175] op_sel_hi:[1,0,1]
	v_mul_f32_e32 v114, v125, v125
	v_mul_f32_e32 v115, v127, v127
	v_mul_f32_e32 v157, v117, v117
	v_mul_f32_e32 v162, v119, v119
	v_cvt_pk_bf16_f32 v112, v124, v125
	v_mul_f32_e32 v125, v121, v121
	v_mul_f32_e32 v163, v161, v161
	v_fmac_f32_e32 v114, v124, v124
	v_fmac_f32_e32 v115, v126, v126
	v_fmac_f32_e32 v157, v116, v116
	v_fmac_f32_e32 v162, v118, v118
	v_cvt_pk_bf16_f32 v113, v126, v127
	v_mul_f32_e32 v127, v123, v123
	v_mul_f32_e32 v164, v159, v159
	v_fmac_f32_e32 v125, v120, v120
	v_fmac_f32_e32 v163, v160, v160
	v_add_f32_e32 v114, v114, v115
	v_add_f32_e32 v115, v157, v162
	v_fmac_f32_e32 v127, v122, v122
	v_fmac_f32_e32 v164, v158, v158
	v_add_f32_e32 v114, v125, v114
	v_add_f32_e32 v115, v163, v115
	v_add_f32_e32 v114, v127, v114
	v_add_f32_e32 v115, v164, v115
	v_add_f32_e32 v124, v114, v115
	ds_bpermute_b32 v125, v156, v124
	v_cvt_pk_bf16_f32 v114, v120, v121
	v_cvt_pk_bf16_f32 v115, v122, v123
	global_store_dwordx4 v[166:167], v[112:115], off
	s_waitcnt lgkmcnt(0)
	s_nop 0
	v_add_f32_e32 v112, v124, v125
	ds_bpermute_b32 v113, v155, v112
	v_cvt_pk_bf16_f32 v114, v116, v117
	v_cvt_pk_bf16_f32 v115, v118, v119
	v_cvt_pk_bf16_f32 v116, v160, v161
	v_cvt_pk_bf16_f32 v117, v158, v159
	global_store_dwordx4 v[166:167], v[114:117], off offset:256
	s_and_saveexec_b64 s[50:51], s[10:11]
	s_cbranch_execz .LBB0_1202
	s_waitcnt lgkmcnt(0)
	v_add_f32_e32 v112, v112, v113
	v_mul_f32_e32 v112, 0x4f800000, v112
	v_trunc_f32_e32 v112, v112
	v_mul_f32_e64 v113, |v112|, s66
	v_floor_f32_e32 v113, v113
	v_fma_f32 v114, v113, s67, |v112|
	v_cvt_u32_f32_e32 v114, v114
	v_cvt_u32_f32_e32 v113, v113
	v_ashrrev_i32_e32 v115, 31, v112
	v_xor_b32_e32 v112, v114, v115
	v_xor_b32_e32 v113, v113, v115
	v_sub_co_u32_e32 v112, vcc, v112, v115
	s_nop 1
	v_subb_co_u32_e32 v113, vcc, v113, v115, vcc
	v_lshl_add_u64 v[114:115], v[146:147], 3, s[36:37]
	global_atomic_add_x2 v[114:115], v[112:113], off
.LBB0_1202:
	s_or_b64 exec, exec, s[50:51]
	v_or_b32_e32 v112, 16, v146
	s_waitcnt lgkmcnt(0)
	v_ashrrev_i32_e32 v113, 31, v112
	v_lshlrev_b64 v[114:115], 11, v[112:113]
	v_lshl_add_u64 v[114:115], s[22:23], 0, v[114:115]
	v_lshl_add_u64 v[122:123], v[144:145], 1, v[114:115]
	s_nop 0
	s_nop 0
	s_waitcnt vmcnt(10)
	v_lshlrev_b32_e32 v124, 16, v190
	v_and_b32_e32 v125, 0xffff0000, v190
	v_lshlrev_b32_e32 v114, 16, v191
	v_and_b32_e32 v115, 0xffff0000, v191
	s_waitcnt vmcnt(9)
	v_lshlrev_b32_e32 v158, 16, v194
	v_and_b32_e32 v159, 0xffff0000, v194
	v_lshlrev_b32_e32 v118, 16, v195
	v_and_b32_e32 v119, 0xffff0000, v195
	v_lshlrev_b32_e32 v126, 16, v192
	v_and_b32_e32 v127, 0xffff0000, v192
	v_lshlrev_b32_e32 v116, 16, v193
	v_and_b32_e32 v117, 0xffff0000, v193
	v_lshlrev_b32_e32 v160, 16, v196
	v_and_b32_e32 v161, 0xffff0000, v196
	v_lshlrev_b32_e32 v120, 16, v197
	v_and_b32_e32 v121, 0xffff0000, v197
	global_load_dwordx4 v[190:193], v[198:199], off
	global_load_dwordx4 v[194:197], v[198:199], off offset:256
	v_lshl_add_u64 v[198:199], v[198:199], 0, s[98:99]
	v_pk_fma_f32 v[110:111], v[110:111], 0.5, v[114:115] op_sel_hi:[1,0,1]
	v_pk_fma_f32 v[108:109], v[108:109], 0.5, v[124:125] op_sel_hi:[1,0,1]
	v_pk_fma_f32 v[102:103], v[102:103], 0.5, v[118:119] op_sel_hi:[1,0,1]
	v_pk_fma_f32 v[100:101], v[100:101], 0.5, v[158:159] op_sel_hi:[1,0,1]
	v_pk_fma_f32 v[106:107], v[106:107], 0.5, v[116:117] op_sel_hi:[1,0,1]
	v_pk_fma_f32 v[104:105], v[104:105], 0.5, v[126:127] op_sel_hi:[1,0,1]
	v_pk_fma_f32 v[114:115], v[98:99], 0.5, v[120:121] op_sel_hi:[1,0,1]
	v_pk_fma_f32 v[116:117], v[96:97], 0.5, v[160:161] op_sel_hi:[1,0,1]
	v_mul_f32_e32 v98, v109, v109
	v_mul_f32_e32 v99, v111, v111
	v_mul_f32_e32 v118, v101, v101
	v_mul_f32_e32 v119, v103, v103
	v_cvt_pk_bf16_f32 v96, v108, v109
	v_mul_f32_e32 v109, v105, v105
	v_mul_f32_e32 v120, v117, v117
	v_fmac_f32_e32 v98, v108, v108
	v_fmac_f32_e32 v99, v110, v110
	v_fmac_f32_e32 v118, v100, v100
	v_fmac_f32_e32 v119, v102, v102
	v_cvt_pk_bf16_f32 v97, v110, v111
	v_mul_f32_e32 v111, v107, v107
	v_mul_f32_e32 v121, v115, v115
	v_fmac_f32_e32 v109, v104, v104
	v_fmac_f32_e32 v120, v116, v116
	v_add_f32_e32 v98, v98, v99
	v_add_f32_e32 v99, v118, v119
	v_fmac_f32_e32 v111, v106, v106
	v_fmac_f32_e32 v121, v114, v114
	v_add_f32_e32 v98, v109, v98
	v_add_f32_e32 v99, v120, v99
	v_add_f32_e32 v98, v111, v98
	v_add_f32_e32 v99, v121, v99
	v_add_f32_e32 v108, v98, v99
	ds_bpermute_b32 v109, v156, v108
	v_cvt_pk_bf16_f32 v98, v104, v105
	v_cvt_pk_bf16_f32 v99, v106, v107
	global_store_dwordx4 v[122:123], v[96:99], off
	s_waitcnt lgkmcnt(0)
	s_nop 0
	v_add_f32_e32 v96, v108, v109
	ds_bpermute_b32 v97, v155, v96
	v_cvt_pk_bf16_f32 v98, v100, v101
	v_cvt_pk_bf16_f32 v99, v102, v103
	v_cvt_pk_bf16_f32 v100, v116, v117
	v_cvt_pk_bf16_f32 v101, v114, v115
	global_store_dwordx4 v[122:123], v[98:101], off offset:256
	s_and_saveexec_b64 s[50:51], s[10:11]
	s_cbranch_execz .LBB0_1204
; __device__ __forceinline__ void fx_add(float* p, size_t idx, float s) { atomicAdd((unsigned long long*)p + idx, (unsigned long long)(long long)(s * 4294967296.0f)); }
; __device__ __forceinline__ unsigned cvtpk(float lo, float hi) { f32x2v_ v = {lo, hi}; bf16x2v_ b = __builtin_convertvector(v, bf16x2v_); return __builtin_bit_cast(unsigned, b); }
;     __device__ __forceinline__ void operator()(const f32x4 (&acc)[2][2][4][2], const Unit& u, int wr, int wc, int fr, int fq) const {
;     ...
;             for (int m = 0; m < 4; ++m) { const int row = row0 + ai * HALF + m * 16; const size_t off = (size_t)row * 1024 + col0; float s = 0.f;
; #pragma unroll
;                 for (int bj = 0; bj < 2; ++bj) { f32x4 a0, a1;
;                     if (xin32) { const float* p = xin32 + off + bj * HALF; a0 = *(const f32x4*)p; a1 = *(const f32x4*)(p + 4); }
;                     else { const u32x4 w = *(const u32x4*)(xb + off + bj * HALF);
;                         a0 = (f32x4){__uint_as_float(w.x << 16), __uint_as_float(w.x & 0xffff0000u), __uint_as_float(w.y << 16), __uint_as_float(w.y & 0xffff0000u)};
;                         a1 = (f32x4){__uint_as_float(w.z << 16), __uint_as_float(w.z & 0xffff0000u), __uint_as_float(w.w << 16), __uint_as_float(w.w & 0xffff0000u)}; }
;                     const f32x4 v0 = a0 + acc[ai][bj][m][0] * alpha, v1 = a1 + acc[ai][bj][m][1] * alpha;
;                     u32x4 w; w.x = cvtpk(v0[0], v0[1]); w.y = cvtpk(v0[2], v0[3]); w.z = cvtpk(v1[0], v1[1]); w.w = cvtpk(v1[2], v1[3]);
;                     *(u32x4*)(xb + off + bj * HALF) = w;
;                     s += (v0[0] * v0[0] + v0[1] * v0[1]) + (v0[2] * v0[2] + v0[3] * v0[3]) + (v1[0] * v1[0] + v1[1] * v1[1]) + (v1[2] * v1[2] + v1[3] * v1[3]); }
;                 s += __shfl_xor(s, 16); s += __shfl_xor(s, 32);
;                 if (fq == 0) fx_add(ssout, row, s); }
	s_waitcnt lgkmcnt(0)
	v_add_f32_e32 v96, v96, v97
	v_mul_f32_e32 v96, 0x4f800000, v96
	v_trunc_f32_e32 v96, v96
	v_mul_f32_e64 v97, |v96|, s66
	v_floor_f32_e32 v97, v97
	v_fma_f32 v98, v97, s67, |v96|
	v_cvt_u32_f32_e32 v98, v98
	v_cvt_u32_f32_e32 v97, v97
	v_ashrrev_i32_e32 v99, 31, v96
	v_xor_b32_e32 v96, v98, v99
	v_xor_b32_e32 v97, v97, v99
	v_sub_co_u32_e32 v96, vcc, v96, v99
	s_nop 1
	v_subb_co_u32_e32 v97, vcc, v97, v99, vcc
	v_lshl_add_u64 v[98:99], v[112:113], 3, s[36:37]
	global_atomic_add_x2 v[98:99], v[96:97], off
.LBB0_1204:
	s_or_b64 exec, exec, s[50:51]
	v_or_b32_e32 v96, 32, v146
	s_waitcnt lgkmcnt(0)
	v_ashrrev_i32_e32 v97, 31, v96
	v_lshlrev_b64 v[98:99], 11, v[96:97]
	v_lshl_add_u64 v[98:99], s[22:23], 0, v[98:99]
	v_lshl_add_u64 v[106:107], v[144:145], 1, v[98:99]
	s_nop 0
	s_nop 0
	s_waitcnt vmcnt(13)
	v_lshlrev_b32_e32 v108, 16, v208
	v_and_b32_e32 v109, 0xffff0000, v208
	v_lshlrev_b32_e32 v98, 16, v209
	v_and_b32_e32 v99, 0xffff0000, v209
	s_waitcnt vmcnt(12)
	v_lshlrev_b32_e32 v112, 16, v212
	v_and_b32_e32 v113, 0xffff0000, v212
	v_lshlrev_b32_e32 v102, 16, v213
	v_and_b32_e32 v103, 0xffff0000, v213
	v_lshlrev_b32_e32 v110, 16, v210
	v_and_b32_e32 v111, 0xffff0000, v210
	v_lshlrev_b32_e32 v100, 16, v211
	v_and_b32_e32 v101, 0xffff0000, v211
	v_lshlrev_b32_e32 v114, 16, v214
	v_and_b32_e32 v115, 0xffff0000, v214
	v_lshlrev_b32_e32 v104, 16, v215
	v_and_b32_e32 v105, 0xffff0000, v215
	global_load_dwordx4 v[208:211], v[198:199], off
	global_load_dwordx4 v[212:215], v[198:199], off offset:256
	v_lshl_add_u64 v[198:199], v[198:199], 0, s[98:99]
	v_pk_fma_f32 v[94:95], v[94:95], 0.5, v[98:99] op_sel_hi:[1,0,1]
	v_pk_fma_f32 v[92:93], v[92:93], 0.5, v[108:109] op_sel_hi:[1,0,1]
	v_pk_fma_f32 v[86:87], v[86:87], 0.5, v[102:103] op_sel_hi:[1,0,1]
	v_pk_fma_f32 v[84:85], v[84:85], 0.5, v[112:113] op_sel_hi:[1,0,1]
	v_pk_fma_f32 v[90:91], v[90:91], 0.5, v[100:101] op_sel_hi:[1,0,1]
	v_pk_fma_f32 v[88:89], v[88:89], 0.5, v[110:111] op_sel_hi:[1,0,1]
	v_pk_fma_f32 v[98:99], v[82:83], 0.5, v[104:105] op_sel_hi:[1,0,1]
	v_pk_fma_f32 v[100:101], v[80:81], 0.5, v[114:115] op_sel_hi:[1,0,1]
	v_mul_f32_e32 v82, v93, v93
	v_mul_f32_e32 v83, v95, v95
	v_mul_f32_e32 v102, v85, v85
	v_mul_f32_e32 v103, v87, v87
	v_cvt_pk_bf16_f32 v80, v92, v93
	v_mul_f32_e32 v93, v89, v89
	v_mul_f32_e32 v104, v101, v101
	v_fmac_f32_e32 v82, v92, v92
	v_fmac_f32_e32 v83, v94, v94
	v_fmac_f32_e32 v102, v84, v84
	v_fmac_f32_e32 v103, v86, v86
	v_cvt_pk_bf16_f32 v81, v94, v95
	v_mul_f32_e32 v95, v91, v91
	v_mul_f32_e32 v105, v99, v99
	v_fmac_f32_e32 v93, v88, v88
	v_fmac_f32_e32 v104, v100, v100
	v_add_f32_e32 v82, v82, v83
	v_add_f32_e32 v83, v102, v103
	v_fmac_f32_e32 v95, v90, v90
	v_fmac_f32_e32 v105, v98, v98
	v_add_f32_e32 v82, v93, v82
	v_add_f32_e32 v83, v104, v83
	v_add_f32_e32 v82, v95, v82
	v_add_f32_e32 v83, v105, v83
	v_add_f32_e32 v92, v82, v83
	ds_bpermute_b32 v93, v156, v92
	v_cvt_pk_bf16_f32 v82, v88, v89
	v_cvt_pk_bf16_f32 v83, v90, v91
	global_store_dwordx4 v[106:107], v[80:83], off
	s_waitcnt lgkmcnt(0)
	s_nop 0
	v_add_f32_e32 v80, v92, v93
	ds_bpermute_b32 v81, v155, v80
	v_cvt_pk_bf16_f32 v82, v84, v85
	v_cvt_pk_bf16_f32 v83, v86, v87
	v_cvt_pk_bf16_f32 v84, v100, v101
	v_cvt_pk_bf16_f32 v85, v98, v99
	global_store_dwordx4 v[106:107], v[82:85], off offset:256
	s_and_saveexec_b64 s[50:51], s[10:11]
	s_cbranch_execz .LBB0_1206
	s_waitcnt lgkmcnt(0)
	v_add_f32_e32 v80, v80, v81
	v_mul_f32_e32 v80, 0x4f800000, v80
	v_trunc_f32_e32 v80, v80
	v_mul_f32_e64 v81, |v80|, s66
	v_floor_f32_e32 v81, v81
	v_fma_f32 v82, v81, s67, |v80|
	v_cvt_u32_f32_e32 v82, v82
	v_cvt_u32_f32_e32 v81, v81
	v_ashrrev_i32_e32 v83, 31, v80
	v_xor_b32_e32 v80, v82, v83
	v_xor_b32_e32 v81, v81, v83
	v_sub_co_u32_e32 v80, vcc, v80, v83
	s_nop 1
	v_subb_co_u32_e32 v81, vcc, v81, v83, vcc
	v_lshl_add_u64 v[82:83], v[96:97], 3, s[36:37]
	global_atomic_add_x2 v[82:83], v[80:81], off
.LBB0_1206:
	s_or_b64 exec, exec, s[50:51]
	v_or_b32_e32 v80, 48, v146
	s_waitcnt lgkmcnt(0)
	v_ashrrev_i32_e32 v81, 31, v80
	v_lshlrev_b64 v[82:83], 11, v[80:81]
	v_lshl_add_u64 v[82:83], s[22:23], 0, v[82:83]
	v_lshl_add_u64 v[90:91], v[144:145], 1, v[82:83]
	s_nop 0
	s_nop 0
	s_waitcnt vmcnt(16)
	v_lshlrev_b32_e32 v92, 16, v216
	v_and_b32_e32 v93, 0xffff0000, v216
	v_lshlrev_b32_e32 v82, 16, v217
	v_and_b32_e32 v83, 0xffff0000, v217
	s_waitcnt vmcnt(15)
	v_lshlrev_b32_e32 v96, 16, v220
	v_and_b32_e32 v97, 0xffff0000, v220
	v_lshlrev_b32_e32 v86, 16, v221
	v_and_b32_e32 v87, 0xffff0000, v221
	v_lshlrev_b32_e32 v94, 16, v218
	v_and_b32_e32 v95, 0xffff0000, v218
	v_lshlrev_b32_e32 v84, 16, v219
	v_and_b32_e32 v85, 0xffff0000, v219
	v_lshlrev_b32_e32 v98, 16, v222
	v_and_b32_e32 v99, 0xffff0000, v222
	v_lshlrev_b32_e32 v88, 16, v223
	v_and_b32_e32 v89, 0xffff0000, v223
	global_load_dwordx4 v[216:219], v[198:199], off
	global_load_dwordx4 v[220:223], v[198:199], off offset:256
	v_pk_fma_f32 v[78:79], v[78:79], 0.5, v[82:83] op_sel_hi:[1,0,1]
	v_pk_fma_f32 v[76:77], v[76:77], 0.5, v[92:93] op_sel_hi:[1,0,1]
	v_pk_fma_f32 v[70:71], v[70:71], 0.5, v[86:87] op_sel_hi:[1,0,1]
	v_pk_fma_f32 v[68:69], v[68:69], 0.5, v[96:97] op_sel_hi:[1,0,1]
	v_pk_fma_f32 v[74:75], v[74:75], 0.5, v[84:85] op_sel_hi:[1,0,1]
	v_pk_fma_f32 v[72:73], v[72:73], 0.5, v[94:95] op_sel_hi:[1,0,1]
	v_pk_fma_f32 v[82:83], v[66:67], 0.5, v[88:89] op_sel_hi:[1,0,1]
	v_pk_fma_f32 v[84:85], v[64:65], 0.5, v[98:99] op_sel_hi:[1,0,1]
	v_mul_f32_e32 v66, v77, v77
	v_mul_f32_e32 v67, v79, v79
	v_mul_f32_e32 v86, v69, v69
	v_mul_f32_e32 v87, v71, v71
	v_cvt_pk_bf16_f32 v64, v76, v77
	v_mul_f32_e32 v77, v73, v73
	v_mul_f32_e32 v88, v85, v85
	v_fmac_f32_e32 v66, v76, v76
	v_fmac_f32_e32 v67, v78, v78
	v_fmac_f32_e32 v86, v68, v68
	v_fmac_f32_e32 v87, v70, v70
	v_cvt_pk_bf16_f32 v65, v78, v79
	v_mul_f32_e32 v79, v75, v75
	v_mul_f32_e32 v89, v83, v83
	v_fmac_f32_e32 v77, v72, v72
	v_fmac_f32_e32 v88, v84, v84
	v_add_f32_e32 v66, v66, v67
	v_add_f32_e32 v67, v86, v87
	v_fmac_f32_e32 v79, v74, v74
	v_fmac_f32_e32 v89, v82, v82
	v_add_f32_e32 v66, v77, v66
	v_add_f32_e32 v67, v88, v67
	v_add_f32_e32 v66, v79, v66
	v_add_f32_e32 v67, v89, v67
	v_add_f32_e32 v76, v66, v67
	ds_bpermute_b32 v77, v156, v76
	v_cvt_pk_bf16_f32 v66, v72, v73
	v_cvt_pk_bf16_f32 v67, v74, v75
	global_store_dwordx4 v[90:91], v[64:67], off
	s_waitcnt lgkmcnt(0)
	s_nop 0
	v_add_f32_e32 v64, v76, v77
	ds_bpermute_b32 v65, v155, v64
	v_cvt_pk_bf16_f32 v66, v68, v69
	v_cvt_pk_bf16_f32 v67, v70, v71
	v_cvt_pk_bf16_f32 v68, v84, v85
	v_cvt_pk_bf16_f32 v69, v82, v83
	global_store_dwordx4 v[90:91], v[66:69], off offset:256
	s_and_saveexec_b64 s[50:51], s[10:11]
	s_cbranch_execz .LBB0_1208
; __device__ __forceinline__ void fx_add(float* p, size_t idx, float s) { atomicAdd((unsigned long long*)p + idx, (unsigned long long)(long long)(s * 4294967296.0f)); }
; __device__ __forceinline__ unsigned cvtpk(float lo, float hi) { f32x2v_ v = {lo, hi}; bf16x2v_ b = __builtin_convertvector(v, bf16x2v_); return __builtin_bit_cast(unsigned, b); }
;     __device__ __forceinline__ void operator()(const f32x4 (&acc)[2][2][4][2], const Unit& u, int wr, int wc, int fr, int fq) const {
;     ...
;             for (int m = 0; m < 4; ++m) { const int row = row0 + ai * HALF + m * 16; const size_t off = (size_t)row * 1024 + col0; float s = 0.f;
; #pragma unroll
;                 for (int bj = 0; bj < 2; ++bj) { f32x4 a0, a1;
;                     if (xin32) { const float* p = xin32 + off + bj * HALF; a0 = *(const f32x4*)p; a1 = *(const f32x4*)(p + 4); }
;                     else { const u32x4 w = *(const u32x4*)(xb + off + bj * HALF);
;                         a0 = (f32x4){__uint_as_float(w.x << 16), __uint_as_float(w.x & 0xffff0000u), __uint_as_float(w.y << 16), __uint_as_float(w.y & 0xffff0000u)};
;                         a1 = (f32x4){__uint_as_float(w.z << 16), __uint_as_float(w.z & 0xffff0000u), __uint_as_float(w.w << 16), __uint_as_float(w.w & 0xffff0000u)}; }
;                     const f32x4 v0 = a0 + acc[ai][bj][m][0] * alpha, v1 = a1 + acc[ai][bj][m][1] * alpha;
;                     u32x4 w; w.x = cvtpk(v0[0], v0[1]); w.y = cvtpk(v0[2], v0[3]); w.z = cvtpk(v1[0], v1[1]); w.w = cvtpk(v1[2], v1[3]);
;                     *(u32x4*)(xb + off + bj * HALF) = w;
;                     s += (v0[0] * v0[0] + v0[1] * v0[1]) + (v0[2] * v0[2] + v0[3] * v0[3]) + (v1[0] * v1[0] + v1[1] * v1[1]) + (v1[2] * v1[2] + v1[3] * v1[3]); }
;                 s += __shfl_xor(s, 16); s += __shfl_xor(s, 32);
;                 if (fq == 0) fx_add(ssout, row, s); }
	s_waitcnt lgkmcnt(0)
	v_add_f32_e32 v64, v64, v65
	v_mul_f32_e32 v64, 0x4f800000, v64
	v_trunc_f32_e32 v64, v64
	v_mul_f32_e64 v65, |v64|, s66
	v_floor_f32_e32 v65, v65
	v_fma_f32 v66, v65, s67, |v64|
	v_cvt_u32_f32_e32 v66, v66
	v_cvt_u32_f32_e32 v65, v65
	v_ashrrev_i32_e32 v67, 31, v64
	v_xor_b32_e32 v64, v66, v67
	v_xor_b32_e32 v65, v65, v67
	v_sub_co_u32_e32 v64, vcc, v64, v67
	s_nop 1
	v_subb_co_u32_e32 v65, vcc, v65, v67, vcc
	v_lshl_add_u64 v[66:67], v[80:81], 3, s[36:37]
	global_atomic_add_x2 v[66:67], v[64:65], off
.LBB0_1208:
	s_or_b64 exec, exec, s[50:51]
	v_add_u32_e32 v64, 0x80, v146
	s_waitcnt lgkmcnt(0)
	v_ashrrev_i32_e32 v65, 31, v64
	v_lshlrev_b64 v[66:67], 11, v[64:65]
	v_lshl_add_u64 v[66:67], s[22:23], 0, v[66:67]
	v_lshl_add_u64 v[74:75], v[144:145], 1, v[66:67]
	s_nop 0
	s_nop 0
	s_waitcnt vmcnt(19)
	v_lshlrev_b32_e32 v76, 16, v182
	v_and_b32_e32 v77, 0xffff0000, v182
	v_lshlrev_b32_e32 v66, 16, v183
	v_and_b32_e32 v67, 0xffff0000, v183
	s_waitcnt vmcnt(18)
	v_lshlrev_b32_e32 v80, 16, v186
	v_and_b32_e32 v81, 0xffff0000, v186
	v_lshlrev_b32_e32 v70, 16, v187
	v_and_b32_e32 v71, 0xffff0000, v187
	v_lshlrev_b32_e32 v78, 16, v184
	v_and_b32_e32 v79, 0xffff0000, v184
	v_lshlrev_b32_e32 v68, 16, v185
	v_and_b32_e32 v69, 0xffff0000, v185
	v_lshlrev_b32_e32 v82, 16, v188
	v_and_b32_e32 v83, 0xffff0000, v188
	v_lshlrev_b32_e32 v72, 16, v189
	v_and_b32_e32 v73, 0xffff0000, v189
	v_pk_fma_f32 v[62:63], v[62:63], 0.5, v[66:67] op_sel_hi:[1,0,1]
	v_pk_fma_f32 v[60:61], v[60:61], 0.5, v[76:77] op_sel_hi:[1,0,1]
	v_pk_fma_f32 v[54:55], v[54:55], 0.5, v[70:71] op_sel_hi:[1,0,1]
	v_pk_fma_f32 v[52:53], v[52:53], 0.5, v[80:81] op_sel_hi:[1,0,1]
	v_pk_fma_f32 v[58:59], v[58:59], 0.5, v[68:69] op_sel_hi:[1,0,1]
	v_pk_fma_f32 v[56:57], v[56:57], 0.5, v[78:79] op_sel_hi:[1,0,1]
	v_pk_fma_f32 v[66:67], v[50:51], 0.5, v[72:73] op_sel_hi:[1,0,1]
	v_pk_fma_f32 v[68:69], v[48:49], 0.5, v[82:83] op_sel_hi:[1,0,1]
	v_mul_f32_e32 v50, v61, v61
	v_mul_f32_e32 v51, v63, v63
	v_mul_f32_e32 v70, v53, v53
	v_mul_f32_e32 v71, v55, v55
	v_cvt_pk_bf16_f32 v48, v60, v61
	v_mul_f32_e32 v61, v57, v57
	v_mul_f32_e32 v72, v69, v69
	v_fmac_f32_e32 v50, v60, v60
	v_fmac_f32_e32 v51, v62, v62
	v_fmac_f32_e32 v70, v52, v52
	v_fmac_f32_e32 v71, v54, v54
	v_cvt_pk_bf16_f32 v49, v62, v63
	v_mul_f32_e32 v63, v59, v59
	v_mul_f32_e32 v73, v67, v67
	v_fmac_f32_e32 v61, v56, v56
	v_fmac_f32_e32 v72, v68, v68
	v_add_f32_e32 v50, v50, v51
	v_add_f32_e32 v51, v70, v71
	v_fmac_f32_e32 v63, v58, v58
	v_fmac_f32_e32 v73, v66, v66
	v_add_f32_e32 v50, v61, v50
	v_add_f32_e32 v51, v72, v51
	v_add_f32_e32 v50, v63, v50
	v_add_f32_e32 v51, v73, v51
	v_add_f32_e32 v60, v50, v51
	ds_bpermute_b32 v61, v156, v60
	v_cvt_pk_bf16_f32 v50, v56, v57
	v_cvt_pk_bf16_f32 v51, v58, v59
	global_store_dwordx4 v[74:75], v[48:51], off
	s_waitcnt lgkmcnt(0)
	s_nop 0
	v_add_f32_e32 v48, v60, v61
	ds_bpermute_b32 v49, v155, v48
	v_cvt_pk_bf16_f32 v50, v52, v53
	v_cvt_pk_bf16_f32 v51, v54, v55
	v_cvt_pk_bf16_f32 v52, v68, v69
	v_cvt_pk_bf16_f32 v53, v66, v67
	global_store_dwordx4 v[74:75], v[50:53], off offset:256
	s_and_saveexec_b64 s[50:51], s[10:11]
	s_cbranch_execz .LBB0_1210
	s_waitcnt lgkmcnt(0)
	v_add_f32_e32 v48, v48, v49
	v_mul_f32_e32 v48, 0x4f800000, v48
	v_trunc_f32_e32 v48, v48
	v_mul_f32_e64 v49, |v48|, s66
	v_floor_f32_e32 v49, v49
	v_fma_f32 v50, v49, s67, |v48|
	v_cvt_u32_f32_e32 v50, v50
	v_cvt_u32_f32_e32 v49, v49
	v_ashrrev_i32_e32 v51, 31, v48
	v_xor_b32_e32 v48, v50, v51
	v_xor_b32_e32 v49, v49, v51
	v_sub_co_u32_e32 v48, vcc, v48, v51
	s_nop 1
	v_subb_co_u32_e32 v49, vcc, v49, v51, vcc
	v_lshl_add_u64 v[50:51], v[64:65], 3, s[36:37]
	global_atomic_add_x2 v[50:51], v[48:49], off
.LBB0_1210:
	s_or_b64 exec, exec, s[50:51]
	v_add_u32_e32 v48, 0x90, v146
	s_waitcnt lgkmcnt(0)
	v_ashrrev_i32_e32 v49, 31, v48
	v_lshlrev_b64 v[50:51], 11, v[48:49]
	v_lshl_add_u64 v[50:51], s[22:23], 0, v[50:51]
	v_lshl_add_u64 v[58:59], v[144:145], 1, v[50:51]
	s_nop 0
	s_nop 0
	s_waitcnt vmcnt(17)
	v_lshlrev_b32_e32 v60, 16, v190
	v_and_b32_e32 v61, 0xffff0000, v190
	v_lshlrev_b32_e32 v50, 16, v191
	v_and_b32_e32 v51, 0xffff0000, v191
	s_waitcnt vmcnt(16)
	v_lshlrev_b32_e32 v64, 16, v194
	v_and_b32_e32 v65, 0xffff0000, v194
	v_lshlrev_b32_e32 v54, 16, v195
	v_and_b32_e32 v55, 0xffff0000, v195
	v_lshlrev_b32_e32 v62, 16, v192
	v_and_b32_e32 v63, 0xffff0000, v192
	v_lshlrev_b32_e32 v52, 16, v193
	v_and_b32_e32 v53, 0xffff0000, v193
	v_lshlrev_b32_e32 v66, 16, v196
	v_and_b32_e32 v67, 0xffff0000, v196
	v_lshlrev_b32_e32 v56, 16, v197
	v_and_b32_e32 v57, 0xffff0000, v197
	v_pk_fma_f32 v[46:47], v[46:47], 0.5, v[50:51] op_sel_hi:[1,0,1]
	v_pk_fma_f32 v[44:45], v[44:45], 0.5, v[60:61] op_sel_hi:[1,0,1]
	v_pk_fma_f32 v[38:39], v[38:39], 0.5, v[54:55] op_sel_hi:[1,0,1]
	v_pk_fma_f32 v[36:37], v[36:37], 0.5, v[64:65] op_sel_hi:[1,0,1]
	v_pk_fma_f32 v[42:43], v[42:43], 0.5, v[52:53] op_sel_hi:[1,0,1]
	v_pk_fma_f32 v[40:41], v[40:41], 0.5, v[62:63] op_sel_hi:[1,0,1]
	v_pk_fma_f32 v[50:51], v[34:35], 0.5, v[56:57] op_sel_hi:[1,0,1]
	v_pk_fma_f32 v[52:53], v[32:33], 0.5, v[66:67] op_sel_hi:[1,0,1]
	v_mul_f32_e32 v34, v45, v45
	v_mul_f32_e32 v35, v47, v47
	v_mul_f32_e32 v54, v37, v37
	v_mul_f32_e32 v55, v39, v39
	v_cvt_pk_bf16_f32 v32, v44, v45
	v_mul_f32_e32 v45, v41, v41
	v_mul_f32_e32 v56, v53, v53
	v_fmac_f32_e32 v34, v44, v44
	v_fmac_f32_e32 v35, v46, v46
	v_fmac_f32_e32 v54, v36, v36
	v_fmac_f32_e32 v55, v38, v38
	v_cvt_pk_bf16_f32 v33, v46, v47
	v_mul_f32_e32 v47, v43, v43
	v_mul_f32_e32 v57, v51, v51
	v_fmac_f32_e32 v45, v40, v40
	v_fmac_f32_e32 v56, v52, v52
	v_add_f32_e32 v34, v34, v35
	v_add_f32_e32 v35, v54, v55
	v_fmac_f32_e32 v47, v42, v42
	v_fmac_f32_e32 v57, v50, v50
	v_add_f32_e32 v34, v45, v34
	v_add_f32_e32 v35, v56, v35
	v_add_f32_e32 v34, v47, v34
	v_add_f32_e32 v35, v57, v35
	v_add_f32_e32 v44, v34, v35
	ds_bpermute_b32 v45, v156, v44
	v_cvt_pk_bf16_f32 v34, v40, v41
	v_cvt_pk_bf16_f32 v35, v42, v43
	global_store_dwordx4 v[58:59], v[32:35], off
	s_waitcnt lgkmcnt(0)
	s_nop 0
	v_add_f32_e32 v32, v44, v45
	ds_bpermute_b32 v33, v155, v32
	v_cvt_pk_bf16_f32 v34, v36, v37
	v_cvt_pk_bf16_f32 v35, v38, v39
	v_cvt_pk_bf16_f32 v36, v52, v53
	v_cvt_pk_bf16_f32 v37, v50, v51
	global_store_dwordx4 v[58:59], v[34:37], off offset:256
	s_and_saveexec_b64 s[50:51], s[10:11]
	s_cbranch_execz .LBB0_1212
	s_waitcnt lgkmcnt(0)
	v_add_f32_e32 v32, v32, v33
	v_mul_f32_e32 v32, 0x4f800000, v32
	v_trunc_f32_e32 v32, v32
	v_mul_f32_e64 v33, |v32|, s66
	v_floor_f32_e32 v33, v33
	v_fma_f32 v34, v33, s67, |v32|
	v_cvt_u32_f32_e32 v34, v34
	v_cvt_u32_f32_e32 v33, v33
	v_ashrrev_i32_e32 v35, 31, v32
	v_xor_b32_e32 v32, v34, v35
	v_xor_b32_e32 v33, v33, v35
	v_sub_co_u32_e32 v32, vcc, v32, v35
	s_nop 1
	v_subb_co_u32_e32 v33, vcc, v33, v35, vcc
	v_lshl_add_u64 v[34:35], v[48:49], 3, s[36:37]
	global_atomic_add_x2 v[34:35], v[32:33], off
; __device__ __forceinline__ void fx_add(float* p, size_t idx, float s) { atomicAdd((unsigned long long*)p + idx, (unsigned long long)(long long)(s * 4294967296.0f)); }
; __device__ __forceinline__ unsigned cvtpk(float lo, float hi) { f32x2v_ v = {lo, hi}; bf16x2v_ b = __builtin_convertvector(v, bf16x2v_); return __builtin_bit_cast(unsigned, b); }
;     __device__ __forceinline__ void operator()(const f32x4 (&acc)[2][2][4][2], const Unit& u, int wr, int wc, int fr, int fq) const {
;     ...
;             for (int m = 0; m < 4; ++m) { const int row = row0 + ai * HALF + m * 16; const size_t off = (size_t)row * 1024 + col0; float s = 0.f;
; #pragma unroll
;                 for (int bj = 0; bj < 2; ++bj) { f32x4 a0, a1;
;                     if (xin32) { const float* p = xin32 + off + bj * HALF; a0 = *(const f32x4*)p; a1 = *(const f32x4*)(p + 4); }
;                     else { const u32x4 w = *(const u32x4*)(xb + off + bj * HALF);
;                         a0 = (f32x4){__uint_as_float(w.x << 16), __uint_as_float(w.x & 0xffff0000u), __uint_as_float(w.y << 16), __uint_as_float(w.y & 0xffff0000u)};
;                         a1 = (f32x4){__uint_as_float(w.z << 16), __uint_as_float(w.z & 0xffff0000u), __uint_as_float(w.w << 16), __uint_as_float(w.w & 0xffff0000u)}; }
;                     const f32x4 v0 = a0 + acc[ai][bj][m][0] * alpha, v1 = a1 + acc[ai][bj][m][1] * alpha;
;                     u32x4 w; w.x = cvtpk(v0[0], v0[1]); w.y = cvtpk(v0[2], v0[3]); w.z = cvtpk(v1[0], v1[1]); w.w = cvtpk(v1[2], v1[3]);
;                     *(u32x4*)(xb + off + bj * HALF) = w;
;                     s += (v0[0] * v0[0] + v0[1] * v0[1]) + (v0[2] * v0[2] + v0[3] * v0[3]) + (v1[0] * v1[0] + v1[1] * v1[1]) + (v1[2] * v1[2] + v1[3] * v1[3]); }
;                 s += __shfl_xor(s, 16); s += __shfl_xor(s, 32);
;                 if (fq == 0) fx_add(ssout, row, s); }
.LBB0_1212:
	s_or_b64 exec, exec, s[50:51]
	v_add_u32_e32 v32, 0xa0, v146
	s_waitcnt lgkmcnt(0)
	v_ashrrev_i32_e32 v33, 31, v32
	v_lshlrev_b64 v[34:35], 11, v[32:33]
	v_lshl_add_u64 v[34:35], s[22:23], 0, v[34:35]
	v_lshl_add_u64 v[42:43], v[144:145], 1, v[34:35]
	s_nop 0
	s_nop 0
	s_waitcnt vmcnt(15)
	v_lshlrev_b32_e32 v44, 16, v208
	v_and_b32_e32 v45, 0xffff0000, v208
	v_lshlrev_b32_e32 v34, 16, v209
	v_and_b32_e32 v35, 0xffff0000, v209
	s_waitcnt vmcnt(14)
	v_lshlrev_b32_e32 v48, 16, v212
	v_and_b32_e32 v49, 0xffff0000, v212
	v_lshlrev_b32_e32 v38, 16, v213
	v_and_b32_e32 v39, 0xffff0000, v213
	v_lshlrev_b32_e32 v46, 16, v210
	v_and_b32_e32 v47, 0xffff0000, v210
	v_lshlrev_b32_e32 v36, 16, v211
	v_and_b32_e32 v37, 0xffff0000, v211
	v_lshlrev_b32_e32 v50, 16, v214
	v_and_b32_e32 v51, 0xffff0000, v214
	v_lshlrev_b32_e32 v40, 16, v215
	v_and_b32_e32 v41, 0xffff0000, v215
	v_pk_fma_f32 v[30:31], v[30:31], 0.5, v[34:35] op_sel_hi:[1,0,1]
	v_pk_fma_f32 v[28:29], v[28:29], 0.5, v[44:45] op_sel_hi:[1,0,1]
	v_pk_fma_f32 v[22:23], v[22:23], 0.5, v[38:39] op_sel_hi:[1,0,1]
	v_pk_fma_f32 v[20:21], v[20:21], 0.5, v[48:49] op_sel_hi:[1,0,1]
	v_pk_fma_f32 v[26:27], v[26:27], 0.5, v[36:37] op_sel_hi:[1,0,1]
	v_pk_fma_f32 v[24:25], v[24:25], 0.5, v[46:47] op_sel_hi:[1,0,1]
	v_pk_fma_f32 v[34:35], v[18:19], 0.5, v[40:41] op_sel_hi:[1,0,1]
	v_pk_fma_f32 v[36:37], v[16:17], 0.5, v[50:51] op_sel_hi:[1,0,1]
	v_mul_f32_e32 v18, v29, v29
	v_mul_f32_e32 v19, v31, v31
	v_mul_f32_e32 v38, v21, v21
	v_mul_f32_e32 v39, v23, v23
	v_cvt_pk_bf16_f32 v16, v28, v29
	v_mul_f32_e32 v29, v25, v25
	v_mul_f32_e32 v40, v37, v37
	v_fmac_f32_e32 v18, v28, v28
	v_fmac_f32_e32 v19, v30, v30
	v_fmac_f32_e32 v38, v20, v20
	v_fmac_f32_e32 v39, v22, v22
	v_cvt_pk_bf16_f32 v17, v30, v31
	v_mul_f32_e32 v31, v27, v27
	v_mul_f32_e32 v41, v35, v35
	v_fmac_f32_e32 v29, v24, v24
	v_fmac_f32_e32 v40, v36, v36
	v_add_f32_e32 v18, v18, v19
	v_add_f32_e32 v19, v38, v39
	v_fmac_f32_e32 v31, v26, v26
	v_fmac_f32_e32 v41, v34, v34
	v_add_f32_e32 v18, v29, v18
	v_add_f32_e32 v19, v40, v19
	v_add_f32_e32 v18, v31, v18
	v_add_f32_e32 v19, v41, v19
	v_add_f32_e32 v28, v18, v19
	ds_bpermute_b32 v29, v156, v28
	v_cvt_pk_bf16_f32 v18, v24, v25
	v_cvt_pk_bf16_f32 v19, v26, v27
	global_store_dwordx4 v[42:43], v[16:19], off
	s_waitcnt lgkmcnt(0)
	s_nop 0
	v_add_f32_e32 v16, v28, v29
	ds_bpermute_b32 v17, v155, v16
	v_cvt_pk_bf16_f32 v18, v20, v21
	v_cvt_pk_bf16_f32 v19, v22, v23
	v_cvt_pk_bf16_f32 v20, v36, v37
	v_cvt_pk_bf16_f32 v21, v34, v35
	global_store_dwordx4 v[42:43], v[18:21], off offset:256
	s_and_saveexec_b64 s[50:51], s[10:11]
	s_cbranch_execz .LBB0_1214
	s_waitcnt lgkmcnt(0)
	v_add_f32_e32 v16, v16, v17
	v_mul_f32_e32 v16, 0x4f800000, v16
	v_trunc_f32_e32 v16, v16
	v_mul_f32_e64 v17, |v16|, s66
	v_floor_f32_e32 v17, v17
	v_fma_f32 v18, v17, s67, |v16|
	v_cvt_u32_f32_e32 v18, v18
	v_cvt_u32_f32_e32 v17, v17
	v_ashrrev_i32_e32 v19, 31, v16
	v_xor_b32_e32 v16, v18, v19
	v_xor_b32_e32 v17, v17, v19
	v_sub_co_u32_e32 v16, vcc, v16, v19
	s_nop 1
	v_subb_co_u32_e32 v17, vcc, v17, v19, vcc
	v_lshl_add_u64 v[18:19], v[32:33], 3, s[36:37]
	global_atomic_add_x2 v[18:19], v[16:17], off
.LBB0_1214:
	s_or_b64 exec, exec, s[50:51]
	v_add_u32_e32 v16, 0xb0, v146
	s_waitcnt lgkmcnt(0)
	v_ashrrev_i32_e32 v17, 31, v16
	v_lshlrev_b64 v[18:19], 11, v[16:17]
	v_lshl_add_u64 v[18:19], s[22:23], 0, v[18:19]
	v_lshl_add_u64 v[26:27], v[144:145], 1, v[18:19]
	s_nop 0
	s_nop 0
	s_waitcnt vmcnt(13)
	v_lshlrev_b32_e32 v28, 16, v216
	v_and_b32_e32 v29, 0xffff0000, v216
	v_lshlrev_b32_e32 v18, 16, v217
	v_and_b32_e32 v19, 0xffff0000, v217
	s_waitcnt vmcnt(12)
	v_lshlrev_b32_e32 v32, 16, v220
	v_and_b32_e32 v33, 0xffff0000, v220
	v_lshlrev_b32_e32 v22, 16, v221
	v_and_b32_e32 v23, 0xffff0000, v221
	v_lshlrev_b32_e32 v30, 16, v218
	v_and_b32_e32 v31, 0xffff0000, v218
	v_lshlrev_b32_e32 v20, 16, v219
	v_and_b32_e32 v21, 0xffff0000, v219
	v_lshlrev_b32_e32 v34, 16, v222
	v_and_b32_e32 v35, 0xffff0000, v222
	v_lshlrev_b32_e32 v24, 16, v223
	v_and_b32_e32 v25, 0xffff0000, v223
	v_pk_fma_f32 v[14:15], v[14:15], 0.5, v[18:19] op_sel_hi:[1,0,1]
	v_pk_fma_f32 v[12:13], v[12:13], 0.5, v[28:29] op_sel_hi:[1,0,1]
	v_pk_fma_f32 v[6:7], v[6:7], 0.5, v[22:23] op_sel_hi:[1,0,1]
	v_pk_fma_f32 v[4:5], v[4:5], 0.5, v[32:33] op_sel_hi:[1,0,1]
	v_pk_fma_f32 v[10:11], v[10:11], 0.5, v[20:21] op_sel_hi:[1,0,1]
	v_pk_fma_f32 v[8:9], v[8:9], 0.5, v[30:31] op_sel_hi:[1,0,1]
	v_pk_fma_f32 v[18:19], v[2:3], 0.5, v[24:25] op_sel_hi:[1,0,1]
	v_pk_fma_f32 v[20:21], v[0:1], 0.5, v[34:35] op_sel_hi:[1,0,1]
	v_mul_f32_e32 v2, v13, v13
	v_mul_f32_e32 v3, v15, v15
	v_mul_f32_e32 v22, v5, v5
	v_mul_f32_e32 v23, v7, v7
	v_cvt_pk_bf16_f32 v0, v12, v13
	v_mul_f32_e32 v13, v9, v9
	v_mul_f32_e32 v24, v21, v21
	v_fmac_f32_e32 v2, v12, v12
	v_fmac_f32_e32 v3, v14, v14
	v_fmac_f32_e32 v22, v4, v4
	v_fmac_f32_e32 v23, v6, v6
	v_cvt_pk_bf16_f32 v1, v14, v15
	v_mul_f32_e32 v15, v11, v11
	v_mul_f32_e32 v25, v19, v19
	v_fmac_f32_e32 v13, v8, v8
	v_fmac_f32_e32 v24, v20, v20
	v_add_f32_e32 v2, v2, v3
	v_add_f32_e32 v3, v22, v23
	v_fmac_f32_e32 v15, v10, v10
	v_fmac_f32_e32 v25, v18, v18
	v_add_f32_e32 v2, v13, v2
	v_add_f32_e32 v3, v24, v3
	v_add_f32_e32 v2, v15, v2
	v_add_f32_e32 v3, v25, v3
	v_add_f32_e32 v12, v2, v3
	ds_bpermute_b32 v13, v156, v12
	v_cvt_pk_bf16_f32 v2, v8, v9
	v_cvt_pk_bf16_f32 v3, v10, v11
	global_store_dwordx4 v[26:27], v[0:3], off
	s_waitcnt lgkmcnt(0)
	s_nop 0
	v_add_f32_e32 v0, v12, v13
	ds_bpermute_b32 v1, v155, v0
	v_cvt_pk_bf16_f32 v2, v4, v5
	v_cvt_pk_bf16_f32 v3, v6, v7
	v_cvt_pk_bf16_f32 v4, v20, v21
	v_cvt_pk_bf16_f32 v5, v18, v19
	global_store_dwordx4 v[26:27], v[2:5], off offset:256
	s_and_saveexec_b64 s[50:51], s[10:11]
	s_cbranch_execz .LBB0_1216
	s_waitcnt lgkmcnt(0)
	v_add_f32_e32 v0, v0, v1
	v_mul_f32_e32 v0, 0x4f800000, v0
	v_trunc_f32_e32 v0, v0
	v_mul_f32_e64 v1, |v0|, s66
	v_floor_f32_e32 v1, v1
	v_fma_f32 v2, v1, s67, |v0|
	v_cvt_u32_f32_e32 v2, v2
	v_cvt_u32_f32_e32 v1, v1
	v_ashrrev_i32_e32 v3, 31, v0
	v_xor_b32_e32 v0, v2, v3
	v_xor_b32_e32 v1, v1, v3
	v_sub_co_u32_e32 v0, vcc, v0, v3
	s_nop 1
	v_subb_co_u32_e32 v1, vcc, v1, v3, vcc
	v_lshl_add_u64 v[2:3], v[16:17], 3, s[36:37]
	global_atomic_add_x2 v[2:3], v[0:1], off

; #define PG8_STAGE(bufoff, gbase, voff) do { _Pragma("unroll") for (int _i = 0; _i < 2; ++_i) \
;         __builtin_amdgcn_global_load_lds((const unsigned*)((const char*)(gbase) + (voff)[_i]), (PG8_LAS unsigned*)(lds + (bufoff) + ldsw + _i * 8192), 16, 0, 0); } while (0)
; #define PG8_LDA(dst, b, h) do { _Pragma("unroll") for (int m = 0; m < 4; ++m) _Pragma("unroll") for (int k = 0; k < 2; ++k) dst[m][k] = *(const PG8_LAS bf16x8*)(lds + PG8_SA(b, h) + aoff + m * 2048 + k * 1024); } while (0)
; #define PG8_LDB(dst, b, h) do { _Pragma("unroll") for (int n = 0; n < 2; ++n) _Pragma("unroll") for (int k = 0; k < 2; ++k) dst[n][k] = *(const PG8_LAS bf16x8*)(lds + PG8_SB(b, h) + boff + n * 2048 + k * 1024); } while (0)
; #define PG8_MMA(ai, bj, At, Bt) do { __builtin_amdgcn_s_setprio(1); _Pragma("unroll") for (int m = 0; m < 4; ++m) _Pragma("unroll") for (int n = 0; n < 2; ++n) _Pragma("unroll") for (int k = 0; k < 2; ++k) \
;         acc[ai][bj][m][n] = __builtin_amdgcn_mfma_f32_16x16x32_bf16(Bt[n][k], At[m][k], acc[ai][bj][m][n], 0, 0, 0); __builtin_amdgcn_s_setprio(0); } while (0)
; #define PG8_WAIT_V(n) asm volatile("s_waitcnt vmcnt(" #n ")" ::: "memory")
; #define PG8_WAIT_L(n) asm volatile("s_waitcnt lgkmcnt(" #n ")" ::: "memory")
; #define PG8_BAR __builtin_amdgcn_s_barrier()
; #define PG8_SCHED __builtin_amdgcn_sched_barrier(0)
; template <class Epi, class Sched, bool ALIGN_EPI = false, bool SP2 = false>
; __device__ __forceinline__ void gemm_phase(PG8_LAS unsigned char* lds, const Gemm g, const Sched& S, const Epi& E) {
;     ...
;             PG8_LDB(B0, 0, 0); PG8_LDB(B1, 0, 1); PG8_SCHED; PG8_LDA(At, 0, 0); PG8_STAGE(PG8_SA(1, 1), a1 + hstep, voffA);
;             PG8_WAIT_V(8); PG8_WAIT_L(0); PG8_BAR; PG8_MMA(0, 0, At, B0); PG8_MMA(0, 1, At, B1); PG8_BAR; PG8_SCHED;
;             PG8_LDA(At, 0, 1); PG8_STAGE(PG8_SB(0, 0), b2, voffB); PG8_STAGE(PG8_SB(0, 1), b2 + hstep, voffB); PG8_STAGE(PG8_SA(0, 0), a2, voffA);
;             PG8_WAIT_V(8); PG8_WAIT_L(0); PG8_BAR; PG8_MMA(1, 0, At, B0); PG8_MMA(1, 1, At, B1); PG8_BAR; PG8_SCHED;
.LBB0_1593:
	ds_read_b128 v[146:149], v152
	ds_read_b128 v[156:159], v152 offset:1024
	ds_read_b128 v[160:163], v152 offset:2048
	ds_read_b128 v[164:167], v152 offset:3072
	ds_read_b128 v[168:171], v153
	ds_read_b128 v[172:175], v153 offset:1024
	ds_read_b128 v[180:183], v153 offset:2048
	ds_read_b128 v[184:187], v153 offset:3072
	s_add_u32 s52, s50, 0xfffc0080
	s_addc_u32 s53, s51, -1
	s_cmp_eq_u32 s67, 12
	s_cselect_b32 s55, s39, s53
	s_cselect_b32 s54, s47, s52
	s_cselect_b32 s53, s37, s66
	s_cselect_b32 s52, s64, s65
	v_lshl_add_u64 v[200:201], s[50:51], 0, v[136:137]
	s_add_i32 m0, s33, 0xc000
	ds_read_b128 v[188:191], v154
	ds_read_b128 v[192:195], v154 offset:1024
	ds_read_b128 v[196:199], v154 offset:2048
	ds_read_b128 v[206:209], v154 offset:3072
	ds_read_b128 v[210:213], v154 offset:4096
	ds_read_b128 v[214:217], v154 offset:5120
	ds_read_b128 v[218:221], v154 offset:6144
	ds_read_b128 v[222:225], v154 offset:7168
	global_load_lds_dwordx4 v[200:201], off
	v_lshl_add_u64 v[200:201], s[50:51], 0, v[138:139]
	s_add_i32 m0, s33, 0xe000
	s_nop 0
	global_load_lds_dwordx4 v[200:201], off
	s_waitcnt vmcnt(8)
	s_waitcnt lgkmcnt(0)
	s_barrier
	s_setprio 1
	s_waitcnt lgkmcnt(0)
	v_mfma_f32_16x16x32_bf16 v[124:127], v[146:149], v[188:191], v[124:127]
	v_mfma_f32_16x16x32_bf16 v[120:123], v[160:163], v[188:191], v[120:123]
	v_mfma_f32_16x16x32_bf16 v[108:111], v[146:149], v[196:199], v[108:111]
	v_mfma_f32_16x16x32_bf16 v[104:107], v[160:163], v[196:199], v[104:107]
	v_mfma_f32_16x16x32_bf16 v[92:95], v[146:149], v[210:213], v[92:95]
	v_mfma_f32_16x16x32_bf16 v[88:91], v[160:163], v[210:213], v[88:91]
	v_mfma_f32_16x16x32_bf16 v[76:79], v[146:149], v[218:221], v[76:79]
	v_mfma_f32_16x16x32_bf16 v[72:75], v[160:163], v[218:221], v[72:75]
	v_mfma_f32_16x16x32_bf16 v[124:127], v[156:159], v[192:195], v[124:127]
	v_mfma_f32_16x16x32_bf16 v[120:123], v[164:167], v[192:195], v[120:123]
	v_mfma_f32_16x16x32_bf16 v[108:111], v[156:159], v[206:209], v[108:111]
	v_mfma_f32_16x16x32_bf16 v[104:107], v[164:167], v[206:209], v[104:107]
	v_mfma_f32_16x16x32_bf16 v[92:95], v[156:159], v[214:217], v[92:95]
	v_mfma_f32_16x16x32_bf16 v[88:91], v[164:167], v[214:217], v[88:91]
	v_mfma_f32_16x16x32_bf16 v[76:79], v[156:159], v[222:225], v[76:79]
	v_mfma_f32_16x16x32_bf16 v[72:75], v[164:167], v[222:225], v[72:75]
	s_setprio 0
	s_setprio 1
	v_mfma_f32_16x16x32_bf16 v[116:119], v[168:171], v[188:191], v[116:119]
	v_mfma_f32_16x16x32_bf16 v[112:115], v[180:183], v[188:191], v[112:115]
	v_mfma_f32_16x16x32_bf16 v[100:103], v[168:171], v[196:199], v[100:103]
	v_mfma_f32_16x16x32_bf16 v[96:99], v[180:183], v[196:199], v[96:99]
	v_mfma_f32_16x16x32_bf16 v[84:87], v[168:171], v[210:213], v[84:87]
	v_mfma_f32_16x16x32_bf16 v[80:83], v[180:183], v[210:213], v[80:83]
	v_mfma_f32_16x16x32_bf16 v[68:71], v[168:171], v[218:221], v[68:71]
	v_mfma_f32_16x16x32_bf16 v[64:67], v[180:183], v[218:221], v[64:67]
	v_mfma_f32_16x16x32_bf16 v[116:119], v[172:175], v[192:195], v[116:119]
	v_mfma_f32_16x16x32_bf16 v[112:115], v[184:187], v[192:195], v[112:115]
	v_mfma_f32_16x16x32_bf16 v[100:103], v[172:175], v[206:209], v[100:103]
	v_mfma_f32_16x16x32_bf16 v[96:99], v[184:187], v[206:209], v[96:99]
	v_mfma_f32_16x16x32_bf16 v[84:87], v[172:175], v[214:217], v[84:87]
	v_mfma_f32_16x16x32_bf16 v[80:83], v[184:187], v[214:217], v[80:83]
	v_mfma_f32_16x16x32_bf16 v[68:71], v[172:175], v[222:225], v[68:71]
	v_mfma_f32_16x16x32_bf16 v[64:67], v[184:187], v[222:225], v[64:67]
	s_setprio 0
	s_barrier
	s_add_i32 s74, s60, s15
	v_lshl_add_u64 v[200:201], s[52:53], 0, v[130:131]
	s_mov_b32 m0, s74
	ds_read_b128 v[188:191], v154 offset:16384
	ds_read_b128 v[192:195], v154 offset:17408
	ds_read_b128 v[196:199], v154 offset:18432
	ds_read_b128 v[206:209], v154 offset:19456
	ds_read_b128 v[210:213], v154 offset:20480
	ds_read_b128 v[214:217], v154 offset:21504
	ds_read_b128 v[218:221], v154 offset:22528
	ds_read_b128 v[222:225], v154 offset:23552
	global_load_lds_dwordx4 v[200:201], off
	s_add_i32 m0, s74, 0x2000
	s_add_u32 s74, s52, 0x40000
	v_lshl_add_u64 v[226:227], s[52:53], 0, v[134:135]
	s_addc_u32 s75, s53, 0
	s_add_i32 s76, s61, s15
	global_load_lds_dwordx4 v[226:227], off
	v_lshl_add_u64 v[228:229], s[74:75], 0, v[130:131]
	s_mov_b32 m0, s76
	v_lshl_add_u64 v[230:231], s[54:55], 0, v[132:133]
	global_load_lds_dwordx4 v[228:229], off
	v_lshl_add_u64 v[228:229], s[74:75], 0, v[134:135]
	s_add_i32 m0, s76, 0x2000
	s_nop 0
	global_load_lds_dwordx4 v[228:229], off
	v_lshl_add_u64 v[228:229], s[54:55], 0, v[128:129]
	s_mov_b32 m0, s33
	s_nop 0
	global_load_lds_dwordx4 v[228:229], off
	s_mov_b32 m0, s34
	s_nop 0
	global_load_lds_dwordx4 v[230:231], off
	s_waitcnt vmcnt(8)
	s_waitcnt lgkmcnt(0)
	s_barrier
; #define PG8_STAGE(bufoff, gbase, voff) do { _Pragma("unroll") for (int _i = 0; _i < 2; ++_i) \
;         __builtin_amdgcn_global_load_lds((const unsigned*)((const char*)(gbase) + (voff)[_i]), (PG8_LAS unsigned*)(lds + (bufoff) + ldsw + _i * 8192), 16, 0, 0); } while (0)
; #define PG8_LDA(dst, b, h) do { _Pragma("unroll") for (int m = 0; m < 4; ++m) _Pragma("unroll") for (int k = 0; k < 2; ++k) dst[m][k] = *(const PG8_LAS bf16x8*)(lds + PG8_SA(b, h) + aoff + m * 2048 + k * 1024); } while (0)
; #define PG8_LDB(dst, b, h) do { _Pragma("unroll") for (int n = 0; n < 2; ++n) _Pragma("unroll") for (int k = 0; k < 2; ++k) dst[n][k] = *(const PG8_LAS bf16x8*)(lds + PG8_SB(b, h) + boff + n * 2048 + k * 1024); } while (0)
; #define PG8_MMA(ai, bj, At, Bt) do { __builtin_amdgcn_s_setprio(1); _Pragma("unroll") for (int m = 0; m < 4; ++m) _Pragma("unroll") for (int n = 0; n < 2; ++n) _Pragma("unroll") for (int k = 0; k < 2; ++k) \
;         acc[ai][bj][m][n] = __builtin_amdgcn_mfma_f32_16x16x32_bf16(Bt[n][k], At[m][k], acc[ai][bj][m][n], 0, 0, 0); __builtin_amdgcn_s_setprio(0); } while (0)
; #define PG8_WAIT_V(n) asm volatile("s_waitcnt vmcnt(" #n ")" ::: "memory")
; #define PG8_WAIT_L(n) asm volatile("s_waitcnt lgkmcnt(" #n ")" ::: "memory")
; #define PG8_BAR __builtin_amdgcn_s_barrier()
; #define PG8_SCHED __builtin_amdgcn_sched_barrier(0)
; template <class Epi, class Sched, bool ALIGN_EPI = false, bool SP2 = false>
; __device__ __forceinline__ void gemm_phase(PG8_LAS unsigned char* lds, const Gemm g, const Sched& S, const Epi& E) {
;     ...
;             PG8_LDA(At, 0, 1); PG8_STAGE(PG8_SB(0, 0), b2, voffB); PG8_STAGE(PG8_SB(0, 1), b2 + hstep, voffB); PG8_STAGE(PG8_SA(0, 0), a2, voffA);
;             PG8_WAIT_V(8); PG8_WAIT_L(0); PG8_BAR; PG8_MMA(1, 0, At, B0); PG8_MMA(1, 1, At, B1); PG8_BAR; PG8_SCHED;
;             PG8_LDB(B0, 1, 0); PG8_LDB(B1, 1, 1); PG8_SCHED; PG8_LDA(At, 1, 0); PG8_STAGE(PG8_SA(0, 1), a2 + hstep, voffA);
;             PG8_WAIT_V(8); PG8_WAIT_L(0); PG8_BAR; PG8_MMA(0, 0, At, B0); PG8_MMA(0, 1, At, B1); PG8_BAR; PG8_SCHED;
	s_setprio 1
	s_waitcnt lgkmcnt(0)
	v_mfma_f32_16x16x32_bf16 v[60:63], v[146:149], v[188:191], v[60:63]
	v_mfma_f32_16x16x32_bf16 v[56:59], v[160:163], v[188:191], v[56:59]
	v_mfma_f32_16x16x32_bf16 v[44:47], v[146:149], v[196:199], v[44:47]
	v_mfma_f32_16x16x32_bf16 v[40:43], v[160:163], v[196:199], v[40:43]
	v_mfma_f32_16x16x32_bf16 v[28:31], v[146:149], v[210:213], v[28:31]
	v_mfma_f32_16x16x32_bf16 v[24:27], v[160:163], v[210:213], v[24:27]
	v_mfma_f32_16x16x32_bf16 v[12:15], v[146:149], v[218:221], v[12:15]
	v_mfma_f32_16x16x32_bf16 v[8:11], v[160:163], v[218:221], v[8:11]
	v_mfma_f32_16x16x32_bf16 v[60:63], v[156:159], v[192:195], v[60:63]
	v_mfma_f32_16x16x32_bf16 v[56:59], v[164:167], v[192:195], v[56:59]
	v_mfma_f32_16x16x32_bf16 v[44:47], v[156:159], v[206:209], v[44:47]
	v_mfma_f32_16x16x32_bf16 v[40:43], v[164:167], v[206:209], v[40:43]
	v_mfma_f32_16x16x32_bf16 v[28:31], v[156:159], v[214:217], v[28:31]
	v_mfma_f32_16x16x32_bf16 v[24:27], v[164:167], v[214:217], v[24:27]
	v_mfma_f32_16x16x32_bf16 v[12:15], v[156:159], v[222:225], v[12:15]
	v_mfma_f32_16x16x32_bf16 v[8:11], v[164:167], v[222:225], v[8:11]
	s_setprio 0
	s_setprio 1
	v_mfma_f32_16x16x32_bf16 v[52:55], v[168:171], v[188:191], v[52:55]
	v_mfma_f32_16x16x32_bf16 v[48:51], v[180:183], v[188:191], v[48:51]
	v_mfma_f32_16x16x32_bf16 v[36:39], v[168:171], v[196:199], v[36:39]
	v_mfma_f32_16x16x32_bf16 v[32:35], v[180:183], v[196:199], v[32:35]
	v_mfma_f32_16x16x32_bf16 v[20:23], v[168:171], v[210:213], v[20:23]
	v_mfma_f32_16x16x32_bf16 v[16:19], v[180:183], v[210:213], v[16:19]
	v_mfma_f32_16x16x32_bf16 v[4:7], v[168:171], v[218:221], v[4:7]
	v_mfma_f32_16x16x32_bf16 v[0:3], v[180:183], v[218:221], v[0:3]
	v_mfma_f32_16x16x32_bf16 v[52:55], v[172:175], v[192:195], v[52:55]
	v_mfma_f32_16x16x32_bf16 v[48:51], v[184:187], v[192:195], v[48:51]
	v_mfma_f32_16x16x32_bf16 v[36:39], v[172:175], v[206:209], v[36:39]
	v_mfma_f32_16x16x32_bf16 v[32:35], v[184:187], v[206:209], v[32:35]
	v_mfma_f32_16x16x32_bf16 v[20:23], v[172:175], v[214:217], v[20:23]
	v_mfma_f32_16x16x32_bf16 v[16:19], v[184:187], v[214:217], v[16:19]
	v_mfma_f32_16x16x32_bf16 v[4:7], v[172:175], v[222:225], v[4:7]
	v_mfma_f32_16x16x32_bf16 v[0:3], v[184:187], v[222:225], v[0:3]
	s_setprio 0
	s_barrier
	s_add_i32 s74, 0, 0x18000
	s_add_i32 s75, 0, 0x1c000
	v_add_u32_e32 v164, s74, v150
	v_add_u32_e32 v179, s75, v150
	ds_read_b128 v[146:149], v164
	ds_read_b128 v[156:159], v164 offset:1024
	ds_read_b128 v[160:163], v164 offset:2048
	ds_read_b128 v[164:167], v164 offset:3072
	ds_read_b128 v[168:171], v179
	ds_read_b128 v[172:175], v179 offset:1024
	ds_read_b128 v[180:183], v179 offset:2048
	ds_read_b128 v[184:187], v179 offset:3072
	s_add_u32 s54, s54, 0x40000
	s_addc_u32 s55, s55, 0
	s_mov_b32 m0, s49
	v_lshl_add_u64 v[232:233], s[54:55], 0, v[128:129]
	ds_read_b128 v[188:191], v154 offset:32768
	ds_read_b128 v[192:195], v154 offset:33792
	ds_read_b128 v[196:199], v154 offset:34816
	ds_read_b128 v[206:209], v154 offset:35840
	ds_read_b128 v[210:213], v154 offset:36864
	ds_read_b128 v[214:217], v154 offset:37888
	ds_read_b128 v[218:221], v154 offset:38912
	ds_read_b128 v[222:225], v154 offset:39936
	global_load_lds_dwordx4 v[232:233], off
	v_lshl_add_u64 v[232:233], s[54:55], 0, v[132:133]
	s_mov_b32 m0, s56
	s_nop 0
	global_load_lds_dwordx4 v[232:233], off
	s_waitcnt vmcnt(8)
	s_waitcnt lgkmcnt(0)
	s_barrier
	s_setprio 1
	s_waitcnt lgkmcnt(0)
	v_mfma_f32_16x16x32_bf16 v[124:127], v[146:149], v[188:191], v[124:127]
	v_mfma_f32_16x16x32_bf16 v[120:123], v[160:163], v[188:191], v[120:123]
	v_mfma_f32_16x16x32_bf16 v[108:111], v[146:149], v[196:199], v[108:111]
	v_mfma_f32_16x16x32_bf16 v[104:107], v[160:163], v[196:199], v[104:107]
	v_mfma_f32_16x16x32_bf16 v[92:95], v[146:149], v[210:213], v[92:95]
	v_mfma_f32_16x16x32_bf16 v[88:91], v[160:163], v[210:213], v[88:91]
	v_mfma_f32_16x16x32_bf16 v[76:79], v[146:149], v[218:221], v[76:79]
	v_mfma_f32_16x16x32_bf16 v[72:75], v[160:163], v[218:221], v[72:75]
	v_mfma_f32_16x16x32_bf16 v[124:127], v[156:159], v[192:195], v[124:127]
	v_mfma_f32_16x16x32_bf16 v[120:123], v[164:167], v[192:195], v[120:123]
	v_mfma_f32_16x16x32_bf16 v[108:111], v[156:159], v[206:209], v[108:111]
	v_mfma_f32_16x16x32_bf16 v[104:107], v[164:167], v[206:209], v[104:107]
	v_mfma_f32_16x16x32_bf16 v[92:95], v[156:159], v[214:217], v[92:95]
	v_mfma_f32_16x16x32_bf16 v[88:91], v[164:167], v[214:217], v[88:91]
	v_mfma_f32_16x16x32_bf16 v[76:79], v[156:159], v[222:225], v[76:79]
	v_mfma_f32_16x16x32_bf16 v[72:75], v[164:167], v[222:225], v[72:75]
	s_setprio 0
	s_setprio 1
	v_mfma_f32_16x16x32_bf16 v[116:119], v[168:171], v[188:191], v[116:119]
	v_mfma_f32_16x16x32_bf16 v[112:115], v[180:183], v[188:191], v[112:115]
	v_mfma_f32_16x16x32_bf16 v[100:103], v[168:171], v[196:199], v[100:103]
	v_mfma_f32_16x16x32_bf16 v[96:99], v[180:183], v[196:199], v[96:99]
	v_mfma_f32_16x16x32_bf16 v[84:87], v[168:171], v[210:213], v[84:87]
	v_mfma_f32_16x16x32_bf16 v[80:83], v[180:183], v[210:213], v[80:83]
	v_mfma_f32_16x16x32_bf16 v[68:71], v[168:171], v[218:221], v[68:71]
	v_mfma_f32_16x16x32_bf16 v[64:67], v[180:183], v[218:221], v[64:67]
	v_mfma_f32_16x16x32_bf16 v[116:119], v[172:175], v[192:195], v[116:119]
	v_mfma_f32_16x16x32_bf16 v[112:115], v[184:187], v[192:195], v[112:115]
	v_mfma_f32_16x16x32_bf16 v[100:103], v[172:175], v[206:209], v[100:103]
	v_mfma_f32_16x16x32_bf16 v[96:99], v[184:187], v[206:209], v[96:99]
	v_mfma_f32_16x16x32_bf16 v[84:87], v[172:175], v[214:217], v[84:87]
	v_mfma_f32_16x16x32_bf16 v[80:83], v[184:187], v[214:217], v[80:83]
	v_mfma_f32_16x16x32_bf16 v[68:71], v[172:175], v[222:225], v[68:71]
	v_mfma_f32_16x16x32_bf16 v[64:67], v[184:187], v[222:225], v[64:67]
	s_setprio 0
	s_barrier
; #define PG8_STAGE(bufoff, gbase, voff) do { _Pragma("unroll") for (int _i = 0; _i < 2; ++_i) \
;         __builtin_amdgcn_global_load_lds((const unsigned*)((const char*)(gbase) + (voff)[_i]), (PG8_LAS unsigned*)(lds + (bufoff) + ldsw + _i * 8192), 16, 0, 0); } while (0)
; #define PG8_LDA(dst, b, h) do { _Pragma("unroll") for (int m = 0; m < 4; ++m) _Pragma("unroll") for (int k = 0; k < 2; ++k) dst[m][k] = *(const PG8_LAS bf16x8*)(lds + PG8_SA(b, h) + aoff + m * 2048 + k * 1024); } while (0)
; #define PG8_MMA(ai, bj, At, Bt) do { __builtin_amdgcn_s_setprio(1); _Pragma("unroll") for (int m = 0; m < 4; ++m) _Pragma("unroll") for (int n = 0; n < 2; ++n) _Pragma("unroll") for (int k = 0; k < 2; ++k) \
;         acc[ai][bj][m][n] = __builtin_amdgcn_mfma_f32_16x16x32_bf16(Bt[n][k], At[m][k], acc[ai][bj][m][n], 0, 0, 0); __builtin_amdgcn_s_setprio(0); } while (0)
; #define PG8_WAIT_V(n) asm volatile("s_waitcnt vmcnt(" #n ")" ::: "memory")
; #define PG8_WAIT_L(n) asm volatile("s_waitcnt lgkmcnt(" #n ")" ::: "memory")
; #define PG8_BAR __builtin_amdgcn_s_barrier()
; #define PG8_SCHED __builtin_amdgcn_sched_barrier(0)
;     __device__ __forceinline__ void operator()(const f32x4 (&acc)[2][2][4][2], const Unit& u, int wr, int wc, int fr, int fq) const {
;     ...
;             for (int m = 0; m < 4; ++m) { const int row = row0 + ai * HALF + m * 16; const size_t off = (size_t)row * 1024 + col0; float s = 0.f;
; #pragma unroll
;                 for (int bj = 0; bj < 2; ++bj) { f32x4 a0, a1;
;                     if (xin32) { const float* p = xin32 + off + bj * HALF; a0 = *(const f32x4*)p; a1 = *(const f32x4*)(p + 4); }
;                     else { const u32x4 w = *(const u32x4*)(xb + off + bj * HALF);
; template <class Epi, class Sched, bool ALIGN_EPI = false, bool SP2 = false>
; __device__ __forceinline__ void gemm_phase(PG8_LAS unsigned char* lds, const Gemm g, const Sched& S, const Epi& E) {
;     ...
;             PG8_LDA(At, 1, 1); PG8_STAGE(PG8_SB(1, 0), b3, voffB); PG8_STAGE(PG8_SB(1, 1), b3 + hstep, voffB); PG8_STAGE(PG8_SA(1, 0), a3, voffA);
;             PG8_WAIT_V(8); PG8_WAIT_L(0); PG8_BAR; PG8_MMA(1, 0, At, B0); PG8_MMA(1, 1, At, B1); PG8_BAR; PG8_SCHED;
	s_add_i32 s54, s74, s15
	v_lshl_add_u64 v[200:201], v[200:201], 0, s[26:27]
	s_mov_b32 m0, s54
	ds_read_b128 v[188:191], v154 offset:49152
	ds_read_b128 v[192:195], v154 offset:50176
	ds_read_b128 v[196:199], v154 offset:51200
	ds_read_b128 v[206:209], v154 offset:52224
	ds_read_b128 v[210:213], v154 offset:53248
	ds_read_b128 v[214:217], v154 offset:54272
	ds_read_b128 v[218:221], v154 offset:55296
	ds_read_b128 v[222:225], v154 offset:56320
	global_load_lds_dwordx4 v[200:201], off
	s_add_i32 m0, s54, 0x2000
	s_add_u32 s52, s52, 0x40080
	v_lshl_add_u64 v[200:201], v[226:227], 0, s[26:27]
	s_addc_u32 s53, s53, 0
	s_add_i32 s54, s75, s15
	global_load_lds_dwordx4 v[200:201], off
	v_lshl_add_u64 v[200:201], s[52:53], 0, v[130:131]
	s_mov_b32 m0, s54
	s_nop 0
	global_load_lds_dwordx4 v[200:201], off
	v_lshl_add_u64 v[200:201], s[52:53], 0, v[134:135]
	s_add_i32 m0, s54, 0x2000
	s_nop 0
	global_load_lds_dwordx4 v[200:201], off
	v_lshl_add_u64 v[200:201], v[228:229], 0, s[26:27]
	s_mov_b32 m0, s58
	s_nop 0
	global_load_lds_dwordx4 v[200:201], off
	v_lshl_add_u64 v[200:201], v[230:231], 0, s[26:27]
	s_mov_b32 m0, s59
	s_nop 0
	global_load_lds_dwordx4 v[200:201], off
	s_waitcnt vmcnt(8)
	s_waitcnt lgkmcnt(0)
	s_barrier
	s_setprio 1
	s_waitcnt lgkmcnt(0)
	v_mfma_f32_16x16x32_bf16 v[60:63], v[146:149], v[188:191], v[60:63]
	v_mfma_f32_16x16x32_bf16 v[56:59], v[160:163], v[188:191], v[56:59]
	v_mfma_f32_16x16x32_bf16 v[44:47], v[146:149], v[196:199], v[44:47]
	v_mfma_f32_16x16x32_bf16 v[40:43], v[160:163], v[196:199], v[40:43]
	v_mfma_f32_16x16x32_bf16 v[28:31], v[146:149], v[210:213], v[28:31]
	v_mfma_f32_16x16x32_bf16 v[24:27], v[160:163], v[210:213], v[24:27]
	v_mfma_f32_16x16x32_bf16 v[12:15], v[146:149], v[218:221], v[12:15]
	v_mfma_f32_16x16x32_bf16 v[8:11], v[160:163], v[218:221], v[8:11]
	v_mfma_f32_16x16x32_bf16 v[60:63], v[156:159], v[192:195], v[60:63]
	v_mfma_f32_16x16x32_bf16 v[56:59], v[164:167], v[192:195], v[56:59]
	v_mfma_f32_16x16x32_bf16 v[44:47], v[156:159], v[206:209], v[44:47]
	v_mfma_f32_16x16x32_bf16 v[40:43], v[164:167], v[206:209], v[40:43]
	v_mfma_f32_16x16x32_bf16 v[28:31], v[156:159], v[214:217], v[28:31]
	v_mfma_f32_16x16x32_bf16 v[24:27], v[164:167], v[214:217], v[24:27]
	v_mfma_f32_16x16x32_bf16 v[12:15], v[156:159], v[222:225], v[12:15]
	v_mfma_f32_16x16x32_bf16 v[8:11], v[164:167], v[222:225], v[8:11]
	s_setprio 0
	s_setprio 1
	v_mfma_f32_16x16x32_bf16 v[52:55], v[168:171], v[188:191], v[52:55]
	v_mfma_f32_16x16x32_bf16 v[48:51], v[180:183], v[188:191], v[48:51]
	v_mfma_f32_16x16x32_bf16 v[36:39], v[168:171], v[196:199], v[36:39]
	v_mfma_f32_16x16x32_bf16 v[32:35], v[180:183], v[196:199], v[32:35]
	v_mfma_f32_16x16x32_bf16 v[20:23], v[168:171], v[210:213], v[20:23]
	v_mfma_f32_16x16x32_bf16 v[16:19], v[180:183], v[210:213], v[16:19]
	v_mfma_f32_16x16x32_bf16 v[4:7], v[168:171], v[218:221], v[4:7]
	v_mfma_f32_16x16x32_bf16 v[0:3], v[180:183], v[218:221], v[0:3]
	v_mfma_f32_16x16x32_bf16 v[52:55], v[172:175], v[192:195], v[52:55]
	v_mfma_f32_16x16x32_bf16 v[48:51], v[184:187], v[192:195], v[48:51]
	v_mfma_f32_16x16x32_bf16 v[36:39], v[172:175], v[206:209], v[36:39]
	v_mfma_f32_16x16x32_bf16 v[32:35], v[184:187], v[206:209], v[32:35]
	v_mfma_f32_16x16x32_bf16 v[20:23], v[172:175], v[214:217], v[20:23]
	v_mfma_f32_16x16x32_bf16 v[16:19], v[184:187], v[214:217], v[16:19]
	v_mfma_f32_16x16x32_bf16 v[4:7], v[172:175], v[222:225], v[4:7]
	v_mfma_f32_16x16x32_bf16 v[0:3], v[184:187], v[222:225], v[0:3]
	s_setprio 0
	s_barrier
	s_add_i32 s67, s67, 2
	s_add_u32 s50, s50, 0x100
	s_addc_u32 s51, s51, 0
	s_add_u32 s65, s65, 0x100
	s_addc_u32 s66, s66, 0
	s_cmp_gt_u32 s67, 13
	s_cbranch_scc0 .LBB0_1593
	v_lshl_add_u32 v148, s48, 8, v145
	v_ashrrev_i32_e32 v149, 31, v148
	v_lshl_or_b32 v146, s46, 8, v151
	v_lshlrev_b64 v[156:157], 11, v[148:149]
	v_ashrrev_i32_e32 v147, 31, v146
	v_lshl_add_u64 v[156:157], s[22:23], 0, v[156:157]
	v_lshl_add_u64 v[166:167], v[146:147], 1, v[156:157]
	s_mov_b64 s[98:99], 0x8000
	s_mov_b64 s[100:101], 0x28000
	global_load_dwordx4 v[182:185], v[166:167], off
	global_load_dwordx4 v[186:189], v[166:167], off offset:256
	v_lshl_add_u64 v[198:199], v[166:167], 0, s[98:99]
	global_load_dwordx4 v[190:193], v[198:199], off
	global_load_dwordx4 v[194:197], v[198:199], off offset:256
	v_lshl_add_u64 v[198:199], v[198:199], 0, s[98:99]
	global_load_dwordx4 v[208:211], v[198:199], off
	global_load_dwordx4 v[212:215], v[198:199], off offset:256
	v_lshl_add_u64 v[198:199], v[198:199], 0, s[98:99]
	global_load_dwordx4 v[216:219], v[198:199], off
	global_load_dwordx4 v[220:223], v[198:199], off offset:256
	v_lshl_add_u64 v[198:199], v[198:199], 0, s[100:101]
	s_and_b64 vcc, exec, s[28:29]
	s_cbranch_vccz .LBB0_1596
	s_barrier
; __device__ __forceinline__ void fx_add(float* p, size_t idx, float s) { atomicAdd((unsigned long long*)p + idx, (unsigned long long)(long long)(s * 4294967296.0f)); }
; __device__ __forceinline__ unsigned cvtpk(float lo, float hi) { f32x2v_ v = {lo, hi}; bf16x2v_ b = __builtin_convertvector(v, bf16x2v_); return __builtin_bit_cast(unsigned, b); }
;     __device__ __forceinline__ void operator()(const f32x4 (&acc)[2][2][4][2], const Unit& u, int wr, int wc, int fr, int fq) const {
;     ...
;             for (int m = 0; m < 4; ++m) { const int row = row0 + ai * HALF + m * 16; const size_t off = (size_t)row * 1024 + col0; float s = 0.f;
; #pragma unroll
;                 for (int bj = 0; bj < 2; ++bj) { f32x4 a0, a1;
;                     if (xin32) { const float* p = xin32 + off + bj * HALF; a0 = *(const f32x4*)p; a1 = *(const f32x4*)(p + 4); }
;                     else { const u32x4 w = *(const u32x4*)(xb + off + bj * HALF);
;                         a0 = (f32x4){__uint_as_float(w.x << 16), __uint_as_float(w.x & 0xffff0000u), __uint_as_float(w.y << 16), __uint_as_float(w.y & 0xffff0000u)};
;                         a1 = (f32x4){__uint_as_float(w.z << 16), __uint_as_float(w.z & 0xffff0000u), __uint_as_float(w.w << 16), __uint_as_float(w.w & 0xffff0000u)}; }
;                     const f32x4 v0 = a0 + acc[ai][bj][m][0] * alpha, v1 = a1 + acc[ai][bj][m][1] * alpha;
;                     u32x4 w; w.x = cvtpk(v0[0], v0[1]); w.y = cvtpk(v0[2], v0[3]); w.z = cvtpk(v1[0], v1[1]); w.w = cvtpk(v1[2], v1[3]);
;                     *(u32x4*)(xb + off + bj * HALF) = w;
;                     s += (v0[0] * v0[0] + v0[1] * v0[1]) + (v0[2] * v0[2] + v0[3] * v0[3]) + (v1[0] * v1[0] + v1[1] * v1[1]) + (v1[2] * v1[2] + v1[3] * v1[3]); }
;                 s += __shfl_xor(s, 16); s += __shfl_xor(s, 32);
;                 if (fq == 0) fx_add(ssout, row, s); }
.LBB0_1596:
	s_nop 0
	s_nop 0
	v_and_b32_e32 v157, 64, v155
	v_xor_b32_e32 v156, 16, v155
	v_add_u32_e32 v157, 64, v157
	v_xor_b32_e32 v168, 32, v155
	v_cmp_lt_i32_e32 vcc, v156, v157
	s_waitcnt vmcnt(6)
	v_and_b32_e32 v169, 0xffff0000, v182
	v_cndmask_b32_e32 v156, v155, v156, vcc
	v_cmp_lt_i32_e32 vcc, v168, v157
	v_lshlrev_b32_e32 v157, 2, v156
	v_lshlrev_b32_e32 v172, 16, v186
	v_cndmask_b32_e32 v168, v155, v168, vcc
	v_lshlrev_b32_e32 v156, 2, v168
	v_lshlrev_b32_e32 v168, 16, v182
	v_lshlrev_b32_e32 v158, 16, v183
	v_and_b32_e32 v159, 0xffff0000, v183
	v_and_b32_e32 v173, 0xffff0000, v186
	v_lshlrev_b32_e32 v162, 16, v187
	v_and_b32_e32 v163, 0xffff0000, v187
	v_lshlrev_b32_e32 v170, 16, v184
	v_and_b32_e32 v171, 0xffff0000, v184
	v_lshlrev_b32_e32 v160, 16, v185
	v_and_b32_e32 v161, 0xffff0000, v185
	v_lshlrev_b32_e32 v174, 16, v188
	v_and_b32_e32 v175, 0xffff0000, v188
	v_lshlrev_b32_e32 v164, 16, v189
	v_and_b32_e32 v165, 0xffff0000, v189
	global_load_dwordx4 v[182:185], v[198:199], off
	global_load_dwordx4 v[186:189], v[198:199], off offset:256
	v_lshl_add_u64 v[198:199], v[198:199], 0, s[98:99]
	v_pk_add_f32 v[126:127], v[126:127], v[158:159]
	v_pk_add_f32 v[124:125], v[124:125], v[168:169]
	v_pk_add_f32 v[118:119], v[118:119], v[162:163]
	v_pk_add_f32 v[116:117], v[116:117], v[172:173]
	v_pk_add_f32 v[122:123], v[122:123], v[160:161]
	v_pk_add_f32 v[120:121], v[120:121], v[170:171]
	v_pk_add_f32 v[158:159], v[114:115], v[164:165]
	v_pk_add_f32 v[160:161], v[112:113], v[174:175]
	v_mul_f32_e32 v114, v125, v125
	v_mul_f32_e32 v115, v127, v127
	v_mul_f32_e32 v162, v117, v117
	v_mul_f32_e32 v163, v119, v119
	v_cvt_pk_bf16_f32 v112, v124, v125
	v_mul_f32_e32 v125, v121, v121
	v_mul_f32_e32 v164, v161, v161
	v_fmac_f32_e32 v114, v124, v124
	v_fmac_f32_e32 v115, v126, v126
	v_fmac_f32_e32 v162, v116, v116
	v_fmac_f32_e32 v163, v118, v118
	v_cvt_pk_bf16_f32 v113, v126, v127
	v_mul_f32_e32 v127, v123, v123
	v_mul_f32_e32 v165, v159, v159
	v_fmac_f32_e32 v125, v120, v120
	v_fmac_f32_e32 v164, v160, v160
	v_add_f32_e32 v114, v114, v115
	v_add_f32_e32 v115, v162, v163
	v_fmac_f32_e32 v127, v122, v122
	v_fmac_f32_e32 v165, v158, v158
	v_add_f32_e32 v114, v125, v114
	v_add_f32_e32 v115, v164, v115
	v_add_f32_e32 v114, v127, v114
	v_add_f32_e32 v115, v165, v115
	v_add_f32_e32 v124, v114, v115
	ds_bpermute_b32 v125, v157, v124
	v_cvt_pk_bf16_f32 v114, v120, v121
	v_cvt_pk_bf16_f32 v115, v122, v123
	global_store_dwordx4 v[166:167], v[112:115], off
	s_waitcnt lgkmcnt(0)
	s_nop 0
	v_add_f32_e32 v112, v124, v125
	ds_bpermute_b32 v113, v156, v112
	v_cvt_pk_bf16_f32 v114, v116, v117
	v_cvt_pk_bf16_f32 v115, v118, v119
	v_cvt_pk_bf16_f32 v116, v160, v161
	v_cvt_pk_bf16_f32 v117, v158, v159
	global_store_dwordx4 v[166:167], v[114:117], off offset:256
	s_and_saveexec_b64 s[46:47], s[4:5]
	s_cbranch_execz .LBB0_1598
	s_waitcnt lgkmcnt(0)
	v_add_f32_e32 v112, v112, v113
	v_mul_f32_e32 v112, 0x4f800000, v112
	v_trunc_f32_e32 v112, v112
	v_mul_f32_e64 v113, |v112|, s62
	v_floor_f32_e32 v113, v113
	v_fma_f32 v114, v113, s63, |v112|
	v_cvt_u32_f32_e32 v114, v114
	v_cvt_u32_f32_e32 v113, v113
	v_ashrrev_i32_e32 v115, 31, v112
	v_xor_b32_e32 v112, v114, v115
	v_xor_b32_e32 v113, v113, v115
	v_sub_co_u32_e32 v112, vcc, v112, v115
	s_nop 1
	v_subb_co_u32_e32 v113, vcc, v113, v115, vcc
	v_lshl_add_u64 v[114:115], v[148:149], 3, s[12:13]
	global_atomic_add_x2 v[114:115], v[112:113], off
.LBB0_1598:
	s_or_b64 exec, exec, s[46:47]
	v_or_b32_e32 v112, 16, v148
	s_waitcnt lgkmcnt(0)
	v_ashrrev_i32_e32 v113, 31, v112
	v_lshlrev_b64 v[114:115], 11, v[112:113]
	v_lshl_add_u64 v[114:115], s[22:23], 0, v[114:115]
	v_lshl_add_u64 v[122:123], v[146:147], 1, v[114:115]
	s_nop 0
	s_nop 0
	s_waitcnt vmcnt(10)
	v_lshlrev_b32_e32 v124, 16, v190
	v_and_b32_e32 v125, 0xffff0000, v190
	v_lshlrev_b32_e32 v114, 16, v191
	v_and_b32_e32 v115, 0xffff0000, v191
	s_waitcnt vmcnt(9)
	v_lshlrev_b32_e32 v158, 16, v194
	v_and_b32_e32 v159, 0xffff0000, v194
	v_lshlrev_b32_e32 v118, 16, v195
	v_and_b32_e32 v119, 0xffff0000, v195
	v_lshlrev_b32_e32 v126, 16, v192
	v_and_b32_e32 v127, 0xffff0000, v192
	v_lshlrev_b32_e32 v116, 16, v193
	v_and_b32_e32 v117, 0xffff0000, v193
	v_lshlrev_b32_e32 v160, 16, v196
	v_and_b32_e32 v161, 0xffff0000, v196
	v_lshlrev_b32_e32 v120, 16, v197
	v_and_b32_e32 v121, 0xffff0000, v197
	global_load_dwordx4 v[190:193], v[198:199], off
	global_load_dwordx4 v[194:197], v[198:199], off offset:256
	v_lshl_add_u64 v[198:199], v[198:199], 0, s[98:99]
	v_pk_add_f32 v[110:111], v[110:111], v[114:115]
	v_pk_add_f32 v[108:109], v[108:109], v[124:125]
	v_pk_add_f32 v[102:103], v[102:103], v[118:119]
	v_pk_add_f32 v[100:101], v[100:101], v[158:159]
	v_pk_add_f32 v[106:107], v[106:107], v[116:117]
	v_pk_add_f32 v[104:105], v[104:105], v[126:127]
	v_pk_add_f32 v[114:115], v[98:99], v[120:121]
	v_pk_add_f32 v[116:117], v[96:97], v[160:161]
	v_mul_f32_e32 v98, v109, v109
	v_mul_f32_e32 v99, v111, v111
	v_mul_f32_e32 v118, v101, v101
	v_mul_f32_e32 v119, v103, v103
	v_cvt_pk_bf16_f32 v96, v108, v109
	v_mul_f32_e32 v109, v105, v105
	v_mul_f32_e32 v120, v117, v117
	v_fmac_f32_e32 v98, v108, v108
	v_fmac_f32_e32 v99, v110, v110
	v_fmac_f32_e32 v118, v100, v100
	v_fmac_f32_e32 v119, v102, v102
	v_cvt_pk_bf16_f32 v97, v110, v111
	v_mul_f32_e32 v111, v107, v107
	v_mul_f32_e32 v121, v115, v115
	v_fmac_f32_e32 v109, v104, v104
	v_fmac_f32_e32 v120, v116, v116
	v_add_f32_e32 v98, v98, v99
	v_add_f32_e32 v99, v118, v119
	v_fmac_f32_e32 v111, v106, v106
	v_fmac_f32_e32 v121, v114, v114
	v_add_f32_e32 v98, v109, v98
	v_add_f32_e32 v99, v120, v99
	v_add_f32_e32 v98, v111, v98
	v_add_f32_e32 v99, v121, v99
	v_add_f32_e32 v108, v98, v99
	ds_bpermute_b32 v109, v157, v108
	v_cvt_pk_bf16_f32 v98, v104, v105
	v_cvt_pk_bf16_f32 v99, v106, v107
	global_store_dwordx4 v[122:123], v[96:99], off
	s_waitcnt lgkmcnt(0)
	s_nop 0
	v_add_f32_e32 v96, v108, v109
	ds_bpermute_b32 v97, v156, v96
	v_cvt_pk_bf16_f32 v98, v100, v101
	v_cvt_pk_bf16_f32 v99, v102, v103
	v_cvt_pk_bf16_f32 v100, v116, v117
	v_cvt_pk_bf16_f32 v101, v114, v115
	global_store_dwordx4 v[122:123], v[98:101], off offset:256
	s_and_saveexec_b64 s[46:47], s[4:5]
	s_cbranch_execz .LBB0_1600
	s_waitcnt lgkmcnt(0)
	v_add_f32_e32 v96, v96, v97
	v_mul_f32_e32 v96, 0x4f800000, v96
	v_trunc_f32_e32 v96, v96
	v_mul_f32_e64 v97, |v96|, s62
	v_floor_f32_e32 v97, v97
	v_fma_f32 v98, v97, s63, |v96|
	v_cvt_u32_f32_e32 v98, v98
	v_cvt_u32_f32_e32 v97, v97
	v_ashrrev_i32_e32 v99, 31, v96
	v_xor_b32_e32 v96, v98, v99
	v_xor_b32_e32 v97, v97, v99
	v_sub_co_u32_e32 v96, vcc, v96, v99
	s_nop 1
	v_subb_co_u32_e32 v97, vcc, v97, v99, vcc
	v_lshl_add_u64 v[98:99], v[112:113], 3, s[12:13]
	global_atomic_add_x2 v[98:99], v[96:97], off
; __device__ __forceinline__ void fx_add(float* p, size_t idx, float s) { atomicAdd((unsigned long long*)p + idx, (unsigned long long)(long long)(s * 4294967296.0f)); }
; __device__ __forceinline__ unsigned cvtpk(float lo, float hi) { f32x2v_ v = {lo, hi}; bf16x2v_ b = __builtin_convertvector(v, bf16x2v_); return __builtin_bit_cast(unsigned, b); }
;     __device__ __forceinline__ void operator()(const f32x4 (&acc)[2][2][4][2], const Unit& u, int wr, int wc, int fr, int fq) const {
;     ...
;             for (int m = 0; m < 4; ++m) { const int row = row0 + ai * HALF + m * 16; const size_t off = (size_t)row * 1024 + col0; float s = 0.f;
; #pragma unroll
;                 for (int bj = 0; bj < 2; ++bj) { f32x4 a0, a1;
;                     if (xin32) { const float* p = xin32 + off + bj * HALF; a0 = *(const f32x4*)p; a1 = *(const f32x4*)(p + 4); }
;                     else { const u32x4 w = *(const u32x4*)(xb + off + bj * HALF);
;                         a0 = (f32x4){__uint_as_float(w.x << 16), __uint_as_float(w.x & 0xffff0000u), __uint_as_float(w.y << 16), __uint_as_float(w.y & 0xffff0000u)};
;                         a1 = (f32x4){__uint_as_float(w.z << 16), __uint_as_float(w.z & 0xffff0000u), __uint_as_float(w.w << 16), __uint_as_float(w.w & 0xffff0000u)}; }
;                     const f32x4 v0 = a0 + acc[ai][bj][m][0] * alpha, v1 = a1 + acc[ai][bj][m][1] * alpha;
;                     u32x4 w; w.x = cvtpk(v0[0], v0[1]); w.y = cvtpk(v0[2], v0[3]); w.z = cvtpk(v1[0], v1[1]); w.w = cvtpk(v1[2], v1[3]);
;                     *(u32x4*)(xb + off + bj * HALF) = w;
;                     s += (v0[0] * v0[0] + v0[1] * v0[1]) + (v0[2] * v0[2] + v0[3] * v0[3]) + (v1[0] * v1[0] + v1[1] * v1[1]) + (v1[2] * v1[2] + v1[3] * v1[3]); }
;                 s += __shfl_xor(s, 16); s += __shfl_xor(s, 32);
;                 if (fq == 0) fx_add(ssout, row, s); }
.LBB0_1600:
	s_or_b64 exec, exec, s[46:47]
	v_or_b32_e32 v96, 32, v148
	s_waitcnt lgkmcnt(0)
	v_ashrrev_i32_e32 v97, 31, v96
	v_lshlrev_b64 v[98:99], 11, v[96:97]
	v_lshl_add_u64 v[98:99], s[22:23], 0, v[98:99]
	v_lshl_add_u64 v[106:107], v[146:147], 1, v[98:99]
	s_nop 0
	s_nop 0
	s_waitcnt vmcnt(13)
	v_lshlrev_b32_e32 v108, 16, v208
	v_and_b32_e32 v109, 0xffff0000, v208
	v_lshlrev_b32_e32 v98, 16, v209
	v_and_b32_e32 v99, 0xffff0000, v209
	s_waitcnt vmcnt(12)
	v_lshlrev_b32_e32 v112, 16, v212
	v_and_b32_e32 v113, 0xffff0000, v212
	v_lshlrev_b32_e32 v102, 16, v213
	v_and_b32_e32 v103, 0xffff0000, v213
	v_lshlrev_b32_e32 v110, 16, v210
	v_and_b32_e32 v111, 0xffff0000, v210
	v_lshlrev_b32_e32 v100, 16, v211
	v_and_b32_e32 v101, 0xffff0000, v211
	v_lshlrev_b32_e32 v114, 16, v214
	v_and_b32_e32 v115, 0xffff0000, v214
	v_lshlrev_b32_e32 v104, 16, v215
	v_and_b32_e32 v105, 0xffff0000, v215
	global_load_dwordx4 v[208:211], v[198:199], off
	global_load_dwordx4 v[212:215], v[198:199], off offset:256
	v_lshl_add_u64 v[198:199], v[198:199], 0, s[98:99]
	v_pk_add_f32 v[94:95], v[94:95], v[98:99]
	v_pk_add_f32 v[92:93], v[92:93], v[108:109]
	v_pk_add_f32 v[86:87], v[86:87], v[102:103]
	v_pk_add_f32 v[84:85], v[84:85], v[112:113]
	v_pk_add_f32 v[90:91], v[90:91], v[100:101]
	v_pk_add_f32 v[88:89], v[88:89], v[110:111]
	v_pk_add_f32 v[98:99], v[82:83], v[104:105]
	v_pk_add_f32 v[100:101], v[80:81], v[114:115]
	v_mul_f32_e32 v82, v93, v93
	v_mul_f32_e32 v83, v95, v95
	v_mul_f32_e32 v102, v85, v85
	v_mul_f32_e32 v103, v87, v87
	v_cvt_pk_bf16_f32 v80, v92, v93
	v_mul_f32_e32 v93, v89, v89
	v_mul_f32_e32 v104, v101, v101
	v_fmac_f32_e32 v82, v92, v92
	v_fmac_f32_e32 v83, v94, v94
	v_fmac_f32_e32 v102, v84, v84
	v_fmac_f32_e32 v103, v86, v86
	v_cvt_pk_bf16_f32 v81, v94, v95
	v_mul_f32_e32 v95, v91, v91
	v_mul_f32_e32 v105, v99, v99
	v_fmac_f32_e32 v93, v88, v88
	v_fmac_f32_e32 v104, v100, v100
	v_add_f32_e32 v82, v82, v83
	v_add_f32_e32 v83, v102, v103
	v_fmac_f32_e32 v95, v90, v90
	v_fmac_f32_e32 v105, v98, v98
	v_add_f32_e32 v82, v93, v82
	v_add_f32_e32 v83, v104, v83
	v_add_f32_e32 v82, v95, v82
	v_add_f32_e32 v83, v105, v83
	v_add_f32_e32 v92, v82, v83
	ds_bpermute_b32 v93, v157, v92
	v_cvt_pk_bf16_f32 v82, v88, v89
	v_cvt_pk_bf16_f32 v83, v90, v91
	global_store_dwordx4 v[106:107], v[80:83], off
	s_waitcnt lgkmcnt(0)
	s_nop 0
	v_add_f32_e32 v80, v92, v93
	ds_bpermute_b32 v81, v156, v80
	v_cvt_pk_bf16_f32 v82, v84, v85
	v_cvt_pk_bf16_f32 v83, v86, v87
	v_cvt_pk_bf16_f32 v84, v100, v101
	v_cvt_pk_bf16_f32 v85, v98, v99
	global_store_dwordx4 v[106:107], v[82:85], off offset:256
	s_and_saveexec_b64 s[46:47], s[4:5]
	s_cbranch_execz .LBB0_1602
	s_waitcnt lgkmcnt(0)
	v_add_f32_e32 v80, v80, v81
	v_mul_f32_e32 v80, 0x4f800000, v80
	v_trunc_f32_e32 v80, v80
	v_mul_f32_e64 v81, |v80|, s62
	v_floor_f32_e32 v81, v81
	v_fma_f32 v82, v81, s63, |v80|
	v_cvt_u32_f32_e32 v82, v82
	v_cvt_u32_f32_e32 v81, v81
	v_ashrrev_i32_e32 v83, 31, v80
	v_xor_b32_e32 v80, v82, v83
	v_xor_b32_e32 v81, v81, v83
	v_sub_co_u32_e32 v80, vcc, v80, v83
	s_nop 1
	v_subb_co_u32_e32 v81, vcc, v81, v83, vcc
	v_lshl_add_u64 v[82:83], v[96:97], 3, s[12:13]
	global_atomic_add_x2 v[82:83], v[80:81], off
.LBB0_1602:
	s_or_b64 exec, exec, s[46:47]
	v_or_b32_e32 v80, 48, v148
	s_waitcnt lgkmcnt(0)
	v_ashrrev_i32_e32 v81, 31, v80
	v_lshlrev_b64 v[82:83], 11, v[80:81]
	v_lshl_add_u64 v[82:83], s[22:23], 0, v[82:83]
	v_lshl_add_u64 v[90:91], v[146:147], 1, v[82:83]
	s_nop 0
	s_nop 0
	s_waitcnt vmcnt(16)
	v_lshlrev_b32_e32 v92, 16, v216
	v_and_b32_e32 v93, 0xffff0000, v216
	v_lshlrev_b32_e32 v82, 16, v217
	v_and_b32_e32 v83, 0xffff0000, v217
	s_waitcnt vmcnt(15)
	v_lshlrev_b32_e32 v96, 16, v220
	v_and_b32_e32 v97, 0xffff0000, v220
	v_lshlrev_b32_e32 v86, 16, v221
	v_and_b32_e32 v87, 0xffff0000, v221
	v_lshlrev_b32_e32 v94, 16, v218
	v_and_b32_e32 v95, 0xffff0000, v218
	v_lshlrev_b32_e32 v84, 16, v219
	v_and_b32_e32 v85, 0xffff0000, v219
	v_lshlrev_b32_e32 v98, 16, v222
	v_and_b32_e32 v99, 0xffff0000, v222
	v_lshlrev_b32_e32 v88, 16, v223
	v_and_b32_e32 v89, 0xffff0000, v223
	global_load_dwordx4 v[216:219], v[198:199], off
	global_load_dwordx4 v[220:223], v[198:199], off offset:256
	v_pk_add_f32 v[78:79], v[78:79], v[82:83]
	v_pk_add_f32 v[76:77], v[76:77], v[92:93]
	v_pk_add_f32 v[70:71], v[70:71], v[86:87]
	v_pk_add_f32 v[68:69], v[68:69], v[96:97]
	v_pk_add_f32 v[74:75], v[74:75], v[84:85]
	v_pk_add_f32 v[72:73], v[72:73], v[94:95]
	v_pk_add_f32 v[82:83], v[66:67], v[88:89]
	v_pk_add_f32 v[84:85], v[64:65], v[98:99]
	v_mul_f32_e32 v66, v77, v77
	v_mul_f32_e32 v67, v79, v79
	v_mul_f32_e32 v86, v69, v69
	v_mul_f32_e32 v87, v71, v71
	v_cvt_pk_bf16_f32 v64, v76, v77
	v_mul_f32_e32 v77, v73, v73
	v_mul_f32_e32 v88, v85, v85
	v_fmac_f32_e32 v66, v76, v76
	v_fmac_f32_e32 v67, v78, v78
	v_fmac_f32_e32 v86, v68, v68
	v_fmac_f32_e32 v87, v70, v70
	v_cvt_pk_bf16_f32 v65, v78, v79
	v_mul_f32_e32 v79, v75, v75
	v_mul_f32_e32 v89, v83, v83
	v_fmac_f32_e32 v77, v72, v72
	v_fmac_f32_e32 v88, v84, v84
	v_add_f32_e32 v66, v66, v67
	v_add_f32_e32 v67, v86, v87
	v_fmac_f32_e32 v79, v74, v74
	v_fmac_f32_e32 v89, v82, v82
	v_add_f32_e32 v66, v77, v66
	v_add_f32_e32 v67, v88, v67
	v_add_f32_e32 v66, v79, v66
	v_add_f32_e32 v67, v89, v67
	v_add_f32_e32 v76, v66, v67
	ds_bpermute_b32 v77, v157, v76
	v_cvt_pk_bf16_f32 v66, v72, v73
	v_cvt_pk_bf16_f32 v67, v74, v75
	global_store_dwordx4 v[90:91], v[64:67], off
	s_waitcnt lgkmcnt(0)
	s_nop 0
	v_add_f32_e32 v64, v76, v77
	ds_bpermute_b32 v65, v156, v64
	v_cvt_pk_bf16_f32 v66, v68, v69
	v_cvt_pk_bf16_f32 v67, v70, v71
	v_cvt_pk_bf16_f32 v68, v84, v85
	v_cvt_pk_bf16_f32 v69, v82, v83
	global_store_dwordx4 v[90:91], v[66:69], off offset:256
	s_and_saveexec_b64 s[46:47], s[4:5]
	s_cbranch_execz .LBB0_1604
	s_waitcnt lgkmcnt(0)
	v_add_f32_e32 v64, v64, v65
	v_mul_f32_e32 v64, 0x4f800000, v64
	v_trunc_f32_e32 v64, v64
	v_mul_f32_e64 v65, |v64|, s62
	v_floor_f32_e32 v65, v65
	v_fma_f32 v66, v65, s63, |v64|
	v_cvt_u32_f32_e32 v66, v66
	v_cvt_u32_f32_e32 v65, v65
	v_ashrrev_i32_e32 v67, 31, v64
	v_xor_b32_e32 v64, v66, v67
	v_xor_b32_e32 v65, v65, v67
	v_sub_co_u32_e32 v64, vcc, v64, v67
	s_nop 1
	v_subb_co_u32_e32 v65, vcc, v65, v67, vcc
	v_lshl_add_u64 v[66:67], v[80:81], 3, s[12:13]
	global_atomic_add_x2 v[66:67], v[64:65], off
; __device__ __forceinline__ void fx_add(float* p, size_t idx, float s) { atomicAdd((unsigned long long*)p + idx, (unsigned long long)(long long)(s * 4294967296.0f)); }
; __device__ __forceinline__ unsigned cvtpk(float lo, float hi) { f32x2v_ v = {lo, hi}; bf16x2v_ b = __builtin_convertvector(v, bf16x2v_); return __builtin_bit_cast(unsigned, b); }
;     __device__ __forceinline__ void operator()(const f32x4 (&acc)[2][2][4][2], const Unit& u, int wr, int wc, int fr, int fq) const {
;     ...
;             for (int m = 0; m < 4; ++m) { const int row = row0 + ai * HALF + m * 16; const size_t off = (size_t)row * 1024 + col0; float s = 0.f;
; #pragma unroll
;                 for (int bj = 0; bj < 2; ++bj) { f32x4 a0, a1;
;                     if (xin32) { const float* p = xin32 + off + bj * HALF; a0 = *(const f32x4*)p; a1 = *(const f32x4*)(p + 4); }
;                     else { const u32x4 w = *(const u32x4*)(xb + off + bj * HALF);
;                         a0 = (f32x4){__uint_as_float(w.x << 16), __uint_as_float(w.x & 0xffff0000u), __uint_as_float(w.y << 16), __uint_as_float(w.y & 0xffff0000u)};
;                         a1 = (f32x4){__uint_as_float(w.z << 16), __uint_as_float(w.z & 0xffff0000u), __uint_as_float(w.w << 16), __uint_as_float(w.w & 0xffff0000u)}; }
;                     const f32x4 v0 = a0 + acc[ai][bj][m][0] * alpha, v1 = a1 + acc[ai][bj][m][1] * alpha;
;                     u32x4 w; w.x = cvtpk(v0[0], v0[1]); w.y = cvtpk(v0[2], v0[3]); w.z = cvtpk(v1[0], v1[1]); w.w = cvtpk(v1[2], v1[3]);
;                     *(u32x4*)(xb + off + bj * HALF) = w;
;                     s += (v0[0] * v0[0] + v0[1] * v0[1]) + (v0[2] * v0[2] + v0[3] * v0[3]) + (v1[0] * v1[0] + v1[1] * v1[1]) + (v1[2] * v1[2] + v1[3] * v1[3]); }
;                 s += __shfl_xor(s, 16); s += __shfl_xor(s, 32);
;                 if (fq == 0) fx_add(ssout, row, s); }
.LBB0_1604:
	s_or_b64 exec, exec, s[46:47]
	v_add_u32_e32 v64, 0x80, v148
	s_waitcnt lgkmcnt(0)
	v_ashrrev_i32_e32 v65, 31, v64
	v_lshlrev_b64 v[66:67], 11, v[64:65]
	v_lshl_add_u64 v[66:67], s[22:23], 0, v[66:67]
	v_lshl_add_u64 v[74:75], v[146:147], 1, v[66:67]
	s_nop 0
	s_nop 0
	s_waitcnt vmcnt(19)
	v_lshlrev_b32_e32 v76, 16, v182
	v_and_b32_e32 v77, 0xffff0000, v182
	v_lshlrev_b32_e32 v66, 16, v183
	v_and_b32_e32 v67, 0xffff0000, v183
	s_waitcnt vmcnt(18)
	v_lshlrev_b32_e32 v80, 16, v186
	v_and_b32_e32 v81, 0xffff0000, v186
	v_lshlrev_b32_e32 v70, 16, v187
	v_and_b32_e32 v71, 0xffff0000, v187
	v_lshlrev_b32_e32 v78, 16, v184
	v_and_b32_e32 v79, 0xffff0000, v184
	v_lshlrev_b32_e32 v68, 16, v185
	v_and_b32_e32 v69, 0xffff0000, v185
	v_lshlrev_b32_e32 v82, 16, v188
	v_and_b32_e32 v83, 0xffff0000, v188
	v_lshlrev_b32_e32 v72, 16, v189
	v_and_b32_e32 v73, 0xffff0000, v189
	v_pk_add_f32 v[62:63], v[62:63], v[66:67]
	v_pk_add_f32 v[60:61], v[60:61], v[76:77]
	v_pk_add_f32 v[54:55], v[54:55], v[70:71]
	v_pk_add_f32 v[52:53], v[52:53], v[80:81]
	v_pk_add_f32 v[58:59], v[58:59], v[68:69]
	v_pk_add_f32 v[56:57], v[56:57], v[78:79]
	v_pk_add_f32 v[66:67], v[50:51], v[72:73]
	v_pk_add_f32 v[68:69], v[48:49], v[82:83]
	v_mul_f32_e32 v50, v61, v61
	v_mul_f32_e32 v51, v63, v63
	v_mul_f32_e32 v70, v53, v53
	v_mul_f32_e32 v71, v55, v55
	v_cvt_pk_bf16_f32 v48, v60, v61
	v_mul_f32_e32 v61, v57, v57
	v_mul_f32_e32 v72, v69, v69
	v_fmac_f32_e32 v50, v60, v60
	v_fmac_f32_e32 v51, v62, v62
	v_fmac_f32_e32 v70, v52, v52
	v_fmac_f32_e32 v71, v54, v54
	v_cvt_pk_bf16_f32 v49, v62, v63
	v_mul_f32_e32 v63, v59, v59
	v_mul_f32_e32 v73, v67, v67
	v_fmac_f32_e32 v61, v56, v56
	v_fmac_f32_e32 v72, v68, v68
	v_add_f32_e32 v50, v50, v51
	v_add_f32_e32 v51, v70, v71
	v_fmac_f32_e32 v63, v58, v58
	v_fmac_f32_e32 v73, v66, v66
	v_add_f32_e32 v50, v61, v50
	v_add_f32_e32 v51, v72, v51
	v_add_f32_e32 v50, v63, v50
	v_add_f32_e32 v51, v73, v51
	v_add_f32_e32 v60, v50, v51
	ds_bpermute_b32 v61, v157, v60
	v_cvt_pk_bf16_f32 v50, v56, v57
	v_cvt_pk_bf16_f32 v51, v58, v59
	global_store_dwordx4 v[74:75], v[48:51], off
	s_waitcnt lgkmcnt(0)
	s_nop 0
	v_add_f32_e32 v48, v60, v61
	ds_bpermute_b32 v49, v156, v48
	v_cvt_pk_bf16_f32 v50, v52, v53
	v_cvt_pk_bf16_f32 v51, v54, v55
	v_cvt_pk_bf16_f32 v52, v68, v69
	v_cvt_pk_bf16_f32 v53, v66, v67
	global_store_dwordx4 v[74:75], v[50:53], off offset:256
	s_and_saveexec_b64 s[46:47], s[4:5]
	s_cbranch_execz .LBB0_1606
	s_waitcnt lgkmcnt(0)
	v_add_f32_e32 v48, v48, v49
	v_mul_f32_e32 v48, 0x4f800000, v48
	v_trunc_f32_e32 v48, v48
	v_mul_f32_e64 v49, |v48|, s62
	v_floor_f32_e32 v49, v49
	v_fma_f32 v50, v49, s63, |v48|
	v_cvt_u32_f32_e32 v50, v50
	v_cvt_u32_f32_e32 v49, v49
	v_ashrrev_i32_e32 v51, 31, v48
	v_xor_b32_e32 v48, v50, v51
	v_xor_b32_e32 v49, v49, v51
	v_sub_co_u32_e32 v48, vcc, v48, v51
	s_nop 1
	v_subb_co_u32_e32 v49, vcc, v49, v51, vcc
	v_lshl_add_u64 v[50:51], v[64:65], 3, s[12:13]
	global_atomic_add_x2 v[50:51], v[48:49], off
.LBB0_1606:
	s_or_b64 exec, exec, s[46:47]
	v_add_u32_e32 v48, 0x90, v148
	s_waitcnt lgkmcnt(0)
	v_ashrrev_i32_e32 v49, 31, v48
	v_lshlrev_b64 v[50:51], 11, v[48:49]
	v_lshl_add_u64 v[50:51], s[22:23], 0, v[50:51]
	v_lshl_add_u64 v[58:59], v[146:147], 1, v[50:51]
	s_nop 0
	s_nop 0
	s_waitcnt vmcnt(17)
	v_lshlrev_b32_e32 v60, 16, v190
	v_and_b32_e32 v61, 0xffff0000, v190
	v_lshlrev_b32_e32 v50, 16, v191
	v_and_b32_e32 v51, 0xffff0000, v191
	s_waitcnt vmcnt(16)
	v_lshlrev_b32_e32 v64, 16, v194
	v_and_b32_e32 v65, 0xffff0000, v194
	v_lshlrev_b32_e32 v54, 16, v195
	v_and_b32_e32 v55, 0xffff0000, v195
	v_lshlrev_b32_e32 v62, 16, v192
	v_and_b32_e32 v63, 0xffff0000, v192
	v_lshlrev_b32_e32 v52, 16, v193
	v_and_b32_e32 v53, 0xffff0000, v193
	v_lshlrev_b32_e32 v66, 16, v196
	v_and_b32_e32 v67, 0xffff0000, v196
	v_lshlrev_b32_e32 v56, 16, v197
	v_and_b32_e32 v57, 0xffff0000, v197
	v_pk_add_f32 v[46:47], v[46:47], v[50:51]
	v_pk_add_f32 v[44:45], v[44:45], v[60:61]
	v_pk_add_f32 v[38:39], v[38:39], v[54:55]
	v_pk_add_f32 v[36:37], v[36:37], v[64:65]
	v_pk_add_f32 v[42:43], v[42:43], v[52:53]
	v_pk_add_f32 v[40:41], v[40:41], v[62:63]
	v_pk_add_f32 v[50:51], v[34:35], v[56:57]
	v_pk_add_f32 v[52:53], v[32:33], v[66:67]
	v_mul_f32_e32 v34, v45, v45
	v_mul_f32_e32 v35, v47, v47
	v_mul_f32_e32 v54, v37, v37
	v_mul_f32_e32 v55, v39, v39
	v_cvt_pk_bf16_f32 v32, v44, v45
	v_mul_f32_e32 v45, v41, v41
	v_mul_f32_e32 v56, v53, v53
	v_fmac_f32_e32 v34, v44, v44
	v_fmac_f32_e32 v35, v46, v46
	v_fmac_f32_e32 v54, v36, v36
	v_fmac_f32_e32 v55, v38, v38
	v_cvt_pk_bf16_f32 v33, v46, v47
	v_mul_f32_e32 v47, v43, v43
	v_mul_f32_e32 v57, v51, v51
	v_fmac_f32_e32 v45, v40, v40
	v_fmac_f32_e32 v56, v52, v52
	v_add_f32_e32 v34, v34, v35
	v_add_f32_e32 v35, v54, v55
	v_fmac_f32_e32 v47, v42, v42
	v_fmac_f32_e32 v57, v50, v50
	v_add_f32_e32 v34, v45, v34
	v_add_f32_e32 v35, v56, v35
	v_add_f32_e32 v34, v47, v34
	v_add_f32_e32 v35, v57, v35
	v_add_f32_e32 v44, v34, v35
	ds_bpermute_b32 v45, v157, v44
	v_cvt_pk_bf16_f32 v34, v40, v41
	v_cvt_pk_bf16_f32 v35, v42, v43
	global_store_dwordx4 v[58:59], v[32:35], off
	s_waitcnt lgkmcnt(0)
	s_nop 0
	v_add_f32_e32 v32, v44, v45
	ds_bpermute_b32 v33, v156, v32
	v_cvt_pk_bf16_f32 v34, v36, v37
	v_cvt_pk_bf16_f32 v35, v38, v39
	v_cvt_pk_bf16_f32 v36, v52, v53
	v_cvt_pk_bf16_f32 v37, v50, v51
	global_store_dwordx4 v[58:59], v[34:37], off offset:256
	s_and_saveexec_b64 s[46:47], s[4:5]
	s_cbranch_execz .LBB0_1608
	s_waitcnt lgkmcnt(0)
	v_add_f32_e32 v32, v32, v33
	v_mul_f32_e32 v32, 0x4f800000, v32
	v_trunc_f32_e32 v32, v32
	v_mul_f32_e64 v33, |v32|, s62
	v_floor_f32_e32 v33, v33
	v_fma_f32 v34, v33, s63, |v32|
	v_cvt_u32_f32_e32 v34, v34
	v_cvt_u32_f32_e32 v33, v33
	v_ashrrev_i32_e32 v35, 31, v32
	v_xor_b32_e32 v32, v34, v35
	v_xor_b32_e32 v33, v33, v35
	v_sub_co_u32_e32 v32, vcc, v32, v35
	s_nop 1
	v_subb_co_u32_e32 v33, vcc, v33, v35, vcc
	v_lshl_add_u64 v[34:35], v[48:49], 3, s[12:13]
	global_atomic_add_x2 v[34:35], v[32:33], off
; __device__ __forceinline__ void fx_add(float* p, size_t idx, float s) { atomicAdd((unsigned long long*)p + idx, (unsigned long long)(long long)(s * 4294967296.0f)); }
; __device__ __forceinline__ unsigned cvtpk(float lo, float hi) { f32x2v_ v = {lo, hi}; bf16x2v_ b = __builtin_convertvector(v, bf16x2v_); return __builtin_bit_cast(unsigned, b); }
;     __device__ __forceinline__ void operator()(const f32x4 (&acc)[2][2][4][2], const Unit& u, int wr, int wc, int fr, int fq) const {
;     ...
;             for (int m = 0; m < 4; ++m) { const int row = row0 + ai * HALF + m * 16; const size_t off = (size_t)row * 1024 + col0; float s = 0.f;
; #pragma unroll
;                 for (int bj = 0; bj < 2; ++bj) { f32x4 a0, a1;
;                     if (xin32) { const float* p = xin32 + off + bj * HALF; a0 = *(const f32x4*)p; a1 = *(const f32x4*)(p + 4); }
;                     else { const u32x4 w = *(const u32x4*)(xb + off + bj * HALF);
;                         a0 = (f32x4){__uint_as_float(w.x << 16), __uint_as_float(w.x & 0xffff0000u), __uint_as_float(w.y << 16), __uint_as_float(w.y & 0xffff0000u)};
;                         a1 = (f32x4){__uint_as_float(w.z << 16), __uint_as_float(w.z & 0xffff0000u), __uint_as_float(w.w << 16), __uint_as_float(w.w & 0xffff0000u)}; }
;                     const f32x4 v0 = a0 + acc[ai][bj][m][0] * alpha, v1 = a1 + acc[ai][bj][m][1] * alpha;
;                     u32x4 w; w.x = cvtpk(v0[0], v0[1]); w.y = cvtpk(v0[2], v0[3]); w.z = cvtpk(v1[0], v1[1]); w.w = cvtpk(v1[2], v1[3]);
;                     *(u32x4*)(xb + off + bj * HALF) = w;
;                     s += (v0[0] * v0[0] + v0[1] * v0[1]) + (v0[2] * v0[2] + v0[3] * v0[3]) + (v1[0] * v1[0] + v1[1] * v1[1]) + (v1[2] * v1[2] + v1[3] * v1[3]); }
;                 s += __shfl_xor(s, 16); s += __shfl_xor(s, 32);
;                 if (fq == 0) fx_add(ssout, row, s); }
.LBB0_1608:
	s_or_b64 exec, exec, s[46:47]
	v_add_u32_e32 v32, 0xa0, v148
	s_waitcnt lgkmcnt(0)
	v_ashrrev_i32_e32 v33, 31, v32
	v_lshlrev_b64 v[34:35], 11, v[32:33]
	v_lshl_add_u64 v[34:35], s[22:23], 0, v[34:35]
	v_lshl_add_u64 v[42:43], v[146:147], 1, v[34:35]
	s_nop 0
	s_nop 0
	s_waitcnt vmcnt(15)
	v_lshlrev_b32_e32 v44, 16, v208
	v_and_b32_e32 v45, 0xffff0000, v208
	v_lshlrev_b32_e32 v34, 16, v209
	v_and_b32_e32 v35, 0xffff0000, v209
	s_waitcnt vmcnt(14)
	v_lshlrev_b32_e32 v48, 16, v212
	v_and_b32_e32 v49, 0xffff0000, v212
	v_lshlrev_b32_e32 v38, 16, v213
	v_and_b32_e32 v39, 0xffff0000, v213
	v_lshlrev_b32_e32 v46, 16, v210
	v_and_b32_e32 v47, 0xffff0000, v210
	v_lshlrev_b32_e32 v36, 16, v211
	v_and_b32_e32 v37, 0xffff0000, v211
	v_lshlrev_b32_e32 v50, 16, v214
	v_and_b32_e32 v51, 0xffff0000, v214
	v_lshlrev_b32_e32 v40, 16, v215
	v_and_b32_e32 v41, 0xffff0000, v215
	v_pk_add_f32 v[30:31], v[30:31], v[34:35]
	v_pk_add_f32 v[28:29], v[28:29], v[44:45]
	v_pk_add_f32 v[22:23], v[22:23], v[38:39]
	v_pk_add_f32 v[20:21], v[20:21], v[48:49]
	v_pk_add_f32 v[26:27], v[26:27], v[36:37]
	v_pk_add_f32 v[24:25], v[24:25], v[46:47]
	v_pk_add_f32 v[34:35], v[18:19], v[40:41]
	v_pk_add_f32 v[36:37], v[16:17], v[50:51]
	v_mul_f32_e32 v18, v29, v29
	v_mul_f32_e32 v19, v31, v31
	v_mul_f32_e32 v38, v21, v21
	v_mul_f32_e32 v39, v23, v23
	v_cvt_pk_bf16_f32 v16, v28, v29
	v_mul_f32_e32 v29, v25, v25
	v_mul_f32_e32 v40, v37, v37
	v_fmac_f32_e32 v18, v28, v28
	v_fmac_f32_e32 v19, v30, v30
	v_fmac_f32_e32 v38, v20, v20
	v_fmac_f32_e32 v39, v22, v22
	v_cvt_pk_bf16_f32 v17, v30, v31
	v_mul_f32_e32 v31, v27, v27
	v_mul_f32_e32 v41, v35, v35
	v_fmac_f32_e32 v29, v24, v24
	v_fmac_f32_e32 v40, v36, v36
	v_add_f32_e32 v18, v18, v19
	v_add_f32_e32 v19, v38, v39
	v_fmac_f32_e32 v31, v26, v26
	v_fmac_f32_e32 v41, v34, v34
	v_add_f32_e32 v18, v29, v18
	v_add_f32_e32 v19, v40, v19
	v_add_f32_e32 v18, v31, v18
	v_add_f32_e32 v19, v41, v19
	v_add_f32_e32 v28, v18, v19
	ds_bpermute_b32 v29, v157, v28
	v_cvt_pk_bf16_f32 v18, v24, v25
	v_cvt_pk_bf16_f32 v19, v26, v27
	global_store_dwordx4 v[42:43], v[16:19], off
	s_waitcnt lgkmcnt(0)
	s_nop 0
	v_add_f32_e32 v16, v28, v29
	ds_bpermute_b32 v17, v156, v16
	v_cvt_pk_bf16_f32 v18, v20, v21
	v_cvt_pk_bf16_f32 v19, v22, v23
	v_cvt_pk_bf16_f32 v20, v36, v37
	v_cvt_pk_bf16_f32 v21, v34, v35
	global_store_dwordx4 v[42:43], v[18:21], off offset:256
	s_and_saveexec_b64 s[46:47], s[4:5]
	s_cbranch_execz .LBB0_1610
	s_waitcnt lgkmcnt(0)
	v_add_f32_e32 v16, v16, v17
	v_mul_f32_e32 v16, 0x4f800000, v16
	v_trunc_f32_e32 v16, v16
	v_mul_f32_e64 v17, |v16|, s62
	v_floor_f32_e32 v17, v17
	v_fma_f32 v18, v17, s63, |v16|
	v_cvt_u32_f32_e32 v18, v18
	v_cvt_u32_f32_e32 v17, v17
	v_ashrrev_i32_e32 v19, 31, v16
	v_xor_b32_e32 v16, v18, v19
	v_xor_b32_e32 v17, v17, v19
	v_sub_co_u32_e32 v16, vcc, v16, v19
	s_nop 1
	v_subb_co_u32_e32 v17, vcc, v17, v19, vcc
	v_lshl_add_u64 v[18:19], v[32:33], 3, s[12:13]
	global_atomic_add_x2 v[18:19], v[16:17], off
.LBB0_1610:
	s_or_b64 exec, exec, s[46:47]
	v_add_u32_e32 v16, 0xb0, v148
	s_waitcnt lgkmcnt(0)
	v_ashrrev_i32_e32 v17, 31, v16
	v_lshlrev_b64 v[18:19], 11, v[16:17]
	v_lshl_add_u64 v[18:19], s[22:23], 0, v[18:19]
	v_lshl_add_u64 v[26:27], v[146:147], 1, v[18:19]
	s_nop 0
	s_nop 0
	s_waitcnt vmcnt(13)
	v_lshlrev_b32_e32 v28, 16, v216
	v_and_b32_e32 v29, 0xffff0000, v216
	v_lshlrev_b32_e32 v18, 16, v217
	v_and_b32_e32 v19, 0xffff0000, v217
	s_waitcnt vmcnt(12)
	v_lshlrev_b32_e32 v32, 16, v220
	v_and_b32_e32 v33, 0xffff0000, v220
	v_lshlrev_b32_e32 v22, 16, v221
	v_and_b32_e32 v23, 0xffff0000, v221
	v_lshlrev_b32_e32 v30, 16, v218
	v_and_b32_e32 v31, 0xffff0000, v218
	v_lshlrev_b32_e32 v20, 16, v219
	v_and_b32_e32 v21, 0xffff0000, v219
	v_lshlrev_b32_e32 v34, 16, v222
	v_and_b32_e32 v35, 0xffff0000, v222
	v_lshlrev_b32_e32 v24, 16, v223
	v_and_b32_e32 v25, 0xffff0000, v223
	v_pk_add_f32 v[14:15], v[14:15], v[18:19]
	v_pk_add_f32 v[12:13], v[12:13], v[28:29]
	v_pk_add_f32 v[6:7], v[6:7], v[22:23]
	v_pk_add_f32 v[4:5], v[4:5], v[32:33]
	v_pk_add_f32 v[10:11], v[10:11], v[20:21]
	v_pk_add_f32 v[8:9], v[8:9], v[30:31]
	v_pk_add_f32 v[18:19], v[2:3], v[24:25]
	v_pk_add_f32 v[20:21], v[0:1], v[34:35]
	v_mul_f32_e32 v2, v13, v13
	v_mul_f32_e32 v3, v15, v15
	v_mul_f32_e32 v22, v5, v5
	v_mul_f32_e32 v23, v7, v7
	v_cvt_pk_bf16_f32 v0, v12, v13
	v_mul_f32_e32 v13, v9, v9
	v_mul_f32_e32 v24, v21, v21
	v_fmac_f32_e32 v2, v12, v12
	v_fmac_f32_e32 v3, v14, v14
	v_fmac_f32_e32 v22, v4, v4
	v_fmac_f32_e32 v23, v6, v6
	v_cvt_pk_bf16_f32 v1, v14, v15
	v_mul_f32_e32 v15, v11, v11
	v_mul_f32_e32 v25, v19, v19
	v_fmac_f32_e32 v13, v8, v8
	v_fmac_f32_e32 v24, v20, v20
	v_add_f32_e32 v2, v2, v3
	v_add_f32_e32 v3, v22, v23
	v_fmac_f32_e32 v15, v10, v10
	v_fmac_f32_e32 v25, v18, v18
	v_add_f32_e32 v2, v13, v2
	v_add_f32_e32 v3, v24, v3
	v_add_f32_e32 v2, v15, v2
	v_add_f32_e32 v3, v25, v3
	v_add_f32_e32 v12, v2, v3
	ds_bpermute_b32 v13, v157, v12
	v_cvt_pk_bf16_f32 v2, v8, v9
	v_cvt_pk_bf16_f32 v3, v10, v11
	global_store_dwordx4 v[26:27], v[0:3], off
	s_waitcnt lgkmcnt(0)
	s_nop 0
	v_add_f32_e32 v0, v12, v13
	ds_bpermute_b32 v1, v156, v0
	v_cvt_pk_bf16_f32 v2, v4, v5
	v_cvt_pk_bf16_f32 v3, v6, v7
	v_cvt_pk_bf16_f32 v4, v20, v21
	v_cvt_pk_bf16_f32 v5, v18, v19
	global_store_dwordx4 v[26:27], v[2:5], off offset:256
	s_and_saveexec_b64 s[46:47], s[4:5]
	s_cbranch_execz .LBB0_1612
	s_waitcnt lgkmcnt(0)
	v_add_f32_e32 v0, v0, v1
	v_mul_f32_e32 v0, 0x4f800000, v0
	v_trunc_f32_e32 v0, v0
	v_mul_f32_e64 v1, |v0|, s62
	v_floor_f32_e32 v1, v1
	v_fma_f32 v2, v1, s63, |v0|
	v_cvt_u32_f32_e32 v2, v2
	v_cvt_u32_f32_e32 v1, v1
	v_ashrrev_i32_e32 v3, 31, v0
	v_xor_b32_e32 v0, v2, v3
	v_xor_b32_e32 v1, v1, v3
	v_sub_co_u32_e32 v0, vcc, v0, v3
	s_nop 1
	v_subb_co_u32_e32 v1, vcc, v1, v3, vcc
	v_lshl_add_u64 v[2:3], v[16:17], 3, s[12:13]
	global_atomic_add_x2 v[2:3], v[0:1], off

; #define PG8_STAGE(bufoff, gbase, voff) do { _Pragma("unroll") for (int _i = 0; _i < 2; ++_i) \
;         __builtin_amdgcn_global_load_lds((const unsigned*)((const char*)(gbase) + (voff)[_i]), (PG8_LAS unsigned*)(lds + (bufoff) + ldsw + _i * 8192), 16, 0, 0); } while (0)
; #define PG8_LDA(dst, b, h) do { _Pragma("unroll") for (int m = 0; m < 4; ++m) _Pragma("unroll") for (int k = 0; k < 2; ++k) dst[m][k] = *(const PG8_LAS bf16x8*)(lds + PG8_SA(b, h) + aoff + m * 2048 + k * 1024); } while (0)
; #define PG8_LDB(dst, b, h) do { _Pragma("unroll") for (int n = 0; n < 2; ++n) _Pragma("unroll") for (int k = 0; k < 2; ++k) dst[n][k] = *(const PG8_LAS bf16x8*)(lds + PG8_SB(b, h) + boff + n * 2048 + k * 1024); } while (0)
; #define PG8_MMA(ai, bj, At, Bt) do { __builtin_amdgcn_s_setprio(1); _Pragma("unroll") for (int m = 0; m < 4; ++m) _Pragma("unroll") for (int n = 0; n < 2; ++n) _Pragma("unroll") for (int k = 0; k < 2; ++k) \
;         acc[ai][bj][m][n] = __builtin_amdgcn_mfma_f32_16x16x32_bf16(Bt[n][k], At[m][k], acc[ai][bj][m][n], 0, 0, 0); __builtin_amdgcn_s_setprio(0); } while (0)
; #define PG8_WAIT_V(n) asm volatile("s_waitcnt vmcnt(" #n ")" ::: "memory")
; #define PG8_WAIT_L(n) asm volatile("s_waitcnt lgkmcnt(" #n ")" ::: "memory")
; #define PG8_BAR __builtin_amdgcn_s_barrier()
; #define PG8_SCHED __builtin_amdgcn_sched_barrier(0)
; template <class Epi, class Sched, bool ALIGN_EPI = false, bool SP2 = false>
; __device__ __forceinline__ void gemm_phase(PG8_LAS unsigned char* lds, const Gemm g, const Sched& S, const Epi& E) {
;     ...
;             PG8_LDB(B0, 0, 0); PG8_LDB(B1, 0, 1); PG8_SCHED; PG8_LDA(At, 0, 0); PG8_STAGE(PG8_SA(1, 1), a1 + hstep, voffA);
;             PG8_WAIT_V(8); PG8_WAIT_L(0); PG8_BAR; PG8_MMA(0, 0, At, B0); PG8_MMA(0, 1, At, B1); PG8_BAR; PG8_SCHED;
;             PG8_LDA(At, 0, 1); PG8_STAGE(PG8_SB(0, 0), b2, voffB); PG8_STAGE(PG8_SB(0, 1), b2 + hstep, voffB); PG8_STAGE(PG8_SA(0, 0), a2, voffA);
;             PG8_WAIT_V(8); PG8_WAIT_L(0); PG8_BAR; PG8_MMA(1, 0, At, B0); PG8_MMA(1, 1, At, B1); PG8_BAR; PG8_SCHED;
.LBB0_1816:
	ds_read_b128 v[144:147], v151
	ds_read_b128 v[156:159], v151 offset:1024
	ds_read_b128 v[160:163], v151 offset:2048
	ds_read_b128 v[164:167], v151 offset:3072
	ds_read_b128 v[168:171], v152
	ds_read_b128 v[172:175], v152 offset:1024
	ds_read_b128 v[176:179], v152 offset:2048
	ds_read_b128 v[180:183], v152 offset:3072
	s_add_u32 s46, s44, 0xfffe0080
	s_addc_u32 s47, s45, -1
	s_cmp_eq_u32 s61, 4
	s_cselect_b32 s49, s29, s47
	s_cselect_b32 s48, s41, s46
	s_cselect_b32 s47, s27, s60
	s_cselect_b32 s46, s58, s59
	v_lshl_add_u64 v[218:219], s[44:45], 0, v[136:137]
	s_add_i32 m0, s33, 0xc000
	ds_read_b128 v[184:187], v153
	ds_read_b128 v[188:191], v153 offset:1024
	ds_read_b128 v[192:195], v153 offset:2048
	ds_read_b128 v[196:199], v153 offset:3072
	ds_read_b128 v[200:203], v153 offset:4096
	ds_read_b128 v[206:209], v153 offset:5120
	ds_read_b128 v[210:213], v153 offset:6144
	ds_read_b128 v[214:217], v153 offset:7168
	global_load_lds_dwordx4 v[218:219], off
	v_lshl_add_u64 v[218:219], s[44:45], 0, v[138:139]
	s_add_i32 m0, s33, 0xe000
	s_nop 0
	global_load_lds_dwordx4 v[218:219], off
	s_waitcnt vmcnt(8)
	s_waitcnt lgkmcnt(0)
	s_barrier
	s_setprio 1
	s_waitcnt lgkmcnt(0)
	v_mfma_f32_16x16x32_bf16 v[124:127], v[144:147], v[184:187], v[124:127]
	v_mfma_f32_16x16x32_bf16 v[120:123], v[160:163], v[184:187], v[120:123]
	v_mfma_f32_16x16x32_bf16 v[108:111], v[144:147], v[192:195], v[108:111]
	v_mfma_f32_16x16x32_bf16 v[104:107], v[160:163], v[192:195], v[104:107]
	v_mfma_f32_16x16x32_bf16 v[92:95], v[144:147], v[200:203], v[92:95]
	v_mfma_f32_16x16x32_bf16 v[88:91], v[160:163], v[200:203], v[88:91]
	v_mfma_f32_16x16x32_bf16 v[76:79], v[144:147], v[210:213], v[76:79]
	v_mfma_f32_16x16x32_bf16 v[72:75], v[160:163], v[210:213], v[72:75]
	v_mfma_f32_16x16x32_bf16 v[124:127], v[156:159], v[188:191], v[124:127]
	v_mfma_f32_16x16x32_bf16 v[120:123], v[164:167], v[188:191], v[120:123]
	v_mfma_f32_16x16x32_bf16 v[108:111], v[156:159], v[196:199], v[108:111]
	v_mfma_f32_16x16x32_bf16 v[104:107], v[164:167], v[196:199], v[104:107]
	v_mfma_f32_16x16x32_bf16 v[92:95], v[156:159], v[206:209], v[92:95]
	v_mfma_f32_16x16x32_bf16 v[88:91], v[164:167], v[206:209], v[88:91]
	v_mfma_f32_16x16x32_bf16 v[76:79], v[156:159], v[214:217], v[76:79]
	v_mfma_f32_16x16x32_bf16 v[72:75], v[164:167], v[214:217], v[72:75]
	s_setprio 0
	s_setprio 1
	v_mfma_f32_16x16x32_bf16 v[116:119], v[168:171], v[184:187], v[116:119]
	v_mfma_f32_16x16x32_bf16 v[112:115], v[176:179], v[184:187], v[112:115]
	v_mfma_f32_16x16x32_bf16 v[100:103], v[168:171], v[192:195], v[100:103]
	v_mfma_f32_16x16x32_bf16 v[96:99], v[176:179], v[192:195], v[96:99]
	v_mfma_f32_16x16x32_bf16 v[84:87], v[168:171], v[200:203], v[84:87]
	v_mfma_f32_16x16x32_bf16 v[80:83], v[176:179], v[200:203], v[80:83]
	v_mfma_f32_16x16x32_bf16 v[68:71], v[168:171], v[210:213], v[68:71]
	v_mfma_f32_16x16x32_bf16 v[64:67], v[176:179], v[210:213], v[64:67]
	v_mfma_f32_16x16x32_bf16 v[116:119], v[172:175], v[188:191], v[116:119]
	v_mfma_f32_16x16x32_bf16 v[112:115], v[180:183], v[188:191], v[112:115]
	v_mfma_f32_16x16x32_bf16 v[100:103], v[172:175], v[196:199], v[100:103]
	v_mfma_f32_16x16x32_bf16 v[96:99], v[180:183], v[196:199], v[96:99]
	v_mfma_f32_16x16x32_bf16 v[84:87], v[172:175], v[206:209], v[84:87]
	v_mfma_f32_16x16x32_bf16 v[80:83], v[180:183], v[206:209], v[80:83]
	v_mfma_f32_16x16x32_bf16 v[68:71], v[172:175], v[214:217], v[68:71]
	v_mfma_f32_16x16x32_bf16 v[64:67], v[180:183], v[214:217], v[64:67]
	s_setprio 0
	s_barrier
	s_add_i32 s62, s54, s15
	v_lshl_add_u64 v[218:219], s[46:47], 0, v[130:131]
	s_mov_b32 m0, s62
	ds_read_b128 v[184:187], v153 offset:16384
	ds_read_b128 v[188:191], v153 offset:17408
	ds_read_b128 v[192:195], v153 offset:18432
	ds_read_b128 v[196:199], v153 offset:19456
	ds_read_b128 v[200:203], v153 offset:20480
	ds_read_b128 v[206:209], v153 offset:21504
	ds_read_b128 v[210:213], v153 offset:22528
	ds_read_b128 v[214:217], v153 offset:23552
	global_load_lds_dwordx4 v[218:219], off
	s_add_i32 m0, s62, 0x2000
	s_add_u32 s62, s46, 0x20000
	v_lshl_add_u64 v[220:221], s[46:47], 0, v[134:135]
	s_addc_u32 s63, s47, 0
	s_add_i32 s64, s55, s15
	global_load_lds_dwordx4 v[220:221], off
	v_lshl_add_u64 v[222:223], s[62:63], 0, v[130:131]
	s_mov_b32 m0, s64
	v_lshl_add_u64 v[224:225], s[48:49], 0, v[132:133]
	global_load_lds_dwordx4 v[222:223], off
	v_lshl_add_u64 v[222:223], s[62:63], 0, v[134:135]
	s_add_i32 m0, s64, 0x2000
	s_nop 0
	global_load_lds_dwordx4 v[222:223], off
	v_lshl_add_u64 v[222:223], s[48:49], 0, v[128:129]
	s_mov_b32 m0, s33
	s_nop 0
	global_load_lds_dwordx4 v[222:223], off
	s_mov_b32 m0, s34
	s_nop 0
	global_load_lds_dwordx4 v[224:225], off
	s_waitcnt vmcnt(8)
	s_waitcnt lgkmcnt(0)
	s_barrier
; #define PG8_STAGE(bufoff, gbase, voff) do { _Pragma("unroll") for (int _i = 0; _i < 2; ++_i) \
;         __builtin_amdgcn_global_load_lds((const unsigned*)((const char*)(gbase) + (voff)[_i]), (PG8_LAS unsigned*)(lds + (bufoff) + ldsw + _i * 8192), 16, 0, 0); } while (0)
; #define PG8_LDA(dst, b, h) do { _Pragma("unroll") for (int m = 0; m < 4; ++m) _Pragma("unroll") for (int k = 0; k < 2; ++k) dst[m][k] = *(const PG8_LAS bf16x8*)(lds + PG8_SA(b, h) + aoff + m * 2048 + k * 1024); } while (0)
; #define PG8_LDB(dst, b, h) do { _Pragma("unroll") for (int n = 0; n < 2; ++n) _Pragma("unroll") for (int k = 0; k < 2; ++k) dst[n][k] = *(const PG8_LAS bf16x8*)(lds + PG8_SB(b, h) + boff + n * 2048 + k * 1024); } while (0)
; #define PG8_MMA(ai, bj, At, Bt) do { __builtin_amdgcn_s_setprio(1); _Pragma("unroll") for (int m = 0; m < 4; ++m) _Pragma("unroll") for (int n = 0; n < 2; ++n) _Pragma("unroll") for (int k = 0; k < 2; ++k) \
;         acc[ai][bj][m][n] = __builtin_amdgcn_mfma_f32_16x16x32_bf16(Bt[n][k], At[m][k], acc[ai][bj][m][n], 0, 0, 0); __builtin_amdgcn_s_setprio(0); } while (0)
; #define PG8_WAIT_V(n) asm volatile("s_waitcnt vmcnt(" #n ")" ::: "memory")
; #define PG8_WAIT_L(n) asm volatile("s_waitcnt lgkmcnt(" #n ")" ::: "memory")
; #define PG8_BAR __builtin_amdgcn_s_barrier()
; #define PG8_SCHED __builtin_amdgcn_sched_barrier(0)
; template <class Epi, class Sched, bool ALIGN_EPI = false, bool SP2 = false>
; __device__ __forceinline__ void gemm_phase(PG8_LAS unsigned char* lds, const Gemm g, const Sched& S, const Epi& E) {
;     ...
;             PG8_LDA(At, 0, 1); PG8_STAGE(PG8_SB(0, 0), b2, voffB); PG8_STAGE(PG8_SB(0, 1), b2 + hstep, voffB); PG8_STAGE(PG8_SA(0, 0), a2, voffA);
;             PG8_WAIT_V(8); PG8_WAIT_L(0); PG8_BAR; PG8_MMA(1, 0, At, B0); PG8_MMA(1, 1, At, B1); PG8_BAR; PG8_SCHED;
;             PG8_LDB(B0, 1, 0); PG8_LDB(B1, 1, 1); PG8_SCHED; PG8_LDA(At, 1, 0); PG8_STAGE(PG8_SA(0, 1), a2 + hstep, voffA);
;             PG8_WAIT_V(8); PG8_WAIT_L(0); PG8_BAR; PG8_MMA(0, 0, At, B0); PG8_MMA(0, 1, At, B1); PG8_BAR; PG8_SCHED;
	s_setprio 1
	s_waitcnt lgkmcnt(0)
	v_mfma_f32_16x16x32_bf16 v[60:63], v[144:147], v[184:187], v[60:63]
	v_mfma_f32_16x16x32_bf16 v[56:59], v[160:163], v[184:187], v[56:59]
	v_mfma_f32_16x16x32_bf16 v[44:47], v[144:147], v[192:195], v[44:47]
	v_mfma_f32_16x16x32_bf16 v[40:43], v[160:163], v[192:195], v[40:43]
	v_mfma_f32_16x16x32_bf16 v[28:31], v[144:147], v[200:203], v[28:31]
	v_mfma_f32_16x16x32_bf16 v[24:27], v[160:163], v[200:203], v[24:27]
	v_mfma_f32_16x16x32_bf16 v[12:15], v[144:147], v[210:213], v[12:15]
	v_mfma_f32_16x16x32_bf16 v[8:11], v[160:163], v[210:213], v[8:11]
	v_mfma_f32_16x16x32_bf16 v[60:63], v[156:159], v[188:191], v[60:63]
	v_mfma_f32_16x16x32_bf16 v[56:59], v[164:167], v[188:191], v[56:59]
	v_mfma_f32_16x16x32_bf16 v[44:47], v[156:159], v[196:199], v[44:47]
	v_mfma_f32_16x16x32_bf16 v[40:43], v[164:167], v[196:199], v[40:43]
	v_mfma_f32_16x16x32_bf16 v[28:31], v[156:159], v[206:209], v[28:31]
	v_mfma_f32_16x16x32_bf16 v[24:27], v[164:167], v[206:209], v[24:27]
	v_mfma_f32_16x16x32_bf16 v[12:15], v[156:159], v[214:217], v[12:15]
	v_mfma_f32_16x16x32_bf16 v[8:11], v[164:167], v[214:217], v[8:11]
	s_setprio 0
	s_setprio 1
	v_mfma_f32_16x16x32_bf16 v[52:55], v[168:171], v[184:187], v[52:55]
	v_mfma_f32_16x16x32_bf16 v[48:51], v[176:179], v[184:187], v[48:51]
	v_mfma_f32_16x16x32_bf16 v[36:39], v[168:171], v[192:195], v[36:39]
	v_mfma_f32_16x16x32_bf16 v[32:35], v[176:179], v[192:195], v[32:35]
	v_mfma_f32_16x16x32_bf16 v[20:23], v[168:171], v[200:203], v[20:23]
	v_mfma_f32_16x16x32_bf16 v[16:19], v[176:179], v[200:203], v[16:19]
	v_mfma_f32_16x16x32_bf16 v[4:7], v[168:171], v[210:213], v[4:7]
	v_mfma_f32_16x16x32_bf16 v[0:3], v[176:179], v[210:213], v[0:3]
	v_mfma_f32_16x16x32_bf16 v[52:55], v[172:175], v[188:191], v[52:55]
	v_mfma_f32_16x16x32_bf16 v[48:51], v[180:183], v[188:191], v[48:51]
	v_mfma_f32_16x16x32_bf16 v[36:39], v[172:175], v[196:199], v[36:39]
	v_mfma_f32_16x16x32_bf16 v[32:35], v[180:183], v[196:199], v[32:35]
	v_mfma_f32_16x16x32_bf16 v[20:23], v[172:175], v[206:209], v[20:23]
	v_mfma_f32_16x16x32_bf16 v[16:19], v[180:183], v[206:209], v[16:19]
	v_mfma_f32_16x16x32_bf16 v[4:7], v[172:175], v[214:217], v[4:7]
	v_mfma_f32_16x16x32_bf16 v[0:3], v[180:183], v[214:217], v[0:3]
	s_setprio 0
	s_barrier
	s_add_i32 s62, 0, 0x18000
	v_add_u32_e32 v155, s62, v149
	s_add_i32 s63, 0, 0x1c000
	ds_read_b128 v[144:147], v155
	ds_read_b128 v[156:159], v155 offset:1024
	ds_read_b128 v[160:163], v155 offset:2048
	ds_read_b128 v[164:167], v155 offset:3072
	v_add_u32_e32 v155, s63, v149
	ds_read_b128 v[168:171], v155
	ds_read_b128 v[172:175], v155 offset:1024
	ds_read_b128 v[176:179], v155 offset:2048
	ds_read_b128 v[180:183], v155 offset:3072
	s_add_u32 s48, s48, 0x20000
	s_addc_u32 s49, s49, 0
	s_mov_b32 m0, s43
	v_lshl_add_u64 v[226:227], s[48:49], 0, v[128:129]
	ds_read_b128 v[184:187], v153 offset:32768
	ds_read_b128 v[188:191], v153 offset:33792
	ds_read_b128 v[192:195], v153 offset:34816
	ds_read_b128 v[196:199], v153 offset:35840
	ds_read_b128 v[200:203], v153 offset:36864
	ds_read_b128 v[206:209], v153 offset:37888
	ds_read_b128 v[210:213], v153 offset:38912
	ds_read_b128 v[214:217], v153 offset:39936
	global_load_lds_dwordx4 v[226:227], off
	v_lshl_add_u64 v[226:227], s[48:49], 0, v[132:133]
	s_mov_b32 m0, s50
	s_nop 0
	global_load_lds_dwordx4 v[226:227], off
	s_waitcnt vmcnt(8)
	s_waitcnt lgkmcnt(0)
	s_barrier
	s_setprio 1
	s_waitcnt lgkmcnt(0)
	v_mfma_f32_16x16x32_bf16 v[124:127], v[144:147], v[184:187], v[124:127]
	v_mfma_f32_16x16x32_bf16 v[120:123], v[160:163], v[184:187], v[120:123]
	v_mfma_f32_16x16x32_bf16 v[108:111], v[144:147], v[192:195], v[108:111]
	v_mfma_f32_16x16x32_bf16 v[104:107], v[160:163], v[192:195], v[104:107]
	v_mfma_f32_16x16x32_bf16 v[92:95], v[144:147], v[200:203], v[92:95]
	v_mfma_f32_16x16x32_bf16 v[88:91], v[160:163], v[200:203], v[88:91]
	v_mfma_f32_16x16x32_bf16 v[76:79], v[144:147], v[210:213], v[76:79]
	v_mfma_f32_16x16x32_bf16 v[72:75], v[160:163], v[210:213], v[72:75]
	v_mfma_f32_16x16x32_bf16 v[124:127], v[156:159], v[188:191], v[124:127]
	v_mfma_f32_16x16x32_bf16 v[120:123], v[164:167], v[188:191], v[120:123]
	v_mfma_f32_16x16x32_bf16 v[108:111], v[156:159], v[196:199], v[108:111]
	v_mfma_f32_16x16x32_bf16 v[104:107], v[164:167], v[196:199], v[104:107]
	v_mfma_f32_16x16x32_bf16 v[92:95], v[156:159], v[206:209], v[92:95]
	v_mfma_f32_16x16x32_bf16 v[88:91], v[164:167], v[206:209], v[88:91]
	v_mfma_f32_16x16x32_bf16 v[76:79], v[156:159], v[214:217], v[76:79]
	v_mfma_f32_16x16x32_bf16 v[72:75], v[164:167], v[214:217], v[72:75]
	s_setprio 0
	s_setprio 1
	v_mfma_f32_16x16x32_bf16 v[116:119], v[168:171], v[184:187], v[116:119]
	v_mfma_f32_16x16x32_bf16 v[112:115], v[176:179], v[184:187], v[112:115]
	v_mfma_f32_16x16x32_bf16 v[100:103], v[168:171], v[192:195], v[100:103]
	v_mfma_f32_16x16x32_bf16 v[96:99], v[176:179], v[192:195], v[96:99]
	v_mfma_f32_16x16x32_bf16 v[84:87], v[168:171], v[200:203], v[84:87]
	v_mfma_f32_16x16x32_bf16 v[80:83], v[176:179], v[200:203], v[80:83]
	v_mfma_f32_16x16x32_bf16 v[68:71], v[168:171], v[210:213], v[68:71]
	v_mfma_f32_16x16x32_bf16 v[64:67], v[176:179], v[210:213], v[64:67]
	v_mfma_f32_16x16x32_bf16 v[116:119], v[172:175], v[188:191], v[116:119]
	v_mfma_f32_16x16x32_bf16 v[112:115], v[180:183], v[188:191], v[112:115]
	v_mfma_f32_16x16x32_bf16 v[100:103], v[172:175], v[196:199], v[100:103]
	v_mfma_f32_16x16x32_bf16 v[96:99], v[180:183], v[196:199], v[96:99]
	v_mfma_f32_16x16x32_bf16 v[84:87], v[172:175], v[206:209], v[84:87]
	v_mfma_f32_16x16x32_bf16 v[80:83], v[180:183], v[206:209], v[80:83]
	v_mfma_f32_16x16x32_bf16 v[68:71], v[172:175], v[214:217], v[68:71]
	v_mfma_f32_16x16x32_bf16 v[64:67], v[180:183], v[214:217], v[64:67]
	s_setprio 0
	s_barrier
; #define PG8_STAGE(bufoff, gbase, voff) do { _Pragma("unroll") for (int _i = 0; _i < 2; ++_i) \
;         __builtin_amdgcn_global_load_lds((const unsigned*)((const char*)(gbase) + (voff)[_i]), (PG8_LAS unsigned*)(lds + (bufoff) + ldsw + _i * 8192), 16, 0, 0); } while (0)
; #define PG8_LDA(dst, b, h) do { _Pragma("unroll") for (int m = 0; m < 4; ++m) _Pragma("unroll") for (int k = 0; k < 2; ++k) dst[m][k] = *(const PG8_LAS bf16x8*)(lds + PG8_SA(b, h) + aoff + m * 2048 + k * 1024); } while (0)
; #define PG8_MMA(ai, bj, At, Bt) do { __builtin_amdgcn_s_setprio(1); _Pragma("unroll") for (int m = 0; m < 4; ++m) _Pragma("unroll") for (int n = 0; n < 2; ++n) _Pragma("unroll") for (int k = 0; k < 2; ++k) \
;         acc[ai][bj][m][n] = __builtin_amdgcn_mfma_f32_16x16x32_bf16(Bt[n][k], At[m][k], acc[ai][bj][m][n], 0, 0, 0); __builtin_amdgcn_s_setprio(0); } while (0)
; #define PG8_WAIT_V(n) asm volatile("s_waitcnt vmcnt(" #n ")" ::: "memory")
; #define PG8_WAIT_L(n) asm volatile("s_waitcnt lgkmcnt(" #n ")" ::: "memory")
; #define PG8_BAR __builtin_amdgcn_s_barrier()
; #define PG8_SCHED __builtin_amdgcn_sched_barrier(0)
;     __device__ __forceinline__ void operator()(const f32x4 (&acc)[2][2][4][2], const Unit& u, int wr, int wc, int fr, int fq) const {
;     ...
;             for (int m = 0; m < 4; ++m) { const int row = row0 + ai * HALF + m * 16; const size_t off = (size_t)row * 1024 + col0; float s = 0.f;
; #pragma unroll
;                 for (int bj = 0; bj < 2; ++bj) { f32x4 a0, a1;
;                     if (xin32) { const float* p = xin32 + off + bj * HALF; a0 = *(const f32x4*)p; a1 = *(const f32x4*)(p + 4); }
;                     else { const u32x4 w = *(const u32x4*)(xb + off + bj * HALF);
; template <class Epi, class Sched, bool ALIGN_EPI = false, bool SP2 = false>
; __device__ __forceinline__ void gemm_phase(PG8_LAS unsigned char* lds, const Gemm g, const Sched& S, const Epi& E) {
;     ...
;             PG8_LDA(At, 1, 1); PG8_STAGE(PG8_SB(1, 0), b3, voffB); PG8_STAGE(PG8_SB(1, 1), b3 + hstep, voffB); PG8_STAGE(PG8_SA(1, 0), a3, voffA);
;             PG8_WAIT_V(8); PG8_WAIT_L(0); PG8_BAR; PG8_MMA(1, 0, At, B0); PG8_MMA(1, 1, At, B1); PG8_BAR; PG8_SCHED;
	s_add_i32 s48, s62, s15
	v_lshl_add_u64 v[218:219], v[218:219], 0, s[12:13]
	s_mov_b32 m0, s48
	ds_read_b128 v[184:187], v153 offset:49152
	ds_read_b128 v[188:191], v153 offset:50176
	ds_read_b128 v[192:195], v153 offset:51200
	ds_read_b128 v[196:199], v153 offset:52224
	ds_read_b128 v[200:203], v153 offset:53248
	ds_read_b128 v[206:209], v153 offset:54272
	ds_read_b128 v[210:213], v153 offset:55296
	ds_read_b128 v[214:217], v153 offset:56320
	global_load_lds_dwordx4 v[218:219], off
	s_add_i32 m0, s48, 0x2000
	s_add_u32 s46, s46, 0x20080
	v_lshl_add_u64 v[218:219], v[220:221], 0, s[12:13]
	s_addc_u32 s47, s47, 0
	s_add_i32 s48, s63, s15
	global_load_lds_dwordx4 v[218:219], off
	v_lshl_add_u64 v[218:219], s[46:47], 0, v[130:131]
	s_mov_b32 m0, s48
	s_nop 0
	global_load_lds_dwordx4 v[218:219], off
	v_lshl_add_u64 v[218:219], s[46:47], 0, v[134:135]
	s_add_i32 m0, s48, 0x2000
	s_nop 0
	global_load_lds_dwordx4 v[218:219], off
	v_lshl_add_u64 v[218:219], v[222:223], 0, s[12:13]
	s_mov_b32 m0, s52
	s_nop 0
	global_load_lds_dwordx4 v[218:219], off
	v_lshl_add_u64 v[218:219], v[224:225], 0, s[12:13]
	s_mov_b32 m0, s53
	s_nop 0
	global_load_lds_dwordx4 v[218:219], off
	s_waitcnt vmcnt(8)
	s_waitcnt lgkmcnt(0)
	s_barrier
	s_setprio 1
	s_waitcnt lgkmcnt(0)
	v_mfma_f32_16x16x32_bf16 v[60:63], v[144:147], v[184:187], v[60:63]
	v_mfma_f32_16x16x32_bf16 v[56:59], v[160:163], v[184:187], v[56:59]
	v_mfma_f32_16x16x32_bf16 v[44:47], v[144:147], v[192:195], v[44:47]
	v_mfma_f32_16x16x32_bf16 v[40:43], v[160:163], v[192:195], v[40:43]
	v_mfma_f32_16x16x32_bf16 v[28:31], v[144:147], v[200:203], v[28:31]
	v_mfma_f32_16x16x32_bf16 v[24:27], v[160:163], v[200:203], v[24:27]
	v_mfma_f32_16x16x32_bf16 v[12:15], v[144:147], v[210:213], v[12:15]
	v_mfma_f32_16x16x32_bf16 v[8:11], v[160:163], v[210:213], v[8:11]
	v_mfma_f32_16x16x32_bf16 v[60:63], v[156:159], v[188:191], v[60:63]
	v_mfma_f32_16x16x32_bf16 v[56:59], v[164:167], v[188:191], v[56:59]
	v_mfma_f32_16x16x32_bf16 v[44:47], v[156:159], v[196:199], v[44:47]
	v_mfma_f32_16x16x32_bf16 v[40:43], v[164:167], v[196:199], v[40:43]
	v_mfma_f32_16x16x32_bf16 v[28:31], v[156:159], v[206:209], v[28:31]
	v_mfma_f32_16x16x32_bf16 v[24:27], v[164:167], v[206:209], v[24:27]
	v_mfma_f32_16x16x32_bf16 v[12:15], v[156:159], v[214:217], v[12:15]
	v_mfma_f32_16x16x32_bf16 v[8:11], v[164:167], v[214:217], v[8:11]
	s_setprio 0
	s_setprio 1
	v_mfma_f32_16x16x32_bf16 v[52:55], v[168:171], v[184:187], v[52:55]
	v_mfma_f32_16x16x32_bf16 v[48:51], v[176:179], v[184:187], v[48:51]
	v_mfma_f32_16x16x32_bf16 v[36:39], v[168:171], v[192:195], v[36:39]
	v_mfma_f32_16x16x32_bf16 v[32:35], v[176:179], v[192:195], v[32:35]
	v_mfma_f32_16x16x32_bf16 v[20:23], v[168:171], v[200:203], v[20:23]
	v_mfma_f32_16x16x32_bf16 v[16:19], v[176:179], v[200:203], v[16:19]
	v_mfma_f32_16x16x32_bf16 v[4:7], v[168:171], v[210:213], v[4:7]
	v_mfma_f32_16x16x32_bf16 v[0:3], v[176:179], v[210:213], v[0:3]
	v_mfma_f32_16x16x32_bf16 v[52:55], v[172:175], v[188:191], v[52:55]
	v_mfma_f32_16x16x32_bf16 v[48:51], v[180:183], v[188:191], v[48:51]
	v_mfma_f32_16x16x32_bf16 v[36:39], v[172:175], v[196:199], v[36:39]
	v_mfma_f32_16x16x32_bf16 v[32:35], v[180:183], v[196:199], v[32:35]
	v_mfma_f32_16x16x32_bf16 v[20:23], v[172:175], v[206:209], v[20:23]
	v_mfma_f32_16x16x32_bf16 v[16:19], v[180:183], v[206:209], v[16:19]
	v_mfma_f32_16x16x32_bf16 v[4:7], v[172:175], v[214:217], v[4:7]
	v_mfma_f32_16x16x32_bf16 v[0:3], v[180:183], v[214:217], v[0:3]
	s_setprio 0
	s_barrier
	s_add_i32 s61, s61, 2
	s_add_u32 s44, s44, 0x100
	s_addc_u32 s45, s45, 0
	s_add_u32 s59, s59, 0x100
	s_addc_u32 s60, s60, 0
	s_cmp_gt_u32 s61, 5
	s_cbranch_scc0 .LBB0_1816
	v_lshl_add_u32 v146, s42, 8, v148
	v_ashrrev_i32_e32 v147, 31, v146
	v_lshl_or_b32 v144, s40, 8, v150
	v_lshlrev_b64 v[156:157], 11, v[146:147]
	v_ashrrev_i32_e32 v145, 31, v144
	v_lshl_add_u64 v[156:157], s[22:23], 0, v[156:157]
	v_lshl_add_u64 v[166:167], v[144:145], 1, v[156:157]
	s_mov_b64 s[98:99], 0x8000
	s_mov_b64 s[100:101], 0x28000
	global_load_dwordx4 v[182:185], v[166:167], off
	global_load_dwordx4 v[186:189], v[166:167], off offset:256
	v_lshl_add_u64 v[198:199], v[166:167], 0, s[98:99]
	global_load_dwordx4 v[190:193], v[198:199], off
	global_load_dwordx4 v[194:197], v[198:199], off offset:256
	v_lshl_add_u64 v[198:199], v[198:199], 0, s[98:99]
	global_load_dwordx4 v[208:211], v[198:199], off
	global_load_dwordx4 v[212:215], v[198:199], off offset:256
	v_lshl_add_u64 v[198:199], v[198:199], 0, s[98:99]
	global_load_dwordx4 v[216:219], v[198:199], off
	global_load_dwordx4 v[220:223], v[198:199], off offset:256
	v_lshl_add_u64 v[198:199], v[198:199], 0, s[100:101]
	s_and_b64 vcc, exec, s[24:25]
	s_cbranch_vccz .LBB0_1819
	s_barrier
; __device__ __forceinline__ void fx_add(float* p, size_t idx, float s) { atomicAdd((unsigned long long*)p + idx, (unsigned long long)(long long)(s * 4294967296.0f)); }
; __device__ __forceinline__ unsigned cvtpk(float lo, float hi) { f32x2v_ v = {lo, hi}; bf16x2v_ b = __builtin_convertvector(v, bf16x2v_); return __builtin_bit_cast(unsigned, b); }
;     __device__ __forceinline__ void operator()(const f32x4 (&acc)[2][2][4][2], const Unit& u, int wr, int wc, int fr, int fq) const {
;     ...
;             for (int m = 0; m < 4; ++m) { const int row = row0 + ai * HALF + m * 16; const size_t off = (size_t)row * 1024 + col0; float s = 0.f;
; #pragma unroll
;                 for (int bj = 0; bj < 2; ++bj) { f32x4 a0, a1;
;                     if (xin32) { const float* p = xin32 + off + bj * HALF; a0 = *(const f32x4*)p; a1 = *(const f32x4*)(p + 4); }
;                     else { const u32x4 w = *(const u32x4*)(xb + off + bj * HALF);
;                         a0 = (f32x4){__uint_as_float(w.x << 16), __uint_as_float(w.x & 0xffff0000u), __uint_as_float(w.y << 16), __uint_as_float(w.y & 0xffff0000u)};
;                         a1 = (f32x4){__uint_as_float(w.z << 16), __uint_as_float(w.z & 0xffff0000u), __uint_as_float(w.w << 16), __uint_as_float(w.w & 0xffff0000u)}; }
;                     const f32x4 v0 = a0 + acc[ai][bj][m][0] * alpha, v1 = a1 + acc[ai][bj][m][1] * alpha;
;                     u32x4 w; w.x = cvtpk(v0[0], v0[1]); w.y = cvtpk(v0[2], v0[3]); w.z = cvtpk(v1[0], v1[1]); w.w = cvtpk(v1[2], v1[3]);
;                     *(u32x4*)(xb + off + bj * HALF) = w;
;                     s += (v0[0] * v0[0] + v0[1] * v0[1]) + (v0[2] * v0[2] + v0[3] * v0[3]) + (v1[0] * v1[0] + v1[1] * v1[1]) + (v1[2] * v1[2] + v1[3] * v1[3]); }
;                 s += __shfl_xor(s, 16); s += __shfl_xor(s, 32);
;                 if (fq == 0) fx_add(ssout, row, s); }
.LBB0_1819:
	s_nop 0
	s_nop 0
	v_and_b32_e32 v156, 64, v154
	v_xor_b32_e32 v155, 16, v154
	v_add_u32_e32 v156, 64, v156
	v_xor_b32_e32 v157, 32, v154
	v_cmp_lt_i32_e32 vcc, v155, v156
	s_waitcnt vmcnt(6)
	v_lshlrev_b32_e32 v168, 16, v182
	v_cndmask_b32_e32 v155, v154, v155, vcc
	v_cmp_lt_i32_e32 vcc, v157, v156
	v_and_b32_e32 v169, 0xffff0000, v182
	v_lshlrev_b32_e32 v158, 16, v183
	v_and_b32_e32 v159, 0xffff0000, v183
	v_lshlrev_b32_e32 v172, 16, v186
	v_and_b32_e32 v173, 0xffff0000, v186
	v_lshlrev_b32_e32 v162, 16, v187
	v_and_b32_e32 v163, 0xffff0000, v187
	v_cndmask_b32_e32 v157, v154, v157, vcc
	v_lshlrev_b32_e32 v170, 16, v184
	v_and_b32_e32 v171, 0xffff0000, v184
	v_lshlrev_b32_e32 v160, 16, v185
	v_and_b32_e32 v161, 0xffff0000, v185
	v_lshlrev_b32_e32 v174, 16, v188
	v_and_b32_e32 v175, 0xffff0000, v188
	v_lshlrev_b32_e32 v164, 16, v189
	v_and_b32_e32 v165, 0xffff0000, v189
	global_load_dwordx4 v[182:185], v[198:199], off
	global_load_dwordx4 v[186:189], v[198:199], off offset:256
	v_lshl_add_u64 v[198:199], v[198:199], 0, s[98:99]
	v_pk_add_f32 v[126:127], v[126:127], v[158:159]
	v_pk_add_f32 v[124:125], v[124:125], v[168:169]
	v_pk_add_f32 v[118:119], v[118:119], v[162:163]
	v_pk_add_f32 v[116:117], v[116:117], v[172:173]
	v_lshlrev_b32_e32 v156, 2, v155
	v_lshlrev_b32_e32 v155, 2, v157
	v_pk_add_f32 v[122:123], v[122:123], v[160:161]
	v_pk_add_f32 v[120:121], v[120:121], v[170:171]
	v_pk_add_f32 v[158:159], v[114:115], v[164:165]
	v_pk_add_f32 v[160:161], v[112:113], v[174:175]
	v_mul_f32_e32 v114, v125, v125
	v_mul_f32_e32 v115, v127, v127
	v_mul_f32_e32 v157, v117, v117
	v_mul_f32_e32 v162, v119, v119
	v_cvt_pk_bf16_f32 v112, v124, v125
	v_mul_f32_e32 v125, v121, v121
	v_mul_f32_e32 v163, v161, v161
	v_fmac_f32_e32 v114, v124, v124
	v_fmac_f32_e32 v115, v126, v126
	v_fmac_f32_e32 v157, v116, v116
	v_fmac_f32_e32 v162, v118, v118
	v_cvt_pk_bf16_f32 v113, v126, v127
	v_mul_f32_e32 v127, v123, v123
	v_mul_f32_e32 v164, v159, v159
	v_fmac_f32_e32 v125, v120, v120
	v_fmac_f32_e32 v163, v160, v160
	v_add_f32_e32 v114, v114, v115
	v_add_f32_e32 v115, v157, v162
	v_fmac_f32_e32 v127, v122, v122
	v_fmac_f32_e32 v164, v158, v158
	v_add_f32_e32 v114, v125, v114
	v_add_f32_e32 v115, v163, v115
	v_add_f32_e32 v114, v127, v114
	v_add_f32_e32 v115, v164, v115
	v_add_f32_e32 v124, v114, v115
	ds_bpermute_b32 v125, v156, v124
	v_cvt_pk_bf16_f32 v114, v120, v121
	v_cvt_pk_bf16_f32 v115, v122, v123
	global_store_dwordx4 v[166:167], v[112:115], off
	s_waitcnt lgkmcnt(0)
	s_nop 0
	v_add_f32_e32 v112, v124, v125
	ds_bpermute_b32 v113, v155, v112
	v_cvt_pk_bf16_f32 v114, v116, v117
	v_cvt_pk_bf16_f32 v115, v118, v119
	v_cvt_pk_bf16_f32 v116, v160, v161
	v_cvt_pk_bf16_f32 v117, v158, v159
	global_store_dwordx4 v[166:167], v[114:117], off offset:256
	s_and_saveexec_b64 s[40:41], s[4:5]
	s_cbranch_execz .LBB0_1821
	s_waitcnt lgkmcnt(0)
	v_add_f32_e32 v112, v112, v113
	v_mul_f32_e32 v112, 0x4f800000, v112
	v_trunc_f32_e32 v112, v112
	v_mul_f32_e64 v113, |v112|, s56
	v_floor_f32_e32 v113, v113
	v_fma_f32 v114, v113, s57, |v112|
	v_cvt_u32_f32_e32 v114, v114
	v_cvt_u32_f32_e32 v113, v113
	v_ashrrev_i32_e32 v115, 31, v112
	v_xor_b32_e32 v112, v114, v115
	v_xor_b32_e32 v113, v113, v115
	v_sub_co_u32_e32 v112, vcc, v112, v115
	s_nop 1
	v_subb_co_u32_e32 v113, vcc, v113, v115, vcc
	v_lshl_add_u64 v[114:115], v[146:147], 3, s[0:1]
	global_atomic_add_x2 v[114:115], v[112:113], off
.LBB0_1821:
	s_or_b64 exec, exec, s[40:41]
	v_or_b32_e32 v112, 16, v146
	s_waitcnt lgkmcnt(0)
	v_ashrrev_i32_e32 v113, 31, v112
	v_lshlrev_b64 v[114:115], 11, v[112:113]
	v_lshl_add_u64 v[114:115], s[22:23], 0, v[114:115]
	v_lshl_add_u64 v[122:123], v[144:145], 1, v[114:115]
	s_nop 0
	s_nop 0
	s_waitcnt vmcnt(10)
	v_lshlrev_b32_e32 v124, 16, v190
	v_and_b32_e32 v125, 0xffff0000, v190
	v_lshlrev_b32_e32 v114, 16, v191
	v_and_b32_e32 v115, 0xffff0000, v191
	s_waitcnt vmcnt(9)
	v_lshlrev_b32_e32 v158, 16, v194
	v_and_b32_e32 v159, 0xffff0000, v194
	v_lshlrev_b32_e32 v118, 16, v195
	v_and_b32_e32 v119, 0xffff0000, v195
	v_lshlrev_b32_e32 v126, 16, v192
	v_and_b32_e32 v127, 0xffff0000, v192
	v_lshlrev_b32_e32 v116, 16, v193
	v_and_b32_e32 v117, 0xffff0000, v193
	v_lshlrev_b32_e32 v160, 16, v196
	v_and_b32_e32 v161, 0xffff0000, v196
	v_lshlrev_b32_e32 v120, 16, v197
	v_and_b32_e32 v121, 0xffff0000, v197
	global_load_dwordx4 v[190:193], v[198:199], off
	global_load_dwordx4 v[194:197], v[198:199], off offset:256
	v_lshl_add_u64 v[198:199], v[198:199], 0, s[98:99]
	v_pk_add_f32 v[110:111], v[110:111], v[114:115]
	v_pk_add_f32 v[108:109], v[108:109], v[124:125]
	v_pk_add_f32 v[102:103], v[102:103], v[118:119]
	v_pk_add_f32 v[100:101], v[100:101], v[158:159]
	v_pk_add_f32 v[106:107], v[106:107], v[116:117]
	v_pk_add_f32 v[104:105], v[104:105], v[126:127]
	v_pk_add_f32 v[114:115], v[98:99], v[120:121]
	v_pk_add_f32 v[116:117], v[96:97], v[160:161]
	v_mul_f32_e32 v98, v109, v109
	v_mul_f32_e32 v99, v111, v111
	v_mul_f32_e32 v118, v101, v101
	v_mul_f32_e32 v119, v103, v103
	v_cvt_pk_bf16_f32 v96, v108, v109
	v_mul_f32_e32 v109, v105, v105
	v_mul_f32_e32 v120, v117, v117
	v_fmac_f32_e32 v98, v108, v108
	v_fmac_f32_e32 v99, v110, v110
	v_fmac_f32_e32 v118, v100, v100
	v_fmac_f32_e32 v119, v102, v102
	v_cvt_pk_bf16_f32 v97, v110, v111
	v_mul_f32_e32 v111, v107, v107
	v_mul_f32_e32 v121, v115, v115
	v_fmac_f32_e32 v109, v104, v104
	v_fmac_f32_e32 v120, v116, v116
	v_add_f32_e32 v98, v98, v99
	v_add_f32_e32 v99, v118, v119
	v_fmac_f32_e32 v111, v106, v106
	v_fmac_f32_e32 v121, v114, v114
	v_add_f32_e32 v98, v109, v98
	v_add_f32_e32 v99, v120, v99
	v_add_f32_e32 v98, v111, v98
	v_add_f32_e32 v99, v121, v99
	v_add_f32_e32 v108, v98, v99
	ds_bpermute_b32 v109, v156, v108
	v_cvt_pk_bf16_f32 v98, v104, v105
	v_cvt_pk_bf16_f32 v99, v106, v107
	global_store_dwordx4 v[122:123], v[96:99], off
	s_waitcnt lgkmcnt(0)
	s_nop 0
	v_add_f32_e32 v96, v108, v109
	ds_bpermute_b32 v97, v155, v96
	v_cvt_pk_bf16_f32 v98, v100, v101
	v_cvt_pk_bf16_f32 v99, v102, v103
	v_cvt_pk_bf16_f32 v100, v116, v117
	v_cvt_pk_bf16_f32 v101, v114, v115
	global_store_dwordx4 v[122:123], v[98:101], off offset:256
	s_and_saveexec_b64 s[40:41], s[4:5]
	s_cbranch_execz .LBB0_1823
	s_waitcnt lgkmcnt(0)
	v_add_f32_e32 v96, v96, v97
	v_mul_f32_e32 v96, 0x4f800000, v96
	v_trunc_f32_e32 v96, v96
	v_mul_f32_e64 v97, |v96|, s56
	v_floor_f32_e32 v97, v97
	v_fma_f32 v98, v97, s57, |v96|
	v_cvt_u32_f32_e32 v98, v98
	v_cvt_u32_f32_e32 v97, v97
	v_ashrrev_i32_e32 v99, 31, v96
	v_xor_b32_e32 v96, v98, v99
	v_xor_b32_e32 v97, v97, v99
	v_sub_co_u32_e32 v96, vcc, v96, v99
	s_nop 1
	v_subb_co_u32_e32 v97, vcc, v97, v99, vcc
	v_lshl_add_u64 v[98:99], v[112:113], 3, s[0:1]
	global_atomic_add_x2 v[98:99], v[96:97], off
; __device__ __forceinline__ void fx_add(float* p, size_t idx, float s) { atomicAdd((unsigned long long*)p + idx, (unsigned long long)(long long)(s * 4294967296.0f)); }
; __device__ __forceinline__ unsigned cvtpk(float lo, float hi) { f32x2v_ v = {lo, hi}; bf16x2v_ b = __builtin_convertvector(v, bf16x2v_); return __builtin_bit_cast(unsigned, b); }
;     __device__ __forceinline__ void operator()(const f32x4 (&acc)[2][2][4][2], const Unit& u, int wr, int wc, int fr, int fq) const {
;     ...
;             for (int m = 0; m < 4; ++m) { const int row = row0 + ai * HALF + m * 16; const size_t off = (size_t)row * 1024 + col0; float s = 0.f;
; #pragma unroll
;                 for (int bj = 0; bj < 2; ++bj) { f32x4 a0, a1;
;                     if (xin32) { const float* p = xin32 + off + bj * HALF; a0 = *(const f32x4*)p; a1 = *(const f32x4*)(p + 4); }
;                     else { const u32x4 w = *(const u32x4*)(xb + off + bj * HALF);
;                         a0 = (f32x4){__uint_as_float(w.x << 16), __uint_as_float(w.x & 0xffff0000u), __uint_as_float(w.y << 16), __uint_as_float(w.y & 0xffff0000u)};
;                         a1 = (f32x4){__uint_as_float(w.z << 16), __uint_as_float(w.z & 0xffff0000u), __uint_as_float(w.w << 16), __uint_as_float(w.w & 0xffff0000u)}; }
;                     const f32x4 v0 = a0 + acc[ai][bj][m][0] * alpha, v1 = a1 + acc[ai][bj][m][1] * alpha;
;                     u32x4 w; w.x = cvtpk(v0[0], v0[1]); w.y = cvtpk(v0[2], v0[3]); w.z = cvtpk(v1[0], v1[1]); w.w = cvtpk(v1[2], v1[3]);
;                     *(u32x4*)(xb + off + bj * HALF) = w;
;                     s += (v0[0] * v0[0] + v0[1] * v0[1]) + (v0[2] * v0[2] + v0[3] * v0[3]) + (v1[0] * v1[0] + v1[1] * v1[1]) + (v1[2] * v1[2] + v1[3] * v1[3]); }
;                 s += __shfl_xor(s, 16); s += __shfl_xor(s, 32);
;                 if (fq == 0) fx_add(ssout, row, s); }
.LBB0_1823:
	s_or_b64 exec, exec, s[40:41]
	v_or_b32_e32 v96, 32, v146
	s_waitcnt lgkmcnt(0)
	v_ashrrev_i32_e32 v97, 31, v96
	v_lshlrev_b64 v[98:99], 11, v[96:97]
	v_lshl_add_u64 v[98:99], s[22:23], 0, v[98:99]
	v_lshl_add_u64 v[106:107], v[144:145], 1, v[98:99]
	s_nop 0
	s_nop 0
	s_waitcnt vmcnt(13)
	v_lshlrev_b32_e32 v108, 16, v208
	v_and_b32_e32 v109, 0xffff0000, v208
	v_lshlrev_b32_e32 v98, 16, v209
	v_and_b32_e32 v99, 0xffff0000, v209
	s_waitcnt vmcnt(12)
	v_lshlrev_b32_e32 v112, 16, v212
	v_and_b32_e32 v113, 0xffff0000, v212
	v_lshlrev_b32_e32 v102, 16, v213
	v_and_b32_e32 v103, 0xffff0000, v213
	v_lshlrev_b32_e32 v110, 16, v210
	v_and_b32_e32 v111, 0xffff0000, v210
	v_lshlrev_b32_e32 v100, 16, v211
	v_and_b32_e32 v101, 0xffff0000, v211
	v_lshlrev_b32_e32 v114, 16, v214
	v_and_b32_e32 v115, 0xffff0000, v214
	v_lshlrev_b32_e32 v104, 16, v215
	v_and_b32_e32 v105, 0xffff0000, v215
	global_load_dwordx4 v[208:211], v[198:199], off
	global_load_dwordx4 v[212:215], v[198:199], off offset:256
	v_lshl_add_u64 v[198:199], v[198:199], 0, s[98:99]
	v_pk_add_f32 v[94:95], v[94:95], v[98:99]
	v_pk_add_f32 v[92:93], v[92:93], v[108:109]
	v_pk_add_f32 v[86:87], v[86:87], v[102:103]
	v_pk_add_f32 v[84:85], v[84:85], v[112:113]
	v_pk_add_f32 v[90:91], v[90:91], v[100:101]
	v_pk_add_f32 v[88:89], v[88:89], v[110:111]
	v_pk_add_f32 v[98:99], v[82:83], v[104:105]
	v_pk_add_f32 v[100:101], v[80:81], v[114:115]
	v_mul_f32_e32 v82, v93, v93
	v_mul_f32_e32 v83, v95, v95
	v_mul_f32_e32 v102, v85, v85
	v_mul_f32_e32 v103, v87, v87
	v_cvt_pk_bf16_f32 v80, v92, v93
	v_mul_f32_e32 v93, v89, v89
	v_mul_f32_e32 v104, v101, v101
	v_fmac_f32_e32 v82, v92, v92
	v_fmac_f32_e32 v83, v94, v94
	v_fmac_f32_e32 v102, v84, v84
	v_fmac_f32_e32 v103, v86, v86
	v_cvt_pk_bf16_f32 v81, v94, v95
	v_mul_f32_e32 v95, v91, v91
	v_mul_f32_e32 v105, v99, v99
	v_fmac_f32_e32 v93, v88, v88
	v_fmac_f32_e32 v104, v100, v100
	v_add_f32_e32 v82, v82, v83
	v_add_f32_e32 v83, v102, v103
	v_fmac_f32_e32 v95, v90, v90
	v_fmac_f32_e32 v105, v98, v98
	v_add_f32_e32 v82, v93, v82
	v_add_f32_e32 v83, v104, v83
	v_add_f32_e32 v82, v95, v82
	v_add_f32_e32 v83, v105, v83
	v_add_f32_e32 v92, v82, v83
	ds_bpermute_b32 v93, v156, v92
	v_cvt_pk_bf16_f32 v82, v88, v89
	v_cvt_pk_bf16_f32 v83, v90, v91
	global_store_dwordx4 v[106:107], v[80:83], off
	s_waitcnt lgkmcnt(0)
	s_nop 0
	v_add_f32_e32 v80, v92, v93
	ds_bpermute_b32 v81, v155, v80
	v_cvt_pk_bf16_f32 v82, v84, v85
	v_cvt_pk_bf16_f32 v83, v86, v87
	v_cvt_pk_bf16_f32 v84, v100, v101
	v_cvt_pk_bf16_f32 v85, v98, v99
	global_store_dwordx4 v[106:107], v[82:85], off offset:256
	s_and_saveexec_b64 s[40:41], s[4:5]
	s_cbranch_execz .LBB0_1825
	s_waitcnt lgkmcnt(0)
	v_add_f32_e32 v80, v80, v81
	v_mul_f32_e32 v80, 0x4f800000, v80
	v_trunc_f32_e32 v80, v80
	v_mul_f32_e64 v81, |v80|, s56
	v_floor_f32_e32 v81, v81
	v_fma_f32 v82, v81, s57, |v80|
	v_cvt_u32_f32_e32 v82, v82
	v_cvt_u32_f32_e32 v81, v81
	v_ashrrev_i32_e32 v83, 31, v80
	v_xor_b32_e32 v80, v82, v83
	v_xor_b32_e32 v81, v81, v83
	v_sub_co_u32_e32 v80, vcc, v80, v83
	s_nop 1
	v_subb_co_u32_e32 v81, vcc, v81, v83, vcc
	v_lshl_add_u64 v[82:83], v[96:97], 3, s[0:1]
	global_atomic_add_x2 v[82:83], v[80:81], off
.LBB0_1825:
	s_or_b64 exec, exec, s[40:41]
	v_or_b32_e32 v80, 48, v146
	s_waitcnt lgkmcnt(0)
	v_ashrrev_i32_e32 v81, 31, v80
	v_lshlrev_b64 v[82:83], 11, v[80:81]
	v_lshl_add_u64 v[82:83], s[22:23], 0, v[82:83]
	v_lshl_add_u64 v[90:91], v[144:145], 1, v[82:83]
	s_nop 0
	s_nop 0
	s_waitcnt vmcnt(16)
	v_lshlrev_b32_e32 v92, 16, v216
	v_and_b32_e32 v93, 0xffff0000, v216
	v_lshlrev_b32_e32 v82, 16, v217
	v_and_b32_e32 v83, 0xffff0000, v217
	s_waitcnt vmcnt(15)
	v_lshlrev_b32_e32 v96, 16, v220
	v_and_b32_e32 v97, 0xffff0000, v220
	v_lshlrev_b32_e32 v86, 16, v221
	v_and_b32_e32 v87, 0xffff0000, v221
	v_lshlrev_b32_e32 v94, 16, v218
	v_and_b32_e32 v95, 0xffff0000, v218
	v_lshlrev_b32_e32 v84, 16, v219
	v_and_b32_e32 v85, 0xffff0000, v219
	v_lshlrev_b32_e32 v98, 16, v222
	v_and_b32_e32 v99, 0xffff0000, v222
	v_lshlrev_b32_e32 v88, 16, v223
	v_and_b32_e32 v89, 0xffff0000, v223
	global_load_dwordx4 v[216:219], v[198:199], off
	global_load_dwordx4 v[220:223], v[198:199], off offset:256
	v_pk_add_f32 v[78:79], v[78:79], v[82:83]
	v_pk_add_f32 v[76:77], v[76:77], v[92:93]
	v_pk_add_f32 v[70:71], v[70:71], v[86:87]
	v_pk_add_f32 v[68:69], v[68:69], v[96:97]
	v_pk_add_f32 v[74:75], v[74:75], v[84:85]
	v_pk_add_f32 v[72:73], v[72:73], v[94:95]
	v_pk_add_f32 v[82:83], v[66:67], v[88:89]
	v_pk_add_f32 v[84:85], v[64:65], v[98:99]
	v_mul_f32_e32 v66, v77, v77
	v_mul_f32_e32 v67, v79, v79
	v_mul_f32_e32 v86, v69, v69
	v_mul_f32_e32 v87, v71, v71
	v_cvt_pk_bf16_f32 v64, v76, v77
	v_mul_f32_e32 v77, v73, v73
	v_mul_f32_e32 v88, v85, v85
	v_fmac_f32_e32 v66, v76, v76
	v_fmac_f32_e32 v67, v78, v78
	v_fmac_f32_e32 v86, v68, v68
	v_fmac_f32_e32 v87, v70, v70
	v_cvt_pk_bf16_f32 v65, v78, v79
	v_mul_f32_e32 v79, v75, v75
	v_mul_f32_e32 v89, v83, v83
	v_fmac_f32_e32 v77, v72, v72
	v_fmac_f32_e32 v88, v84, v84
	v_add_f32_e32 v66, v66, v67
	v_add_f32_e32 v67, v86, v87
	v_fmac_f32_e32 v79, v74, v74
	v_fmac_f32_e32 v89, v82, v82
	v_add_f32_e32 v66, v77, v66
	v_add_f32_e32 v67, v88, v67
	v_add_f32_e32 v66, v79, v66
	v_add_f32_e32 v67, v89, v67
	v_add_f32_e32 v76, v66, v67
	ds_bpermute_b32 v77, v156, v76
	v_cvt_pk_bf16_f32 v66, v72, v73
	v_cvt_pk_bf16_f32 v67, v74, v75
	global_store_dwordx4 v[90:91], v[64:67], off
	s_waitcnt lgkmcnt(0)
	s_nop 0
	v_add_f32_e32 v64, v76, v77
	ds_bpermute_b32 v65, v155, v64
	v_cvt_pk_bf16_f32 v66, v68, v69
	v_cvt_pk_bf16_f32 v67, v70, v71
	v_cvt_pk_bf16_f32 v68, v84, v85
	v_cvt_pk_bf16_f32 v69, v82, v83
	global_store_dwordx4 v[90:91], v[66:69], off offset:256
	s_and_saveexec_b64 s[40:41], s[4:5]
	s_cbranch_execz .LBB0_1827
	s_waitcnt lgkmcnt(0)
	v_add_f32_e32 v64, v64, v65
	v_mul_f32_e32 v64, 0x4f800000, v64
	v_trunc_f32_e32 v64, v64
	v_mul_f32_e64 v65, |v64|, s56
	v_floor_f32_e32 v65, v65
	v_fma_f32 v66, v65, s57, |v64|
	v_cvt_u32_f32_e32 v66, v66
	v_cvt_u32_f32_e32 v65, v65
	v_ashrrev_i32_e32 v67, 31, v64
	v_xor_b32_e32 v64, v66, v67
	v_xor_b32_e32 v65, v65, v67
	v_sub_co_u32_e32 v64, vcc, v64, v67
	s_nop 1
	v_subb_co_u32_e32 v65, vcc, v65, v67, vcc
	v_lshl_add_u64 v[66:67], v[80:81], 3, s[0:1]
	global_atomic_add_x2 v[66:67], v[64:65], off
; __device__ __forceinline__ void fx_add(float* p, size_t idx, float s) { atomicAdd((unsigned long long*)p + idx, (unsigned long long)(long long)(s * 4294967296.0f)); }
; __device__ __forceinline__ unsigned cvtpk(float lo, float hi) { f32x2v_ v = {lo, hi}; bf16x2v_ b = __builtin_convertvector(v, bf16x2v_); return __builtin_bit_cast(unsigned, b); }
;     __device__ __forceinline__ void operator()(const f32x4 (&acc)[2][2][4][2], const Unit& u, int wr, int wc, int fr, int fq) const {
;     ...
;             for (int m = 0; m < 4; ++m) { const int row = row0 + ai * HALF + m * 16; const size_t off = (size_t)row * 1024 + col0; float s = 0.f;
; #pragma unroll
;                 for (int bj = 0; bj < 2; ++bj) { f32x4 a0, a1;
;                     if (xin32) { const float* p = xin32 + off + bj * HALF; a0 = *(const f32x4*)p; a1 = *(const f32x4*)(p + 4); }
;                     else { const u32x4 w = *(const u32x4*)(xb + off + bj * HALF);
;                         a0 = (f32x4){__uint_as_float(w.x << 16), __uint_as_float(w.x & 0xffff0000u), __uint_as_float(w.y << 16), __uint_as_float(w.y & 0xffff0000u)};
;                         a1 = (f32x4){__uint_as_float(w.z << 16), __uint_as_float(w.z & 0xffff0000u), __uint_as_float(w.w << 16), __uint_as_float(w.w & 0xffff0000u)}; }
;                     const f32x4 v0 = a0 + acc[ai][bj][m][0] * alpha, v1 = a1 + acc[ai][bj][m][1] * alpha;
;                     u32x4 w; w.x = cvtpk(v0[0], v0[1]); w.y = cvtpk(v0[2], v0[3]); w.z = cvtpk(v1[0], v1[1]); w.w = cvtpk(v1[2], v1[3]);
;                     *(u32x4*)(xb + off + bj * HALF) = w;
;                     s += (v0[0] * v0[0] + v0[1] * v0[1]) + (v0[2] * v0[2] + v0[3] * v0[3]) + (v1[0] * v1[0] + v1[1] * v1[1]) + (v1[2] * v1[2] + v1[3] * v1[3]); }
;                 s += __shfl_xor(s, 16); s += __shfl_xor(s, 32);
;                 if (fq == 0) fx_add(ssout, row, s); }
.LBB0_1827:
	s_or_b64 exec, exec, s[40:41]
	v_add_u32_e32 v64, 0x80, v146
	s_waitcnt lgkmcnt(0)
	v_ashrrev_i32_e32 v65, 31, v64
	v_lshlrev_b64 v[66:67], 11, v[64:65]
	v_lshl_add_u64 v[66:67], s[22:23], 0, v[66:67]
	v_lshl_add_u64 v[74:75], v[144:145], 1, v[66:67]
	s_nop 0
	s_nop 0
	s_waitcnt vmcnt(19)
	v_lshlrev_b32_e32 v76, 16, v182
	v_and_b32_e32 v77, 0xffff0000, v182
	v_lshlrev_b32_e32 v66, 16, v183
	v_and_b32_e32 v67, 0xffff0000, v183
	s_waitcnt vmcnt(18)
	v_lshlrev_b32_e32 v80, 16, v186
	v_and_b32_e32 v81, 0xffff0000, v186
	v_lshlrev_b32_e32 v70, 16, v187
	v_and_b32_e32 v71, 0xffff0000, v187
	v_lshlrev_b32_e32 v78, 16, v184
	v_and_b32_e32 v79, 0xffff0000, v184
	v_lshlrev_b32_e32 v68, 16, v185
	v_and_b32_e32 v69, 0xffff0000, v185
	v_lshlrev_b32_e32 v82, 16, v188
	v_and_b32_e32 v83, 0xffff0000, v188
	v_lshlrev_b32_e32 v72, 16, v189
	v_and_b32_e32 v73, 0xffff0000, v189
	v_pk_add_f32 v[62:63], v[62:63], v[66:67]
	v_pk_add_f32 v[60:61], v[60:61], v[76:77]
	v_pk_add_f32 v[54:55], v[54:55], v[70:71]
	v_pk_add_f32 v[52:53], v[52:53], v[80:81]
	v_pk_add_f32 v[58:59], v[58:59], v[68:69]
	v_pk_add_f32 v[56:57], v[56:57], v[78:79]
	v_pk_add_f32 v[66:67], v[50:51], v[72:73]
	v_pk_add_f32 v[68:69], v[48:49], v[82:83]
	v_mul_f32_e32 v50, v61, v61
	v_mul_f32_e32 v51, v63, v63
	v_mul_f32_e32 v70, v53, v53
	v_mul_f32_e32 v71, v55, v55
	v_cvt_pk_bf16_f32 v48, v60, v61
	v_mul_f32_e32 v61, v57, v57
	v_mul_f32_e32 v72, v69, v69
	v_fmac_f32_e32 v50, v60, v60
	v_fmac_f32_e32 v51, v62, v62
	v_fmac_f32_e32 v70, v52, v52
	v_fmac_f32_e32 v71, v54, v54
	v_cvt_pk_bf16_f32 v49, v62, v63
	v_mul_f32_e32 v63, v59, v59
	v_mul_f32_e32 v73, v67, v67
	v_fmac_f32_e32 v61, v56, v56
	v_fmac_f32_e32 v72, v68, v68
	v_add_f32_e32 v50, v50, v51
	v_add_f32_e32 v51, v70, v71
	v_fmac_f32_e32 v63, v58, v58
	v_fmac_f32_e32 v73, v66, v66
	v_add_f32_e32 v50, v61, v50
	v_add_f32_e32 v51, v72, v51
	v_add_f32_e32 v50, v63, v50
	v_add_f32_e32 v51, v73, v51
	v_add_f32_e32 v60, v50, v51
	ds_bpermute_b32 v61, v156, v60
	v_cvt_pk_bf16_f32 v50, v56, v57
	v_cvt_pk_bf16_f32 v51, v58, v59
	global_store_dwordx4 v[74:75], v[48:51], off
	s_waitcnt lgkmcnt(0)
	s_nop 0
	v_add_f32_e32 v48, v60, v61
	ds_bpermute_b32 v49, v155, v48
	v_cvt_pk_bf16_f32 v50, v52, v53
	v_cvt_pk_bf16_f32 v51, v54, v55
	v_cvt_pk_bf16_f32 v52, v68, v69
	v_cvt_pk_bf16_f32 v53, v66, v67
	global_store_dwordx4 v[74:75], v[50:53], off offset:256
	s_and_saveexec_b64 s[40:41], s[4:5]
	s_cbranch_execz .LBB0_1829
	s_waitcnt lgkmcnt(0)
	v_add_f32_e32 v48, v48, v49
	v_mul_f32_e32 v48, 0x4f800000, v48
	v_trunc_f32_e32 v48, v48
	v_mul_f32_e64 v49, |v48|, s56
	v_floor_f32_e32 v49, v49
	v_fma_f32 v50, v49, s57, |v48|
	v_cvt_u32_f32_e32 v50, v50
	v_cvt_u32_f32_e32 v49, v49
	v_ashrrev_i32_e32 v51, 31, v48
	v_xor_b32_e32 v48, v50, v51
	v_xor_b32_e32 v49, v49, v51
	v_sub_co_u32_e32 v48, vcc, v48, v51
	s_nop 1
	v_subb_co_u32_e32 v49, vcc, v49, v51, vcc
	v_lshl_add_u64 v[50:51], v[64:65], 3, s[0:1]
	global_atomic_add_x2 v[50:51], v[48:49], off
.LBB0_1829:
	s_or_b64 exec, exec, s[40:41]
	v_add_u32_e32 v48, 0x90, v146
	s_waitcnt lgkmcnt(0)
	v_ashrrev_i32_e32 v49, 31, v48
	v_lshlrev_b64 v[50:51], 11, v[48:49]
	v_lshl_add_u64 v[50:51], s[22:23], 0, v[50:51]
	v_lshl_add_u64 v[58:59], v[144:145], 1, v[50:51]
	s_nop 0
	s_nop 0
	s_waitcnt vmcnt(17)
	v_lshlrev_b32_e32 v60, 16, v190
	v_and_b32_e32 v61, 0xffff0000, v190
	v_lshlrev_b32_e32 v50, 16, v191
	v_and_b32_e32 v51, 0xffff0000, v191
	s_waitcnt vmcnt(16)
	v_lshlrev_b32_e32 v64, 16, v194
	v_and_b32_e32 v65, 0xffff0000, v194
	v_lshlrev_b32_e32 v54, 16, v195
	v_and_b32_e32 v55, 0xffff0000, v195
	v_lshlrev_b32_e32 v62, 16, v192
	v_and_b32_e32 v63, 0xffff0000, v192
	v_lshlrev_b32_e32 v52, 16, v193
	v_and_b32_e32 v53, 0xffff0000, v193
	v_lshlrev_b32_e32 v66, 16, v196
	v_and_b32_e32 v67, 0xffff0000, v196
	v_lshlrev_b32_e32 v56, 16, v197
	v_and_b32_e32 v57, 0xffff0000, v197
	v_pk_add_f32 v[46:47], v[46:47], v[50:51]
	v_pk_add_f32 v[44:45], v[44:45], v[60:61]
	v_pk_add_f32 v[38:39], v[38:39], v[54:55]
	v_pk_add_f32 v[36:37], v[36:37], v[64:65]
	v_pk_add_f32 v[42:43], v[42:43], v[52:53]
	v_pk_add_f32 v[40:41], v[40:41], v[62:63]
	v_pk_add_f32 v[50:51], v[34:35], v[56:57]
	v_pk_add_f32 v[52:53], v[32:33], v[66:67]
	v_mul_f32_e32 v34, v45, v45
	v_mul_f32_e32 v35, v47, v47
	v_mul_f32_e32 v54, v37, v37
	v_mul_f32_e32 v55, v39, v39
	v_cvt_pk_bf16_f32 v32, v44, v45
	v_mul_f32_e32 v45, v41, v41
	v_mul_f32_e32 v56, v53, v53
	v_fmac_f32_e32 v34, v44, v44
	v_fmac_f32_e32 v35, v46, v46
	v_fmac_f32_e32 v54, v36, v36
	v_fmac_f32_e32 v55, v38, v38
	v_cvt_pk_bf16_f32 v33, v46, v47
	v_mul_f32_e32 v47, v43, v43
	v_mul_f32_e32 v57, v51, v51
	v_fmac_f32_e32 v45, v40, v40
	v_fmac_f32_e32 v56, v52, v52
	v_add_f32_e32 v34, v34, v35
	v_add_f32_e32 v35, v54, v55
	v_fmac_f32_e32 v47, v42, v42
	v_fmac_f32_e32 v57, v50, v50
	v_add_f32_e32 v34, v45, v34
	v_add_f32_e32 v35, v56, v35
	v_add_f32_e32 v34, v47, v34
	v_add_f32_e32 v35, v57, v35
	v_add_f32_e32 v44, v34, v35
	ds_bpermute_b32 v45, v156, v44
	v_cvt_pk_bf16_f32 v34, v40, v41
	v_cvt_pk_bf16_f32 v35, v42, v43
	global_store_dwordx4 v[58:59], v[32:35], off
	s_waitcnt lgkmcnt(0)
	s_nop 0
	v_add_f32_e32 v32, v44, v45
	ds_bpermute_b32 v33, v155, v32
	v_cvt_pk_bf16_f32 v34, v36, v37
	v_cvt_pk_bf16_f32 v35, v38, v39
	v_cvt_pk_bf16_f32 v36, v52, v53
	v_cvt_pk_bf16_f32 v37, v50, v51
	global_store_dwordx4 v[58:59], v[34:37], off offset:256
	s_and_saveexec_b64 s[40:41], s[4:5]
	s_cbranch_execz .LBB0_1831
	s_waitcnt lgkmcnt(0)
	v_add_f32_e32 v32, v32, v33
	v_mul_f32_e32 v32, 0x4f800000, v32
	v_trunc_f32_e32 v32, v32
	v_mul_f32_e64 v33, |v32|, s56
	v_floor_f32_e32 v33, v33
	v_fma_f32 v34, v33, s57, |v32|
	v_cvt_u32_f32_e32 v34, v34
	v_cvt_u32_f32_e32 v33, v33
	v_ashrrev_i32_e32 v35, 31, v32
	v_xor_b32_e32 v32, v34, v35
	v_xor_b32_e32 v33, v33, v35
	v_sub_co_u32_e32 v32, vcc, v32, v35
	s_nop 1
	v_subb_co_u32_e32 v33, vcc, v33, v35, vcc
	v_lshl_add_u64 v[34:35], v[48:49], 3, s[0:1]
	global_atomic_add_x2 v[34:35], v[32:33], off
; __device__ __forceinline__ void fx_add(float* p, size_t idx, float s) { atomicAdd((unsigned long long*)p + idx, (unsigned long long)(long long)(s * 4294967296.0f)); }
; __device__ __forceinline__ unsigned cvtpk(float lo, float hi) { f32x2v_ v = {lo, hi}; bf16x2v_ b = __builtin_convertvector(v, bf16x2v_); return __builtin_bit_cast(unsigned, b); }
;     __device__ __forceinline__ void operator()(const f32x4 (&acc)[2][2][4][2], const Unit& u, int wr, int wc, int fr, int fq) const {
;     ...
;             for (int m = 0; m < 4; ++m) { const int row = row0 + ai * HALF + m * 16; const size_t off = (size_t)row * 1024 + col0; float s = 0.f;
; #pragma unroll
;                 for (int bj = 0; bj < 2; ++bj) { f32x4 a0, a1;
;                     if (xin32) { const float* p = xin32 + off + bj * HALF; a0 = *(const f32x4*)p; a1 = *(const f32x4*)(p + 4); }
;                     else { const u32x4 w = *(const u32x4*)(xb + off + bj * HALF);
;                         a0 = (f32x4){__uint_as_float(w.x << 16), __uint_as_float(w.x & 0xffff0000u), __uint_as_float(w.y << 16), __uint_as_float(w.y & 0xffff0000u)};
;                         a1 = (f32x4){__uint_as_float(w.z << 16), __uint_as_float(w.z & 0xffff0000u), __uint_as_float(w.w << 16), __uint_as_float(w.w & 0xffff0000u)}; }
;                     const f32x4 v0 = a0 + acc[ai][bj][m][0] * alpha, v1 = a1 + acc[ai][bj][m][1] * alpha;
;                     u32x4 w; w.x = cvtpk(v0[0], v0[1]); w.y = cvtpk(v0[2], v0[3]); w.z = cvtpk(v1[0], v1[1]); w.w = cvtpk(v1[2], v1[3]);
;                     *(u32x4*)(xb + off + bj * HALF) = w;
;                     s += (v0[0] * v0[0] + v0[1] * v0[1]) + (v0[2] * v0[2] + v0[3] * v0[3]) + (v1[0] * v1[0] + v1[1] * v1[1]) + (v1[2] * v1[2] + v1[3] * v1[3]); }
;                 s += __shfl_xor(s, 16); s += __shfl_xor(s, 32);
;                 if (fq == 0) fx_add(ssout, row, s); }
.LBB0_1831:
	s_or_b64 exec, exec, s[40:41]
	v_add_u32_e32 v32, 0xa0, v146
	s_waitcnt lgkmcnt(0)
	v_ashrrev_i32_e32 v33, 31, v32
	v_lshlrev_b64 v[34:35], 11, v[32:33]
	v_lshl_add_u64 v[34:35], s[22:23], 0, v[34:35]
	v_lshl_add_u64 v[42:43], v[144:145], 1, v[34:35]
	s_nop 0
	s_nop 0
	s_waitcnt vmcnt(15)
	v_lshlrev_b32_e32 v44, 16, v208
	v_and_b32_e32 v45, 0xffff0000, v208
	v_lshlrev_b32_e32 v34, 16, v209
	v_and_b32_e32 v35, 0xffff0000, v209
	s_waitcnt vmcnt(14)
	v_lshlrev_b32_e32 v48, 16, v212
	v_and_b32_e32 v49, 0xffff0000, v212
	v_lshlrev_b32_e32 v38, 16, v213
	v_and_b32_e32 v39, 0xffff0000, v213
	v_lshlrev_b32_e32 v46, 16, v210
	v_and_b32_e32 v47, 0xffff0000, v210
	v_lshlrev_b32_e32 v36, 16, v211
	v_and_b32_e32 v37, 0xffff0000, v211
	v_lshlrev_b32_e32 v50, 16, v214
	v_and_b32_e32 v51, 0xffff0000, v214
	v_lshlrev_b32_e32 v40, 16, v215
	v_and_b32_e32 v41, 0xffff0000, v215
	v_pk_add_f32 v[30:31], v[30:31], v[34:35]
	v_pk_add_f32 v[28:29], v[28:29], v[44:45]
	v_pk_add_f32 v[22:23], v[22:23], v[38:39]
	v_pk_add_f32 v[20:21], v[20:21], v[48:49]
	v_pk_add_f32 v[26:27], v[26:27], v[36:37]
	v_pk_add_f32 v[24:25], v[24:25], v[46:47]
	v_pk_add_f32 v[34:35], v[18:19], v[40:41]
	v_pk_add_f32 v[36:37], v[16:17], v[50:51]
	v_mul_f32_e32 v18, v29, v29
	v_mul_f32_e32 v19, v31, v31
	v_mul_f32_e32 v38, v21, v21
	v_mul_f32_e32 v39, v23, v23
	v_cvt_pk_bf16_f32 v16, v28, v29
	v_mul_f32_e32 v29, v25, v25
	v_mul_f32_e32 v40, v37, v37
	v_fmac_f32_e32 v18, v28, v28
	v_fmac_f32_e32 v19, v30, v30
	v_fmac_f32_e32 v38, v20, v20
	v_fmac_f32_e32 v39, v22, v22
	v_cvt_pk_bf16_f32 v17, v30, v31
	v_mul_f32_e32 v31, v27, v27
	v_mul_f32_e32 v41, v35, v35
	v_fmac_f32_e32 v29, v24, v24
	v_fmac_f32_e32 v40, v36, v36
	v_add_f32_e32 v18, v18, v19
	v_add_f32_e32 v19, v38, v39
	v_fmac_f32_e32 v31, v26, v26
	v_fmac_f32_e32 v41, v34, v34
	v_add_f32_e32 v18, v29, v18
	v_add_f32_e32 v19, v40, v19
	v_add_f32_e32 v18, v31, v18
	v_add_f32_e32 v19, v41, v19
	v_add_f32_e32 v28, v18, v19
	ds_bpermute_b32 v29, v156, v28
	v_cvt_pk_bf16_f32 v18, v24, v25
	v_cvt_pk_bf16_f32 v19, v26, v27
	global_store_dwordx4 v[42:43], v[16:19], off
	s_waitcnt lgkmcnt(0)
	s_nop 0
	v_add_f32_e32 v16, v28, v29
	ds_bpermute_b32 v17, v155, v16
	v_cvt_pk_bf16_f32 v18, v20, v21
	v_cvt_pk_bf16_f32 v19, v22, v23
	v_cvt_pk_bf16_f32 v20, v36, v37
	v_cvt_pk_bf16_f32 v21, v34, v35
	global_store_dwordx4 v[42:43], v[18:21], off offset:256
	s_and_saveexec_b64 s[40:41], s[4:5]
	s_cbranch_execz .LBB0_1833
	s_waitcnt lgkmcnt(0)
	v_add_f32_e32 v16, v16, v17
	v_mul_f32_e32 v16, 0x4f800000, v16
	v_trunc_f32_e32 v16, v16
	v_mul_f32_e64 v17, |v16|, s56
	v_floor_f32_e32 v17, v17
	v_fma_f32 v18, v17, s57, |v16|
	v_cvt_u32_f32_e32 v18, v18
	v_cvt_u32_f32_e32 v17, v17
	v_ashrrev_i32_e32 v19, 31, v16
	v_xor_b32_e32 v16, v18, v19
	v_xor_b32_e32 v17, v17, v19
	v_sub_co_u32_e32 v16, vcc, v16, v19
	s_nop 1
	v_subb_co_u32_e32 v17, vcc, v17, v19, vcc
	v_lshl_add_u64 v[18:19], v[32:33], 3, s[0:1]
	global_atomic_add_x2 v[18:19], v[16:17], off
.LBB0_1833:
	s_or_b64 exec, exec, s[40:41]
	v_add_u32_e32 v16, 0xb0, v146
	s_waitcnt lgkmcnt(0)
	v_ashrrev_i32_e32 v17, 31, v16
	v_lshlrev_b64 v[18:19], 11, v[16:17]
	v_lshl_add_u64 v[18:19], s[22:23], 0, v[18:19]
	v_lshl_add_u64 v[26:27], v[144:145], 1, v[18:19]
	s_nop 0
	s_nop 0
	s_waitcnt vmcnt(13)
	v_lshlrev_b32_e32 v28, 16, v216
	v_and_b32_e32 v29, 0xffff0000, v216
	v_lshlrev_b32_e32 v18, 16, v217
	v_and_b32_e32 v19, 0xffff0000, v217
	s_waitcnt vmcnt(12)
	v_lshlrev_b32_e32 v32, 16, v220
	v_and_b32_e32 v33, 0xffff0000, v220
	v_lshlrev_b32_e32 v22, 16, v221
	v_and_b32_e32 v23, 0xffff0000, v221
	v_lshlrev_b32_e32 v30, 16, v218
	v_and_b32_e32 v31, 0xffff0000, v218
	v_lshlrev_b32_e32 v20, 16, v219
	v_and_b32_e32 v21, 0xffff0000, v219
	v_lshlrev_b32_e32 v34, 16, v222
	v_and_b32_e32 v35, 0xffff0000, v222
	v_lshlrev_b32_e32 v24, 16, v223
	v_and_b32_e32 v25, 0xffff0000, v223
	v_pk_add_f32 v[14:15], v[14:15], v[18:19]
	v_pk_add_f32 v[12:13], v[12:13], v[28:29]
	v_pk_add_f32 v[6:7], v[6:7], v[22:23]
	v_pk_add_f32 v[4:5], v[4:5], v[32:33]
	v_pk_add_f32 v[10:11], v[10:11], v[20:21]
	v_pk_add_f32 v[8:9], v[8:9], v[30:31]
	v_pk_add_f32 v[18:19], v[2:3], v[24:25]
	v_pk_add_f32 v[20:21], v[0:1], v[34:35]
	v_mul_f32_e32 v2, v13, v13
	v_mul_f32_e32 v3, v15, v15
	v_mul_f32_e32 v22, v5, v5
	v_mul_f32_e32 v23, v7, v7
	v_cvt_pk_bf16_f32 v0, v12, v13
	v_mul_f32_e32 v13, v9, v9
	v_mul_f32_e32 v24, v21, v21
	v_fmac_f32_e32 v2, v12, v12
	v_fmac_f32_e32 v3, v14, v14
	v_fmac_f32_e32 v22, v4, v4
	v_fmac_f32_e32 v23, v6, v6
	v_cvt_pk_bf16_f32 v1, v14, v15
	v_mul_f32_e32 v15, v11, v11
	v_mul_f32_e32 v25, v19, v19
	v_fmac_f32_e32 v13, v8, v8
	v_fmac_f32_e32 v24, v20, v20
	v_add_f32_e32 v2, v2, v3
	v_add_f32_e32 v3, v22, v23
	v_fmac_f32_e32 v15, v10, v10
	v_fmac_f32_e32 v25, v18, v18
	v_add_f32_e32 v2, v13, v2
	v_add_f32_e32 v3, v24, v3
	v_add_f32_e32 v2, v15, v2
	v_add_f32_e32 v3, v25, v3
	v_add_f32_e32 v12, v2, v3
	ds_bpermute_b32 v13, v156, v12
	v_cvt_pk_bf16_f32 v2, v8, v9
	v_cvt_pk_bf16_f32 v3, v10, v11
	global_store_dwordx4 v[26:27], v[0:3], off
	s_waitcnt lgkmcnt(0)
	s_nop 0
	v_add_f32_e32 v0, v12, v13
	ds_bpermute_b32 v1, v155, v0
	v_cvt_pk_bf16_f32 v2, v4, v5
	v_cvt_pk_bf16_f32 v3, v6, v7
	v_cvt_pk_bf16_f32 v4, v20, v21
	v_cvt_pk_bf16_f32 v5, v18, v19
	global_store_dwordx4 v[26:27], v[2:5], off offset:256
	s_and_saveexec_b64 s[40:41], s[4:5]
	s_cbranch_execz .LBB0_1835
	s_waitcnt lgkmcnt(0)
	v_add_f32_e32 v0, v0, v1
	v_mul_f32_e32 v0, 0x4f800000, v0
	v_trunc_f32_e32 v0, v0
	v_mul_f32_e64 v1, |v0|, s56
	v_floor_f32_e32 v1, v1
	v_fma_f32 v2, v1, s57, |v0|
	v_cvt_u32_f32_e32 v2, v2
	v_cvt_u32_f32_e32 v1, v1
	v_ashrrev_i32_e32 v3, 31, v0
	v_xor_b32_e32 v0, v2, v3
	v_xor_b32_e32 v1, v1, v3
	v_sub_co_u32_e32 v0, vcc, v0, v3
	s_nop 1
	v_subb_co_u32_e32 v1, vcc, v1, v3, vcc
	v_lshl_add_u64 v[2:3], v[16:17], 3, s[0:1]
	global_atomic_add_x2 v[2:3], v[0:1], off

; #define PG8_STAGE(bufoff, gbase, voff) do { _Pragma("unroll") for (int _i = 0; _i < 2; ++_i) \
;         __builtin_amdgcn_global_load_lds((const unsigned*)((const char*)(gbase) + (voff)[_i]), (PG8_LAS unsigned*)(lds + (bufoff) + ldsw + _i * 8192), 16, 0, 0); } while (0)
; #define PG8_LDA(dst, b, h) do { _Pragma("unroll") for (int m = 0; m < 4; ++m) _Pragma("unroll") for (int k = 0; k < 2; ++k) dst[m][k] = *(const PG8_LAS bf16x8*)(lds + PG8_SA(b, h) + aoff + m * 2048 + k * 1024); } while (0)
; #define PG8_LDB(dst, b, h) do { _Pragma("unroll") for (int n = 0; n < 2; ++n) _Pragma("unroll") for (int k = 0; k < 2; ++k) dst[n][k] = *(const PG8_LAS bf16x8*)(lds + PG8_SB(b, h) + boff + n * 2048 + k * 1024); } while (0)
; #define PG8_MMA(ai, bj, At, Bt) do { __builtin_amdgcn_s_setprio(1); _Pragma("unroll") for (int m = 0; m < 4; ++m) _Pragma("unroll") for (int n = 0; n < 2; ++n) _Pragma("unroll") for (int k = 0; k < 2; ++k) \
;         acc[ai][bj][m][n] = __builtin_amdgcn_mfma_f32_16x16x32_bf16(Bt[n][k], At[m][k], acc[ai][bj][m][n], 0, 0, 0); __builtin_amdgcn_s_setprio(0); } while (0)
; #define PG8_WAIT_V(n) asm volatile("s_waitcnt vmcnt(" #n ")" ::: "memory")
; #define PG8_WAIT_L(n) asm volatile("s_waitcnt lgkmcnt(" #n ")" ::: "memory")
; #define PG8_BAR __builtin_amdgcn_s_barrier()
; #define PG8_SCHED __builtin_amdgcn_sched_barrier(0)
; template <class Epi, class Sched, bool ALIGN_EPI = false, bool SP2 = false>
; __device__ __forceinline__ void gemm_phase(PG8_LAS unsigned char* lds, const Gemm g, const Sched& S, const Epi& E) {
;     ...
;             PG8_LDB(B0, 0, 0); PG8_LDB(B1, 0, 1); PG8_SCHED; PG8_LDA(At, 0, 0); PG8_STAGE(PG8_SA(1, 1), a1 + hstep, voffA);
;             PG8_WAIT_V(8); PG8_WAIT_L(0); PG8_BAR; PG8_MMA(0, 0, At, B0); PG8_MMA(0, 1, At, B1); PG8_BAR; PG8_SCHED;
;             PG8_LDA(At, 0, 1); PG8_STAGE(PG8_SB(0, 0), b2, voffB); PG8_STAGE(PG8_SB(0, 1), b2 + hstep, voffB); PG8_STAGE(PG8_SA(0, 0), a2, voffA);
;             PG8_WAIT_V(8); PG8_WAIT_L(0); PG8_BAR; PG8_MMA(1, 0, At, B0); PG8_MMA(1, 1, At, B1); PG8_BAR; PG8_SCHED;
.LBB0_1978:
	ds_read_b128 v[144:147], v151
	ds_read_b128 v[156:159], v151 offset:1024
	ds_read_b128 v[160:163], v151 offset:2048
	ds_read_b128 v[164:167], v151 offset:3072
	ds_read_b128 v[168:171], v152
	ds_read_b128 v[172:175], v152 offset:1024
	ds_read_b128 v[176:179], v152 offset:2048
	ds_read_b128 v[180:183], v152 offset:3072
	s_add_u32 s28, s26, 0x100
	s_addc_u32 s29, s27, 0
	s_cmp_eq_u32 s55, 40
	s_cselect_b32 s39, s1, s29
	s_cselect_b32 s38, s0, s28
	s_cselect_b32 s37, s25, s54
	s_cselect_b32 s36, s24, s53
	v_lshl_add_u64 v[218:219], s[26:27], 0, v[136:137]
	s_add_i32 m0, s33, 0xc000
	ds_read_b128 v[184:187], v153
	ds_read_b128 v[188:191], v153 offset:1024
	ds_read_b128 v[192:195], v153 offset:2048
	ds_read_b128 v[196:199], v153 offset:3072
	ds_read_b128 v[200:203], v153 offset:4096
	ds_read_b128 v[206:209], v153 offset:5120
	ds_read_b128 v[210:213], v153 offset:6144
	ds_read_b128 v[214:217], v153 offset:7168
	global_load_lds_dwordx4 v[218:219], off
	v_lshl_add_u64 v[218:219], s[26:27], 0, v[138:139]
	s_add_i32 m0, s33, 0xe000
	s_nop 0
	global_load_lds_dwordx4 v[218:219], off
	s_waitcnt vmcnt(8)
	s_waitcnt lgkmcnt(0)
	s_barrier
	s_setprio 1
	s_waitcnt lgkmcnt(0)
	v_mfma_f32_16x16x32_bf16 v[124:127], v[144:147], v[184:187], v[124:127]
	v_mfma_f32_16x16x32_bf16 v[120:123], v[160:163], v[184:187], v[120:123]
	v_mfma_f32_16x16x32_bf16 v[108:111], v[144:147], v[192:195], v[108:111]
	v_mfma_f32_16x16x32_bf16 v[104:107], v[160:163], v[192:195], v[104:107]
	v_mfma_f32_16x16x32_bf16 v[92:95], v[144:147], v[200:203], v[92:95]
	v_mfma_f32_16x16x32_bf16 v[88:91], v[160:163], v[200:203], v[88:91]
	v_mfma_f32_16x16x32_bf16 v[76:79], v[144:147], v[210:213], v[76:79]
	v_mfma_f32_16x16x32_bf16 v[72:75], v[160:163], v[210:213], v[72:75]
	v_mfma_f32_16x16x32_bf16 v[124:127], v[156:159], v[188:191], v[124:127]
	v_mfma_f32_16x16x32_bf16 v[120:123], v[164:167], v[188:191], v[120:123]
	v_mfma_f32_16x16x32_bf16 v[108:111], v[156:159], v[196:199], v[108:111]
	v_mfma_f32_16x16x32_bf16 v[104:107], v[164:167], v[196:199], v[104:107]
	v_mfma_f32_16x16x32_bf16 v[92:95], v[156:159], v[206:209], v[92:95]
	v_mfma_f32_16x16x32_bf16 v[88:91], v[164:167], v[206:209], v[88:91]
	v_mfma_f32_16x16x32_bf16 v[76:79], v[156:159], v[214:217], v[76:79]
	v_mfma_f32_16x16x32_bf16 v[72:75], v[164:167], v[214:217], v[72:75]
	s_setprio 0
	s_setprio 1
	v_mfma_f32_16x16x32_bf16 v[116:119], v[168:171], v[184:187], v[116:119]
	v_mfma_f32_16x16x32_bf16 v[112:115], v[176:179], v[184:187], v[112:115]
	v_mfma_f32_16x16x32_bf16 v[100:103], v[168:171], v[192:195], v[100:103]
	v_mfma_f32_16x16x32_bf16 v[96:99], v[176:179], v[192:195], v[96:99]
	v_mfma_f32_16x16x32_bf16 v[84:87], v[168:171], v[200:203], v[84:87]
	v_mfma_f32_16x16x32_bf16 v[80:83], v[176:179], v[200:203], v[80:83]
	v_mfma_f32_16x16x32_bf16 v[68:71], v[168:171], v[210:213], v[68:71]
	v_mfma_f32_16x16x32_bf16 v[64:67], v[176:179], v[210:213], v[64:67]
	v_mfma_f32_16x16x32_bf16 v[116:119], v[172:175], v[188:191], v[116:119]
	v_mfma_f32_16x16x32_bf16 v[112:115], v[180:183], v[188:191], v[112:115]
	v_mfma_f32_16x16x32_bf16 v[100:103], v[172:175], v[196:199], v[100:103]
	v_mfma_f32_16x16x32_bf16 v[96:99], v[180:183], v[196:199], v[96:99]
	v_mfma_f32_16x16x32_bf16 v[84:87], v[172:175], v[206:209], v[84:87]
	v_mfma_f32_16x16x32_bf16 v[80:83], v[180:183], v[206:209], v[80:83]
	v_mfma_f32_16x16x32_bf16 v[68:71], v[172:175], v[214:217], v[68:71]
	v_mfma_f32_16x16x32_bf16 v[64:67], v[180:183], v[214:217], v[64:67]
	s_setprio 0
	s_barrier
	s_add_i32 s26, s45, s15
	v_lshl_add_u64 v[218:219], s[36:37], 0, v[130:131]
	s_mov_b32 m0, s26
	ds_read_b128 v[184:187], v153 offset:16384
	ds_read_b128 v[188:191], v153 offset:17408
	ds_read_b128 v[192:195], v153 offset:18432
	ds_read_b128 v[196:199], v153 offset:19456
	ds_read_b128 v[200:203], v153 offset:20480
	ds_read_b128 v[206:209], v153 offset:21504
	ds_read_b128 v[210:213], v153 offset:22528
	ds_read_b128 v[214:217], v153 offset:23552
	global_load_lds_dwordx4 v[218:219], off
	s_add_i32 m0, s26, 0x2000
	s_add_u32 s26, s36, 0xb0000
	v_lshl_add_u64 v[220:221], s[36:37], 0, v[134:135]
	s_addc_u32 s27, s37, 0
	s_add_i32 s56, s46, s15
	global_load_lds_dwordx4 v[220:221], off
	v_lshl_add_u64 v[222:223], s[26:27], 0, v[130:131]
	s_mov_b32 m0, s56
	v_lshl_add_u64 v[224:225], s[38:39], 0, v[132:133]
	global_load_lds_dwordx4 v[222:223], off
	v_lshl_add_u64 v[222:223], s[26:27], 0, v[134:135]
	s_add_i32 m0, s56, 0x2000
	s_nop 0
	global_load_lds_dwordx4 v[222:223], off
	v_lshl_add_u64 v[222:223], s[38:39], 0, v[128:129]
	s_mov_b32 m0, s33
	s_nop 0
	global_load_lds_dwordx4 v[222:223], off
	s_mov_b32 m0, s34
	s_nop 0
	global_load_lds_dwordx4 v[224:225], off
	s_waitcnt vmcnt(8)
	s_waitcnt lgkmcnt(0)
	s_barrier
; #define PG8_STAGE(bufoff, gbase, voff) do { _Pragma("unroll") for (int _i = 0; _i < 2; ++_i) \
;         __builtin_amdgcn_global_load_lds((const unsigned*)((const char*)(gbase) + (voff)[_i]), (PG8_LAS unsigned*)(lds + (bufoff) + ldsw + _i * 8192), 16, 0, 0); } while (0)
; #define PG8_LDA(dst, b, h) do { _Pragma("unroll") for (int m = 0; m < 4; ++m) _Pragma("unroll") for (int k = 0; k < 2; ++k) dst[m][k] = *(const PG8_LAS bf16x8*)(lds + PG8_SA(b, h) + aoff + m * 2048 + k * 1024); } while (0)
; #define PG8_LDB(dst, b, h) do { _Pragma("unroll") for (int n = 0; n < 2; ++n) _Pragma("unroll") for (int k = 0; k < 2; ++k) dst[n][k] = *(const PG8_LAS bf16x8*)(lds + PG8_SB(b, h) + boff + n * 2048 + k * 1024); } while (0)
; #define PG8_MMA(ai, bj, At, Bt) do { __builtin_amdgcn_s_setprio(1); _Pragma("unroll") for (int m = 0; m < 4; ++m) _Pragma("unroll") for (int n = 0; n < 2; ++n) _Pragma("unroll") for (int k = 0; k < 2; ++k) \
;         acc[ai][bj][m][n] = __builtin_amdgcn_mfma_f32_16x16x32_bf16(Bt[n][k], At[m][k], acc[ai][bj][m][n], 0, 0, 0); __builtin_amdgcn_s_setprio(0); } while (0)
; #define PG8_WAIT_V(n) asm volatile("s_waitcnt vmcnt(" #n ")" ::: "memory")
; #define PG8_WAIT_L(n) asm volatile("s_waitcnt lgkmcnt(" #n ")" ::: "memory")
; #define PG8_BAR __builtin_amdgcn_s_barrier()
; #define PG8_SCHED __builtin_amdgcn_sched_barrier(0)
; template <class Epi, class Sched, bool ALIGN_EPI = false, bool SP2 = false>
; __device__ __forceinline__ void gemm_phase(PG8_LAS unsigned char* lds, const Gemm g, const Sched& S, const Epi& E) {
;     ...
;             PG8_WAIT_V(8); PG8_WAIT_L(0); PG8_BAR; PG8_MMA(1, 0, At, B0); PG8_MMA(1, 1, At, B1); PG8_BAR; PG8_SCHED;
;             PG8_LDB(B0, 1, 0); PG8_LDB(B1, 1, 1); PG8_SCHED; PG8_LDA(At, 1, 0); PG8_STAGE(PG8_SA(0, 1), a2 + hstep, voffA);
;             PG8_WAIT_V(8); PG8_WAIT_L(0); PG8_BAR; PG8_MMA(0, 0, At, B0); PG8_MMA(0, 1, At, B1); PG8_BAR; PG8_SCHED;
	s_setprio 1
	s_waitcnt lgkmcnt(0)
	v_mfma_f32_16x16x32_bf16 v[60:63], v[144:147], v[184:187], v[60:63]
	v_mfma_f32_16x16x32_bf16 v[56:59], v[160:163], v[184:187], v[56:59]
	v_mfma_f32_16x16x32_bf16 v[44:47], v[144:147], v[192:195], v[44:47]
	v_mfma_f32_16x16x32_bf16 v[40:43], v[160:163], v[192:195], v[40:43]
	v_mfma_f32_16x16x32_bf16 v[28:31], v[144:147], v[200:203], v[28:31]
	v_mfma_f32_16x16x32_bf16 v[24:27], v[160:163], v[200:203], v[24:27]
	v_mfma_f32_16x16x32_bf16 v[12:15], v[144:147], v[210:213], v[12:15]
	v_mfma_f32_16x16x32_bf16 v[8:11], v[160:163], v[210:213], v[8:11]
	v_mfma_f32_16x16x32_bf16 v[60:63], v[156:159], v[188:191], v[60:63]
	v_mfma_f32_16x16x32_bf16 v[56:59], v[164:167], v[188:191], v[56:59]
	v_mfma_f32_16x16x32_bf16 v[44:47], v[156:159], v[196:199], v[44:47]
	v_mfma_f32_16x16x32_bf16 v[40:43], v[164:167], v[196:199], v[40:43]
	v_mfma_f32_16x16x32_bf16 v[28:31], v[156:159], v[206:209], v[28:31]
	v_mfma_f32_16x16x32_bf16 v[24:27], v[164:167], v[206:209], v[24:27]
	v_mfma_f32_16x16x32_bf16 v[12:15], v[156:159], v[214:217], v[12:15]
	v_mfma_f32_16x16x32_bf16 v[8:11], v[164:167], v[214:217], v[8:11]
	s_setprio 0
	s_setprio 1
	v_mfma_f32_16x16x32_bf16 v[52:55], v[168:171], v[184:187], v[52:55]
	v_mfma_f32_16x16x32_bf16 v[48:51], v[176:179], v[184:187], v[48:51]
	v_mfma_f32_16x16x32_bf16 v[36:39], v[168:171], v[192:195], v[36:39]
	v_mfma_f32_16x16x32_bf16 v[32:35], v[176:179], v[192:195], v[32:35]
	v_mfma_f32_16x16x32_bf16 v[20:23], v[168:171], v[200:203], v[20:23]
	v_mfma_f32_16x16x32_bf16 v[16:19], v[176:179], v[200:203], v[16:19]
	v_mfma_f32_16x16x32_bf16 v[4:7], v[168:171], v[210:213], v[4:7]
	v_mfma_f32_16x16x32_bf16 v[0:3], v[176:179], v[210:213], v[0:3]
	v_mfma_f32_16x16x32_bf16 v[52:55], v[172:175], v[188:191], v[52:55]
	v_mfma_f32_16x16x32_bf16 v[48:51], v[180:183], v[188:191], v[48:51]
	v_mfma_f32_16x16x32_bf16 v[36:39], v[172:175], v[196:199], v[36:39]
	v_mfma_f32_16x16x32_bf16 v[32:35], v[180:183], v[196:199], v[32:35]
	v_mfma_f32_16x16x32_bf16 v[20:23], v[172:175], v[206:209], v[20:23]
	v_mfma_f32_16x16x32_bf16 v[16:19], v[180:183], v[206:209], v[16:19]
	v_mfma_f32_16x16x32_bf16 v[4:7], v[172:175], v[214:217], v[4:7]
	v_mfma_f32_16x16x32_bf16 v[0:3], v[180:183], v[214:217], v[0:3]
	s_setprio 0
	s_barrier
	s_add_i32 s56, 0, 0x18000
	v_add_u32_e32 v155, s56, v149
	s_add_i32 s57, 0, 0x1c000
	ds_read_b128 v[144:147], v155
	ds_read_b128 v[156:159], v155 offset:1024
	ds_read_b128 v[160:163], v155 offset:2048
	ds_read_b128 v[164:167], v155 offset:3072
	v_add_u32_e32 v155, s57, v149
	ds_read_b128 v[168:171], v155
	ds_read_b128 v[172:175], v155 offset:1024
	ds_read_b128 v[176:179], v155 offset:2048
	ds_read_b128 v[180:183], v155 offset:3072
	s_add_u32 s26, s38, 0xb0000
	s_addc_u32 s27, s39, 0
	s_mov_b32 m0, s40
	v_lshl_add_u64 v[226:227], s[26:27], 0, v[128:129]
	ds_read_b128 v[184:187], v153 offset:32768
	ds_read_b128 v[188:191], v153 offset:33792
	ds_read_b128 v[192:195], v153 offset:34816
	ds_read_b128 v[196:199], v153 offset:35840
	ds_read_b128 v[200:203], v153 offset:36864
	ds_read_b128 v[206:209], v153 offset:37888
	ds_read_b128 v[210:213], v153 offset:38912
	ds_read_b128 v[214:217], v153 offset:39936
	global_load_lds_dwordx4 v[226:227], off
	v_lshl_add_u64 v[226:227], s[26:27], 0, v[132:133]
	s_mov_b32 m0, s41
	s_nop 0
	global_load_lds_dwordx4 v[226:227], off
	s_waitcnt vmcnt(8)
	s_waitcnt lgkmcnt(0)
	s_barrier
	s_setprio 1
	s_waitcnt lgkmcnt(0)
	v_mfma_f32_16x16x32_bf16 v[124:127], v[144:147], v[184:187], v[124:127]
	v_mfma_f32_16x16x32_bf16 v[120:123], v[160:163], v[184:187], v[120:123]
	v_mfma_f32_16x16x32_bf16 v[108:111], v[144:147], v[192:195], v[108:111]
	v_mfma_f32_16x16x32_bf16 v[104:107], v[160:163], v[192:195], v[104:107]
	v_mfma_f32_16x16x32_bf16 v[92:95], v[144:147], v[200:203], v[92:95]
	v_mfma_f32_16x16x32_bf16 v[88:91], v[160:163], v[200:203], v[88:91]
	v_mfma_f32_16x16x32_bf16 v[76:79], v[144:147], v[210:213], v[76:79]
	v_mfma_f32_16x16x32_bf16 v[72:75], v[160:163], v[210:213], v[72:75]
	v_mfma_f32_16x16x32_bf16 v[124:127], v[156:159], v[188:191], v[124:127]
	v_mfma_f32_16x16x32_bf16 v[120:123], v[164:167], v[188:191], v[120:123]
	v_mfma_f32_16x16x32_bf16 v[108:111], v[156:159], v[196:199], v[108:111]
	v_mfma_f32_16x16x32_bf16 v[104:107], v[164:167], v[196:199], v[104:107]
	v_mfma_f32_16x16x32_bf16 v[92:95], v[156:159], v[206:209], v[92:95]
	v_mfma_f32_16x16x32_bf16 v[88:91], v[164:167], v[206:209], v[88:91]
	v_mfma_f32_16x16x32_bf16 v[76:79], v[156:159], v[214:217], v[76:79]
	v_mfma_f32_16x16x32_bf16 v[72:75], v[164:167], v[214:217], v[72:75]
	s_setprio 0
	s_setprio 1
	v_mfma_f32_16x16x32_bf16 v[116:119], v[168:171], v[184:187], v[116:119]
	v_mfma_f32_16x16x32_bf16 v[112:115], v[176:179], v[184:187], v[112:115]
	v_mfma_f32_16x16x32_bf16 v[100:103], v[168:171], v[192:195], v[100:103]
	v_mfma_f32_16x16x32_bf16 v[96:99], v[176:179], v[192:195], v[96:99]
	v_mfma_f32_16x16x32_bf16 v[84:87], v[168:171], v[200:203], v[84:87]
	v_mfma_f32_16x16x32_bf16 v[80:83], v[176:179], v[200:203], v[80:83]
	v_mfma_f32_16x16x32_bf16 v[68:71], v[168:171], v[210:213], v[68:71]
	v_mfma_f32_16x16x32_bf16 v[64:67], v[176:179], v[210:213], v[64:67]
	v_mfma_f32_16x16x32_bf16 v[116:119], v[172:175], v[188:191], v[116:119]
	v_mfma_f32_16x16x32_bf16 v[112:115], v[180:183], v[188:191], v[112:115]
	v_mfma_f32_16x16x32_bf16 v[100:103], v[172:175], v[196:199], v[100:103]
	v_mfma_f32_16x16x32_bf16 v[96:99], v[180:183], v[196:199], v[96:99]
	v_mfma_f32_16x16x32_bf16 v[84:87], v[172:175], v[206:209], v[84:87]
	v_mfma_f32_16x16x32_bf16 v[80:83], v[180:183], v[206:209], v[80:83]
	v_mfma_f32_16x16x32_bf16 v[68:71], v[172:175], v[214:217], v[68:71]
	v_mfma_f32_16x16x32_bf16 v[64:67], v[180:183], v[214:217], v[64:67]
	s_setprio 0
	s_barrier
; #define PG8_STAGE(bufoff, gbase, voff) do { _Pragma("unroll") for (int _i = 0; _i < 2; ++_i) \
;         __builtin_amdgcn_global_load_lds((const unsigned*)((const char*)(gbase) + (voff)[_i]), (PG8_LAS unsigned*)(lds + (bufoff) + ldsw + _i * 8192), 16, 0, 0); } while (0)
; #define PG8_LDA(dst, b, h) do { _Pragma("unroll") for (int m = 0; m < 4; ++m) _Pragma("unroll") for (int k = 0; k < 2; ++k) dst[m][k] = *(const PG8_LAS bf16x8*)(lds + PG8_SA(b, h) + aoff + m * 2048 + k * 1024); } while (0)
; #define PG8_MMA(ai, bj, At, Bt) do { __builtin_amdgcn_s_setprio(1); _Pragma("unroll") for (int m = 0; m < 4; ++m) _Pragma("unroll") for (int n = 0; n < 2; ++n) _Pragma("unroll") for (int k = 0; k < 2; ++k) \
;         acc[ai][bj][m][n] = __builtin_amdgcn_mfma_f32_16x16x32_bf16(Bt[n][k], At[m][k], acc[ai][bj][m][n], 0, 0, 0); __builtin_amdgcn_s_setprio(0); } while (0)
; #define PG8_WAIT_V(n) asm volatile("s_waitcnt vmcnt(" #n ")" ::: "memory")
; #define PG8_WAIT_L(n) asm volatile("s_waitcnt lgkmcnt(" #n ")" ::: "memory")
; #define PG8_BAR __builtin_amdgcn_s_barrier()
; #define PG8_SCHED __builtin_amdgcn_sched_barrier(0)
;     __device__ __forceinline__ void operator()(const f32x4 (&acc)[2][2][4][2], const Unit& u, int wr, int wc, int fr, int fq) const {
;     ...
;             for (int m = 0; m < 4; ++m) { const int row = row0 + ai * HALF + m * 16; const size_t off = (size_t)row * 1024 + col0; float s = 0.f;
; #pragma unroll
;                 for (int bj = 0; bj < 2; ++bj) { f32x4 a0, a1;
;                     if (xin32) { const float* p = xin32 + off + bj * HALF; a0 = *(const f32x4*)p; a1 = *(const f32x4*)(p + 4); }
;                     else { const u32x4 w = *(const u32x4*)(xb + off + bj * HALF);
; template <class Epi, class Sched, bool ALIGN_EPI = false, bool SP2 = false>
; __device__ __forceinline__ void gemm_phase(PG8_LAS unsigned char* lds, const Gemm g, const Sched& S, const Epi& E) {
;     ...
;             PG8_LDA(At, 1, 1); PG8_STAGE(PG8_SB(1, 0), b3, voffB); PG8_STAGE(PG8_SB(1, 1), b3 + hstep, voffB); PG8_STAGE(PG8_SA(1, 0), a3, voffA);
;             PG8_WAIT_V(8); PG8_WAIT_L(0); PG8_BAR; PG8_MMA(1, 0, At, B0); PG8_MMA(1, 1, At, B1); PG8_BAR; PG8_SCHED;
	s_add_i32 s26, s56, s15
	v_lshl_add_u64 v[218:219], v[218:219], 0, s[12:13]
	s_mov_b32 m0, s26
	ds_read_b128 v[184:187], v153 offset:49152
	ds_read_b128 v[188:191], v153 offset:50176
	ds_read_b128 v[192:195], v153 offset:51200
	ds_read_b128 v[196:199], v153 offset:52224
	ds_read_b128 v[200:203], v153 offset:53248
	ds_read_b128 v[206:209], v153 offset:54272
	ds_read_b128 v[210:213], v153 offset:55296
	ds_read_b128 v[214:217], v153 offset:56320
	global_load_lds_dwordx4 v[218:219], off
	s_add_i32 m0, s26, 0x2000
	s_add_u32 s26, s36, 0xb0080
	v_lshl_add_u64 v[218:219], v[220:221], 0, s[12:13]
	s_addc_u32 s27, s37, 0
	s_add_i32 s36, s57, s15
	global_load_lds_dwordx4 v[218:219], off
	v_lshl_add_u64 v[218:219], s[26:27], 0, v[130:131]
	s_mov_b32 m0, s36
	s_nop 0
	global_load_lds_dwordx4 v[218:219], off
	v_lshl_add_u64 v[218:219], s[26:27], 0, v[134:135]
	s_add_i32 m0, s36, 0x2000
	s_nop 0
	global_load_lds_dwordx4 v[218:219], off
	v_lshl_add_u64 v[218:219], v[222:223], 0, s[12:13]
	s_mov_b32 m0, s43
	s_nop 0
	global_load_lds_dwordx4 v[218:219], off
	v_lshl_add_u64 v[218:219], v[224:225], 0, s[12:13]
	s_mov_b32 m0, s44
	s_nop 0
	global_load_lds_dwordx4 v[218:219], off
	s_waitcnt vmcnt(8)
	s_waitcnt lgkmcnt(0)
	s_barrier
	s_setprio 1
	s_waitcnt lgkmcnt(0)
	v_mfma_f32_16x16x32_bf16 v[60:63], v[144:147], v[184:187], v[60:63]
	v_mfma_f32_16x16x32_bf16 v[56:59], v[160:163], v[184:187], v[56:59]
	v_mfma_f32_16x16x32_bf16 v[44:47], v[144:147], v[192:195], v[44:47]
	v_mfma_f32_16x16x32_bf16 v[40:43], v[160:163], v[192:195], v[40:43]
	v_mfma_f32_16x16x32_bf16 v[28:31], v[144:147], v[200:203], v[28:31]
	v_mfma_f32_16x16x32_bf16 v[24:27], v[160:163], v[200:203], v[24:27]
	v_mfma_f32_16x16x32_bf16 v[12:15], v[144:147], v[210:213], v[12:15]
	v_mfma_f32_16x16x32_bf16 v[8:11], v[160:163], v[210:213], v[8:11]
	v_mfma_f32_16x16x32_bf16 v[60:63], v[156:159], v[188:191], v[60:63]
	v_mfma_f32_16x16x32_bf16 v[56:59], v[164:167], v[188:191], v[56:59]
	v_mfma_f32_16x16x32_bf16 v[44:47], v[156:159], v[196:199], v[44:47]
	v_mfma_f32_16x16x32_bf16 v[40:43], v[164:167], v[196:199], v[40:43]
	v_mfma_f32_16x16x32_bf16 v[28:31], v[156:159], v[206:209], v[28:31]
	v_mfma_f32_16x16x32_bf16 v[24:27], v[164:167], v[206:209], v[24:27]
	v_mfma_f32_16x16x32_bf16 v[12:15], v[156:159], v[214:217], v[12:15]
	v_mfma_f32_16x16x32_bf16 v[8:11], v[164:167], v[214:217], v[8:11]
	s_setprio 0
	s_setprio 1
	v_mfma_f32_16x16x32_bf16 v[52:55], v[168:171], v[184:187], v[52:55]
	v_mfma_f32_16x16x32_bf16 v[48:51], v[176:179], v[184:187], v[48:51]
	v_mfma_f32_16x16x32_bf16 v[36:39], v[168:171], v[192:195], v[36:39]
	v_mfma_f32_16x16x32_bf16 v[32:35], v[176:179], v[192:195], v[32:35]
	v_mfma_f32_16x16x32_bf16 v[20:23], v[168:171], v[200:203], v[20:23]
	v_mfma_f32_16x16x32_bf16 v[16:19], v[176:179], v[200:203], v[16:19]
	v_mfma_f32_16x16x32_bf16 v[4:7], v[168:171], v[210:213], v[4:7]
	v_mfma_f32_16x16x32_bf16 v[0:3], v[176:179], v[210:213], v[0:3]
	v_mfma_f32_16x16x32_bf16 v[52:55], v[172:175], v[188:191], v[52:55]
	v_mfma_f32_16x16x32_bf16 v[48:51], v[180:183], v[188:191], v[48:51]
	v_mfma_f32_16x16x32_bf16 v[36:39], v[172:175], v[196:199], v[36:39]
	v_mfma_f32_16x16x32_bf16 v[32:35], v[180:183], v[196:199], v[32:35]
	v_mfma_f32_16x16x32_bf16 v[20:23], v[172:175], v[206:209], v[20:23]
	v_mfma_f32_16x16x32_bf16 v[16:19], v[180:183], v[206:209], v[16:19]
	v_mfma_f32_16x16x32_bf16 v[4:7], v[172:175], v[214:217], v[4:7]
	v_mfma_f32_16x16x32_bf16 v[0:3], v[180:183], v[214:217], v[0:3]
	s_setprio 0
	s_barrier
	s_add_i32 s55, s55, 2
	s_add_u32 s53, s53, 0x100
	s_addc_u32 s54, s54, 0
	s_cmp_gt_u32 s55, 41
	s_mov_b64 s[26:27], s[28:29]
	s_cbranch_scc0 .LBB0_1978
	v_lshl_add_u32 v146, s52, 8, v148
	v_ashrrev_i32_e32 v147, 31, v146
	v_lshl_or_b32 v144, s51, 8, v150
	v_lshlrev_b64 v[156:157], 11, v[146:147]
	v_ashrrev_i32_e32 v145, 31, v144
	v_lshl_add_u64 v[156:157], s[22:23], 0, v[156:157]
	v_lshl_add_u64 v[166:167], v[144:145], 1, v[156:157]
	s_mov_b64 s[98:99], 0x8000
	s_mov_b64 s[100:101], 0x28000
	global_load_dwordx4 v[182:185], v[166:167], off
	global_load_dwordx4 v[186:189], v[166:167], off offset:256
	v_lshl_add_u64 v[198:199], v[166:167], 0, s[98:99]
	global_load_dwordx4 v[190:193], v[198:199], off
	global_load_dwordx4 v[194:197], v[198:199], off offset:256
	v_lshl_add_u64 v[198:199], v[198:199], 0, s[98:99]
	global_load_dwordx4 v[208:211], v[198:199], off
	global_load_dwordx4 v[212:215], v[198:199], off offset:256
	v_lshl_add_u64 v[198:199], v[198:199], 0, s[98:99]
	global_load_dwordx4 v[216:219], v[198:199], off
	global_load_dwordx4 v[220:223], v[198:199], off offset:256
	v_lshl_add_u64 v[198:199], v[198:199], 0, s[100:101]
	s_and_b64 vcc, exec, s[16:17]
	s_cbranch_vccz .LBB0_1981
	s_barrier
; __device__ __forceinline__ void fx_add(float* p, size_t idx, float s) { atomicAdd((unsigned long long*)p + idx, (unsigned long long)(long long)(s * 4294967296.0f)); }
; __device__ __forceinline__ unsigned cvtpk(float lo, float hi) { f32x2v_ v = {lo, hi}; bf16x2v_ b = __builtin_convertvector(v, bf16x2v_); return __builtin_bit_cast(unsigned, b); }
;     __device__ __forceinline__ void operator()(const f32x4 (&acc)[2][2][4][2], const Unit& u, int wr, int wc, int fr, int fq) const {
;     ...
;             for (int m = 0; m < 4; ++m) { const int row = row0 + ai * HALF + m * 16; const size_t off = (size_t)row * 1024 + col0; float s = 0.f;
; #pragma unroll
;                 for (int bj = 0; bj < 2; ++bj) { f32x4 a0, a1;
;                     if (xin32) { const float* p = xin32 + off + bj * HALF; a0 = *(const f32x4*)p; a1 = *(const f32x4*)(p + 4); }
;                     else { const u32x4 w = *(const u32x4*)(xb + off + bj * HALF);
;                         a0 = (f32x4){__uint_as_float(w.x << 16), __uint_as_float(w.x & 0xffff0000u), __uint_as_float(w.y << 16), __uint_as_float(w.y & 0xffff0000u)};
;                         a1 = (f32x4){__uint_as_float(w.z << 16), __uint_as_float(w.z & 0xffff0000u), __uint_as_float(w.w << 16), __uint_as_float(w.w & 0xffff0000u)}; }
;                     const f32x4 v0 = a0 + acc[ai][bj][m][0] * alpha, v1 = a1 + acc[ai][bj][m][1] * alpha;
;                     u32x4 w; w.x = cvtpk(v0[0], v0[1]); w.y = cvtpk(v0[2], v0[3]); w.z = cvtpk(v1[0], v1[1]); w.w = cvtpk(v1[2], v1[3]);
;                     *(u32x4*)(xb + off + bj * HALF) = w;
;                     s += (v0[0] * v0[0] + v0[1] * v0[1]) + (v0[2] * v0[2] + v0[3] * v0[3]) + (v1[0] * v1[0] + v1[1] * v1[1]) + (v1[2] * v1[2] + v1[3] * v1[3]); }
;                 s += __shfl_xor(s, 16); s += __shfl_xor(s, 32);
;                 if (fq == 0) fx_add(ssout, row, s); }
.LBB0_1981:
	s_nop 0
	s_nop 0
	v_and_b32_e32 v156, 64, v154
	v_xor_b32_e32 v155, 16, v154
	v_add_u32_e32 v156, 64, v156
	v_xor_b32_e32 v157, 32, v154
	v_cmp_lt_i32_e32 vcc, v155, v156
	s_waitcnt vmcnt(6)
	v_lshlrev_b32_e32 v168, 16, v182
	v_cndmask_b32_e32 v155, v154, v155, vcc
	v_cmp_lt_i32_e32 vcc, v157, v156
	v_and_b32_e32 v169, 0xffff0000, v182
	v_lshlrev_b32_e32 v158, 16, v183
	v_and_b32_e32 v159, 0xffff0000, v183
	v_lshlrev_b32_e32 v172, 16, v186
	v_and_b32_e32 v173, 0xffff0000, v186
	v_lshlrev_b32_e32 v162, 16, v187
	v_and_b32_e32 v163, 0xffff0000, v187
	v_cndmask_b32_e32 v157, v154, v157, vcc
	v_lshlrev_b32_e32 v170, 16, v184
	v_and_b32_e32 v171, 0xffff0000, v184
	v_lshlrev_b32_e32 v160, 16, v185
	v_and_b32_e32 v161, 0xffff0000, v185
	v_lshlrev_b32_e32 v174, 16, v188
	v_and_b32_e32 v175, 0xffff0000, v188
	v_lshlrev_b32_e32 v164, 16, v189
	v_and_b32_e32 v165, 0xffff0000, v189
	global_load_dwordx4 v[182:185], v[198:199], off
	global_load_dwordx4 v[186:189], v[198:199], off offset:256
	v_lshl_add_u64 v[198:199], v[198:199], 0, s[98:99]
	v_pk_fma_f32 v[126:127], v[126:127], 0.5, v[158:159] op_sel_hi:[1,0,1]
	v_pk_fma_f32 v[124:125], v[124:125], 0.5, v[168:169] op_sel_hi:[1,0,1]
	v_pk_fma_f32 v[118:119], v[118:119], 0.5, v[162:163] op_sel_hi:[1,0,1]
	v_pk_fma_f32 v[116:117], v[116:117], 0.5, v[172:173] op_sel_hi:[1,0,1]
	v_lshlrev_b32_e32 v156, 2, v155
	v_lshlrev_b32_e32 v155, 2, v157
	v_pk_fma_f32 v[122:123], v[122:123], 0.5, v[160:161] op_sel_hi:[1,0,1]
	v_pk_fma_f32 v[120:121], v[120:121], 0.5, v[170:171] op_sel_hi:[1,0,1]
	v_pk_fma_f32 v[158:159], v[114:115], 0.5, v[164:165] op_sel_hi:[1,0,1]
	v_pk_fma_f32 v[160:161], v[112:113], 0.5, v[174:175] op_sel_hi:[1,0,1]
	v_mul_f32_e32 v114, v125, v125
	v_mul_f32_e32 v115, v127, v127
	v_mul_f32_e32 v157, v117, v117
	v_mul_f32_e32 v162, v119, v119
	v_cvt_pk_bf16_f32 v112, v124, v125
	v_mul_f32_e32 v125, v121, v121
	v_mul_f32_e32 v163, v161, v161
	v_fmac_f32_e32 v114, v124, v124
	v_fmac_f32_e32 v115, v126, v126
	v_fmac_f32_e32 v157, v116, v116
	v_fmac_f32_e32 v162, v118, v118
	v_cvt_pk_bf16_f32 v113, v126, v127
	v_mul_f32_e32 v127, v123, v123
	v_mul_f32_e32 v164, v159, v159
	v_fmac_f32_e32 v125, v120, v120
	v_fmac_f32_e32 v163, v160, v160
	v_add_f32_e32 v114, v114, v115
	v_add_f32_e32 v115, v157, v162
	v_fmac_f32_e32 v127, v122, v122
	v_fmac_f32_e32 v164, v158, v158
	v_add_f32_e32 v114, v125, v114
	v_add_f32_e32 v115, v163, v115
	v_add_f32_e32 v114, v127, v114
	v_add_f32_e32 v115, v164, v115
	v_add_f32_e32 v124, v114, v115
	ds_bpermute_b32 v125, v156, v124
	v_cvt_pk_bf16_f32 v114, v120, v121
	v_cvt_pk_bf16_f32 v115, v122, v123
	global_store_dwordx4 v[166:167], v[112:115], off
	s_waitcnt lgkmcnt(0)
	s_nop 0
	v_add_f32_e32 v112, v124, v125
	ds_bpermute_b32 v113, v155, v112
	v_cvt_pk_bf16_f32 v114, v116, v117
	v_cvt_pk_bf16_f32 v115, v118, v119
	v_cvt_pk_bf16_f32 v116, v160, v161
	v_cvt_pk_bf16_f32 v117, v158, v159
	global_store_dwordx4 v[166:167], v[114:117], off offset:256
	s_and_saveexec_b64 s[26:27], s[6:7]
	s_cbranch_execz .LBB0_1983
	s_waitcnt lgkmcnt(0)
	v_add_f32_e32 v112, v112, v113
	v_mul_f32_e32 v112, 0x4f800000, v112
	v_trunc_f32_e32 v112, v112
	v_mul_f32_e64 v113, |v112|, s47
	v_floor_f32_e32 v113, v113
	v_fma_f32 v114, v113, s48, |v112|
	v_cvt_u32_f32_e32 v114, v114
	v_cvt_u32_f32_e32 v113, v113
	v_ashrrev_i32_e32 v115, 31, v112
	v_xor_b32_e32 v112, v114, v115
	v_xor_b32_e32 v113, v113, v115
	v_sub_co_u32_e32 v112, vcc, v112, v115
	s_nop 1
	v_subb_co_u32_e32 v113, vcc, v113, v115, vcc
	v_lshl_add_u64 v[114:115], v[146:147], 3, s[10:11]
	global_atomic_add_x2 v[114:115], v[112:113], off
.LBB0_1983:
	s_or_b64 exec, exec, s[26:27]
	v_or_b32_e32 v112, 16, v146
	s_waitcnt lgkmcnt(0)
	v_ashrrev_i32_e32 v113, 31, v112
	v_lshlrev_b64 v[114:115], 11, v[112:113]
	v_lshl_add_u64 v[114:115], s[22:23], 0, v[114:115]
	v_lshl_add_u64 v[122:123], v[144:145], 1, v[114:115]
	s_nop 0
	s_nop 0
	s_waitcnt vmcnt(10)
	v_lshlrev_b32_e32 v124, 16, v190
	v_and_b32_e32 v125, 0xffff0000, v190
	v_lshlrev_b32_e32 v114, 16, v191
	v_and_b32_e32 v115, 0xffff0000, v191
	s_waitcnt vmcnt(9)
	v_lshlrev_b32_e32 v158, 16, v194
	v_and_b32_e32 v159, 0xffff0000, v194
	v_lshlrev_b32_e32 v118, 16, v195
	v_and_b32_e32 v119, 0xffff0000, v195
	v_lshlrev_b32_e32 v126, 16, v192
	v_and_b32_e32 v127, 0xffff0000, v192
	v_lshlrev_b32_e32 v116, 16, v193
	v_and_b32_e32 v117, 0xffff0000, v193
	v_lshlrev_b32_e32 v160, 16, v196
	v_and_b32_e32 v161, 0xffff0000, v196
	v_lshlrev_b32_e32 v120, 16, v197
	v_and_b32_e32 v121, 0xffff0000, v197
	global_load_dwordx4 v[190:193], v[198:199], off
	global_load_dwordx4 v[194:197], v[198:199], off offset:256
	v_lshl_add_u64 v[198:199], v[198:199], 0, s[98:99]
	v_pk_fma_f32 v[110:111], v[110:111], 0.5, v[114:115] op_sel_hi:[1,0,1]
	v_pk_fma_f32 v[108:109], v[108:109], 0.5, v[124:125] op_sel_hi:[1,0,1]
	v_pk_fma_f32 v[102:103], v[102:103], 0.5, v[118:119] op_sel_hi:[1,0,1]
	v_pk_fma_f32 v[100:101], v[100:101], 0.5, v[158:159] op_sel_hi:[1,0,1]
	v_pk_fma_f32 v[106:107], v[106:107], 0.5, v[116:117] op_sel_hi:[1,0,1]
	v_pk_fma_f32 v[104:105], v[104:105], 0.5, v[126:127] op_sel_hi:[1,0,1]
	v_pk_fma_f32 v[114:115], v[98:99], 0.5, v[120:121] op_sel_hi:[1,0,1]
	v_pk_fma_f32 v[116:117], v[96:97], 0.5, v[160:161] op_sel_hi:[1,0,1]
	v_mul_f32_e32 v98, v109, v109
	v_mul_f32_e32 v99, v111, v111
	v_mul_f32_e32 v118, v101, v101
	v_mul_f32_e32 v119, v103, v103
	v_cvt_pk_bf16_f32 v96, v108, v109
	v_mul_f32_e32 v109, v105, v105
	v_mul_f32_e32 v120, v117, v117
	v_fmac_f32_e32 v98, v108, v108
	v_fmac_f32_e32 v99, v110, v110
	v_fmac_f32_e32 v118, v100, v100
	v_fmac_f32_e32 v119, v102, v102
	v_cvt_pk_bf16_f32 v97, v110, v111
	v_mul_f32_e32 v111, v107, v107
	v_mul_f32_e32 v121, v115, v115
	v_fmac_f32_e32 v109, v104, v104
	v_fmac_f32_e32 v120, v116, v116
	v_add_f32_e32 v98, v98, v99
	v_add_f32_e32 v99, v118, v119
	v_fmac_f32_e32 v111, v106, v106
	v_fmac_f32_e32 v121, v114, v114
	v_add_f32_e32 v98, v109, v98
	v_add_f32_e32 v99, v120, v99
	v_add_f32_e32 v98, v111, v98
	v_add_f32_e32 v99, v121, v99
	v_add_f32_e32 v108, v98, v99
	ds_bpermute_b32 v109, v156, v108
	v_cvt_pk_bf16_f32 v98, v104, v105
	v_cvt_pk_bf16_f32 v99, v106, v107
	global_store_dwordx4 v[122:123], v[96:99], off
	s_waitcnt lgkmcnt(0)
	s_nop 0
	v_add_f32_e32 v96, v108, v109
	ds_bpermute_b32 v97, v155, v96
	v_cvt_pk_bf16_f32 v98, v100, v101
	v_cvt_pk_bf16_f32 v99, v102, v103
	v_cvt_pk_bf16_f32 v100, v116, v117
	v_cvt_pk_bf16_f32 v101, v114, v115
	global_store_dwordx4 v[122:123], v[98:101], off offset:256
	s_and_saveexec_b64 s[26:27], s[6:7]
	s_cbranch_execz .LBB0_1985
; __device__ __forceinline__ void fx_add(float* p, size_t idx, float s) { atomicAdd((unsigned long long*)p + idx, (unsigned long long)(long long)(s * 4294967296.0f)); }
; __device__ __forceinline__ unsigned cvtpk(float lo, float hi) { f32x2v_ v = {lo, hi}; bf16x2v_ b = __builtin_convertvector(v, bf16x2v_); return __builtin_bit_cast(unsigned, b); }
;     __device__ __forceinline__ void operator()(const f32x4 (&acc)[2][2][4][2], const Unit& u, int wr, int wc, int fr, int fq) const {
;     ...
;             for (int m = 0; m < 4; ++m) { const int row = row0 + ai * HALF + m * 16; const size_t off = (size_t)row * 1024 + col0; float s = 0.f;
; #pragma unroll
;                 for (int bj = 0; bj < 2; ++bj) { f32x4 a0, a1;
;                     if (xin32) { const float* p = xin32 + off + bj * HALF; a0 = *(const f32x4*)p; a1 = *(const f32x4*)(p + 4); }
;                     else { const u32x4 w = *(const u32x4*)(xb + off + bj * HALF);
;                         a0 = (f32x4){__uint_as_float(w.x << 16), __uint_as_float(w.x & 0xffff0000u), __uint_as_float(w.y << 16), __uint_as_float(w.y & 0xffff0000u)};
;                         a1 = (f32x4){__uint_as_float(w.z << 16), __uint_as_float(w.z & 0xffff0000u), __uint_as_float(w.w << 16), __uint_as_float(w.w & 0xffff0000u)}; }
;                     const f32x4 v0 = a0 + acc[ai][bj][m][0] * alpha, v1 = a1 + acc[ai][bj][m][1] * alpha;
;                     u32x4 w; w.x = cvtpk(v0[0], v0[1]); w.y = cvtpk(v0[2], v0[3]); w.z = cvtpk(v1[0], v1[1]); w.w = cvtpk(v1[2], v1[3]);
;                     *(u32x4*)(xb + off + bj * HALF) = w;
;                     s += (v0[0] * v0[0] + v0[1] * v0[1]) + (v0[2] * v0[2] + v0[3] * v0[3]) + (v1[0] * v1[0] + v1[1] * v1[1]) + (v1[2] * v1[2] + v1[3] * v1[3]); }
;                 s += __shfl_xor(s, 16); s += __shfl_xor(s, 32);
;                 if (fq == 0) fx_add(ssout, row, s); }
	s_waitcnt lgkmcnt(0)
	v_add_f32_e32 v96, v96, v97
	v_mul_f32_e32 v96, 0x4f800000, v96
	v_trunc_f32_e32 v96, v96
	v_mul_f32_e64 v97, |v96|, s47
	v_floor_f32_e32 v97, v97
	v_fma_f32 v98, v97, s48, |v96|
	v_cvt_u32_f32_e32 v98, v98
	v_cvt_u32_f32_e32 v97, v97
	v_ashrrev_i32_e32 v99, 31, v96
	v_xor_b32_e32 v96, v98, v99
	v_xor_b32_e32 v97, v97, v99
	v_sub_co_u32_e32 v96, vcc, v96, v99
	s_nop 1
	v_subb_co_u32_e32 v97, vcc, v97, v99, vcc
	v_lshl_add_u64 v[98:99], v[112:113], 3, s[10:11]
	global_atomic_add_x2 v[98:99], v[96:97], off
.LBB0_1985:
	s_or_b64 exec, exec, s[26:27]
	v_or_b32_e32 v96, 32, v146
	s_waitcnt lgkmcnt(0)
	v_ashrrev_i32_e32 v97, 31, v96
	v_lshlrev_b64 v[98:99], 11, v[96:97]
	v_lshl_add_u64 v[98:99], s[22:23], 0, v[98:99]
	v_lshl_add_u64 v[106:107], v[144:145], 1, v[98:99]
	s_nop 0
	s_nop 0
	s_waitcnt vmcnt(13)
	v_lshlrev_b32_e32 v108, 16, v208
	v_and_b32_e32 v109, 0xffff0000, v208
	v_lshlrev_b32_e32 v98, 16, v209
	v_and_b32_e32 v99, 0xffff0000, v209
	s_waitcnt vmcnt(12)
	v_lshlrev_b32_e32 v112, 16, v212
	v_and_b32_e32 v113, 0xffff0000, v212
	v_lshlrev_b32_e32 v102, 16, v213
	v_and_b32_e32 v103, 0xffff0000, v213
	v_lshlrev_b32_e32 v110, 16, v210
	v_and_b32_e32 v111, 0xffff0000, v210
	v_lshlrev_b32_e32 v100, 16, v211
	v_and_b32_e32 v101, 0xffff0000, v211
	v_lshlrev_b32_e32 v114, 16, v214
	v_and_b32_e32 v115, 0xffff0000, v214
	v_lshlrev_b32_e32 v104, 16, v215
	v_and_b32_e32 v105, 0xffff0000, v215
	global_load_dwordx4 v[208:211], v[198:199], off
	global_load_dwordx4 v[212:215], v[198:199], off offset:256
	v_lshl_add_u64 v[198:199], v[198:199], 0, s[98:99]
	v_pk_fma_f32 v[94:95], v[94:95], 0.5, v[98:99] op_sel_hi:[1,0,1]
	v_pk_fma_f32 v[92:93], v[92:93], 0.5, v[108:109] op_sel_hi:[1,0,1]
	v_pk_fma_f32 v[86:87], v[86:87], 0.5, v[102:103] op_sel_hi:[1,0,1]
	v_pk_fma_f32 v[84:85], v[84:85], 0.5, v[112:113] op_sel_hi:[1,0,1]
	v_pk_fma_f32 v[90:91], v[90:91], 0.5, v[100:101] op_sel_hi:[1,0,1]
	v_pk_fma_f32 v[88:89], v[88:89], 0.5, v[110:111] op_sel_hi:[1,0,1]
	v_pk_fma_f32 v[98:99], v[82:83], 0.5, v[104:105] op_sel_hi:[1,0,1]
	v_pk_fma_f32 v[100:101], v[80:81], 0.5, v[114:115] op_sel_hi:[1,0,1]
	v_mul_f32_e32 v82, v93, v93
	v_mul_f32_e32 v83, v95, v95
	v_mul_f32_e32 v102, v85, v85
	v_mul_f32_e32 v103, v87, v87
	v_cvt_pk_bf16_f32 v80, v92, v93
	v_mul_f32_e32 v93, v89, v89
	v_mul_f32_e32 v104, v101, v101
	v_fmac_f32_e32 v82, v92, v92
	v_fmac_f32_e32 v83, v94, v94
	v_fmac_f32_e32 v102, v84, v84
	v_fmac_f32_e32 v103, v86, v86
	v_cvt_pk_bf16_f32 v81, v94, v95
	v_mul_f32_e32 v95, v91, v91
	v_mul_f32_e32 v105, v99, v99
	v_fmac_f32_e32 v93, v88, v88
	v_fmac_f32_e32 v104, v100, v100
	v_add_f32_e32 v82, v82, v83
	v_add_f32_e32 v83, v102, v103
	v_fmac_f32_e32 v95, v90, v90
	v_fmac_f32_e32 v105, v98, v98
	v_add_f32_e32 v82, v93, v82
	v_add_f32_e32 v83, v104, v83
	v_add_f32_e32 v82, v95, v82
	v_add_f32_e32 v83, v105, v83
	v_add_f32_e32 v92, v82, v83
	ds_bpermute_b32 v93, v156, v92
	v_cvt_pk_bf16_f32 v82, v88, v89
	v_cvt_pk_bf16_f32 v83, v90, v91
	global_store_dwordx4 v[106:107], v[80:83], off
	s_waitcnt lgkmcnt(0)
	s_nop 0
	v_add_f32_e32 v80, v92, v93
	ds_bpermute_b32 v81, v155, v80
	v_cvt_pk_bf16_f32 v82, v84, v85
	v_cvt_pk_bf16_f32 v83, v86, v87
	v_cvt_pk_bf16_f32 v84, v100, v101
	v_cvt_pk_bf16_f32 v85, v98, v99
	global_store_dwordx4 v[106:107], v[82:85], off offset:256
	s_and_saveexec_b64 s[26:27], s[6:7]
	s_cbranch_execz .LBB0_1987
	s_waitcnt lgkmcnt(0)
	v_add_f32_e32 v80, v80, v81
	v_mul_f32_e32 v80, 0x4f800000, v80
	v_trunc_f32_e32 v80, v80
	v_mul_f32_e64 v81, |v80|, s47
	v_floor_f32_e32 v81, v81
	v_fma_f32 v82, v81, s48, |v80|
	v_cvt_u32_f32_e32 v82, v82
	v_cvt_u32_f32_e32 v81, v81
	v_ashrrev_i32_e32 v83, 31, v80
	v_xor_b32_e32 v80, v82, v83
	v_xor_b32_e32 v81, v81, v83
	v_sub_co_u32_e32 v80, vcc, v80, v83
	s_nop 1
	v_subb_co_u32_e32 v81, vcc, v81, v83, vcc
	v_lshl_add_u64 v[82:83], v[96:97], 3, s[10:11]
	global_atomic_add_x2 v[82:83], v[80:81], off
.LBB0_1987:
	s_or_b64 exec, exec, s[26:27]
	v_or_b32_e32 v80, 48, v146
	s_waitcnt lgkmcnt(0)
	v_ashrrev_i32_e32 v81, 31, v80
	v_lshlrev_b64 v[82:83], 11, v[80:81]
	v_lshl_add_u64 v[82:83], s[22:23], 0, v[82:83]
	v_lshl_add_u64 v[90:91], v[144:145], 1, v[82:83]
	s_nop 0
	s_nop 0
	s_waitcnt vmcnt(16)
	v_lshlrev_b32_e32 v92, 16, v216
	v_and_b32_e32 v93, 0xffff0000, v216
	v_lshlrev_b32_e32 v82, 16, v217
	v_and_b32_e32 v83, 0xffff0000, v217
	s_waitcnt vmcnt(15)
	v_lshlrev_b32_e32 v96, 16, v220
	v_and_b32_e32 v97, 0xffff0000, v220
	v_lshlrev_b32_e32 v86, 16, v221
	v_and_b32_e32 v87, 0xffff0000, v221
	v_lshlrev_b32_e32 v94, 16, v218
	v_and_b32_e32 v95, 0xffff0000, v218
	v_lshlrev_b32_e32 v84, 16, v219
	v_and_b32_e32 v85, 0xffff0000, v219
	v_lshlrev_b32_e32 v98, 16, v222
	v_and_b32_e32 v99, 0xffff0000, v222
	v_lshlrev_b32_e32 v88, 16, v223
	v_and_b32_e32 v89, 0xffff0000, v223
	global_load_dwordx4 v[216:219], v[198:199], off
	global_load_dwordx4 v[220:223], v[198:199], off offset:256
	v_pk_fma_f32 v[78:79], v[78:79], 0.5, v[82:83] op_sel_hi:[1,0,1]
	v_pk_fma_f32 v[76:77], v[76:77], 0.5, v[92:93] op_sel_hi:[1,0,1]
	v_pk_fma_f32 v[70:71], v[70:71], 0.5, v[86:87] op_sel_hi:[1,0,1]
	v_pk_fma_f32 v[68:69], v[68:69], 0.5, v[96:97] op_sel_hi:[1,0,1]
	v_pk_fma_f32 v[74:75], v[74:75], 0.5, v[84:85] op_sel_hi:[1,0,1]
	v_pk_fma_f32 v[72:73], v[72:73], 0.5, v[94:95] op_sel_hi:[1,0,1]
	v_pk_fma_f32 v[82:83], v[66:67], 0.5, v[88:89] op_sel_hi:[1,0,1]
	v_pk_fma_f32 v[84:85], v[64:65], 0.5, v[98:99] op_sel_hi:[1,0,1]
	v_mul_f32_e32 v66, v77, v77
	v_mul_f32_e32 v67, v79, v79
	v_mul_f32_e32 v86, v69, v69
	v_mul_f32_e32 v87, v71, v71
	v_cvt_pk_bf16_f32 v64, v76, v77
	v_mul_f32_e32 v77, v73, v73
	v_mul_f32_e32 v88, v85, v85
	v_fmac_f32_e32 v66, v76, v76
	v_fmac_f32_e32 v67, v78, v78
	v_fmac_f32_e32 v86, v68, v68
	v_fmac_f32_e32 v87, v70, v70
	v_cvt_pk_bf16_f32 v65, v78, v79
	v_mul_f32_e32 v79, v75, v75
	v_mul_f32_e32 v89, v83, v83
	v_fmac_f32_e32 v77, v72, v72
	v_fmac_f32_e32 v88, v84, v84
	v_add_f32_e32 v66, v66, v67
	v_add_f32_e32 v67, v86, v87
	v_fmac_f32_e32 v79, v74, v74
	v_fmac_f32_e32 v89, v82, v82
	v_add_f32_e32 v66, v77, v66
	v_add_f32_e32 v67, v88, v67
	v_add_f32_e32 v66, v79, v66
	v_add_f32_e32 v67, v89, v67
	v_add_f32_e32 v76, v66, v67
	ds_bpermute_b32 v77, v156, v76
	v_cvt_pk_bf16_f32 v66, v72, v73
	v_cvt_pk_bf16_f32 v67, v74, v75
	global_store_dwordx4 v[90:91], v[64:67], off
	s_waitcnt lgkmcnt(0)
	s_nop 0
	v_add_f32_e32 v64, v76, v77
	ds_bpermute_b32 v65, v155, v64
	v_cvt_pk_bf16_f32 v66, v68, v69
	v_cvt_pk_bf16_f32 v67, v70, v71
	v_cvt_pk_bf16_f32 v68, v84, v85
	v_cvt_pk_bf16_f32 v69, v82, v83
	global_store_dwordx4 v[90:91], v[66:69], off offset:256
	s_and_saveexec_b64 s[26:27], s[6:7]
	s_cbranch_execz .LBB0_1989
; __device__ __forceinline__ void fx_add(float* p, size_t idx, float s) { atomicAdd((unsigned long long*)p + idx, (unsigned long long)(long long)(s * 4294967296.0f)); }
; __device__ __forceinline__ unsigned cvtpk(float lo, float hi) { f32x2v_ v = {lo, hi}; bf16x2v_ b = __builtin_convertvector(v, bf16x2v_); return __builtin_bit_cast(unsigned, b); }
;     __device__ __forceinline__ void operator()(const f32x4 (&acc)[2][2][4][2], const Unit& u, int wr, int wc, int fr, int fq) const {
;     ...
;             for (int m = 0; m < 4; ++m) { const int row = row0 + ai * HALF + m * 16; const size_t off = (size_t)row * 1024 + col0; float s = 0.f;
; #pragma unroll
;                 for (int bj = 0; bj < 2; ++bj) { f32x4 a0, a1;
;                     if (xin32) { const float* p = xin32 + off + bj * HALF; a0 = *(const f32x4*)p; a1 = *(const f32x4*)(p + 4); }
;                     else { const u32x4 w = *(const u32x4*)(xb + off + bj * HALF);
;                         a0 = (f32x4){__uint_as_float(w.x << 16), __uint_as_float(w.x & 0xffff0000u), __uint_as_float(w.y << 16), __uint_as_float(w.y & 0xffff0000u)};
;                         a1 = (f32x4){__uint_as_float(w.z << 16), __uint_as_float(w.z & 0xffff0000u), __uint_as_float(w.w << 16), __uint_as_float(w.w & 0xffff0000u)}; }
;                     const f32x4 v0 = a0 + acc[ai][bj][m][0] * alpha, v1 = a1 + acc[ai][bj][m][1] * alpha;
;                     u32x4 w; w.x = cvtpk(v0[0], v0[1]); w.y = cvtpk(v0[2], v0[3]); w.z = cvtpk(v1[0], v1[1]); w.w = cvtpk(v1[2], v1[3]);
;                     *(u32x4*)(xb + off + bj * HALF) = w;
;                     s += (v0[0] * v0[0] + v0[1] * v0[1]) + (v0[2] * v0[2] + v0[3] * v0[3]) + (v1[0] * v1[0] + v1[1] * v1[1]) + (v1[2] * v1[2] + v1[3] * v1[3]); }
;                 s += __shfl_xor(s, 16); s += __shfl_xor(s, 32);
;                 if (fq == 0) fx_add(ssout, row, s); }
	s_waitcnt lgkmcnt(0)
	v_add_f32_e32 v64, v64, v65
	v_mul_f32_e32 v64, 0x4f800000, v64
	v_trunc_f32_e32 v64, v64
	v_mul_f32_e64 v65, |v64|, s47
	v_floor_f32_e32 v65, v65
	v_fma_f32 v66, v65, s48, |v64|
	v_cvt_u32_f32_e32 v66, v66
	v_cvt_u32_f32_e32 v65, v65
	v_ashrrev_i32_e32 v67, 31, v64
	v_xor_b32_e32 v64, v66, v67
	v_xor_b32_e32 v65, v65, v67
	v_sub_co_u32_e32 v64, vcc, v64, v67
	s_nop 1
	v_subb_co_u32_e32 v65, vcc, v65, v67, vcc
	v_lshl_add_u64 v[66:67], v[80:81], 3, s[10:11]
	global_atomic_add_x2 v[66:67], v[64:65], off
.LBB0_1989:
	s_or_b64 exec, exec, s[26:27]
	v_add_u32_e32 v64, 0x80, v146
	s_waitcnt lgkmcnt(0)
	v_ashrrev_i32_e32 v65, 31, v64
	v_lshlrev_b64 v[66:67], 11, v[64:65]
	v_lshl_add_u64 v[66:67], s[22:23], 0, v[66:67]
	v_lshl_add_u64 v[74:75], v[144:145], 1, v[66:67]
	s_nop 0
	s_nop 0
	s_waitcnt vmcnt(19)
	v_lshlrev_b32_e32 v76, 16, v182
	v_and_b32_e32 v77, 0xffff0000, v182
	v_lshlrev_b32_e32 v66, 16, v183
	v_and_b32_e32 v67, 0xffff0000, v183
	s_waitcnt vmcnt(18)
	v_lshlrev_b32_e32 v80, 16, v186
	v_and_b32_e32 v81, 0xffff0000, v186
	v_lshlrev_b32_e32 v70, 16, v187
	v_and_b32_e32 v71, 0xffff0000, v187
	v_lshlrev_b32_e32 v78, 16, v184
	v_and_b32_e32 v79, 0xffff0000, v184
	v_lshlrev_b32_e32 v68, 16, v185
	v_and_b32_e32 v69, 0xffff0000, v185
	v_lshlrev_b32_e32 v82, 16, v188
	v_and_b32_e32 v83, 0xffff0000, v188
	v_lshlrev_b32_e32 v72, 16, v189
	v_and_b32_e32 v73, 0xffff0000, v189
	v_pk_fma_f32 v[62:63], v[62:63], 0.5, v[66:67] op_sel_hi:[1,0,1]
	v_pk_fma_f32 v[60:61], v[60:61], 0.5, v[76:77] op_sel_hi:[1,0,1]
	v_pk_fma_f32 v[54:55], v[54:55], 0.5, v[70:71] op_sel_hi:[1,0,1]
	v_pk_fma_f32 v[52:53], v[52:53], 0.5, v[80:81] op_sel_hi:[1,0,1]
	v_pk_fma_f32 v[58:59], v[58:59], 0.5, v[68:69] op_sel_hi:[1,0,1]
	v_pk_fma_f32 v[56:57], v[56:57], 0.5, v[78:79] op_sel_hi:[1,0,1]
	v_pk_fma_f32 v[66:67], v[50:51], 0.5, v[72:73] op_sel_hi:[1,0,1]
	v_pk_fma_f32 v[68:69], v[48:49], 0.5, v[82:83] op_sel_hi:[1,0,1]
	v_mul_f32_e32 v50, v61, v61
	v_mul_f32_e32 v51, v63, v63
	v_mul_f32_e32 v70, v53, v53
	v_mul_f32_e32 v71, v55, v55
	v_cvt_pk_bf16_f32 v48, v60, v61
	v_mul_f32_e32 v61, v57, v57
	v_mul_f32_e32 v72, v69, v69
	v_fmac_f32_e32 v50, v60, v60
	v_fmac_f32_e32 v51, v62, v62
	v_fmac_f32_e32 v70, v52, v52
	v_fmac_f32_e32 v71, v54, v54
	v_cvt_pk_bf16_f32 v49, v62, v63
	v_mul_f32_e32 v63, v59, v59
	v_mul_f32_e32 v73, v67, v67
	v_fmac_f32_e32 v61, v56, v56
	v_fmac_f32_e32 v72, v68, v68
	v_add_f32_e32 v50, v50, v51
	v_add_f32_e32 v51, v70, v71
	v_fmac_f32_e32 v63, v58, v58
	v_fmac_f32_e32 v73, v66, v66
	v_add_f32_e32 v50, v61, v50
	v_add_f32_e32 v51, v72, v51
	v_add_f32_e32 v50, v63, v50
	v_add_f32_e32 v51, v73, v51
	v_add_f32_e32 v60, v50, v51
	ds_bpermute_b32 v61, v156, v60
	v_cvt_pk_bf16_f32 v50, v56, v57
	v_cvt_pk_bf16_f32 v51, v58, v59
	global_store_dwordx4 v[74:75], v[48:51], off
	s_waitcnt lgkmcnt(0)
	s_nop 0
	v_add_f32_e32 v48, v60, v61
	ds_bpermute_b32 v49, v155, v48
	v_cvt_pk_bf16_f32 v50, v52, v53
	v_cvt_pk_bf16_f32 v51, v54, v55
	v_cvt_pk_bf16_f32 v52, v68, v69
	v_cvt_pk_bf16_f32 v53, v66, v67
	global_store_dwordx4 v[74:75], v[50:53], off offset:256
	s_and_saveexec_b64 s[26:27], s[6:7]
	s_cbranch_execz .LBB0_1991
	s_waitcnt lgkmcnt(0)
	v_add_f32_e32 v48, v48, v49
	v_mul_f32_e32 v48, 0x4f800000, v48
	v_trunc_f32_e32 v48, v48
	v_mul_f32_e64 v49, |v48|, s47
	v_floor_f32_e32 v49, v49
	v_fma_f32 v50, v49, s48, |v48|
	v_cvt_u32_f32_e32 v50, v50
	v_cvt_u32_f32_e32 v49, v49
	v_ashrrev_i32_e32 v51, 31, v48
	v_xor_b32_e32 v48, v50, v51
	v_xor_b32_e32 v49, v49, v51
	v_sub_co_u32_e32 v48, vcc, v48, v51
	s_nop 1
	v_subb_co_u32_e32 v49, vcc, v49, v51, vcc
	v_lshl_add_u64 v[50:51], v[64:65], 3, s[10:11]
	global_atomic_add_x2 v[50:51], v[48:49], off
.LBB0_1991:
	s_or_b64 exec, exec, s[26:27]
	v_add_u32_e32 v48, 0x90, v146
	s_waitcnt lgkmcnt(0)
	v_ashrrev_i32_e32 v49, 31, v48
	v_lshlrev_b64 v[50:51], 11, v[48:49]
	v_lshl_add_u64 v[50:51], s[22:23], 0, v[50:51]
	v_lshl_add_u64 v[58:59], v[144:145], 1, v[50:51]
	s_nop 0
	s_nop 0
	s_waitcnt vmcnt(17)
	v_lshlrev_b32_e32 v60, 16, v190
	v_and_b32_e32 v61, 0xffff0000, v190
	v_lshlrev_b32_e32 v50, 16, v191
	v_and_b32_e32 v51, 0xffff0000, v191
	s_waitcnt vmcnt(16)
	v_lshlrev_b32_e32 v64, 16, v194
	v_and_b32_e32 v65, 0xffff0000, v194
	v_lshlrev_b32_e32 v54, 16, v195
	v_and_b32_e32 v55, 0xffff0000, v195
	v_lshlrev_b32_e32 v62, 16, v192
	v_and_b32_e32 v63, 0xffff0000, v192
	v_lshlrev_b32_e32 v52, 16, v193
	v_and_b32_e32 v53, 0xffff0000, v193
	v_lshlrev_b32_e32 v66, 16, v196
	v_and_b32_e32 v67, 0xffff0000, v196
	v_lshlrev_b32_e32 v56, 16, v197
	v_and_b32_e32 v57, 0xffff0000, v197
	v_pk_fma_f32 v[46:47], v[46:47], 0.5, v[50:51] op_sel_hi:[1,0,1]
	v_pk_fma_f32 v[44:45], v[44:45], 0.5, v[60:61] op_sel_hi:[1,0,1]
	v_pk_fma_f32 v[38:39], v[38:39], 0.5, v[54:55] op_sel_hi:[1,0,1]
	v_pk_fma_f32 v[36:37], v[36:37], 0.5, v[64:65] op_sel_hi:[1,0,1]
	v_pk_fma_f32 v[42:43], v[42:43], 0.5, v[52:53] op_sel_hi:[1,0,1]
	v_pk_fma_f32 v[40:41], v[40:41], 0.5, v[62:63] op_sel_hi:[1,0,1]
	v_pk_fma_f32 v[50:51], v[34:35], 0.5, v[56:57] op_sel_hi:[1,0,1]
	v_pk_fma_f32 v[52:53], v[32:33], 0.5, v[66:67] op_sel_hi:[1,0,1]
	v_mul_f32_e32 v34, v45, v45
	v_mul_f32_e32 v35, v47, v47
	v_mul_f32_e32 v54, v37, v37
	v_mul_f32_e32 v55, v39, v39
	v_cvt_pk_bf16_f32 v32, v44, v45
	v_mul_f32_e32 v45, v41, v41
	v_mul_f32_e32 v56, v53, v53
	v_fmac_f32_e32 v34, v44, v44
	v_fmac_f32_e32 v35, v46, v46
	v_fmac_f32_e32 v54, v36, v36
	v_fmac_f32_e32 v55, v38, v38
	v_cvt_pk_bf16_f32 v33, v46, v47
	v_mul_f32_e32 v47, v43, v43
	v_mul_f32_e32 v57, v51, v51
	v_fmac_f32_e32 v45, v40, v40
	v_fmac_f32_e32 v56, v52, v52
	v_add_f32_e32 v34, v34, v35
	v_add_f32_e32 v35, v54, v55
	v_fmac_f32_e32 v47, v42, v42
	v_fmac_f32_e32 v57, v50, v50
	v_add_f32_e32 v34, v45, v34
	v_add_f32_e32 v35, v56, v35
	v_add_f32_e32 v34, v47, v34
	v_add_f32_e32 v35, v57, v35
	v_add_f32_e32 v44, v34, v35
	ds_bpermute_b32 v45, v156, v44
	v_cvt_pk_bf16_f32 v34, v40, v41
	v_cvt_pk_bf16_f32 v35, v42, v43
	global_store_dwordx4 v[58:59], v[32:35], off
	s_waitcnt lgkmcnt(0)
	s_nop 0
	v_add_f32_e32 v32, v44, v45
	ds_bpermute_b32 v33, v155, v32
	v_cvt_pk_bf16_f32 v34, v36, v37
	v_cvt_pk_bf16_f32 v35, v38, v39
	v_cvt_pk_bf16_f32 v36, v52, v53
	v_cvt_pk_bf16_f32 v37, v50, v51
	global_store_dwordx4 v[58:59], v[34:37], off offset:256
	s_and_saveexec_b64 s[26:27], s[6:7]
	s_cbranch_execz .LBB0_1993
	s_waitcnt lgkmcnt(0)
	v_add_f32_e32 v32, v32, v33
	v_mul_f32_e32 v32, 0x4f800000, v32
	v_trunc_f32_e32 v32, v32
	v_mul_f32_e64 v33, |v32|, s47
	v_floor_f32_e32 v33, v33
	v_fma_f32 v34, v33, s48, |v32|
	v_cvt_u32_f32_e32 v34, v34
	v_cvt_u32_f32_e32 v33, v33
	v_ashrrev_i32_e32 v35, 31, v32
	v_xor_b32_e32 v32, v34, v35
	v_xor_b32_e32 v33, v33, v35
	v_sub_co_u32_e32 v32, vcc, v32, v35
	s_nop 1
	v_subb_co_u32_e32 v33, vcc, v33, v35, vcc
	v_lshl_add_u64 v[34:35], v[48:49], 3, s[10:11]
	global_atomic_add_x2 v[34:35], v[32:33], off
; __device__ __forceinline__ void fx_add(float* p, size_t idx, float s) { atomicAdd((unsigned long long*)p + idx, (unsigned long long)(long long)(s * 4294967296.0f)); }
; __device__ __forceinline__ unsigned cvtpk(float lo, float hi) { f32x2v_ v = {lo, hi}; bf16x2v_ b = __builtin_convertvector(v, bf16x2v_); return __builtin_bit_cast(unsigned, b); }
;     __device__ __forceinline__ void operator()(const f32x4 (&acc)[2][2][4][2], const Unit& u, int wr, int wc, int fr, int fq) const {
;     ...
;             for (int m = 0; m < 4; ++m) { const int row = row0 + ai * HALF + m * 16; const size_t off = (size_t)row * 1024 + col0; float s = 0.f;
; #pragma unroll
;                 for (int bj = 0; bj < 2; ++bj) { f32x4 a0, a1;
;                     if (xin32) { const float* p = xin32 + off + bj * HALF; a0 = *(const f32x4*)p; a1 = *(const f32x4*)(p + 4); }
;                     else { const u32x4 w = *(const u32x4*)(xb + off + bj * HALF);
;                         a0 = (f32x4){__uint_as_float(w.x << 16), __uint_as_float(w.x & 0xffff0000u), __uint_as_float(w.y << 16), __uint_as_float(w.y & 0xffff0000u)};
;                         a1 = (f32x4){__uint_as_float(w.z << 16), __uint_as_float(w.z & 0xffff0000u), __uint_as_float(w.w << 16), __uint_as_float(w.w & 0xffff0000u)}; }
;                     const f32x4 v0 = a0 + acc[ai][bj][m][0] * alpha, v1 = a1 + acc[ai][bj][m][1] * alpha;
;                     u32x4 w; w.x = cvtpk(v0[0], v0[1]); w.y = cvtpk(v0[2], v0[3]); w.z = cvtpk(v1[0], v1[1]); w.w = cvtpk(v1[2], v1[3]);
;                     *(u32x4*)(xb + off + bj * HALF) = w;
;                     s += (v0[0] * v0[0] + v0[1] * v0[1]) + (v0[2] * v0[2] + v0[3] * v0[3]) + (v1[0] * v1[0] + v1[1] * v1[1]) + (v1[2] * v1[2] + v1[3] * v1[3]); }
;                 s += __shfl_xor(s, 16); s += __shfl_xor(s, 32);
;                 if (fq == 0) fx_add(ssout, row, s); }
.LBB0_1993:
	s_or_b64 exec, exec, s[26:27]
	v_add_u32_e32 v32, 0xa0, v146
	s_waitcnt lgkmcnt(0)
	v_ashrrev_i32_e32 v33, 31, v32
	v_lshlrev_b64 v[34:35], 11, v[32:33]
	v_lshl_add_u64 v[34:35], s[22:23], 0, v[34:35]
	v_lshl_add_u64 v[42:43], v[144:145], 1, v[34:35]
	s_nop 0
	s_nop 0
	s_waitcnt vmcnt(15)
	v_lshlrev_b32_e32 v44, 16, v208
	v_and_b32_e32 v45, 0xffff0000, v208
	v_lshlrev_b32_e32 v34, 16, v209
	v_and_b32_e32 v35, 0xffff0000, v209
	s_waitcnt vmcnt(14)
	v_lshlrev_b32_e32 v48, 16, v212
	v_and_b32_e32 v49, 0xffff0000, v212
	v_lshlrev_b32_e32 v38, 16, v213
	v_and_b32_e32 v39, 0xffff0000, v213
	v_lshlrev_b32_e32 v46, 16, v210
	v_and_b32_e32 v47, 0xffff0000, v210
	v_lshlrev_b32_e32 v36, 16, v211
	v_and_b32_e32 v37, 0xffff0000, v211
	v_lshlrev_b32_e32 v50, 16, v214
	v_and_b32_e32 v51, 0xffff0000, v214
	v_lshlrev_b32_e32 v40, 16, v215
	v_and_b32_e32 v41, 0xffff0000, v215
	v_pk_fma_f32 v[30:31], v[30:31], 0.5, v[34:35] op_sel_hi:[1,0,1]
	v_pk_fma_f32 v[28:29], v[28:29], 0.5, v[44:45] op_sel_hi:[1,0,1]
	v_pk_fma_f32 v[22:23], v[22:23], 0.5, v[38:39] op_sel_hi:[1,0,1]
	v_pk_fma_f32 v[20:21], v[20:21], 0.5, v[48:49] op_sel_hi:[1,0,1]
	v_pk_fma_f32 v[26:27], v[26:27], 0.5, v[36:37] op_sel_hi:[1,0,1]
	v_pk_fma_f32 v[24:25], v[24:25], 0.5, v[46:47] op_sel_hi:[1,0,1]
	v_pk_fma_f32 v[34:35], v[18:19], 0.5, v[40:41] op_sel_hi:[1,0,1]
	v_pk_fma_f32 v[36:37], v[16:17], 0.5, v[50:51] op_sel_hi:[1,0,1]
	v_mul_f32_e32 v18, v29, v29
	v_mul_f32_e32 v19, v31, v31
	v_mul_f32_e32 v38, v21, v21
	v_mul_f32_e32 v39, v23, v23
	v_cvt_pk_bf16_f32 v16, v28, v29
	v_mul_f32_e32 v29, v25, v25
	v_mul_f32_e32 v40, v37, v37
	v_fmac_f32_e32 v18, v28, v28
	v_fmac_f32_e32 v19, v30, v30
	v_fmac_f32_e32 v38, v20, v20
	v_fmac_f32_e32 v39, v22, v22
	v_cvt_pk_bf16_f32 v17, v30, v31
	v_mul_f32_e32 v31, v27, v27
	v_mul_f32_e32 v41, v35, v35
	v_fmac_f32_e32 v29, v24, v24
	v_fmac_f32_e32 v40, v36, v36
	v_add_f32_e32 v18, v18, v19
	v_add_f32_e32 v19, v38, v39
	v_fmac_f32_e32 v31, v26, v26
	v_fmac_f32_e32 v41, v34, v34
	v_add_f32_e32 v18, v29, v18
	v_add_f32_e32 v19, v40, v19
	v_add_f32_e32 v18, v31, v18
	v_add_f32_e32 v19, v41, v19
	v_add_f32_e32 v28, v18, v19
	ds_bpermute_b32 v29, v156, v28
	v_cvt_pk_bf16_f32 v18, v24, v25
	v_cvt_pk_bf16_f32 v19, v26, v27
	global_store_dwordx4 v[42:43], v[16:19], off
	s_waitcnt lgkmcnt(0)
	s_nop 0
	v_add_f32_e32 v16, v28, v29
	ds_bpermute_b32 v17, v155, v16
	v_cvt_pk_bf16_f32 v18, v20, v21
	v_cvt_pk_bf16_f32 v19, v22, v23
	v_cvt_pk_bf16_f32 v20, v36, v37
	v_cvt_pk_bf16_f32 v21, v34, v35
	global_store_dwordx4 v[42:43], v[18:21], off offset:256
	s_and_saveexec_b64 s[26:27], s[6:7]
	s_cbranch_execz .LBB0_1995
	s_waitcnt lgkmcnt(0)
	v_add_f32_e32 v16, v16, v17
	v_mul_f32_e32 v16, 0x4f800000, v16
	v_trunc_f32_e32 v16, v16
	v_mul_f32_e64 v17, |v16|, s47
	v_floor_f32_e32 v17, v17
	v_fma_f32 v18, v17, s48, |v16|
	v_cvt_u32_f32_e32 v18, v18
	v_cvt_u32_f32_e32 v17, v17
	v_ashrrev_i32_e32 v19, 31, v16
	v_xor_b32_e32 v16, v18, v19
	v_xor_b32_e32 v17, v17, v19
	v_sub_co_u32_e32 v16, vcc, v16, v19
	s_nop 1
	v_subb_co_u32_e32 v17, vcc, v17, v19, vcc
	v_lshl_add_u64 v[18:19], v[32:33], 3, s[10:11]
	global_atomic_add_x2 v[18:19], v[16:17], off
.LBB0_1995:
	s_or_b64 exec, exec, s[26:27]
	v_add_u32_e32 v16, 0xb0, v146
	s_waitcnt lgkmcnt(0)
	v_ashrrev_i32_e32 v17, 31, v16
	v_lshlrev_b64 v[18:19], 11, v[16:17]
	v_lshl_add_u64 v[18:19], s[22:23], 0, v[18:19]
	v_lshl_add_u64 v[26:27], v[144:145], 1, v[18:19]
	s_nop 0
	s_nop 0
	s_waitcnt vmcnt(13)
	v_lshlrev_b32_e32 v28, 16, v216
	v_and_b32_e32 v29, 0xffff0000, v216
	v_lshlrev_b32_e32 v18, 16, v217
	v_and_b32_e32 v19, 0xffff0000, v217
	s_waitcnt vmcnt(12)
	v_lshlrev_b32_e32 v32, 16, v220
	v_and_b32_e32 v33, 0xffff0000, v220
	v_lshlrev_b32_e32 v22, 16, v221
	v_and_b32_e32 v23, 0xffff0000, v221
	v_lshlrev_b32_e32 v30, 16, v218
	v_and_b32_e32 v31, 0xffff0000, v218
	v_lshlrev_b32_e32 v20, 16, v219
	v_and_b32_e32 v21, 0xffff0000, v219
	v_lshlrev_b32_e32 v34, 16, v222
	v_and_b32_e32 v35, 0xffff0000, v222
	v_lshlrev_b32_e32 v24, 16, v223
	v_and_b32_e32 v25, 0xffff0000, v223
	v_pk_fma_f32 v[14:15], v[14:15], 0.5, v[18:19] op_sel_hi:[1,0,1]
	v_pk_fma_f32 v[12:13], v[12:13], 0.5, v[28:29] op_sel_hi:[1,0,1]
	v_pk_fma_f32 v[6:7], v[6:7], 0.5, v[22:23] op_sel_hi:[1,0,1]
	v_pk_fma_f32 v[4:5], v[4:5], 0.5, v[32:33] op_sel_hi:[1,0,1]
	v_pk_fma_f32 v[10:11], v[10:11], 0.5, v[20:21] op_sel_hi:[1,0,1]
	v_pk_fma_f32 v[8:9], v[8:9], 0.5, v[30:31] op_sel_hi:[1,0,1]
	v_pk_fma_f32 v[18:19], v[2:3], 0.5, v[24:25] op_sel_hi:[1,0,1]
	v_pk_fma_f32 v[20:21], v[0:1], 0.5, v[34:35] op_sel_hi:[1,0,1]
	v_mul_f32_e32 v2, v13, v13
	v_mul_f32_e32 v3, v15, v15
	v_mul_f32_e32 v22, v5, v5
	v_mul_f32_e32 v23, v7, v7
	v_cvt_pk_bf16_f32 v0, v12, v13
	v_mul_f32_e32 v13, v9, v9
	v_mul_f32_e32 v24, v21, v21
	v_fmac_f32_e32 v2, v12, v12
	v_fmac_f32_e32 v3, v14, v14
	v_fmac_f32_e32 v22, v4, v4
	v_fmac_f32_e32 v23, v6, v6
	v_cvt_pk_bf16_f32 v1, v14, v15
	v_mul_f32_e32 v15, v11, v11
	v_mul_f32_e32 v25, v19, v19
	v_fmac_f32_e32 v13, v8, v8
	v_fmac_f32_e32 v24, v20, v20
	v_add_f32_e32 v2, v2, v3
	v_add_f32_e32 v3, v22, v23
	v_fmac_f32_e32 v15, v10, v10
	v_fmac_f32_e32 v25, v18, v18
	v_add_f32_e32 v2, v13, v2
	v_add_f32_e32 v3, v24, v3
	v_add_f32_e32 v2, v15, v2
	v_add_f32_e32 v3, v25, v3
	v_add_f32_e32 v12, v2, v3
	ds_bpermute_b32 v13, v156, v12
	v_cvt_pk_bf16_f32 v2, v8, v9
	v_cvt_pk_bf16_f32 v3, v10, v11
	global_store_dwordx4 v[26:27], v[0:3], off
	s_waitcnt lgkmcnt(0)
	s_nop 0
	v_add_f32_e32 v0, v12, v13
	ds_bpermute_b32 v1, v155, v0
	v_cvt_pk_bf16_f32 v2, v4, v5
	v_cvt_pk_bf16_f32 v3, v6, v7
	v_cvt_pk_bf16_f32 v4, v20, v21
	v_cvt_pk_bf16_f32 v5, v18, v19
	global_store_dwordx4 v[26:27], v[2:5], off offset:256
	s_and_saveexec_b64 s[26:27], s[6:7]
	s_cbranch_execz .LBB0_1997
	s_waitcnt lgkmcnt(0)
	v_add_f32_e32 v0, v0, v1
	v_mul_f32_e32 v0, 0x4f800000, v0
	v_trunc_f32_e32 v0, v0
	v_mul_f32_e64 v1, |v0|, s47
	v_floor_f32_e32 v1, v1
	v_fma_f32 v2, v1, s48, |v0|
	v_cvt_u32_f32_e32 v2, v2
	v_cvt_u32_f32_e32 v1, v1
	v_ashrrev_i32_e32 v3, 31, v0
	v_xor_b32_e32 v0, v2, v3
	v_xor_b32_e32 v1, v1, v3
	v_sub_co_u32_e32 v0, vcc, v0, v3
	s_nop 1
	v_subb_co_u32_e32 v1, vcc, v1, v3, vcc
	v_lshl_add_u64 v[2:3], v[16:17], 3, s[10:11]
	global_atomic_add_x2 v[2:3], v[0:1], off

; __global__ void __launch_bounds__(NWAVES * 64, 2) mk_fwd(Args args) {
	.amdhsa_kernel _Z6mk_fwd4Args
		.amdhsa_group_segment_fixed_size 0
		.amdhsa_private_segment_fixed_size 0
		.amdhsa_kernarg_size 464
		.amdhsa_user_sgpr_count 2
		.amdhsa_user_sgpr_dispatch_ptr 0
		.amdhsa_user_sgpr_queue_ptr 0
		.amdhsa_user_sgpr_kernarg_segment_ptr 1
		.amdhsa_user_sgpr_dispatch_id 0
		.amdhsa_user_sgpr_kernarg_preload_length 0
		.amdhsa_user_sgpr_kernarg_preload_offset 0
		.amdhsa_user_sgpr_private_segment_size 0
		.amdhsa_uses_dynamic_stack 0
		.amdhsa_enable_private_segment 0
		.amdhsa_system_sgpr_workgroup_id_x 1
		.amdhsa_system_sgpr_workgroup_id_y 0
		.amdhsa_system_sgpr_workgroup_id_z 0
		.amdhsa_system_sgpr_workgroup_info 0
		.amdhsa_system_vgpr_workitem_id 2
		.amdhsa_next_free_vgpr 251
		.amdhsa_next_free_sgpr 102
		.amdhsa_accum_offset 252
		.amdhsa_reserve_vcc 1
		.amdhsa_float_round_mode_32 0
		.amdhsa_float_round_mode_16_64 0
		.amdhsa_float_denorm_mode_32 3
		.amdhsa_float_denorm_mode_16_64 3
		.amdhsa_dx10_clamp 1
		.amdhsa_ieee_mode 1
		.amdhsa_fp16_overflow 0
		.amdhsa_tg_split 0
		.amdhsa_exception_fp_ieee_invalid_op 0
		.amdhsa_exception_fp_denorm_src 0
		.amdhsa_exception_fp_ieee_div_zero 0
		.amdhsa_exception_fp_ieee_overflow 0
		.amdhsa_exception_fp_ieee_underflow 0
		.amdhsa_exception_fp_ieee_inexact 0
		.amdhsa_exception_int_div_zero 0
	.end_amdhsa_kernel

; __global__ void __launch_bounds__(NWAVES * 64, 2) mk_fwd(Args args) {
.Lfunc_end0:
	.size	_Z6mk_fwd4Args, .Lfunc_end0-_Z6mk_fwd4Args
	.set _Z6mk_fwd4Args.num_vgpr, 251
	.set _Z6mk_fwd4Args.num_agpr, 0
	.set _Z6mk_fwd4Args.numbered_sgpr, 102
	.set _Z6mk_fwd4Args.num_named_barrier, 0
	.set _Z6mk_fwd4Args.private_seg_size, 0
	.set _Z6mk_fwd4Args.uses_vcc, 1
	.set _Z6mk_fwd4Args.uses_flat_scratch, 0
	.set _Z6mk_fwd4Args.has_dyn_sized_stack, 0
	.set _Z6mk_fwd4Args.has_recursion, 0
	.set _Z6mk_fwd4Args.has_indirect_call, 0

; __global__ void __launch_bounds__(NWAVES * 64, 2) mk_fwd(Args args) {
amdhsa.kernels:
  - .agpr_count:     0
    .args:
      - .offset:         0
        .size:           208
        .value_kind:     by_value
      - .offset:         208
        .size:           4
        .value_kind:     hidden_block_count_x
      - .offset:         212
        .size:           4
        .value_kind:     hidden_block_count_y
      - .offset:         216
        .size:           4
        .value_kind:     hidden_block_count_z
      - .offset:         220
        .size:           2
        .value_kind:     hidden_group_size_x
      - .offset:         222
        .size:           2
        .value_kind:     hidden_group_size_y
      - .offset:         224
        .size:           2
        .value_kind:     hidden_group_size_z
      - .offset:         226
        .size:           2
        .value_kind:     hidden_remainder_x
      - .offset:         228
        .size:           2
        .value_kind:     hidden_remainder_y
      - .offset:         230
        .size:           2
        .value_kind:     hidden_remainder_z
      - .offset:         248
        .size:           8
        .value_kind:     hidden_global_offset_x
      - .offset:         256
        .size:           8
        .value_kind:     hidden_global_offset_y
      - .offset:         264
        .size:           8
        .value_kind:     hidden_global_offset_z
      - .offset:         272
        .size:           2
        .value_kind:     hidden_grid_dims
      - .offset:         296
        .size:           8
        .value_kind:     hidden_multigrid_sync_arg
      - .offset:         328
        .size:           4
        .value_kind:     hidden_dynamic_lds_size
    .group_segment_fixed_size: 0
    .kernarg_segment_align: 8
    .kernarg_segment_size: 464
    .language:       OpenCL C
    .language_version:
      - 2
      - 0
    .max_flat_workgroup_size: 512
    .name:           _Z6mk_fwd4Args
    .private_segment_fixed_size: 0
    .sgpr_count:     108
    .sgpr_spill_count: 23
    .symbol:         _Z6mk_fwd4Args.kd
    .uniform_work_group_size: 1
    .uses_dynamic_stack: false
    .vgpr_count:     251
    .vgpr_spill_count: 0
    .wavefront_size: 64
